# GEMM epilogue stores marked non-temporal to keep A/B tiles L2-resident
# baseline (speedup 1.0000x reference)
; __device__ __forceinline__ v4u pack8(const float (&f)[8]) { v4u w; w.x = cvt_pk_bf16(f[0], f[1]); w.y = cvt_pk_bf16(f[2], f[3]); w.z = cvt_pk_bf16(f[4], f[5]); w.w = cvt_pk_bf16(f[6], f[7]); return w; }
; __device__ __forceinline__ float sigmoidf_(float x) { return rcpf_(1.f + __expf(-x)); }
; __device__ __forceinline__ float tanhf_(float x) { return 1.f - 2.f * rcpf_(1.f + __expf(2.f * x)); }
;     __device__ __forceinline__ void operator()(const f32x4 (&acc)[2][2][4][2], const Unit& u, int wr, int wc, int fr, int fq) const {
;     ...
;                     if (c < KL2) {
;                         const int kd = c < 64 ? 1 : ((c >= 128 && c < 288) ? 2 : 0);
; #pragma unroll
;                         for (int ai = 0; ai < 2; ++ai)
; #pragma unroll
;                             for (int m = 0; m < 4; ++m) if (rrow[ai][m] >= 0) { float o[8];
; #pragma unroll
;                                 for (int n = 0; n < 2; ++n)
; #pragma unroll
;                                     for (int j = 0; j < 4; ++j) { const float x = acc[ai][bj][m][n][j]; o[n * 4 + j] = kd == 1 ? tanhf_(x) : (kd == 2 ? sigmoidf_(x) : x); }
;                                 *(v4u*)(A2 + (size_t)rrow[ai][m] * KL2 + c) = pack8(o); }
.LBB0_693:
	s_or_b64 exec, exec, s[44:45]
	v_mad_u64_u32 v[152:153], s[18:19], v144, s83, v[146:147]
	v_cvt_pk_bf16_f32 v148, v0, v133
	v_cvt_pk_bf16_f32 v149, v135, v137
	v_cvt_pk_bf16_f32 v150, v139, v141
	v_cvt_pk_bf16_f32 v151, v143, v145
	global_store_dwordx4 v[152:153], v[148:151], off nt
	s_or_b64 exec, exec, s[10:11]
	v_cmp_lt_i32_e32 vcc, -1, v142
	s_and_saveexec_b64 s[10:11], vcc
	s_cbranch_execnz .LBB0_888

; __device__ __forceinline__ v4u pack8(const float (&f)[8]) { v4u w; w.x = cvt_pk_bf16(f[0], f[1]); w.y = cvt_pk_bf16(f[2], f[3]); w.z = cvt_pk_bf16(f[4], f[5]); w.w = cvt_pk_bf16(f[6], f[7]); return w; }
; __device__ __forceinline__ float sigmoidf_(float x) { return rcpf_(1.f + __expf(-x)); }
; __device__ __forceinline__ float tanhf_(float x) { return 1.f - 2.f * rcpf_(1.f + __expf(2.f * x)); }
;     __device__ __forceinline__ void operator()(const f32x4 (&acc)[2][2][4][2], const Unit& u, int wr, int wc, int fr, int fq) const {
;     ...
;                     if (c < KL2) {
;                         const int kd = c < 64 ? 1 : ((c >= 128 && c < 288) ? 2 : 0);
; #pragma unroll
;                         for (int ai = 0; ai < 2; ++ai)
; #pragma unroll
;                             for (int m = 0; m < 4; ++m) if (rrow[ai][m] >= 0) { float o[8];
; #pragma unroll
;                                 for (int n = 0; n < 2; ++n)
; #pragma unroll
;                                     for (int j = 0; j < 4; ++j) { const float x = acc[ai][bj][m][n][j]; o[n * 4 + j] = kd == 1 ? tanhf_(x) : (kd == 2 ? sigmoidf_(x) : x); }
;                                 *(v4u*)(A2 + (size_t)rrow[ai][m] * KL2 + c) = pack8(o); }
.LBB0_743:
	s_or_b64 exec, exec, s[44:45]
	v_mad_u64_u32 v[152:153], s[18:19], v140, s83, v[146:147]
	v_cvt_pk_bf16_f32 v148, v0, v133
	v_cvt_pk_bf16_f32 v149, v135, v137
	v_cvt_pk_bf16_f32 v150, v139, v141
	v_cvt_pk_bf16_f32 v151, v143, v145
	global_store_dwordx4 v[152:153], v[148:151], off nt
	s_or_b64 exec, exec, s[10:11]
	v_cmp_lt_i32_e32 vcc, -1, v138
	s_and_saveexec_b64 s[10:11], vcc
	s_cbranch_execnz .LBB0_938

; __device__ __forceinline__ v4u pack8(const float (&f)[8]) { v4u w; w.x = cvt_pk_bf16(f[0], f[1]); w.y = cvt_pk_bf16(f[2], f[3]); w.z = cvt_pk_bf16(f[4], f[5]); w.w = cvt_pk_bf16(f[6], f[7]); return w; }
; __device__ __forceinline__ float sigmoidf_(float x) { return rcpf_(1.f + __expf(-x)); }
; __device__ __forceinline__ float tanhf_(float x) { return 1.f - 2.f * rcpf_(1.f + __expf(2.f * x)); }
;     __device__ __forceinline__ void operator()(const f32x4 (&acc)[2][2][4][2], const Unit& u, int wr, int wc, int fr, int fq) const {
;     ...
;                     if (c < KL2) {
;                         const int kd = c < 64 ? 1 : ((c >= 128 && c < 288) ? 2 : 0);
; #pragma unroll
;                         for (int ai = 0; ai < 2; ++ai)
; #pragma unroll
;                             for (int m = 0; m < 4; ++m) if (rrow[ai][m] >= 0) { float o[8];
; #pragma unroll
;                                 for (int n = 0; n < 2; ++n)
; #pragma unroll
;                                     for (int j = 0; j < 4; ++j) { const float x = acc[ai][bj][m][n][j]; o[n * 4 + j] = kd == 1 ? tanhf_(x) : (kd == 2 ? sigmoidf_(x) : x); }
;                                 *(v4u*)(A2 + (size_t)rrow[ai][m] * KL2 + c) = pack8(o); }
.LBB0_793:
	s_or_b64 exec, exec, s[44:45]
	v_mad_u64_u32 v[152:153], s[18:19], v136, s83, v[146:147]
	v_cvt_pk_bf16_f32 v148, v0, v133
	v_cvt_pk_bf16_f32 v149, v135, v137
	v_cvt_pk_bf16_f32 v150, v139, v141
	v_cvt_pk_bf16_f32 v151, v143, v145
	global_store_dwordx4 v[152:153], v[148:151], off nt
	s_or_b64 exec, exec, s[10:11]
	v_cmp_lt_i32_e32 vcc, -1, v134
	s_and_saveexec_b64 s[10:11], vcc
	s_cbranch_execnz .LBB0_988

; __device__ __forceinline__ v4u pack8(const float (&f)[8]) { v4u w; w.x = cvt_pk_bf16(f[0], f[1]); w.y = cvt_pk_bf16(f[2], f[3]); w.z = cvt_pk_bf16(f[4], f[5]); w.w = cvt_pk_bf16(f[6], f[7]); return w; }
; __device__ __forceinline__ float sigmoidf_(float x) { return rcpf_(1.f + __expf(-x)); }
; __device__ __forceinline__ float tanhf_(float x) { return 1.f - 2.f * rcpf_(1.f + __expf(2.f * x)); }
;     __device__ __forceinline__ void operator()(const f32x4 (&acc)[2][2][4][2], const Unit& u, int wr, int wc, int fr, int fq) const {
;     ...
;                     if (c < KL2) {
;                         const int kd = c < 64 ? 1 : ((c >= 128 && c < 288) ? 2 : 0);
; #pragma unroll
;                         for (int ai = 0; ai < 2; ++ai)
; #pragma unroll
;                             for (int m = 0; m < 4; ++m) if (rrow[ai][m] >= 0) { float o[8];
; #pragma unroll
;                                 for (int n = 0; n < 2; ++n)
; #pragma unroll
;                                     for (int j = 0; j < 4; ++j) { const float x = acc[ai][bj][m][n][j]; o[n * 4 + j] = kd == 1 ? tanhf_(x) : (kd == 2 ? sigmoidf_(x) : x); }
;                                 *(v4u*)(A2 + (size_t)rrow[ai][m] * KL2 + c) = pack8(o); }
.LBB0_843:
	s_or_b64 exec, exec, s[44:45]
	v_mad_u64_u32 v[152:153], s[18:19], v132, s83, v[146:147]
	v_cvt_pk_bf16_f32 v148, v0, v133
	v_cvt_pk_bf16_f32 v149, v135, v137
	v_cvt_pk_bf16_f32 v150, v139, v141
	v_cvt_pk_bf16_f32 v151, v143, v145
	global_store_dwordx4 v[152:153], v[148:151], off nt
	s_or_b64 exec, exec, s[10:11]
	s_waitcnt lgkmcnt(0)
	v_cmp_lt_i32_e32 vcc, -1, v130
	s_and_b64 exec, exec, vcc
	s_cbranch_execz .LBB0_1087
	s_branch .LBB0_1038

; __device__ __forceinline__ unsigned cvt_pk_bf16(float lo, float hi) { unsigned r; asm("v_cvt_pk_bf16_f32 %0, %1, %2" : "=v"(r) : "v"(lo), "v"(hi)); return r; }
;     __device__ __forceinline__ void operator()(const f32x4 (&acc)[2][2][4][2], const Unit& u, int wr, int wc, int fr, int fq) const {
;     ...
;             for (int am = 0; am < 4; ++am) { const int ai = am >> 1, mb = (am & 1) * 2;
;                 v4u xv[2][2];
; #pragma unroll
;                 for (int mm = 0; mm < 2; ++mm) { const int m = mb + mm; const bf16* rp = (const bf16*)(ws + WS_XB) + (size_t)(row0 + ai * 128 + m * 16) * D + colw;
; #pragma unroll
;                     for (int bj = 0; bj < 2; ++bj) xv[mm][bj] = *(const v4u*)(rp + bj * 128); }
; #pragma unroll
;                 for (int mm = 0; mm < 2; ++mm) { const int m = mb + mm;
;                     const int row = row0 + ai * 128 + m * 16;
;                     bf16* xb = (bf16*)(ws + WS_XB) + (size_t)row * D + colw;
;                     float ssq = 0.f;
; #pragma unroll
;                     for (int bj = 0; bj < 2; ++bj) {
;                         const auto s0 = __builtin_amdgcn_permlane16_swap(xv[mm][bj].x, xv[mm][bj].z, false, false), s1 = __builtin_amdgcn_permlane16_swap(xv[mm][bj].y, xv[mm][bj].w, false, false);
;                         const unsigned xn[2][2] = {{s0[0], s1[0]}, {s0[1], s1[1]}};
;                         unsigned wn[2][2];
; #pragma unroll
;                         for (int n = 0; n < 2; ++n) {
;                             const f32x4 v = (f32x4){bf_lo(xn[n][0]), bf_hi(xn[n][0]), bf_lo(xn[n][1]), bf_hi(xn[n][1])} + acc[ai][bj][m][n] * amul;
;                             wn[n][0] = cvt_pk_bf16(v.x, v.y); wn[n][1] = cvt_pk_bf16(v.z, v.w);
;                             if (slot >= 0) ssq += (v.x * v.x + v.y * v.y) + (v.z * v.z + v.w * v.w); }
;                         const auto t0 = __builtin_amdgcn_permlane16_swap(wn[0][0], wn[1][0], false, false), t1 = __builtin_amdgcn_permlane16_swap(wn[0][1], wn[1][1], false, false);
;                         *(v4u*)(xb + bj * 128) = (v4u){t0[0], t1[0], t0[1], t1[1]};
;                     }
;                     if (slot >= 0) { ssq += shfl_xor_l(ssq, 16, fq * 16 + fr); ssq += shfl_xor_l(ssq, 32, fq * 16 + fr); if (fq == 0) ((float*)(ws + WS_SS))[((size_t)slot * M + row) * 16 + u.pn * 4 + wc] = ssq; }
;                 }
.LBB0_851:
	v_lshl_or_b32 v138, s87, 8, v244
	v_ashrrev_i32_e32 v139, 31, v138
	v_lshlrev_b64 v[150:151], 1, v[138:139]
	v_ashrrev_i32_e32 v211, 31, v210
	v_lshl_add_u64 v[140:141], s[90:91], 0, v[150:151]
	v_lshlrev_b64 v[152:153], 11, v[210:211]
	s_waitcnt lgkmcnt(0)
	v_lshl_add_u64 v[130:131], v[140:141], 0, v[152:153]
	global_load_dwordx4 v[146:149], v[130:131], off
	global_load_dwordx4 v[154:157], v[130:131], off offset:256
	v_or_b32_e32 v142, 16, v210
	v_ashrrev_i32_e32 v143, 31, v142
	v_lshlrev_b64 v[144:145], 11, v[142:143]
	v_lshl_add_u64 v[130:131], v[140:141], 0, v[144:145]
	global_load_dwordx4 v[134:137], v[130:131], off
	s_nop 0
	global_load_dwordx4 v[130:133], v[130:131], off offset:256
	v_lshl_add_u64 v[152:153], s[90:91], 0, v[152:153]
	v_lshl_add_u64 v[166:167], v[152:153], 0, v[150:151]
	s_andn2_b64 vcc, exec, s[36:37]
	s_waitcnt vmcnt(0)
	v_mov_b32_e32 v0, v148
	s_nop 1
	v_permlane16_swap_b32_e32 v146, v0
	v_mov_b32_e32 v160, v149
	s_nop 1
	v_permlane16_swap_b32_e32 v147, v160
	v_lshlrev_b32_e32 v148, 16, v146
	v_and_b32_e32 v149, 0xffff0000, v146
	v_lshlrev_b32_e32 v146, 16, v147
	v_and_b32_e32 v147, 0xffff0000, v147
	v_pk_add_f32 v[150:151], v[122:123], v[148:149]
	v_lshlrev_b32_e32 v152, 16, v0
	v_and_b32_e32 v153, 0xffff0000, v0
	v_lshlrev_b32_e32 v148, 16, v160
	v_and_b32_e32 v149, 0xffff0000, v160
	v_mov_b32_e32 v0, v156
	v_pk_add_f32 v[146:147], v[124:125], v[146:147]
	v_cvt_pk_bf16_f32 v158, v150, v151
	v_pk_add_f32 v[148:149], v[116:117], v[148:149]
	v_cvt_pk_bf16_f32 v159, v146, v147
	v_pk_add_f32 v[152:153], v[114:115], v[152:153]
	v_cvt_pk_bf16_f32 v161, v148, v149
	v_permlane16_swap_b32_e32 v154, v0
	v_cvt_pk_bf16_f32 v160, v152, v153
	v_mov_b32_e32 v164, v157
	v_permlane16_swap_b32_e32 v158, v160
	v_permlane16_swap_b32_e32 v159, v161
	v_permlane16_swap_b32_e32 v155, v164
	v_lshlrev_b32_e32 v156, 16, v154
	v_and_b32_e32 v157, 0xffff0000, v154
	global_store_dwordx4 v[166:167], v[158:161], off nt
	v_lshlrev_b32_e32 v154, 16, v155
	v_and_b32_e32 v155, 0xffff0000, v155
	v_pk_add_f32 v[158:159], v[126:127], v[156:157]
	v_lshlrev_b32_e32 v160, 16, v0
	v_and_b32_e32 v161, 0xffff0000, v0
	v_lshlrev_b32_e32 v156, 16, v164
	v_and_b32_e32 v157, 0xffff0000, v164
	v_pk_add_f32 v[154:155], v[128:129], v[154:155]
	v_cvt_pk_bf16_f32 v162, v158, v159
	v_pk_add_f32 v[156:157], v[120:121], v[156:157]
	v_cvt_pk_bf16_f32 v163, v154, v155
	v_pk_add_f32 v[160:161], v[118:119], v[160:161]
	v_cvt_pk_bf16_f32 v165, v156, v157
	v_cndmask_b32_e64 v0, 0, 1, s[36:37]
	v_cvt_pk_bf16_f32 v164, v160, v161
	v_permlane16_swap_b32_e32 v163, v165
	v_permlane16_swap_b32_e32 v162, v164
	v_cmp_ne_u32_e64 s[10:11], 1, v0
	global_store_dwordx4 v[166:167], v[162:165], off offset:256 nt
	s_cbranch_vccnz .LBB0_855
	v_mul_f32_e32 v0, v151, v151
	v_mul_f32_e32 v147, v147, v147
	v_fmac_f32_e32 v0, v150, v150
	v_fmac_f32_e32 v147, v146, v146
	v_add_f32_e32 v0, v0, v147
	v_mul_f32_e32 v146, v153, v153
	v_mul_f32_e32 v147, v149, v149
	v_fmac_f32_e32 v146, v152, v152
	v_fmac_f32_e32 v147, v148, v148
	v_add_f32_e32 v146, v146, v147
	v_add_f32_e32 v0, v0, v146
	v_mul_f32_e32 v146, v159, v159
	v_mul_f32_e32 v147, v155, v155
	v_fmac_f32_e32 v146, v158, v158
	v_fmac_f32_e32 v147, v154, v154
	v_add_f32_e32 v146, v146, v147
	v_add_f32_e32 v0, v0, v146
	v_mul_f32_e32 v146, v161, v161
	v_mul_f32_e32 v147, v157, v157
	v_fmac_f32_e32 v146, v160, v160
	v_fmac_f32_e32 v147, v156, v156
	v_add_f32_e32 v146, v146, v147
	v_add_f32_e32 v0, v146, v0
	ds_bpermute_b32 v146, v241, v0
	s_waitcnt lgkmcnt(0)
	v_add_f32_e32 v0, v0, v146
	ds_bpermute_b32 v146, v242, v0
	s_and_saveexec_b64 s[0:1], s[6:7]
	s_cbranch_execz .LBB0_854
	s_waitcnt lgkmcnt(0)
	v_add_f32_e32 v0, v0, v146
	v_lshl_add_u64 v[146:147], s[38:39], 0, v[210:211]
	v_readlane_b32 s18, v252, 23
	s_lshl_b32 s2, s87, 2
	v_lshlrev_b64 v[146:147], 6, v[146:147]
	v_readlane_b32 s19, v252, 24
	s_ashr_i32 s3, s2, 31
	s_lshl_b32 s94, s65, 2
	v_lshl_add_u64 v[146:147], s[18:19], 0, v[146:147]
	v_lshl_add_u64 v[146:147], s[2:3], 2, v[146:147]
	v_lshl_add_u64 v[146:147], v[146:147], 0, s[94:95]
	global_store_dword v[146:147], v0, off nt

; __device__ __forceinline__ unsigned cvt_pk_bf16(float lo, float hi) { unsigned r; asm("v_cvt_pk_bf16_f32 %0, %1, %2" : "=v"(r) : "v"(lo), "v"(hi)); return r; }
;     __device__ __forceinline__ void operator()(const f32x4 (&acc)[2][2][4][2], const Unit& u, int wr, int wc, int fr, int fq) const {
;     ...
;             for (int am = 0; am < 4; ++am) { const int ai = am >> 1, mb = (am & 1) * 2;
;                 v4u xv[2][2];
; #pragma unroll
;                 for (int mm = 0; mm < 2; ++mm) { const int m = mb + mm; const bf16* rp = (const bf16*)(ws + WS_XB) + (size_t)(row0 + ai * 128 + m * 16) * D + colw;
; #pragma unroll
;                     for (int bj = 0; bj < 2; ++bj) xv[mm][bj] = *(const v4u*)(rp + bj * 128); }
; #pragma unroll
;                 for (int mm = 0; mm < 2; ++mm) { const int m = mb + mm;
;                     const int row = row0 + ai * 128 + m * 16;
;                     bf16* xb = (bf16*)(ws + WS_XB) + (size_t)row * D + colw;
;                     float ssq = 0.f;
; #pragma unroll
;                     for (int bj = 0; bj < 2; ++bj) {
;                         const auto s0 = __builtin_amdgcn_permlane16_swap(xv[mm][bj].x, xv[mm][bj].z, false, false), s1 = __builtin_amdgcn_permlane16_swap(xv[mm][bj].y, xv[mm][bj].w, false, false);
;                         const unsigned xn[2][2] = {{s0[0], s1[0]}, {s0[1], s1[1]}};
;                         unsigned wn[2][2];
; #pragma unroll
;                         for (int n = 0; n < 2; ++n) {
;                             const f32x4 v = (f32x4){bf_lo(xn[n][0]), bf_hi(xn[n][0]), bf_lo(xn[n][1]), bf_hi(xn[n][1])} + acc[ai][bj][m][n] * amul;
;                             wn[n][0] = cvt_pk_bf16(v.x, v.y); wn[n][1] = cvt_pk_bf16(v.z, v.w);
;                             if (slot >= 0) ssq += (v.x * v.x + v.y * v.y) + (v.z * v.z + v.w * v.w); }
;                         const auto t0 = __builtin_amdgcn_permlane16_swap(wn[0][0], wn[1][0], false, false), t1 = __builtin_amdgcn_permlane16_swap(wn[0][1], wn[1][1], false, false);
;                         *(v4u*)(xb + bj * 128) = (v4u){t0[0], t1[0], t0[1], t1[1]};
;                     }
;                     if (slot >= 0) { ssq += shfl_xor_l(ssq, 16, fq * 16 + fr); ssq += shfl_xor_l(ssq, 32, fq * 16 + fr); if (fq == 0) ((float*)(ws + WS_SS))[((size_t)slot * M + row) * 16 + u.pn * 4 + wc] = ssq; }
;                 }
.LBB0_855:
	v_lshl_add_u64 v[144:145], s[90:91], 0, v[144:145]
	v_lshl_add_u64 v[156:157], v[138:139], 1, v[144:145]
	v_mov_b32_e32 v0, v136
	v_mov_b32_e32 v145, v137
	s_nop 0
	v_permlane16_swap_b32_e32 v134, v0
	v_permlane16_swap_b32_e32 v135, v145
	v_lshlrev_b32_e32 v136, 16, v134
	v_and_b32_e32 v137, 0xffff0000, v134
	v_lshlrev_b32_e32 v134, 16, v135
	v_and_b32_e32 v135, 0xffff0000, v135
	s_waitcnt lgkmcnt(0)
	v_lshlrev_b32_e32 v146, 16, v0
	v_and_b32_e32 v147, 0xffff0000, v0
	v_lshlrev_b32_e32 v144, 16, v145
	v_and_b32_e32 v145, 0xffff0000, v145
	v_pk_add_f32 v[134:135], v[108:109], v[134:135]
	v_pk_add_f32 v[136:137], v[106:107], v[136:137]
	v_cvt_pk_bf16_f32 v149, v134, v135
	v_pk_add_f32 v[144:145], v[100:101], v[144:145]
	v_cvt_pk_bf16_f32 v148, v136, v137
	v_pk_add_f32 v[146:147], v[98:99], v[146:147]
	v_cvt_pk_bf16_f32 v151, v144, v145
	v_mov_b32_e32 v0, v132
	v_cvt_pk_bf16_f32 v150, v146, v147
	v_permlane16_swap_b32_e32 v149, v151
	v_permlane16_swap_b32_e32 v148, v150
	global_store_dwordx4 v[156:157], v[148:151], off nt
	v_permlane16_swap_b32_e32 v130, v0
	s_nop 0
	v_mov_b32_e32 v149, v133
	s_nop 1
	v_permlane16_swap_b32_e32 v131, v149
	v_lshlrev_b32_e32 v132, 16, v130
	v_and_b32_e32 v133, 0xffff0000, v130
	v_lshlrev_b32_e32 v130, 16, v131
	v_and_b32_e32 v131, 0xffff0000, v131
	v_lshlrev_b32_e32 v150, 16, v0
	v_and_b32_e32 v151, 0xffff0000, v0
	v_lshlrev_b32_e32 v148, 16, v149
	v_and_b32_e32 v149, 0xffff0000, v149
	v_pk_add_f32 v[130:131], v[112:113], v[130:131]
	v_pk_add_f32 v[132:133], v[110:111], v[132:133]
	v_cvt_pk_bf16_f32 v153, v130, v131
	v_pk_add_f32 v[148:149], v[104:105], v[148:149]
	v_cvt_pk_bf16_f32 v152, v132, v133
	v_pk_add_f32 v[150:151], v[102:103], v[150:151]
	v_cvt_pk_bf16_f32 v155, v148, v149
	s_and_b64 vcc, exec, s[10:11]
	v_cvt_pk_bf16_f32 v154, v150, v151
	v_permlane16_swap_b32_e32 v153, v155
	v_permlane16_swap_b32_e32 v152, v154
	global_store_dwordx4 v[156:157], v[152:155], off offset:256 nt
	s_cbranch_vccnz .LBB0_859
	v_mul_f32_e32 v0, v137, v137
	v_mul_f32_e32 v135, v135, v135
	v_fmac_f32_e32 v0, v136, v136
	v_fmac_f32_e32 v135, v134, v134
	v_add_f32_e32 v0, v0, v135
	v_mul_f32_e32 v134, v147, v147
	v_mul_f32_e32 v135, v145, v145
	v_fmac_f32_e32 v134, v146, v146
	v_fmac_f32_e32 v135, v144, v144
	v_mul_f32_e32 v133, v133, v133
	v_mul_f32_e32 v131, v131, v131
	v_add_f32_e32 v134, v134, v135
	v_fmac_f32_e32 v133, v132, v132
	v_fmac_f32_e32 v131, v130, v130
	v_add_f32_e32 v0, v0, v134
	v_add_f32_e32 v130, v133, v131
	v_add_f32_e32 v0, v0, v130
	v_mul_f32_e32 v130, v151, v151
	v_mul_f32_e32 v131, v149, v149
	v_fmac_f32_e32 v130, v150, v150
	v_fmac_f32_e32 v131, v148, v148
	v_add_f32_e32 v130, v130, v131
	v_add_f32_e32 v0, v130, v0
	ds_bpermute_b32 v130, v241, v0
	s_waitcnt lgkmcnt(0)
	v_add_f32_e32 v0, v0, v130
	ds_bpermute_b32 v130, v242, v0
	s_and_saveexec_b64 s[0:1], s[6:7]
	s_cbranch_execz .LBB0_858
	s_waitcnt lgkmcnt(0)
	v_add_f32_e32 v0, v0, v130
	v_lshl_add_u64 v[130:131], s[38:39], 0, v[142:143]
	v_readlane_b32 s18, v252, 23
	s_lshl_b32 s2, s87, 2
	v_lshlrev_b64 v[130:131], 6, v[130:131]
	v_readlane_b32 s19, v252, 24
	s_ashr_i32 s3, s2, 31
	s_lshl_b32 s94, s65, 2
	v_lshl_add_u64 v[130:131], s[18:19], 0, v[130:131]
	v_lshl_add_u64 v[130:131], s[2:3], 2, v[130:131]
	v_lshl_add_u64 v[130:131], v[130:131], 0, s[94:95]
	global_store_dword v[130:131], v0, off nt

; __device__ __forceinline__ unsigned cvt_pk_bf16(float lo, float hi) { unsigned r; asm("v_cvt_pk_bf16_f32 %0, %1, %2" : "=v"(r) : "v"(lo), "v"(hi)); return r; }
;     __device__ __forceinline__ void operator()(const f32x4 (&acc)[2][2][4][2], const Unit& u, int wr, int wc, int fr, int fq) const {
;     ...
;             for (int am = 0; am < 4; ++am) { const int ai = am >> 1, mb = (am & 1) * 2;
;                 v4u xv[2][2];
; #pragma unroll
;                 for (int mm = 0; mm < 2; ++mm) { const int m = mb + mm; const bf16* rp = (const bf16*)(ws + WS_XB) + (size_t)(row0 + ai * 128 + m * 16) * D + colw;
; #pragma unroll
;                     for (int bj = 0; bj < 2; ++bj) xv[mm][bj] = *(const v4u*)(rp + bj * 128); }
; #pragma unroll
;                 for (int mm = 0; mm < 2; ++mm) { const int m = mb + mm;
;                     const int row = row0 + ai * 128 + m * 16;
;                     bf16* xb = (bf16*)(ws + WS_XB) + (size_t)row * D + colw;
;                     float ssq = 0.f;
; #pragma unroll
;                     for (int bj = 0; bj < 2; ++bj) {
;                         const auto s0 = __builtin_amdgcn_permlane16_swap(xv[mm][bj].x, xv[mm][bj].z, false, false), s1 = __builtin_amdgcn_permlane16_swap(xv[mm][bj].y, xv[mm][bj].w, false, false);
;                         const unsigned xn[2][2] = {{s0[0], s1[0]}, {s0[1], s1[1]}};
;                         unsigned wn[2][2];
; #pragma unroll
;                         for (int n = 0; n < 2; ++n) {
;                             const f32x4 v = (f32x4){bf_lo(xn[n][0]), bf_hi(xn[n][0]), bf_lo(xn[n][1]), bf_hi(xn[n][1])} + acc[ai][bj][m][n] * amul;
;                             wn[n][0] = cvt_pk_bf16(v.x, v.y); wn[n][1] = cvt_pk_bf16(v.z, v.w);
;                             if (slot >= 0) ssq += (v.x * v.x + v.y * v.y) + (v.z * v.z + v.w * v.w); }
;                         const auto t0 = __builtin_amdgcn_permlane16_swap(wn[0][0], wn[1][0], false, false), t1 = __builtin_amdgcn_permlane16_swap(wn[0][1], wn[1][1], false, false);
;                         *(v4u*)(xb + bj * 128) = (v4u){t0[0], t1[0], t0[1], t1[1]};
;                     }
;                     if (slot >= 0) { ssq += shfl_xor_l(ssq, 16, fq * 16 + fr); ssq += shfl_xor_l(ssq, 32, fq * 16 + fr); if (fq == 0) ((float*)(ws + WS_SS))[((size_t)slot * M + row) * 16 + u.pn * 4 + wc] = ssq; }
;                 }
.LBB0_859:
	v_or_b32_e32 v146, 32, v210
	v_ashrrev_i32_e32 v147, 31, v146
	v_lshlrev_b64 v[152:153], 11, v[146:147]
	s_waitcnt lgkmcnt(0)
	v_lshl_add_u64 v[130:131], v[140:141], 0, v[152:153]
	global_load_dwordx4 v[148:151], v[130:131], off
	global_load_dwordx4 v[156:159], v[130:131], off offset:256
	v_or_b32_e32 v142, 48, v210
	v_ashrrev_i32_e32 v143, 31, v142
	v_lshlrev_b64 v[144:145], 11, v[142:143]
	v_lshl_add_u64 v[130:131], v[140:141], 0, v[144:145]
	global_load_dwordx4 v[134:137], v[130:131], off
	s_nop 0
	global_load_dwordx4 v[130:133], v[130:131], off offset:256
	v_lshl_add_u64 v[152:153], s[90:91], 0, v[152:153]
	v_lshl_add_u64 v[168:169], v[138:139], 1, v[152:153]
	s_and_b64 vcc, exec, s[10:11]
	s_waitcnt vmcnt(3)
	v_mov_b32_e32 v0, v150
	s_nop 1
	v_permlane16_swap_b32_e32 v148, v0
	v_mov_b32_e32 v162, v151
	s_nop 1
	v_permlane16_swap_b32_e32 v149, v162
	v_lshlrev_b32_e32 v150, 16, v148
	v_and_b32_e32 v151, 0xffff0000, v148
	v_lshlrev_b32_e32 v148, 16, v149
	v_and_b32_e32 v149, 0xffff0000, v149
	v_pk_add_f32 v[152:153], v[90:91], v[150:151]
	v_lshlrev_b32_e32 v154, 16, v0
	v_and_b32_e32 v155, 0xffff0000, v0
	v_lshlrev_b32_e32 v150, 16, v162
	v_and_b32_e32 v151, 0xffff0000, v162
	s_waitcnt vmcnt(2)
	v_mov_b32_e32 v0, v158
	v_pk_add_f32 v[148:149], v[92:93], v[148:149]
	v_cvt_pk_bf16_f32 v160, v152, v153
	v_pk_add_f32 v[150:151], v[84:85], v[150:151]
	v_cvt_pk_bf16_f32 v161, v148, v149
	v_pk_add_f32 v[154:155], v[82:83], v[154:155]
	v_cvt_pk_bf16_f32 v163, v150, v151
	v_permlane16_swap_b32_e32 v156, v0
	v_cvt_pk_bf16_f32 v162, v154, v155
	v_mov_b32_e32 v166, v159
	v_permlane16_swap_b32_e32 v160, v162
	v_permlane16_swap_b32_e32 v161, v163
	v_permlane16_swap_b32_e32 v157, v166
	v_lshlrev_b32_e32 v158, 16, v156
	v_and_b32_e32 v159, 0xffff0000, v156
	global_store_dwordx4 v[168:169], v[160:163], off nt
	v_lshlrev_b32_e32 v156, 16, v157
	v_and_b32_e32 v157, 0xffff0000, v157
	v_pk_add_f32 v[160:161], v[94:95], v[158:159]
	v_lshlrev_b32_e32 v162, 16, v0
	v_and_b32_e32 v163, 0xffff0000, v0
	v_lshlrev_b32_e32 v158, 16, v166
	v_and_b32_e32 v159, 0xffff0000, v166
	v_pk_add_f32 v[156:157], v[96:97], v[156:157]
	v_cvt_pk_bf16_f32 v164, v160, v161
	v_pk_add_f32 v[158:159], v[88:89], v[158:159]
	v_cvt_pk_bf16_f32 v165, v156, v157
	v_pk_add_f32 v[162:163], v[86:87], v[162:163]
	v_cvt_pk_bf16_f32 v167, v158, v159
	s_nop 0
	v_cvt_pk_bf16_f32 v166, v162, v163
	v_permlane16_swap_b32_e32 v165, v167
	v_permlane16_swap_b32_e32 v164, v166
	global_store_dwordx4 v[168:169], v[164:167], off offset:256 nt
	s_cbranch_vccnz .LBB0_863
	v_mul_f32_e32 v0, v153, v153
	v_mul_f32_e32 v149, v149, v149
	v_fmac_f32_e32 v0, v152, v152
	v_fmac_f32_e32 v149, v148, v148
	v_add_f32_e32 v0, v0, v149
	v_mul_f32_e32 v148, v155, v155
	v_mul_f32_e32 v149, v151, v151
	v_fmac_f32_e32 v148, v154, v154
	v_fmac_f32_e32 v149, v150, v150
	v_add_f32_e32 v148, v148, v149
	v_add_f32_e32 v0, v0, v148
	v_mul_f32_e32 v148, v161, v161
	v_mul_f32_e32 v149, v157, v157
	v_fmac_f32_e32 v148, v160, v160
	v_fmac_f32_e32 v149, v156, v156
	v_add_f32_e32 v148, v148, v149
	v_add_f32_e32 v0, v0, v148
	v_mul_f32_e32 v148, v163, v163
	v_mul_f32_e32 v149, v159, v159
	v_fmac_f32_e32 v148, v162, v162
	v_fmac_f32_e32 v149, v158, v158
	v_add_f32_e32 v148, v148, v149
	v_add_f32_e32 v0, v148, v0
	ds_bpermute_b32 v148, v241, v0
	s_waitcnt lgkmcnt(0)
	v_add_f32_e32 v0, v0, v148
	ds_bpermute_b32 v148, v242, v0
	s_and_saveexec_b64 s[0:1], s[6:7]
	s_cbranch_execz .LBB0_862
	v_lshl_add_u64 v[146:147], s[38:39], 0, v[146:147]
	v_readlane_b32 s18, v252, 23
	s_lshl_b32 s2, s87, 2
	v_lshlrev_b64 v[146:147], 6, v[146:147]
	v_readlane_b32 s19, v252, 24
	s_ashr_i32 s3, s2, 31
	s_lshl_b32 s94, s65, 2
	v_lshl_add_u64 v[146:147], s[18:19], 0, v[146:147]
	v_lshl_add_u64 v[146:147], s[2:3], 2, v[146:147]
	s_waitcnt lgkmcnt(0)
	v_add_f32_e32 v0, v0, v148
	v_lshl_add_u64 v[146:147], v[146:147], 0, s[94:95]
	global_store_dword v[146:147], v0, off nt

; __device__ __forceinline__ unsigned cvt_pk_bf16(float lo, float hi) { unsigned r; asm("v_cvt_pk_bf16_f32 %0, %1, %2" : "=v"(r) : "v"(lo), "v"(hi)); return r; }
;     __device__ __forceinline__ void operator()(const f32x4 (&acc)[2][2][4][2], const Unit& u, int wr, int wc, int fr, int fq) const {
;     ...
;             for (int am = 0; am < 4; ++am) { const int ai = am >> 1, mb = (am & 1) * 2;
;                 v4u xv[2][2];
; #pragma unroll
;                 for (int mm = 0; mm < 2; ++mm) { const int m = mb + mm; const bf16* rp = (const bf16*)(ws + WS_XB) + (size_t)(row0 + ai * 128 + m * 16) * D + colw;
; #pragma unroll
;                     for (int bj = 0; bj < 2; ++bj) xv[mm][bj] = *(const v4u*)(rp + bj * 128); }
; #pragma unroll
;                 for (int mm = 0; mm < 2; ++mm) { const int m = mb + mm;
;                     const int row = row0 + ai * 128 + m * 16;
;                     bf16* xb = (bf16*)(ws + WS_XB) + (size_t)row * D + colw;
;                     float ssq = 0.f;
; #pragma unroll
;                     for (int bj = 0; bj < 2; ++bj) {
;                         const auto s0 = __builtin_amdgcn_permlane16_swap(xv[mm][bj].x, xv[mm][bj].z, false, false), s1 = __builtin_amdgcn_permlane16_swap(xv[mm][bj].y, xv[mm][bj].w, false, false);
;                         const unsigned xn[2][2] = {{s0[0], s1[0]}, {s0[1], s1[1]}};
;                         unsigned wn[2][2];
; #pragma unroll
;                         for (int n = 0; n < 2; ++n) {
;                             const f32x4 v = (f32x4){bf_lo(xn[n][0]), bf_hi(xn[n][0]), bf_lo(xn[n][1]), bf_hi(xn[n][1])} + acc[ai][bj][m][n] * amul;
;                             wn[n][0] = cvt_pk_bf16(v.x, v.y); wn[n][1] = cvt_pk_bf16(v.z, v.w);
;                             if (slot >= 0) ssq += (v.x * v.x + v.y * v.y) + (v.z * v.z + v.w * v.w); }
;                         const auto t0 = __builtin_amdgcn_permlane16_swap(wn[0][0], wn[1][0], false, false), t1 = __builtin_amdgcn_permlane16_swap(wn[0][1], wn[1][1], false, false);
;                         *(v4u*)(xb + bj * 128) = (v4u){t0[0], t1[0], t0[1], t1[1]};
;                     }
;                     if (slot >= 0) { ssq += shfl_xor_l(ssq, 16, fq * 16 + fr); ssq += shfl_xor_l(ssq, 32, fq * 16 + fr); if (fq == 0) ((float*)(ws + WS_SS))[((size_t)slot * M + row) * 16 + u.pn * 4 + wc] = ssq; }
;                 }
.LBB0_863:
	v_lshl_add_u64 v[144:145], s[90:91], 0, v[144:145]
	v_lshl_add_u64 v[156:157], v[138:139], 1, v[144:145]
	s_waitcnt vmcnt(3)
	v_mov_b32_e32 v0, v136
	v_mov_b32_e32 v145, v137
	s_nop 0
	v_permlane16_swap_b32_e32 v134, v0
	v_permlane16_swap_b32_e32 v135, v145
	v_lshlrev_b32_e32 v136, 16, v134
	v_and_b32_e32 v137, 0xffff0000, v134
	v_lshlrev_b32_e32 v134, 16, v135
	v_and_b32_e32 v135, 0xffff0000, v135
	v_lshlrev_b32_e32 v146, 16, v0
	v_and_b32_e32 v147, 0xffff0000, v0
	v_lshlrev_b32_e32 v144, 16, v145
	v_and_b32_e32 v145, 0xffff0000, v145
	v_pk_add_f32 v[134:135], v[76:77], v[134:135]
	v_pk_add_f32 v[136:137], v[74:75], v[136:137]
	v_cvt_pk_bf16_f32 v149, v134, v135
	v_pk_add_f32 v[144:145], v[68:69], v[144:145]
	s_waitcnt lgkmcnt(0)
	v_cvt_pk_bf16_f32 v148, v136, v137
	v_pk_add_f32 v[146:147], v[66:67], v[146:147]
	v_cvt_pk_bf16_f32 v151, v144, v145
	s_waitcnt vmcnt(2)
	v_mov_b32_e32 v0, v132
	v_cvt_pk_bf16_f32 v150, v146, v147
	v_permlane16_swap_b32_e32 v149, v151
	v_permlane16_swap_b32_e32 v148, v150
	global_store_dwordx4 v[156:157], v[148:151], off nt
	v_permlane16_swap_b32_e32 v130, v0
	s_nop 0
	v_mov_b32_e32 v149, v133
	s_nop 1
	v_permlane16_swap_b32_e32 v131, v149
	v_lshlrev_b32_e32 v132, 16, v130
	v_and_b32_e32 v133, 0xffff0000, v130
	v_lshlrev_b32_e32 v130, 16, v131
	v_and_b32_e32 v131, 0xffff0000, v131
	v_lshlrev_b32_e32 v150, 16, v0
	v_and_b32_e32 v151, 0xffff0000, v0
	v_lshlrev_b32_e32 v148, 16, v149
	v_and_b32_e32 v149, 0xffff0000, v149
	v_pk_add_f32 v[130:131], v[80:81], v[130:131]
	v_pk_add_f32 v[132:133], v[78:79], v[132:133]
	v_cvt_pk_bf16_f32 v153, v130, v131
	v_pk_add_f32 v[148:149], v[72:73], v[148:149]
	v_cvt_pk_bf16_f32 v152, v132, v133
	v_pk_add_f32 v[150:151], v[70:71], v[150:151]
	v_cvt_pk_bf16_f32 v155, v148, v149
	s_and_b64 vcc, exec, s[10:11]
	v_cvt_pk_bf16_f32 v154, v150, v151
	v_permlane16_swap_b32_e32 v153, v155
	v_permlane16_swap_b32_e32 v152, v154
	global_store_dwordx4 v[156:157], v[152:155], off offset:256 nt
	s_cbranch_vccnz .LBB0_867
	v_mul_f32_e32 v0, v137, v137
	v_mul_f32_e32 v135, v135, v135
	v_fmac_f32_e32 v0, v136, v136
	v_fmac_f32_e32 v135, v134, v134
	v_add_f32_e32 v0, v0, v135
	v_mul_f32_e32 v134, v147, v147
	v_mul_f32_e32 v135, v145, v145
	v_fmac_f32_e32 v134, v146, v146
	v_fmac_f32_e32 v135, v144, v144
	v_mul_f32_e32 v133, v133, v133
	v_mul_f32_e32 v131, v131, v131
	v_add_f32_e32 v134, v134, v135
	v_fmac_f32_e32 v133, v132, v132
	v_fmac_f32_e32 v131, v130, v130
	v_add_f32_e32 v0, v0, v134
	v_add_f32_e32 v130, v133, v131
	v_add_f32_e32 v0, v0, v130
	v_mul_f32_e32 v130, v151, v151
	v_mul_f32_e32 v131, v149, v149
	v_fmac_f32_e32 v130, v150, v150
	v_fmac_f32_e32 v131, v148, v148
	v_add_f32_e32 v130, v130, v131
	v_add_f32_e32 v0, v130, v0
	ds_bpermute_b32 v130, v241, v0
	s_waitcnt lgkmcnt(0)
	v_add_f32_e32 v0, v0, v130
	ds_bpermute_b32 v130, v242, v0
	s_and_saveexec_b64 s[0:1], s[6:7]
	s_cbranch_execz .LBB0_866
	s_waitcnt lgkmcnt(0)
	v_add_f32_e32 v0, v0, v130
	v_lshl_add_u64 v[130:131], s[38:39], 0, v[142:143]
	v_readlane_b32 s18, v252, 23
	s_lshl_b32 s2, s87, 2
	v_lshlrev_b64 v[130:131], 6, v[130:131]
	v_readlane_b32 s19, v252, 24
	s_ashr_i32 s3, s2, 31
	s_lshl_b32 s94, s65, 2
	v_lshl_add_u64 v[130:131], s[18:19], 0, v[130:131]
	v_lshl_add_u64 v[130:131], s[2:3], 2, v[130:131]
	v_lshl_add_u64 v[130:131], v[130:131], 0, s[94:95]
	global_store_dword v[130:131], v0, off nt

; __device__ __forceinline__ unsigned cvt_pk_bf16(float lo, float hi) { unsigned r; asm("v_cvt_pk_bf16_f32 %0, %1, %2" : "=v"(r) : "v"(lo), "v"(hi)); return r; }
;     __device__ __forceinline__ void operator()(const f32x4 (&acc)[2][2][4][2], const Unit& u, int wr, int wc, int fr, int fq) const {
;     ...
;             for (int am = 0; am < 4; ++am) { const int ai = am >> 1, mb = (am & 1) * 2;
;                 v4u xv[2][2];
; #pragma unroll
;                 for (int mm = 0; mm < 2; ++mm) { const int m = mb + mm; const bf16* rp = (const bf16*)(ws + WS_XB) + (size_t)(row0 + ai * 128 + m * 16) * D + colw;
; #pragma unroll
;                     for (int bj = 0; bj < 2; ++bj) xv[mm][bj] = *(const v4u*)(rp + bj * 128); }
; #pragma unroll
;                 for (int mm = 0; mm < 2; ++mm) { const int m = mb + mm;
;                     const int row = row0 + ai * 128 + m * 16;
;                     bf16* xb = (bf16*)(ws + WS_XB) + (size_t)row * D + colw;
;                     float ssq = 0.f;
; #pragma unroll
;                     for (int bj = 0; bj < 2; ++bj) {
;                         const auto s0 = __builtin_amdgcn_permlane16_swap(xv[mm][bj].x, xv[mm][bj].z, false, false), s1 = __builtin_amdgcn_permlane16_swap(xv[mm][bj].y, xv[mm][bj].w, false, false);
;                         const unsigned xn[2][2] = {{s0[0], s1[0]}, {s0[1], s1[1]}};
;                         unsigned wn[2][2];
; #pragma unroll
;                         for (int n = 0; n < 2; ++n) {
;                             const f32x4 v = (f32x4){bf_lo(xn[n][0]), bf_hi(xn[n][0]), bf_lo(xn[n][1]), bf_hi(xn[n][1])} + acc[ai][bj][m][n] * amul;
;                             wn[n][0] = cvt_pk_bf16(v.x, v.y); wn[n][1] = cvt_pk_bf16(v.z, v.w);
;                             if (slot >= 0) ssq += (v.x * v.x + v.y * v.y) + (v.z * v.z + v.w * v.w); }
;                         const auto t0 = __builtin_amdgcn_permlane16_swap(wn[0][0], wn[1][0], false, false), t1 = __builtin_amdgcn_permlane16_swap(wn[0][1], wn[1][1], false, false);
;                         *(v4u*)(xb + bj * 128) = (v4u){t0[0], t1[0], t0[1], t1[1]};
;                     }
;                     if (slot >= 0) { ssq += shfl_xor_l(ssq, 16, fq * 16 + fr); ssq += shfl_xor_l(ssq, 32, fq * 16 + fr); if (fq == 0) ((float*)(ws + WS_SS))[((size_t)slot * M + row) * 16 + u.pn * 4 + wc] = ssq; }
;                 }
.LBB0_867:
	v_add_u32_e32 v146, 0x80, v210
	v_ashrrev_i32_e32 v147, 31, v146
	v_lshlrev_b64 v[152:153], 11, v[146:147]
	s_waitcnt lgkmcnt(0)
	v_lshl_add_u64 v[130:131], v[140:141], 0, v[152:153]
	global_load_dwordx4 v[148:151], v[130:131], off
	global_load_dwordx4 v[156:159], v[130:131], off offset:256
	v_add_u32_e32 v142, 0x90, v210
	v_ashrrev_i32_e32 v143, 31, v142
	v_lshlrev_b64 v[144:145], 11, v[142:143]
	v_lshl_add_u64 v[130:131], v[140:141], 0, v[144:145]
	global_load_dwordx4 v[134:137], v[130:131], off
	s_nop 0
	global_load_dwordx4 v[130:133], v[130:131], off offset:256
	v_lshl_add_u64 v[152:153], s[90:91], 0, v[152:153]
	v_lshl_add_u64 v[168:169], v[138:139], 1, v[152:153]
	s_and_b64 vcc, exec, s[10:11]
	s_waitcnt vmcnt(3)
	v_mov_b32_e32 v0, v150
	s_nop 1
	v_permlane16_swap_b32_e32 v148, v0
	v_mov_b32_e32 v162, v151
	s_nop 1
	v_permlane16_swap_b32_e32 v149, v162
	v_lshlrev_b32_e32 v150, 16, v148
	v_and_b32_e32 v151, 0xffff0000, v148
	v_lshlrev_b32_e32 v148, 16, v149
	v_and_b32_e32 v149, 0xffff0000, v149
	v_pk_add_f32 v[152:153], v[58:59], v[150:151]
	v_lshlrev_b32_e32 v154, 16, v0
	v_and_b32_e32 v155, 0xffff0000, v0
	v_lshlrev_b32_e32 v150, 16, v162
	v_and_b32_e32 v151, 0xffff0000, v162
	s_waitcnt vmcnt(2)
	v_mov_b32_e32 v0, v158
	v_pk_add_f32 v[148:149], v[60:61], v[148:149]
	v_cvt_pk_bf16_f32 v160, v152, v153
	v_pk_add_f32 v[150:151], v[52:53], v[150:151]
	v_cvt_pk_bf16_f32 v161, v148, v149
	v_pk_add_f32 v[154:155], v[50:51], v[154:155]
	v_cvt_pk_bf16_f32 v163, v150, v151
	v_permlane16_swap_b32_e32 v156, v0
	v_cvt_pk_bf16_f32 v162, v154, v155
	v_mov_b32_e32 v166, v159
	v_permlane16_swap_b32_e32 v160, v162
	v_permlane16_swap_b32_e32 v161, v163
	v_permlane16_swap_b32_e32 v157, v166
	v_lshlrev_b32_e32 v158, 16, v156
	v_and_b32_e32 v159, 0xffff0000, v156
	global_store_dwordx4 v[168:169], v[160:163], off nt
	v_lshlrev_b32_e32 v156, 16, v157
	v_and_b32_e32 v157, 0xffff0000, v157
	v_pk_add_f32 v[160:161], v[62:63], v[158:159]
	v_lshlrev_b32_e32 v162, 16, v0
	v_and_b32_e32 v163, 0xffff0000, v0
	v_lshlrev_b32_e32 v158, 16, v166
	v_and_b32_e32 v159, 0xffff0000, v166
	v_pk_add_f32 v[156:157], v[64:65], v[156:157]
	v_cvt_pk_bf16_f32 v164, v160, v161
	v_pk_add_f32 v[158:159], v[56:57], v[158:159]
	v_cvt_pk_bf16_f32 v165, v156, v157
	v_pk_add_f32 v[162:163], v[54:55], v[162:163]
	v_cvt_pk_bf16_f32 v167, v158, v159
	s_nop 0
	v_cvt_pk_bf16_f32 v166, v162, v163
	v_permlane16_swap_b32_e32 v165, v167
	v_permlane16_swap_b32_e32 v164, v166
	global_store_dwordx4 v[168:169], v[164:167], off offset:256 nt
	s_cbranch_vccnz .LBB0_871
	v_mul_f32_e32 v0, v153, v153
	v_mul_f32_e32 v149, v149, v149
	v_fmac_f32_e32 v0, v152, v152
	v_fmac_f32_e32 v149, v148, v148
	v_add_f32_e32 v0, v0, v149
	v_mul_f32_e32 v148, v155, v155
	v_mul_f32_e32 v149, v151, v151
	v_fmac_f32_e32 v148, v154, v154
	v_fmac_f32_e32 v149, v150, v150
	v_add_f32_e32 v148, v148, v149
	v_add_f32_e32 v0, v0, v148
	v_mul_f32_e32 v148, v161, v161
	v_mul_f32_e32 v149, v157, v157
	v_fmac_f32_e32 v148, v160, v160
	v_fmac_f32_e32 v149, v156, v156
	v_add_f32_e32 v148, v148, v149
	v_add_f32_e32 v0, v0, v148
	v_mul_f32_e32 v148, v163, v163
	v_mul_f32_e32 v149, v159, v159
	v_fmac_f32_e32 v148, v162, v162
	v_fmac_f32_e32 v149, v158, v158
	v_add_f32_e32 v148, v148, v149
	v_add_f32_e32 v0, v148, v0
	ds_bpermute_b32 v148, v241, v0
	s_waitcnt lgkmcnt(0)
	v_add_f32_e32 v0, v0, v148
	ds_bpermute_b32 v148, v242, v0
	s_and_saveexec_b64 s[0:1], s[6:7]
	s_cbranch_execz .LBB0_870
	v_lshl_add_u64 v[146:147], s[38:39], 0, v[146:147]
	v_readlane_b32 s18, v252, 23
	s_lshl_b32 s2, s87, 2
	v_lshlrev_b64 v[146:147], 6, v[146:147]
	v_readlane_b32 s19, v252, 24
	s_ashr_i32 s3, s2, 31
	s_lshl_b32 s94, s65, 2
	v_lshl_add_u64 v[146:147], s[18:19], 0, v[146:147]
	v_lshl_add_u64 v[146:147], s[2:3], 2, v[146:147]
	s_waitcnt lgkmcnt(0)
	v_add_f32_e32 v0, v0, v148
	v_lshl_add_u64 v[146:147], v[146:147], 0, s[94:95]
	global_store_dword v[146:147], v0, off nt

; __device__ __forceinline__ unsigned cvt_pk_bf16(float lo, float hi) { unsigned r; asm("v_cvt_pk_bf16_f32 %0, %1, %2" : "=v"(r) : "v"(lo), "v"(hi)); return r; }
;     __device__ __forceinline__ void operator()(const f32x4 (&acc)[2][2][4][2], const Unit& u, int wr, int wc, int fr, int fq) const {
;     ...
;             for (int am = 0; am < 4; ++am) { const int ai = am >> 1, mb = (am & 1) * 2;
;                 v4u xv[2][2];
; #pragma unroll
;                 for (int mm = 0; mm < 2; ++mm) { const int m = mb + mm; const bf16* rp = (const bf16*)(ws + WS_XB) + (size_t)(row0 + ai * 128 + m * 16) * D + colw;
; #pragma unroll
;                     for (int bj = 0; bj < 2; ++bj) xv[mm][bj] = *(const v4u*)(rp + bj * 128); }
; #pragma unroll
;                 for (int mm = 0; mm < 2; ++mm) { const int m = mb + mm;
;                     const int row = row0 + ai * 128 + m * 16;
;                     bf16* xb = (bf16*)(ws + WS_XB) + (size_t)row * D + colw;
;                     float ssq = 0.f;
; #pragma unroll
;                     for (int bj = 0; bj < 2; ++bj) {
;                         const auto s0 = __builtin_amdgcn_permlane16_swap(xv[mm][bj].x, xv[mm][bj].z, false, false), s1 = __builtin_amdgcn_permlane16_swap(xv[mm][bj].y, xv[mm][bj].w, false, false);
;                         const unsigned xn[2][2] = {{s0[0], s1[0]}, {s0[1], s1[1]}};
;                         unsigned wn[2][2];
; #pragma unroll
;                         for (int n = 0; n < 2; ++n) {
;                             const f32x4 v = (f32x4){bf_lo(xn[n][0]), bf_hi(xn[n][0]), bf_lo(xn[n][1]), bf_hi(xn[n][1])} + acc[ai][bj][m][n] * amul;
;                             wn[n][0] = cvt_pk_bf16(v.x, v.y); wn[n][1] = cvt_pk_bf16(v.z, v.w);
;                             if (slot >= 0) ssq += (v.x * v.x + v.y * v.y) + (v.z * v.z + v.w * v.w); }
;                         const auto t0 = __builtin_amdgcn_permlane16_swap(wn[0][0], wn[1][0], false, false), t1 = __builtin_amdgcn_permlane16_swap(wn[0][1], wn[1][1], false, false);
;                         *(v4u*)(xb + bj * 128) = (v4u){t0[0], t1[0], t0[1], t1[1]};
;                     }
;                     if (slot >= 0) { ssq += shfl_xor_l(ssq, 16, fq * 16 + fr); ssq += shfl_xor_l(ssq, 32, fq * 16 + fr); if (fq == 0) ((float*)(ws + WS_SS))[((size_t)slot * M + row) * 16 + u.pn * 4 + wc] = ssq; }
;                 }
.LBB0_871:
	v_lshl_add_u64 v[144:145], s[90:91], 0, v[144:145]
	v_lshl_add_u64 v[156:157], v[138:139], 1, v[144:145]
	s_waitcnt vmcnt(3)
	v_mov_b32_e32 v0, v136
	v_mov_b32_e32 v145, v137
	s_nop 0
	v_permlane16_swap_b32_e32 v134, v0
	v_permlane16_swap_b32_e32 v135, v145
	v_lshlrev_b32_e32 v136, 16, v134
	v_and_b32_e32 v137, 0xffff0000, v134
	v_lshlrev_b32_e32 v134, 16, v135
	v_and_b32_e32 v135, 0xffff0000, v135
	v_lshlrev_b32_e32 v146, 16, v0
	v_and_b32_e32 v147, 0xffff0000, v0
	v_lshlrev_b32_e32 v144, 16, v145
	v_and_b32_e32 v145, 0xffff0000, v145
	v_pk_add_f32 v[134:135], v[44:45], v[134:135]
	v_pk_add_f32 v[136:137], v[42:43], v[136:137]
	v_cvt_pk_bf16_f32 v149, v134, v135
	v_pk_add_f32 v[144:145], v[36:37], v[144:145]
	s_waitcnt lgkmcnt(0)
	v_cvt_pk_bf16_f32 v148, v136, v137
	v_pk_add_f32 v[146:147], v[34:35], v[146:147]
	v_cvt_pk_bf16_f32 v151, v144, v145
	s_waitcnt vmcnt(2)
	v_mov_b32_e32 v0, v132
	v_cvt_pk_bf16_f32 v150, v146, v147
	v_permlane16_swap_b32_e32 v149, v151
	v_permlane16_swap_b32_e32 v148, v150
	global_store_dwordx4 v[156:157], v[148:151], off nt
	v_permlane16_swap_b32_e32 v130, v0
	s_nop 0
	v_mov_b32_e32 v149, v133
	s_nop 1
	v_permlane16_swap_b32_e32 v131, v149
	v_lshlrev_b32_e32 v132, 16, v130
	v_and_b32_e32 v133, 0xffff0000, v130
	v_lshlrev_b32_e32 v130, 16, v131
	v_and_b32_e32 v131, 0xffff0000, v131
	v_lshlrev_b32_e32 v150, 16, v0
	v_and_b32_e32 v151, 0xffff0000, v0
	v_lshlrev_b32_e32 v148, 16, v149
	v_and_b32_e32 v149, 0xffff0000, v149
	v_pk_add_f32 v[130:131], v[48:49], v[130:131]
	v_pk_add_f32 v[132:133], v[46:47], v[132:133]
	v_cvt_pk_bf16_f32 v153, v130, v131
	v_pk_add_f32 v[148:149], v[40:41], v[148:149]
	v_cvt_pk_bf16_f32 v152, v132, v133
	v_pk_add_f32 v[150:151], v[38:39], v[150:151]
	v_cvt_pk_bf16_f32 v155, v148, v149
	s_and_b64 vcc, exec, s[10:11]
	v_cvt_pk_bf16_f32 v154, v150, v151
	v_permlane16_swap_b32_e32 v153, v155
	v_permlane16_swap_b32_e32 v152, v154
	global_store_dwordx4 v[156:157], v[152:155], off offset:256 nt
	s_cbranch_vccnz .LBB0_875
	v_mul_f32_e32 v0, v137, v137
	v_mul_f32_e32 v135, v135, v135
	v_fmac_f32_e32 v0, v136, v136
	v_fmac_f32_e32 v135, v134, v134
	v_add_f32_e32 v0, v0, v135
	v_mul_f32_e32 v134, v147, v147
	v_mul_f32_e32 v135, v145, v145
	v_fmac_f32_e32 v134, v146, v146
	v_fmac_f32_e32 v135, v144, v144
	v_mul_f32_e32 v133, v133, v133
	v_mul_f32_e32 v131, v131, v131
	v_add_f32_e32 v134, v134, v135
	v_fmac_f32_e32 v133, v132, v132
	v_fmac_f32_e32 v131, v130, v130
	v_add_f32_e32 v0, v0, v134
	v_add_f32_e32 v130, v133, v131
	v_add_f32_e32 v0, v0, v130
	v_mul_f32_e32 v130, v151, v151
	v_mul_f32_e32 v131, v149, v149
	v_fmac_f32_e32 v130, v150, v150
	v_fmac_f32_e32 v131, v148, v148
	v_add_f32_e32 v130, v130, v131
	v_add_f32_e32 v0, v130, v0
	ds_bpermute_b32 v130, v241, v0
	s_waitcnt lgkmcnt(0)
	v_add_f32_e32 v0, v0, v130
	ds_bpermute_b32 v130, v242, v0
	s_and_saveexec_b64 s[0:1], s[6:7]
	s_cbranch_execz .LBB0_874
	s_waitcnt lgkmcnt(0)
	v_add_f32_e32 v0, v0, v130
	v_lshl_add_u64 v[130:131], s[38:39], 0, v[142:143]
	v_readlane_b32 s18, v252, 23
	s_lshl_b32 s2, s87, 2
	v_lshlrev_b64 v[130:131], 6, v[130:131]
	v_readlane_b32 s19, v252, 24
	s_ashr_i32 s3, s2, 31
	s_lshl_b32 s94, s65, 2
	v_lshl_add_u64 v[130:131], s[18:19], 0, v[130:131]
	v_lshl_add_u64 v[130:131], s[2:3], 2, v[130:131]
	v_lshl_add_u64 v[130:131], v[130:131], 0, s[94:95]
	global_store_dword v[130:131], v0, off nt

; __device__ __forceinline__ unsigned cvt_pk_bf16(float lo, float hi) { unsigned r; asm("v_cvt_pk_bf16_f32 %0, %1, %2" : "=v"(r) : "v"(lo), "v"(hi)); return r; }
;     __device__ __forceinline__ void operator()(const f32x4 (&acc)[2][2][4][2], const Unit& u, int wr, int wc, int fr, int fq) const {
;     ...
;             for (int am = 0; am < 4; ++am) { const int ai = am >> 1, mb = (am & 1) * 2;
;                 v4u xv[2][2];
; #pragma unroll
;                 for (int mm = 0; mm < 2; ++mm) { const int m = mb + mm; const bf16* rp = (const bf16*)(ws + WS_XB) + (size_t)(row0 + ai * 128 + m * 16) * D + colw;
; #pragma unroll
;                     for (int bj = 0; bj < 2; ++bj) xv[mm][bj] = *(const v4u*)(rp + bj * 128); }
; #pragma unroll
;                 for (int mm = 0; mm < 2; ++mm) { const int m = mb + mm;
;                     const int row = row0 + ai * 128 + m * 16;
;                     bf16* xb = (bf16*)(ws + WS_XB) + (size_t)row * D + colw;
;                     float ssq = 0.f;
; #pragma unroll
;                     for (int bj = 0; bj < 2; ++bj) {
;                         const auto s0 = __builtin_amdgcn_permlane16_swap(xv[mm][bj].x, xv[mm][bj].z, false, false), s1 = __builtin_amdgcn_permlane16_swap(xv[mm][bj].y, xv[mm][bj].w, false, false);
;                         const unsigned xn[2][2] = {{s0[0], s1[0]}, {s0[1], s1[1]}};
;                         unsigned wn[2][2];
; #pragma unroll
;                         for (int n = 0; n < 2; ++n) {
;                             const f32x4 v = (f32x4){bf_lo(xn[n][0]), bf_hi(xn[n][0]), bf_lo(xn[n][1]), bf_hi(xn[n][1])} + acc[ai][bj][m][n] * amul;
;                             wn[n][0] = cvt_pk_bf16(v.x, v.y); wn[n][1] = cvt_pk_bf16(v.z, v.w);
;                             if (slot >= 0) ssq += (v.x * v.x + v.y * v.y) + (v.z * v.z + v.w * v.w); }
;                         const auto t0 = __builtin_amdgcn_permlane16_swap(wn[0][0], wn[1][0], false, false), t1 = __builtin_amdgcn_permlane16_swap(wn[0][1], wn[1][1], false, false);
;                         *(v4u*)(xb + bj * 128) = (v4u){t0[0], t1[0], t0[1], t1[1]};
;                     }
;                     if (slot >= 0) { ssq += shfl_xor_l(ssq, 16, fq * 16 + fr); ssq += shfl_xor_l(ssq, 32, fq * 16 + fr); if (fq == 0) ((float*)(ws + WS_SS))[((size_t)slot * M + row) * 16 + u.pn * 4 + wc] = ssq; }
;                 }
.LBB0_875:
	v_add_u32_e32 v146, 0xa0, v210
	v_ashrrev_i32_e32 v147, 31, v146
	v_lshlrev_b64 v[152:153], 11, v[146:147]
	s_waitcnt lgkmcnt(0)
	v_lshl_add_u64 v[130:131], v[140:141], 0, v[152:153]
	global_load_dwordx4 v[148:151], v[130:131], off
	global_load_dwordx4 v[154:157], v[130:131], off offset:256
	v_add_u32_e32 v142, 0xb0, v210
	v_ashrrev_i32_e32 v143, 31, v142
	v_lshlrev_b64 v[144:145], 11, v[142:143]
	v_lshl_add_u64 v[130:131], v[140:141], 0, v[144:145]
	global_load_dwordx4 v[134:137], v[130:131], off
	s_nop 0
	global_load_dwordx4 v[130:133], v[130:131], off offset:256
	v_lshl_add_u64 v[140:141], s[90:91], 0, v[152:153]
	v_lshl_add_u64 v[166:167], v[138:139], 1, v[140:141]
	s_and_b64 vcc, exec, s[10:11]
	s_waitcnt vmcnt(3)
	v_mov_b32_e32 v0, v150
	v_mov_b32_e32 v160, v151
	s_nop 0
	v_permlane16_swap_b32_e32 v148, v0
	v_permlane16_swap_b32_e32 v149, v160
	v_lshlrev_b32_e32 v150, 16, v148
	v_and_b32_e32 v151, 0xffff0000, v148
	v_lshlrev_b32_e32 v140, 16, v149
	v_and_b32_e32 v141, 0xffff0000, v149
	v_lshlrev_b32_e32 v152, 16, v0
	v_and_b32_e32 v153, 0xffff0000, v0
	v_lshlrev_b32_e32 v148, 16, v160
	v_and_b32_e32 v149, 0xffff0000, v160
	s_waitcnt vmcnt(2)
	v_mov_b32_e32 v0, v156
	v_pk_add_f32 v[140:141], v[28:29], v[140:141]
	v_pk_add_f32 v[150:151], v[26:27], v[150:151]
	v_cvt_pk_bf16_f32 v159, v140, v141
	v_pk_add_f32 v[148:149], v[20:21], v[148:149]
	v_cvt_pk_bf16_f32 v158, v150, v151
	v_pk_add_f32 v[152:153], v[18:19], v[152:153]
	v_cvt_pk_bf16_f32 v161, v148, v149
	v_permlane16_swap_b32_e32 v154, v0
	v_cvt_pk_bf16_f32 v160, v152, v153
	v_mov_b32_e32 v164, v157
	v_permlane16_swap_b32_e32 v158, v160
	v_permlane16_swap_b32_e32 v159, v161
	v_permlane16_swap_b32_e32 v155, v164
	v_lshlrev_b32_e32 v156, 16, v154
	v_and_b32_e32 v157, 0xffff0000, v154
	global_store_dwordx4 v[166:167], v[158:161], off nt
	v_lshlrev_b32_e32 v154, 16, v155
	v_and_b32_e32 v155, 0xffff0000, v155
	v_pk_add_f32 v[158:159], v[30:31], v[156:157]
	v_lshlrev_b32_e32 v160, 16, v0
	v_and_b32_e32 v161, 0xffff0000, v0
	v_lshlrev_b32_e32 v156, 16, v164
	v_and_b32_e32 v157, 0xffff0000, v164
	v_pk_add_f32 v[154:155], v[32:33], v[154:155]
	v_cvt_pk_bf16_f32 v162, v158, v159
	v_pk_add_f32 v[156:157], v[24:25], v[156:157]
	v_cvt_pk_bf16_f32 v163, v154, v155
	v_pk_add_f32 v[160:161], v[22:23], v[160:161]
	v_cvt_pk_bf16_f32 v165, v156, v157
	s_nop 0
	v_cvt_pk_bf16_f32 v164, v160, v161
	v_permlane16_swap_b32_e32 v163, v165
	v_permlane16_swap_b32_e32 v162, v164
	global_store_dwordx4 v[166:167], v[162:165], off offset:256 nt
	s_cbranch_vccnz .LBB0_879
	v_mul_f32_e32 v0, v151, v151
	v_mul_f32_e32 v141, v141, v141
	v_fmac_f32_e32 v0, v150, v150
	v_fmac_f32_e32 v141, v140, v140
	v_add_f32_e32 v0, v0, v141
	v_mul_f32_e32 v140, v153, v153
	v_mul_f32_e32 v141, v149, v149
	v_fmac_f32_e32 v140, v152, v152
	v_fmac_f32_e32 v141, v148, v148
	v_add_f32_e32 v140, v140, v141
	v_add_f32_e32 v0, v0, v140
	v_mul_f32_e32 v140, v159, v159
	v_mul_f32_e32 v141, v155, v155
	v_fmac_f32_e32 v140, v158, v158
	v_fmac_f32_e32 v141, v154, v154
	v_add_f32_e32 v140, v140, v141
	v_add_f32_e32 v0, v0, v140
	v_mul_f32_e32 v140, v161, v161
	v_mul_f32_e32 v141, v157, v157
	v_fmac_f32_e32 v140, v160, v160
	v_fmac_f32_e32 v141, v156, v156
	v_add_f32_e32 v140, v140, v141
	v_add_f32_e32 v0, v140, v0
	ds_bpermute_b32 v140, v241, v0
	s_waitcnt lgkmcnt(0)
	v_add_f32_e32 v0, v0, v140
	ds_bpermute_b32 v140, v242, v0
	s_and_saveexec_b64 s[0:1], s[6:7]
	s_cbranch_execz .LBB0_878
	s_waitcnt lgkmcnt(0)
	v_add_f32_e32 v0, v0, v140
	v_lshl_add_u64 v[140:141], s[38:39], 0, v[146:147]
	v_readlane_b32 s18, v252, 23
	s_lshl_b32 s2, s87, 2
	v_lshlrev_b64 v[140:141], 6, v[140:141]
	v_readlane_b32 s19, v252, 24
	s_ashr_i32 s3, s2, 31
	s_lshl_b32 s94, s65, 2
	v_lshl_add_u64 v[140:141], s[18:19], 0, v[140:141]
	v_lshl_add_u64 v[140:141], s[2:3], 2, v[140:141]
	v_lshl_add_u64 v[140:141], v[140:141], 0, s[94:95]
	global_store_dword v[140:141], v0, off nt

; __device__ __forceinline__ unsigned cvt_pk_bf16(float lo, float hi) { unsigned r; asm("v_cvt_pk_bf16_f32 %0, %1, %2" : "=v"(r) : "v"(lo), "v"(hi)); return r; }
;     __device__ __forceinline__ void operator()(const f32x4 (&acc)[2][2][4][2], const Unit& u, int wr, int wc, int fr, int fq) const {
;     ...
;             for (int am = 0; am < 4; ++am) { const int ai = am >> 1, mb = (am & 1) * 2;
;                 v4u xv[2][2];
; #pragma unroll
;                 for (int mm = 0; mm < 2; ++mm) { const int m = mb + mm; const bf16* rp = (const bf16*)(ws + WS_XB) + (size_t)(row0 + ai * 128 + m * 16) * D + colw;
; #pragma unroll
;                     for (int bj = 0; bj < 2; ++bj) xv[mm][bj] = *(const v4u*)(rp + bj * 128); }
; #pragma unroll
;                 for (int mm = 0; mm < 2; ++mm) { const int m = mb + mm;
;                     const int row = row0 + ai * 128 + m * 16;
;                     bf16* xb = (bf16*)(ws + WS_XB) + (size_t)row * D + colw;
;                     float ssq = 0.f;
; #pragma unroll
;                     for (int bj = 0; bj < 2; ++bj) {
;                         const auto s0 = __builtin_amdgcn_permlane16_swap(xv[mm][bj].x, xv[mm][bj].z, false, false), s1 = __builtin_amdgcn_permlane16_swap(xv[mm][bj].y, xv[mm][bj].w, false, false);
;                         const unsigned xn[2][2] = {{s0[0], s1[0]}, {s0[1], s1[1]}};
;                         unsigned wn[2][2];
; #pragma unroll
;                         for (int n = 0; n < 2; ++n) {
;                             const f32x4 v = (f32x4){bf_lo(xn[n][0]), bf_hi(xn[n][0]), bf_lo(xn[n][1]), bf_hi(xn[n][1])} + acc[ai][bj][m][n] * amul;
;                             wn[n][0] = cvt_pk_bf16(v.x, v.y); wn[n][1] = cvt_pk_bf16(v.z, v.w);
;                             if (slot >= 0) ssq += (v.x * v.x + v.y * v.y) + (v.z * v.z + v.w * v.w); }
;                         const auto t0 = __builtin_amdgcn_permlane16_swap(wn[0][0], wn[1][0], false, false), t1 = __builtin_amdgcn_permlane16_swap(wn[0][1], wn[1][1], false, false);
;                         *(v4u*)(xb + bj * 128) = (v4u){t0[0], t1[0], t0[1], t1[1]};
;                     }
;                     if (slot >= 0) { ssq += shfl_xor_l(ssq, 16, fq * 16 + fr); ssq += shfl_xor_l(ssq, 32, fq * 16 + fr); if (fq == 0) ((float*)(ws + WS_SS))[((size_t)slot * M + row) * 16 + u.pn * 4 + wc] = ssq; }
;                 }
.LBB0_879:
	s_waitcnt lgkmcnt(0)
	v_lshl_add_u64 v[140:141], s[90:91], 0, v[144:145]
	v_lshl_add_u64 v[152:153], v[138:139], 1, v[140:141]
	s_waitcnt vmcnt(3)
	v_mov_b32_e32 v0, v136
	v_mov_b32_e32 v139, v137
	s_nop 0
	v_permlane16_swap_b32_e32 v134, v0
	v_permlane16_swap_b32_e32 v135, v139
	v_lshlrev_b32_e32 v136, 16, v134
	v_and_b32_e32 v137, 0xffff0000, v134
	v_lshlrev_b32_e32 v134, 16, v135
	v_and_b32_e32 v135, 0xffff0000, v135
	v_lshlrev_b32_e32 v140, 16, v0
	v_and_b32_e32 v141, 0xffff0000, v0
	v_lshlrev_b32_e32 v138, 16, v139
	v_and_b32_e32 v139, 0xffff0000, v139
	v_pk_add_f32 v[134:135], v[12:13], v[134:135]
	v_pk_add_f32 v[136:137], v[10:11], v[136:137]
	v_cvt_pk_bf16_f32 v145, v134, v135
	v_pk_add_f32 v[138:139], v[8:9], v[138:139]
	v_cvt_pk_bf16_f32 v144, v136, v137
	v_pk_add_f32 v[140:141], v[6:7], v[140:141]
	v_cvt_pk_bf16_f32 v147, v138, v139
	s_waitcnt vmcnt(2)
	v_mov_b32_e32 v0, v132
	v_cvt_pk_bf16_f32 v146, v140, v141
	v_permlane16_swap_b32_e32 v145, v147
	v_permlane16_swap_b32_e32 v144, v146
	global_store_dwordx4 v[152:153], v[144:147], off nt
	v_permlane16_swap_b32_e32 v130, v0
	s_nop 0
	v_mov_b32_e32 v145, v133
	s_nop 1
	v_permlane16_swap_b32_e32 v131, v145
	v_lshlrev_b32_e32 v132, 16, v130
	v_and_b32_e32 v133, 0xffff0000, v130
	v_lshlrev_b32_e32 v130, 16, v131
	v_and_b32_e32 v131, 0xffff0000, v131
	v_lshlrev_b32_e32 v146, 16, v0
	v_and_b32_e32 v147, 0xffff0000, v0
	v_lshlrev_b32_e32 v144, 16, v145
	v_and_b32_e32 v145, 0xffff0000, v145
	v_pk_add_f32 v[130:131], v[16:17], v[130:131]
	v_pk_add_f32 v[132:133], v[14:15], v[132:133]
	v_cvt_pk_bf16_f32 v149, v130, v131
	v_pk_add_f32 v[144:145], v[4:5], v[144:145]
	v_cvt_pk_bf16_f32 v148, v132, v133
	v_pk_add_f32 v[146:147], v[2:3], v[146:147]
	v_cvt_pk_bf16_f32 v151, v144, v145
	s_and_b64 vcc, exec, s[10:11]
	v_cvt_pk_bf16_f32 v150, v146, v147
	v_permlane16_swap_b32_e32 v149, v151
	v_permlane16_swap_b32_e32 v148, v150
	global_store_dwordx4 v[152:153], v[148:151], off offset:256 nt
	s_cbranch_vccnz .LBB0_883
	v_mul_f32_e32 v0, v137, v137
	v_mul_f32_e32 v135, v135, v135
	v_fmac_f32_e32 v0, v136, v136
	v_fmac_f32_e32 v135, v134, v134
	v_add_f32_e32 v0, v0, v135
	v_mul_f32_e32 v134, v141, v141
	v_mul_f32_e32 v135, v139, v139
	v_fmac_f32_e32 v134, v140, v140
	v_fmac_f32_e32 v135, v138, v138
	v_mul_f32_e32 v133, v133, v133
	v_mul_f32_e32 v131, v131, v131
	v_add_f32_e32 v134, v134, v135
	v_fmac_f32_e32 v133, v132, v132
	v_fmac_f32_e32 v131, v130, v130
	v_add_f32_e32 v0, v0, v134
	v_add_f32_e32 v130, v133, v131
	v_add_f32_e32 v0, v0, v130
	v_mul_f32_e32 v130, v147, v147
	v_mul_f32_e32 v131, v145, v145
	v_fmac_f32_e32 v130, v146, v146
	v_fmac_f32_e32 v131, v144, v144
	v_add_f32_e32 v130, v130, v131
	v_add_f32_e32 v0, v130, v0
	ds_bpermute_b32 v130, v241, v0
	s_waitcnt lgkmcnt(0)
	v_add_f32_e32 v0, v0, v130
	ds_bpermute_b32 v130, v242, v0
	s_and_saveexec_b64 s[0:1], s[6:7]
	s_cbranch_execz .LBB0_882
	s_waitcnt lgkmcnt(0)
	v_add_f32_e32 v0, v0, v130
	v_lshl_add_u64 v[130:131], s[38:39], 0, v[142:143]
	v_readlane_b32 s10, v252, 23
	s_lshl_b32 s2, s87, 2
	v_lshlrev_b64 v[130:131], 6, v[130:131]
	v_readlane_b32 s11, v252, 24
	s_ashr_i32 s3, s2, 31
	s_lshl_b32 s94, s65, 2
	v_lshl_add_u64 v[130:131], s[10:11], 0, v[130:131]
	v_lshl_add_u64 v[130:131], s[2:3], 2, v[130:131]
	v_lshl_add_u64 v[130:131], v[130:131], 0, s[94:95]
	global_store_dword v[130:131], v0, off nt

; __device__ __forceinline__ v4u pack8(const float (&f)[8]) { v4u w; w.x = cvt_pk_bf16(f[0], f[1]); w.y = cvt_pk_bf16(f[2], f[3]); w.z = cvt_pk_bf16(f[4], f[5]); w.w = cvt_pk_bf16(f[6], f[7]); return w; }
; __device__ __forceinline__ float sigmoidf_(float x) { return rcpf_(1.f + __expf(-x)); }
; __device__ __forceinline__ float tanhf_(float x) { return 1.f - 2.f * rcpf_(1.f + __expf(2.f * x)); }
;     __device__ __forceinline__ void operator()(const f32x4 (&acc)[2][2][4][2], const Unit& u, int wr, int wc, int fr, int fq) const {
;     ...
;                     if (c < KL2) {
;                         const int kd = c < 64 ? 1 : ((c >= 128 && c < 288) ? 2 : 0);
; #pragma unroll
;                         for (int ai = 0; ai < 2; ++ai)
; #pragma unroll
;                             for (int m = 0; m < 4; ++m) if (rrow[ai][m] >= 0) { float o[8];
; #pragma unroll
;                                 for (int n = 0; n < 2; ++n)
; #pragma unroll
;                                     for (int j = 0; j < 4; ++j) { const float x = acc[ai][bj][m][n][j]; o[n * 4 + j] = kd == 1 ? tanhf_(x) : (kd == 2 ? sigmoidf_(x) : x); }
;                                 *(v4u*)(A2 + (size_t)rrow[ai][m] * KL2 + c) = pack8(o); }
.LBB0_936:
	s_or_b64 exec, exec, s[44:45]
	v_mad_u64_u32 v[152:153], s[18:19], v142, s83, v[146:147]
	v_cvt_pk_bf16_f32 v148, v0, v133
	v_cvt_pk_bf16_f32 v149, v135, v137
	v_cvt_pk_bf16_f32 v150, v139, v141
	v_cvt_pk_bf16_f32 v151, v143, v145
	global_store_dwordx4 v[152:153], v[148:151], off nt
	s_or_b64 exec, exec, s[10:11]
	v_cmp_lt_i32_e32 vcc, -1, v140
	s_and_saveexec_b64 s[10:11], vcc
	s_cbranch_execnz .LBB0_695

; __device__ __forceinline__ v4u pack8(const float (&f)[8]) { v4u w; w.x = cvt_pk_bf16(f[0], f[1]); w.y = cvt_pk_bf16(f[2], f[3]); w.z = cvt_pk_bf16(f[4], f[5]); w.w = cvt_pk_bf16(f[6], f[7]); return w; }
; __device__ __forceinline__ float sigmoidf_(float x) { return rcpf_(1.f + __expf(-x)); }
; __device__ __forceinline__ float tanhf_(float x) { return 1.f - 2.f * rcpf_(1.f + __expf(2.f * x)); }
;     __device__ __forceinline__ void operator()(const f32x4 (&acc)[2][2][4][2], const Unit& u, int wr, int wc, int fr, int fq) const {
;     ...
;                     if (c < KL2) {
;                         const int kd = c < 64 ? 1 : ((c >= 128 && c < 288) ? 2 : 0);
; #pragma unroll
;                         for (int ai = 0; ai < 2; ++ai)
; #pragma unroll
;                             for (int m = 0; m < 4; ++m) if (rrow[ai][m] >= 0) { float o[8];
; #pragma unroll
;                                 for (int n = 0; n < 2; ++n)
; #pragma unroll
;                                     for (int j = 0; j < 4; ++j) { const float x = acc[ai][bj][m][n][j]; o[n * 4 + j] = kd == 1 ? tanhf_(x) : (kd == 2 ? sigmoidf_(x) : x); }
;                                 *(v4u*)(A2 + (size_t)rrow[ai][m] * KL2 + c) = pack8(o); }
.LBB0_986:
	s_or_b64 exec, exec, s[44:45]
	v_mad_u64_u32 v[152:153], s[18:19], v138, s83, v[146:147]
	v_cvt_pk_bf16_f32 v148, v0, v133
	v_cvt_pk_bf16_f32 v149, v135, v137
	v_cvt_pk_bf16_f32 v150, v139, v141
	v_cvt_pk_bf16_f32 v151, v143, v145
	global_store_dwordx4 v[152:153], v[148:151], off nt
	s_or_b64 exec, exec, s[10:11]
	v_cmp_lt_i32_e32 vcc, -1, v136
	s_and_saveexec_b64 s[10:11], vcc
	s_cbranch_execnz .LBB0_745

; __device__ __forceinline__ v4u pack8(const float (&f)[8]) { v4u w; w.x = cvt_pk_bf16(f[0], f[1]); w.y = cvt_pk_bf16(f[2], f[3]); w.z = cvt_pk_bf16(f[4], f[5]); w.w = cvt_pk_bf16(f[6], f[7]); return w; }
; __device__ __forceinline__ float sigmoidf_(float x) { return rcpf_(1.f + __expf(-x)); }
; __device__ __forceinline__ float tanhf_(float x) { return 1.f - 2.f * rcpf_(1.f + __expf(2.f * x)); }
;     __device__ __forceinline__ void operator()(const f32x4 (&acc)[2][2][4][2], const Unit& u, int wr, int wc, int fr, int fq) const {
;     ...
;                     if (c < KL2) {
;                         const int kd = c < 64 ? 1 : ((c >= 128 && c < 288) ? 2 : 0);
; #pragma unroll
;                         for (int ai = 0; ai < 2; ++ai)
; #pragma unroll
;                             for (int m = 0; m < 4; ++m) if (rrow[ai][m] >= 0) { float o[8];
; #pragma unroll
;                                 for (int n = 0; n < 2; ++n)
; #pragma unroll
;                                     for (int j = 0; j < 4; ++j) { const float x = acc[ai][bj][m][n][j]; o[n * 4 + j] = kd == 1 ? tanhf_(x) : (kd == 2 ? sigmoidf_(x) : x); }
;                                 *(v4u*)(A2 + (size_t)rrow[ai][m] * KL2 + c) = pack8(o); }
.LBB0_1036:
	s_or_b64 exec, exec, s[44:45]
	v_mad_u64_u32 v[152:153], s[18:19], v134, s83, v[146:147]
	v_cvt_pk_bf16_f32 v148, v0, v133
	v_cvt_pk_bf16_f32 v149, v135, v137
	v_cvt_pk_bf16_f32 v150, v139, v141
	v_cvt_pk_bf16_f32 v151, v143, v145
	global_store_dwordx4 v[152:153], v[148:151], off nt
	s_or_b64 exec, exec, s[10:11]
	v_cmp_lt_i32_e32 vcc, -1, v132
	s_and_saveexec_b64 s[10:11], vcc
	s_cbranch_execnz .LBB0_795

; __device__ __forceinline__ v4u pack8(const float (&f)[8]) { v4u w; w.x = cvt_pk_bf16(f[0], f[1]); w.y = cvt_pk_bf16(f[2], f[3]); w.z = cvt_pk_bf16(f[4], f[5]); w.w = cvt_pk_bf16(f[6], f[7]); return w; }
; __device__ __forceinline__ float sigmoidf_(float x) { return rcpf_(1.f + __expf(-x)); }
; __device__ __forceinline__ float tanhf_(float x) { return 1.f - 2.f * rcpf_(1.f + __expf(2.f * x)); }
;     __device__ __forceinline__ void operator()(const f32x4 (&acc)[2][2][4][2], const Unit& u, int wr, int wc, int fr, int fq) const {
;     ...
;                     if (c < KL2) {
;                         const int kd = c < 64 ? 1 : ((c >= 128 && c < 288) ? 2 : 0);
; #pragma unroll
;                         for (int ai = 0; ai < 2; ++ai)
; #pragma unroll
;                             for (int m = 0; m < 4; ++m) if (rrow[ai][m] >= 0) { float o[8];
; #pragma unroll
;                                 for (int n = 0; n < 2; ++n)
; #pragma unroll
;                                     for (int j = 0; j < 4; ++j) { const float x = acc[ai][bj][m][n][j]; o[n * 4 + j] = kd == 1 ? tanhf_(x) : (kd == 2 ? sigmoidf_(x) : x); }
;                                 *(v4u*)(A2 + (size_t)rrow[ai][m] * KL2 + c) = pack8(o); }
.LBB0_1086:
	s_or_b64 exec, exec, s[10:11]
	v_mad_u64_u32 v[146:147], s[10:11], v130, s83, v[146:147]
	v_cvt_pk_bf16_f32 v148, v0, v133
	v_cvt_pk_bf16_f32 v149, v135, v137
	v_cvt_pk_bf16_f32 v150, v139, v141
	v_cvt_pk_bf16_f32 v151, v143, v145
	global_store_dwordx4 v[146:147], v[148:151], off nt
.LBB0_1087:
	s_or_b64 exec, exec, s[0:1]
	v_add_u32_e32 v0, s13, v240
	s_movk_i32 s0, 0x180
	v_cmp_gt_i32_e32 vcc, s0, v0
	s_and_saveexec_b64 s[10:11], vcc
	s_cbranch_execz .LBB0_1104
	v_add_u32_e32 v131, 0xffffff80, v0
	s_movk_i32 s0, 0xa0
	v_cmp_gt_u32_e32 vcc, s0, v131
	v_readlane_b32 s0, v252, 16
	v_readlane_b32 s1, v252, 17
	s_nop 1
	v_lshl_add_u64 v[146:147], v[0:1], 1, s[0:1]
	v_cmp_lt_i32_e64 s[0:1], -1, v144
	s_and_saveexec_b64 s[44:45], s[0:1]
	s_cbranch_execz .LBB0_1096
	v_mul_f32_e32 v0, 0xbfb8aa3b, v126
	v_mul_f32_e32 v131, 0xbfb8aa3b, v127
	v_mul_f32_e32 v133, 0xbfb8aa3b, v128
	v_mul_f32_e32 v135, 0xbfb8aa3b, v129
	v_mul_f32_e32 v137, 0xbfb8aa3b, v118
	v_mul_f32_e32 v139, 0xbfb8aa3b, v119
	v_mul_f32_e32 v141, 0xbfb8aa3b, v120
	v_mul_f32_e32 v143, 0xbfb8aa3b, v121
	v_exp_f32_e32 v0, v0
	v_exp_f32_e32 v131, v131
	v_exp_f32_e32 v133, v133
	v_exp_f32_e32 v135, v135
	v_exp_f32_e32 v137, v137
	v_exp_f32_e32 v139, v139
	v_exp_f32_e32 v141, v141
	v_exp_f32_e32 v143, v143
	v_add_f32_e32 v0, 1.0, v0
	v_add_f32_e32 v131, 1.0, v131
	v_add_f32_e32 v133, 1.0, v133
	v_add_f32_e32 v135, 1.0, v135
	v_add_f32_e32 v137, 1.0, v137
	v_add_f32_e32 v139, 1.0, v139
	v_add_f32_e32 v141, 1.0, v141
	v_add_f32_e32 v143, 1.0, v143
	v_rcp_f32_e32 v0, v0
	v_rcp_f32_e32 v131, v131
	v_rcp_f32_e32 v133, v133
	v_rcp_f32_e32 v135, v135
	v_rcp_f32_e32 v137, v137
	v_rcp_f32_e32 v139, v139
	v_rcp_f32_e32 v141, v141
	v_rcp_f32_e32 v143, v143
	v_mad_u64_u32 v[152:153], s[0:1], v144, s83, v[146:147]
	v_cndmask_b32_e32 v0, v126, v0, vcc
	v_cndmask_b32_e32 v131, v127, v131, vcc
	v_cndmask_b32_e32 v133, v128, v133, vcc
	v_cndmask_b32_e32 v135, v129, v135, vcc
	v_cndmask_b32_e32 v137, v118, v137, vcc
	v_cndmask_b32_e32 v139, v119, v139, vcc
	v_cndmask_b32_e32 v141, v120, v141, vcc
	v_cndmask_b32_e32 v143, v121, v143, vcc
	v_cvt_pk_bf16_f32 v148, v0, v131
	v_cvt_pk_bf16_f32 v149, v133, v135
	v_cvt_pk_bf16_f32 v150, v137, v139
	v_cvt_pk_bf16_f32 v151, v141, v143
	global_store_dwordx4 v[152:153], v[148:151], off nt
	s_or_b64 exec, exec, s[44:45]
	v_cmp_lt_i32_e64 s[0:1], -1, v142
	s_and_saveexec_b64 s[44:45], s[0:1]
	s_cbranch_execnz .LBB0_1097

; __device__ __forceinline__ v4u pack8(const float (&f)[8]) { v4u w; w.x = cvt_pk_bf16(f[0], f[1]); w.y = cvt_pk_bf16(f[2], f[3]); w.z = cvt_pk_bf16(f[4], f[5]); w.w = cvt_pk_bf16(f[6], f[7]); return w; }
; __device__ __forceinline__ float sigmoidf_(float x) { return rcpf_(1.f + __expf(-x)); }
; __device__ __forceinline__ float tanhf_(float x) { return 1.f - 2.f * rcpf_(1.f + __expf(2.f * x)); }
;     __device__ __forceinline__ void operator()(const f32x4 (&acc)[2][2][4][2], const Unit& u, int wr, int wc, int fr, int fq) const {
;     ...
;                         for (int ai = 0; ai < 2; ++ai)
; #pragma unroll
;                             for (int m = 0; m < 4; ++m) if (rrow[ai][m] >= 0) { float o[8];
; #pragma unroll
;                                 for (int n = 0; n < 2; ++n)
; #pragma unroll
;                                     for (int j = 0; j < 4; ++j) { const float x = acc[ai][bj][m][n][j]; o[n * 4 + j] = kd == 1 ? tanhf_(x) : (kd == 2 ? sigmoidf_(x) : x); }
;                                 *(v4u*)(A2 + (size_t)rrow[ai][m] * KL2 + c) = pack8(o); }
.LBB0_1091:
	v_mul_f32_e32 v0, 0xbfb8aa3b, v94
	v_mul_f32_e32 v131, 0xbfb8aa3b, v95
	v_mul_f32_e32 v133, 0xbfb8aa3b, v96
	v_mul_f32_e32 v135, 0xbfb8aa3b, v97
	v_mul_f32_e32 v137, 0xbfb8aa3b, v86
	v_mul_f32_e32 v139, 0xbfb8aa3b, v87
	v_mul_f32_e32 v141, 0xbfb8aa3b, v88
	v_mul_f32_e32 v143, 0xbfb8aa3b, v89
	v_exp_f32_e32 v0, v0
	v_exp_f32_e32 v131, v131
	v_exp_f32_e32 v133, v133
	v_exp_f32_e32 v135, v135
	v_exp_f32_e32 v137, v137
	v_exp_f32_e32 v139, v139
	v_exp_f32_e32 v141, v141
	v_exp_f32_e32 v143, v143
	v_add_f32_e32 v0, 1.0, v0
	v_add_f32_e32 v131, 1.0, v131
	v_add_f32_e32 v133, 1.0, v133
	v_add_f32_e32 v135, 1.0, v135
	v_add_f32_e32 v137, 1.0, v137
	v_add_f32_e32 v139, 1.0, v139
	v_add_f32_e32 v141, 1.0, v141
	v_add_f32_e32 v143, 1.0, v143
	v_rcp_f32_e32 v0, v0
	v_rcp_f32_e32 v131, v131
	v_rcp_f32_e32 v133, v133
	v_rcp_f32_e32 v135, v135
	v_rcp_f32_e32 v137, v137
	v_rcp_f32_e32 v139, v139
	v_rcp_f32_e32 v141, v141
	v_rcp_f32_e32 v143, v143
	v_mad_u64_u32 v[152:153], s[0:1], v140, s83, v[146:147]
	v_cndmask_b32_e32 v0, v94, v0, vcc
	v_cndmask_b32_e32 v131, v95, v131, vcc
	v_cndmask_b32_e32 v133, v96, v133, vcc
	v_cndmask_b32_e32 v135, v97, v135, vcc
	v_cndmask_b32_e32 v137, v86, v137, vcc
	v_cndmask_b32_e32 v139, v87, v139, vcc
	v_cndmask_b32_e32 v141, v88, v141, vcc
	v_cndmask_b32_e32 v143, v89, v143, vcc
	v_cvt_pk_bf16_f32 v148, v0, v131
	v_cvt_pk_bf16_f32 v149, v133, v135
	v_cvt_pk_bf16_f32 v150, v137, v139
	v_cvt_pk_bf16_f32 v151, v141, v143
	global_store_dwordx4 v[152:153], v[148:151], off nt
	s_or_b64 exec, exec, s[44:45]
	v_cmp_lt_i32_e64 s[0:1], -1, v138
	s_and_saveexec_b64 s[44:45], s[0:1]
	s_cbranch_execnz .LBB0_1099

; __device__ __forceinline__ v4u pack8(const float (&f)[8]) { v4u w; w.x = cvt_pk_bf16(f[0], f[1]); w.y = cvt_pk_bf16(f[2], f[3]); w.z = cvt_pk_bf16(f[4], f[5]); w.w = cvt_pk_bf16(f[6], f[7]); return w; }
; __device__ __forceinline__ float sigmoidf_(float x) { return rcpf_(1.f + __expf(-x)); }
; __device__ __forceinline__ float tanhf_(float x) { return 1.f - 2.f * rcpf_(1.f + __expf(2.f * x)); }
;     __device__ __forceinline__ void operator()(const f32x4 (&acc)[2][2][4][2], const Unit& u, int wr, int wc, int fr, int fq) const {
;     ...
;                         for (int ai = 0; ai < 2; ++ai)
; #pragma unroll
;                             for (int m = 0; m < 4; ++m) if (rrow[ai][m] >= 0) { float o[8];
; #pragma unroll
;                                 for (int n = 0; n < 2; ++n)
; #pragma unroll
;                                     for (int j = 0; j < 4; ++j) { const float x = acc[ai][bj][m][n][j]; o[n * 4 + j] = kd == 1 ? tanhf_(x) : (kd == 2 ? sigmoidf_(x) : x); }
;                                 *(v4u*)(A2 + (size_t)rrow[ai][m] * KL2 + c) = pack8(o); }
.LBB0_1093:
	v_mul_f32_e32 v0, 0xbfb8aa3b, v62
	v_mul_f32_e32 v131, 0xbfb8aa3b, v63
	v_mul_f32_e32 v133, 0xbfb8aa3b, v64
	v_mul_f32_e32 v135, 0xbfb8aa3b, v65
	v_mul_f32_e32 v137, 0xbfb8aa3b, v54
	v_mul_f32_e32 v139, 0xbfb8aa3b, v55
	v_mul_f32_e32 v141, 0xbfb8aa3b, v56
	v_mul_f32_e32 v143, 0xbfb8aa3b, v57
	v_exp_f32_e32 v0, v0
	v_exp_f32_e32 v131, v131
	v_exp_f32_e32 v133, v133
	v_exp_f32_e32 v135, v135
	v_exp_f32_e32 v137, v137
	v_exp_f32_e32 v139, v139
	v_exp_f32_e32 v141, v141
	v_exp_f32_e32 v143, v143
	v_add_f32_e32 v0, 1.0, v0
	v_add_f32_e32 v131, 1.0, v131
	v_add_f32_e32 v133, 1.0, v133
	v_add_f32_e32 v135, 1.0, v135
	v_add_f32_e32 v137, 1.0, v137
	v_add_f32_e32 v139, 1.0, v139
	v_add_f32_e32 v141, 1.0, v141
	v_add_f32_e32 v143, 1.0, v143
	v_rcp_f32_e32 v0, v0
	v_rcp_f32_e32 v131, v131
	v_rcp_f32_e32 v133, v133
	v_rcp_f32_e32 v135, v135
	v_rcp_f32_e32 v137, v137
	v_rcp_f32_e32 v139, v139
	v_rcp_f32_e32 v141, v141
	v_rcp_f32_e32 v143, v143
	v_mad_u64_u32 v[152:153], s[0:1], v136, s83, v[146:147]
	v_cndmask_b32_e32 v0, v62, v0, vcc
	v_cndmask_b32_e32 v131, v63, v131, vcc
	v_cndmask_b32_e32 v133, v64, v133, vcc
	v_cndmask_b32_e32 v135, v65, v135, vcc
	v_cndmask_b32_e32 v137, v54, v137, vcc
	v_cndmask_b32_e32 v139, v55, v139, vcc
	v_cndmask_b32_e32 v141, v56, v141, vcc
	v_cndmask_b32_e32 v143, v57, v143, vcc
	v_cvt_pk_bf16_f32 v148, v0, v131
	v_cvt_pk_bf16_f32 v149, v133, v135
	v_cvt_pk_bf16_f32 v150, v137, v139
	v_cvt_pk_bf16_f32 v151, v141, v143
	global_store_dwordx4 v[152:153], v[148:151], off nt
	s_or_b64 exec, exec, s[44:45]
	v_cmp_lt_i32_e64 s[0:1], -1, v134
	s_and_saveexec_b64 s[44:45], s[0:1]
	s_cbranch_execnz .LBB0_1101

; __device__ __forceinline__ v4u pack8(const float (&f)[8]) { v4u w; w.x = cvt_pk_bf16(f[0], f[1]); w.y = cvt_pk_bf16(f[2], f[3]); w.z = cvt_pk_bf16(f[4], f[5]); w.w = cvt_pk_bf16(f[6], f[7]); return w; }
; __device__ __forceinline__ float sigmoidf_(float x) { return rcpf_(1.f + __expf(-x)); }
; __device__ __forceinline__ float tanhf_(float x) { return 1.f - 2.f * rcpf_(1.f + __expf(2.f * x)); }
;     __device__ __forceinline__ void operator()(const f32x4 (&acc)[2][2][4][2], const Unit& u, int wr, int wc, int fr, int fq) const {
;     ...
;                         for (int ai = 0; ai < 2; ++ai)
; #pragma unroll
;                             for (int m = 0; m < 4; ++m) if (rrow[ai][m] >= 0) { float o[8];
; #pragma unroll
;                                 for (int n = 0; n < 2; ++n)
; #pragma unroll
;                                     for (int j = 0; j < 4; ++j) { const float x = acc[ai][bj][m][n][j]; o[n * 4 + j] = kd == 1 ? tanhf_(x) : (kd == 2 ? sigmoidf_(x) : x); }
;                                 *(v4u*)(A2 + (size_t)rrow[ai][m] * KL2 + c) = pack8(o); }
.LBB0_1095:
	v_mul_f32_e32 v0, 0xbfb8aa3b, v30
	v_mul_f32_e32 v131, 0xbfb8aa3b, v31
	v_mul_f32_e32 v133, 0xbfb8aa3b, v32
	v_mul_f32_e32 v135, 0xbfb8aa3b, v33
	v_mul_f32_e32 v137, 0xbfb8aa3b, v22
	v_mul_f32_e32 v139, 0xbfb8aa3b, v23
	v_mul_f32_e32 v141, 0xbfb8aa3b, v24
	v_mul_f32_e32 v143, 0xbfb8aa3b, v25
	v_exp_f32_e32 v0, v0
	v_exp_f32_e32 v131, v131
	v_exp_f32_e32 v133, v133
	v_exp_f32_e32 v135, v135
	v_exp_f32_e32 v137, v137
	v_exp_f32_e32 v139, v139
	v_exp_f32_e32 v141, v141
	v_exp_f32_e32 v143, v143
	v_add_f32_e32 v0, 1.0, v0
	v_add_f32_e32 v131, 1.0, v131
	v_add_f32_e32 v133, 1.0, v133
	v_add_f32_e32 v135, 1.0, v135
	v_add_f32_e32 v137, 1.0, v137
	v_add_f32_e32 v139, 1.0, v139
	v_add_f32_e32 v141, 1.0, v141
	v_add_f32_e32 v143, 1.0, v143
	v_rcp_f32_e32 v0, v0
	v_rcp_f32_e32 v131, v131
	v_rcp_f32_e32 v133, v133
	v_rcp_f32_e32 v135, v135
	v_rcp_f32_e32 v137, v137
	v_rcp_f32_e32 v139, v139
	v_rcp_f32_e32 v141, v141
	v_rcp_f32_e32 v143, v143
	v_mad_u64_u32 v[152:153], s[0:1], v132, s83, v[146:147]
	v_cndmask_b32_e32 v0, v30, v0, vcc
	v_cndmask_b32_e32 v131, v31, v131, vcc
	v_cndmask_b32_e32 v133, v32, v133, vcc
	v_cndmask_b32_e32 v135, v33, v135, vcc
	v_cndmask_b32_e32 v137, v22, v137, vcc
	v_cndmask_b32_e32 v139, v23, v139, vcc
	v_cndmask_b32_e32 v141, v24, v141, vcc
	v_cndmask_b32_e32 v143, v25, v143, vcc
	v_cvt_pk_bf16_f32 v148, v0, v131
	v_cvt_pk_bf16_f32 v149, v133, v135
	v_cvt_pk_bf16_f32 v150, v137, v139
	v_cvt_pk_bf16_f32 v151, v141, v143
	global_store_dwordx4 v[152:153], v[148:151], off nt
	s_or_b64 exec, exec, s[44:45]
	s_waitcnt lgkmcnt(0)
	v_cmp_lt_i32_e64 s[0:1], -1, v130
	s_and_b64 exec, exec, s[0:1]
	s_cbranch_execnz .LBB0_1103
	s_branch .LBB0_1104

; __device__ __forceinline__ v4u pack8(const float (&f)[8]) { v4u w; w.x = cvt_pk_bf16(f[0], f[1]); w.y = cvt_pk_bf16(f[2], f[3]); w.z = cvt_pk_bf16(f[4], f[5]); w.w = cvt_pk_bf16(f[6], f[7]); return w; }
; __device__ __forceinline__ float sigmoidf_(float x) { return rcpf_(1.f + __expf(-x)); }
; __device__ __forceinline__ float tanhf_(float x) { return 1.f - 2.f * rcpf_(1.f + __expf(2.f * x)); }
;     __device__ __forceinline__ void operator()(const f32x4 (&acc)[2][2][4][2], const Unit& u, int wr, int wc, int fr, int fq) const {
;     ...
;                         for (int ai = 0; ai < 2; ++ai)
; #pragma unroll
;                             for (int m = 0; m < 4; ++m) if (rrow[ai][m] >= 0) { float o[8];
; #pragma unroll
;                                 for (int n = 0; n < 2; ++n)
; #pragma unroll
;                                     for (int j = 0; j < 4; ++j) { const float x = acc[ai][bj][m][n][j]; o[n * 4 + j] = kd == 1 ? tanhf_(x) : (kd == 2 ? sigmoidf_(x) : x); }
;                                 *(v4u*)(A2 + (size_t)rrow[ai][m] * KL2 + c) = pack8(o); }
.LBB0_1097:
	v_mul_f32_e32 v0, 0xbfb8aa3b, v110
	v_mul_f32_e32 v131, 0xbfb8aa3b, v111
	v_mul_f32_e32 v133, 0xbfb8aa3b, v112
	v_mul_f32_e32 v135, 0xbfb8aa3b, v113
	v_mul_f32_e32 v137, 0xbfb8aa3b, v102
	v_mul_f32_e32 v139, 0xbfb8aa3b, v103
	v_mul_f32_e32 v141, 0xbfb8aa3b, v104
	v_mul_f32_e32 v143, 0xbfb8aa3b, v105
	v_exp_f32_e32 v0, v0
	v_exp_f32_e32 v131, v131
	v_exp_f32_e32 v133, v133
	v_exp_f32_e32 v135, v135
	v_exp_f32_e32 v137, v137
	v_exp_f32_e32 v139, v139
	v_exp_f32_e32 v141, v141
	v_exp_f32_e32 v143, v143
	v_add_f32_e32 v0, 1.0, v0
	v_add_f32_e32 v131, 1.0, v131
	v_add_f32_e32 v133, 1.0, v133
	v_add_f32_e32 v135, 1.0, v135
	v_add_f32_e32 v137, 1.0, v137
	v_add_f32_e32 v139, 1.0, v139
	v_add_f32_e32 v141, 1.0, v141
	v_add_f32_e32 v143, 1.0, v143
	v_rcp_f32_e32 v0, v0
	v_rcp_f32_e32 v131, v131
	v_rcp_f32_e32 v133, v133
	v_rcp_f32_e32 v135, v135
	v_rcp_f32_e32 v137, v137
	v_rcp_f32_e32 v139, v139
	v_rcp_f32_e32 v141, v141
	v_rcp_f32_e32 v143, v143
	v_mad_u64_u32 v[152:153], s[0:1], v142, s83, v[146:147]
	v_cndmask_b32_e32 v0, v110, v0, vcc
	v_cndmask_b32_e32 v131, v111, v131, vcc
	v_cndmask_b32_e32 v133, v112, v133, vcc
	v_cndmask_b32_e32 v135, v113, v135, vcc
	v_cndmask_b32_e32 v137, v102, v137, vcc
	v_cndmask_b32_e32 v139, v103, v139, vcc
	v_cndmask_b32_e32 v141, v104, v141, vcc
	v_cndmask_b32_e32 v143, v105, v143, vcc
	v_cvt_pk_bf16_f32 v148, v0, v131
	v_cvt_pk_bf16_f32 v149, v133, v135
	v_cvt_pk_bf16_f32 v150, v137, v139
	v_cvt_pk_bf16_f32 v151, v141, v143
	global_store_dwordx4 v[152:153], v[148:151], off nt
	s_or_b64 exec, exec, s[44:45]
	v_cmp_lt_i32_e64 s[0:1], -1, v140
	s_and_saveexec_b64 s[44:45], s[0:1]
	s_cbranch_execnz .LBB0_1091

; __device__ __forceinline__ v4u pack8(const float (&f)[8]) { v4u w; w.x = cvt_pk_bf16(f[0], f[1]); w.y = cvt_pk_bf16(f[2], f[3]); w.z = cvt_pk_bf16(f[4], f[5]); w.w = cvt_pk_bf16(f[6], f[7]); return w; }
; __device__ __forceinline__ float sigmoidf_(float x) { return rcpf_(1.f + __expf(-x)); }
; __device__ __forceinline__ float tanhf_(float x) { return 1.f - 2.f * rcpf_(1.f + __expf(2.f * x)); }
;     __device__ __forceinline__ void operator()(const f32x4 (&acc)[2][2][4][2], const Unit& u, int wr, int wc, int fr, int fq) const {
;     ...
;                         for (int ai = 0; ai < 2; ++ai)
; #pragma unroll
;                             for (int m = 0; m < 4; ++m) if (rrow[ai][m] >= 0) { float o[8];
; #pragma unroll
;                                 for (int n = 0; n < 2; ++n)
; #pragma unroll
;                                     for (int j = 0; j < 4; ++j) { const float x = acc[ai][bj][m][n][j]; o[n * 4 + j] = kd == 1 ? tanhf_(x) : (kd == 2 ? sigmoidf_(x) : x); }
;                                 *(v4u*)(A2 + (size_t)rrow[ai][m] * KL2 + c) = pack8(o); }
.LBB0_1099:
	v_mul_f32_e32 v0, 0xbfb8aa3b, v78
	v_mul_f32_e32 v131, 0xbfb8aa3b, v79
	v_mul_f32_e32 v133, 0xbfb8aa3b, v80
	v_mul_f32_e32 v135, 0xbfb8aa3b, v81
	v_mul_f32_e32 v137, 0xbfb8aa3b, v70
	v_mul_f32_e32 v139, 0xbfb8aa3b, v71
	v_mul_f32_e32 v141, 0xbfb8aa3b, v72
	v_mul_f32_e32 v143, 0xbfb8aa3b, v73
	v_exp_f32_e32 v0, v0
	v_exp_f32_e32 v131, v131
	v_exp_f32_e32 v133, v133
	v_exp_f32_e32 v135, v135
	v_exp_f32_e32 v137, v137
	v_exp_f32_e32 v139, v139
	v_exp_f32_e32 v141, v141
	v_exp_f32_e32 v143, v143
	v_add_f32_e32 v0, 1.0, v0
	v_add_f32_e32 v131, 1.0, v131
	v_add_f32_e32 v133, 1.0, v133
	v_add_f32_e32 v135, 1.0, v135
	v_add_f32_e32 v137, 1.0, v137
	v_add_f32_e32 v139, 1.0, v139
	v_add_f32_e32 v141, 1.0, v141
	v_add_f32_e32 v143, 1.0, v143
	v_rcp_f32_e32 v0, v0
	v_rcp_f32_e32 v131, v131
	v_rcp_f32_e32 v133, v133
	v_rcp_f32_e32 v135, v135
	v_rcp_f32_e32 v137, v137
	v_rcp_f32_e32 v139, v139
	v_rcp_f32_e32 v141, v141
	v_rcp_f32_e32 v143, v143
	v_mad_u64_u32 v[152:153], s[0:1], v138, s83, v[146:147]
	v_cndmask_b32_e32 v0, v78, v0, vcc
	v_cndmask_b32_e32 v131, v79, v131, vcc
	v_cndmask_b32_e32 v133, v80, v133, vcc
	v_cndmask_b32_e32 v135, v81, v135, vcc
	v_cndmask_b32_e32 v137, v70, v137, vcc
	v_cndmask_b32_e32 v139, v71, v139, vcc
	v_cndmask_b32_e32 v141, v72, v141, vcc
	v_cndmask_b32_e32 v143, v73, v143, vcc
	v_cvt_pk_bf16_f32 v148, v0, v131
	v_cvt_pk_bf16_f32 v149, v133, v135
	v_cvt_pk_bf16_f32 v150, v137, v139
	v_cvt_pk_bf16_f32 v151, v141, v143
	global_store_dwordx4 v[152:153], v[148:151], off nt
	s_or_b64 exec, exec, s[44:45]
	v_cmp_lt_i32_e64 s[0:1], -1, v136
	s_and_saveexec_b64 s[44:45], s[0:1]
	s_cbranch_execnz .LBB0_1093

; __device__ __forceinline__ v4u pack8(const float (&f)[8]) { v4u w; w.x = cvt_pk_bf16(f[0], f[1]); w.y = cvt_pk_bf16(f[2], f[3]); w.z = cvt_pk_bf16(f[4], f[5]); w.w = cvt_pk_bf16(f[6], f[7]); return w; }
; __device__ __forceinline__ float sigmoidf_(float x) { return rcpf_(1.f + __expf(-x)); }
; __device__ __forceinline__ float tanhf_(float x) { return 1.f - 2.f * rcpf_(1.f + __expf(2.f * x)); }
;     __device__ __forceinline__ void operator()(const f32x4 (&acc)[2][2][4][2], const Unit& u, int wr, int wc, int fr, int fq) const {
;     ...
;                         for (int ai = 0; ai < 2; ++ai)
; #pragma unroll
;                             for (int m = 0; m < 4; ++m) if (rrow[ai][m] >= 0) { float o[8];
; #pragma unroll
;                                 for (int n = 0; n < 2; ++n)
; #pragma unroll
;                                     for (int j = 0; j < 4; ++j) { const float x = acc[ai][bj][m][n][j]; o[n * 4 + j] = kd == 1 ? tanhf_(x) : (kd == 2 ? sigmoidf_(x) : x); }
;                                 *(v4u*)(A2 + (size_t)rrow[ai][m] * KL2 + c) = pack8(o); }
.LBB0_1101:
	v_mul_f32_e32 v0, 0xbfb8aa3b, v46
	v_mul_f32_e32 v131, 0xbfb8aa3b, v47
	v_mul_f32_e32 v133, 0xbfb8aa3b, v48
	v_mul_f32_e32 v135, 0xbfb8aa3b, v49
	v_mul_f32_e32 v137, 0xbfb8aa3b, v38
	v_mul_f32_e32 v139, 0xbfb8aa3b, v39
	v_mul_f32_e32 v141, 0xbfb8aa3b, v40
	v_mul_f32_e32 v143, 0xbfb8aa3b, v41
	v_exp_f32_e32 v0, v0
	v_exp_f32_e32 v131, v131
	v_exp_f32_e32 v133, v133
	v_exp_f32_e32 v135, v135
	v_exp_f32_e32 v137, v137
	v_exp_f32_e32 v139, v139
	v_exp_f32_e32 v141, v141
	v_exp_f32_e32 v143, v143
	v_add_f32_e32 v0, 1.0, v0
	v_add_f32_e32 v131, 1.0, v131
	v_add_f32_e32 v133, 1.0, v133
	v_add_f32_e32 v135, 1.0, v135
	v_add_f32_e32 v137, 1.0, v137
	v_add_f32_e32 v139, 1.0, v139
	v_add_f32_e32 v141, 1.0, v141
	v_add_f32_e32 v143, 1.0, v143
	v_rcp_f32_e32 v0, v0
	v_rcp_f32_e32 v131, v131
	v_rcp_f32_e32 v133, v133
	v_rcp_f32_e32 v135, v135
	v_rcp_f32_e32 v137, v137
	v_rcp_f32_e32 v139, v139
	v_rcp_f32_e32 v141, v141
	v_rcp_f32_e32 v143, v143
	v_mad_u64_u32 v[152:153], s[0:1], v134, s83, v[146:147]
	v_cndmask_b32_e32 v0, v46, v0, vcc
	v_cndmask_b32_e32 v131, v47, v131, vcc
	v_cndmask_b32_e32 v133, v48, v133, vcc
	v_cndmask_b32_e32 v135, v49, v135, vcc
	v_cndmask_b32_e32 v137, v38, v137, vcc
	v_cndmask_b32_e32 v139, v39, v139, vcc
	v_cndmask_b32_e32 v141, v40, v141, vcc
	v_cndmask_b32_e32 v143, v41, v143, vcc
	v_cvt_pk_bf16_f32 v148, v0, v131
	v_cvt_pk_bf16_f32 v149, v133, v135
	v_cvt_pk_bf16_f32 v150, v137, v139
	v_cvt_pk_bf16_f32 v151, v141, v143
	global_store_dwordx4 v[152:153], v[148:151], off nt
	s_or_b64 exec, exec, s[44:45]
	v_cmp_lt_i32_e64 s[0:1], -1, v132
	s_and_saveexec_b64 s[44:45], s[0:1]
	s_cbranch_execnz .LBB0_1095

; __device__ __forceinline__ v4u pack8(const float (&f)[8]) { v4u w; w.x = cvt_pk_bf16(f[0], f[1]); w.y = cvt_pk_bf16(f[2], f[3]); w.z = cvt_pk_bf16(f[4], f[5]); w.w = cvt_pk_bf16(f[6], f[7]); return w; }
; __device__ __forceinline__ float sigmoidf_(float x) { return rcpf_(1.f + __expf(-x)); }
; __device__ __forceinline__ float tanhf_(float x) { return 1.f - 2.f * rcpf_(1.f + __expf(2.f * x)); }
;     __device__ __forceinline__ void operator()(const f32x4 (&acc)[2][2][4][2], const Unit& u, int wr, int wc, int fr, int fq) const {
;     ...
;                         for (int ai = 0; ai < 2; ++ai)
; #pragma unroll
;                             for (int m = 0; m < 4; ++m) if (rrow[ai][m] >= 0) { float o[8];
; #pragma unroll
;                                 for (int n = 0; n < 2; ++n)
; #pragma unroll
;                                     for (int j = 0; j < 4; ++j) { const float x = acc[ai][bj][m][n][j]; o[n * 4 + j] = kd == 1 ? tanhf_(x) : (kd == 2 ? sigmoidf_(x) : x); }
;                                 *(v4u*)(A2 + (size_t)rrow[ai][m] * KL2 + c) = pack8(o); }
.LBB0_1103:
	v_mul_f32_e32 v0, 0xbfb8aa3b, v14
	v_mul_f32_e32 v131, 0xbfb8aa3b, v15
	v_mul_f32_e32 v133, 0xbfb8aa3b, v16
	v_mul_f32_e32 v135, 0xbfb8aa3b, v17
	v_mul_f32_e32 v137, 0xbfb8aa3b, v2
	v_mul_f32_e32 v139, 0xbfb8aa3b, v3
	v_mul_f32_e32 v141, 0xbfb8aa3b, v4
	v_mul_f32_e32 v143, 0xbfb8aa3b, v5
	v_exp_f32_e32 v0, v0
	v_exp_f32_e32 v131, v131
	v_exp_f32_e32 v133, v133
	v_exp_f32_e32 v135, v135
	v_exp_f32_e32 v137, v137
	v_exp_f32_e32 v139, v139
	v_exp_f32_e32 v141, v141
	v_exp_f32_e32 v143, v143
	v_add_f32_e32 v0, 1.0, v0
	v_add_f32_e32 v131, 1.0, v131
	v_add_f32_e32 v133, 1.0, v133
	v_add_f32_e32 v135, 1.0, v135
	v_add_f32_e32 v137, 1.0, v137
	v_add_f32_e32 v139, 1.0, v139
	v_add_f32_e32 v141, 1.0, v141
	v_add_f32_e32 v143, 1.0, v143
	v_rcp_f32_e32 v0, v0
	v_rcp_f32_e32 v131, v131
	v_rcp_f32_e32 v133, v133
	v_rcp_f32_e32 v135, v135
	v_rcp_f32_e32 v137, v137
	v_rcp_f32_e32 v139, v139
	v_rcp_f32_e32 v141, v141
	v_rcp_f32_e32 v143, v143
	v_mad_u64_u32 v[146:147], s[0:1], v130, s83, v[146:147]
	v_cndmask_b32_e32 v0, v14, v0, vcc
	v_cndmask_b32_e32 v131, v15, v131, vcc
	v_cndmask_b32_e32 v133, v16, v133, vcc
	v_cndmask_b32_e32 v135, v17, v135, vcc
	v_cndmask_b32_e32 v137, v2, v137, vcc
	v_cndmask_b32_e32 v139, v3, v139, vcc
	v_cndmask_b32_e32 v141, v4, v141, vcc
	v_cndmask_b32_e32 v143, v5, v143, vcc
	v_cvt_pk_bf16_f32 v148, v0, v131
	v_cvt_pk_bf16_f32 v149, v133, v135
	v_cvt_pk_bf16_f32 v150, v137, v139
	v_cvt_pk_bf16_f32 v151, v141, v143
	global_store_dwordx4 v[146:147], v[148:151], off nt

; __device__ __forceinline__ v4u pack8(const float (&f)[8]) { v4u w; w.x = cvt_pk_bf16(f[0], f[1]); w.y = cvt_pk_bf16(f[2], f[3]); w.z = cvt_pk_bf16(f[4], f[5]); w.w = cvt_pk_bf16(f[6], f[7]); return w; }
;     __device__ __forceinline__ void operator()(const f32x4 (&acc)[2][2][4][2], const Unit& u, int wr, int wc, int fr, int fq) const {
;     ...
;             if (u.pn < 12) {
;                 bf16* dst = (bf16*)(ws + (u.pn < 4 ? WS_R : (u.pn < 8 ? WS_K : (jl == 0 ? WS_VF : WS_VB)))) + (u.pn & 3) * 256 + cw;
; #pragma unroll
;                 for (int ai = 0; ai < 2; ++ai)
; #pragma unroll
;                     for (int m = 0; m < 4; ++m) if (rrow[ai][m] >= 0) {
;                         bf16* rp = dst + (size_t)rrow[ai][m] * D;
; #pragma unroll
;                         for (int bj = 0; bj < 2; ++bj) { float o[8];
; #pragma unroll
;                             for (int n = 0; n < 2; ++n)
; #pragma unroll
;                                 for (int j = 0; j < 4; ++j) o[n * 4 + j] = acc[ai][bj][m][n][j];
;                             *(v4u*)(rp + bj * 128) = pack8(o); }
;                     }
.LBB0_1105:
	s_cmp_gt_u32 s87, 7
	s_cselect_b32 s0, s15, 0x19000000
	s_cselect_b32 s1, 0, 0
	s_cmp_gt_i32 s87, 3
	v_readlane_b32 s20, v254, 38
	s_cselect_b32 s0, s0, 0x14f00000
	v_readlane_b32 s22, v254, 40
	s_cselect_b32 s1, s1, 0
	v_readlane_b32 s23, v254, 41
	s_add_u32 s0, s22, s0
	s_addc_u32 s1, s23, s1
	s_lshl_b32 s10, s87, 9
	s_and_b32 s10, s10, 0x600
	s_add_u32 s0, s0, s10
	s_addc_u32 s1, s1, 0
	v_lshlrev_b32_e32 v0, 1, v204
	v_lshl_add_u64 v[146:147], s[0:1], 0, v[0:1]
	v_cmp_lt_i32_e32 vcc, -1, v144
	v_readlane_b32 s21, v254, 39
	s_and_saveexec_b64 s[0:1], vcc
	s_cbranch_execz .LBB0_1113
	v_mov_b32_e32 v145, v1
	v_lshlrev_b64 v[144:145], 11, v[144:145]
	v_lshl_add_u64 v[144:145], v[146:147], 0, v[144:145]
	v_cvt_pk_bf16_f32 v148, v122, v123
	v_cvt_pk_bf16_f32 v149, v124, v125
	v_cvt_pk_bf16_f32 v150, v114, v115
	v_cvt_pk_bf16_f32 v151, v116, v117
	global_store_dwordx4 v[144:145], v[148:151], off nt
	s_nop 1
	v_cvt_pk_bf16_f32 v148, v126, v127
	v_cvt_pk_bf16_f32 v149, v128, v129
	v_cvt_pk_bf16_f32 v150, v118, v119
	v_cvt_pk_bf16_f32 v151, v120, v121
	global_store_dwordx4 v[144:145], v[148:151], off offset:256 nt
	s_or_b64 exec, exec, s[0:1]
	v_cmp_lt_i32_e32 vcc, -1, v142
	s_and_saveexec_b64 s[0:1], vcc
	s_cbranch_execnz .LBB0_1114

; __device__ __forceinline__ v4u pack8(const float (&f)[8]) { v4u w; w.x = cvt_pk_bf16(f[0], f[1]); w.y = cvt_pk_bf16(f[2], f[3]); w.z = cvt_pk_bf16(f[4], f[5]); w.w = cvt_pk_bf16(f[6], f[7]); return w; }
;     __device__ __forceinline__ void operator()(const f32x4 (&acc)[2][2][4][2], const Unit& u, int wr, int wc, int fr, int fq) const {
;     ...
;                     for (int m = 0; m < 4; ++m) if (rrow[ai][m] >= 0) {
;                         bf16* rp = dst + (size_t)rrow[ai][m] * D;
; #pragma unroll
;                         for (int bj = 0; bj < 2; ++bj) { float o[8];
; #pragma unroll
;                             for (int n = 0; n < 2; ++n)
; #pragma unroll
;                                 for (int j = 0; j < 4; ++j) o[n * 4 + j] = acc[ai][bj][m][n][j];
;                             *(v4u*)(rp + bj * 128) = pack8(o); }
;                     }
.LBB0_1108:
	v_mov_b32_e32 v141, v1
	v_lshlrev_b64 v[140:141], 11, v[140:141]
	v_lshl_add_u64 v[144:145], v[146:147], 0, v[140:141]
	v_cvt_pk_bf16_f32 v140, v90, v91
	v_cvt_pk_bf16_f32 v141, v92, v93
	v_cvt_pk_bf16_f32 v142, v82, v83
	v_cvt_pk_bf16_f32 v143, v84, v85
	global_store_dwordx4 v[144:145], v[140:143], off nt
	s_nop 1
	v_cvt_pk_bf16_f32 v140, v94, v95
	v_cvt_pk_bf16_f32 v141, v96, v97
	v_cvt_pk_bf16_f32 v142, v86, v87
	v_cvt_pk_bf16_f32 v143, v88, v89
	global_store_dwordx4 v[144:145], v[140:143], off offset:256 nt
	s_or_b64 exec, exec, s[0:1]
	v_cmp_lt_i32_e32 vcc, -1, v138
	s_and_saveexec_b64 s[0:1], vcc
	s_cbranch_execnz .LBB0_1116

; __device__ __forceinline__ v4u pack8(const float (&f)[8]) { v4u w; w.x = cvt_pk_bf16(f[0], f[1]); w.y = cvt_pk_bf16(f[2], f[3]); w.z = cvt_pk_bf16(f[4], f[5]); w.w = cvt_pk_bf16(f[6], f[7]); return w; }
;     __device__ __forceinline__ void operator()(const f32x4 (&acc)[2][2][4][2], const Unit& u, int wr, int wc, int fr, int fq) const {
;     ...
;                     for (int m = 0; m < 4; ++m) if (rrow[ai][m] >= 0) {
;                         bf16* rp = dst + (size_t)rrow[ai][m] * D;
; #pragma unroll
;                         for (int bj = 0; bj < 2; ++bj) { float o[8];
; #pragma unroll
;                             for (int n = 0; n < 2; ++n)
; #pragma unroll
;                                 for (int j = 0; j < 4; ++j) o[n * 4 + j] = acc[ai][bj][m][n][j];
;                             *(v4u*)(rp + bj * 128) = pack8(o); }
;                     }
.LBB0_1110:
	v_mov_b32_e32 v137, v1
	v_lshlrev_b64 v[136:137], 11, v[136:137]
	v_lshl_add_u64 v[140:141], v[146:147], 0, v[136:137]
	v_cvt_pk_bf16_f32 v136, v58, v59
	v_cvt_pk_bf16_f32 v137, v60, v61
	v_cvt_pk_bf16_f32 v138, v50, v51
	v_cvt_pk_bf16_f32 v139, v52, v53
	global_store_dwordx4 v[140:141], v[136:139], off nt
	s_nop 1
	v_cvt_pk_bf16_f32 v136, v62, v63
	v_cvt_pk_bf16_f32 v137, v64, v65
	v_cvt_pk_bf16_f32 v138, v54, v55
	v_cvt_pk_bf16_f32 v139, v56, v57
	global_store_dwordx4 v[140:141], v[136:139], off offset:256 nt
	s_or_b64 exec, exec, s[0:1]
	v_cmp_lt_i32_e32 vcc, -1, v134
	s_and_saveexec_b64 s[0:1], vcc
	s_cbranch_execnz .LBB0_1118

; __device__ __forceinline__ v4u pack8(const float (&f)[8]) { v4u w; w.x = cvt_pk_bf16(f[0], f[1]); w.y = cvt_pk_bf16(f[2], f[3]); w.z = cvt_pk_bf16(f[4], f[5]); w.w = cvt_pk_bf16(f[6], f[7]); return w; }
;     __device__ __forceinline__ void operator()(const f32x4 (&acc)[2][2][4][2], const Unit& u, int wr, int wc, int fr, int fq) const {
;     ...
;                     for (int m = 0; m < 4; ++m) if (rrow[ai][m] >= 0) {
;                         bf16* rp = dst + (size_t)rrow[ai][m] * D;
; #pragma unroll
;                         for (int bj = 0; bj < 2; ++bj) { float o[8];
; #pragma unroll
;                             for (int n = 0; n < 2; ++n)
; #pragma unroll
;                                 for (int j = 0; j < 4; ++j) o[n * 4 + j] = acc[ai][bj][m][n][j];
;                             *(v4u*)(rp + bj * 128) = pack8(o); }
;                     }
.LBB0_1112:
	v_mov_b32_e32 v133, v1
	v_lshlrev_b64 v[132:133], 11, v[132:133]
	v_lshl_add_u64 v[136:137], v[146:147], 0, v[132:133]
	v_cvt_pk_bf16_f32 v132, v26, v27
	v_cvt_pk_bf16_f32 v133, v28, v29
	v_cvt_pk_bf16_f32 v134, v18, v19
	v_cvt_pk_bf16_f32 v135, v20, v21
	global_store_dwordx4 v[136:137], v[132:135], off nt
	s_nop 1
	v_cvt_pk_bf16_f32 v132, v30, v31
	v_cvt_pk_bf16_f32 v133, v32, v33
	v_cvt_pk_bf16_f32 v134, v22, v23
	v_cvt_pk_bf16_f32 v135, v24, v25
	global_store_dwordx4 v[136:137], v[132:135], off offset:256 nt
	s_or_b64 exec, exec, s[0:1]
	s_waitcnt lgkmcnt(0)
	v_cmp_lt_i32_e32 vcc, -1, v130
	s_and_saveexec_b64 s[0:1], vcc
	s_cbranch_execnz .LBB0_1120
	s_branch .LBB0_1121

; __device__ __forceinline__ v4u pack8(const float (&f)[8]) { v4u w; w.x = cvt_pk_bf16(f[0], f[1]); w.y = cvt_pk_bf16(f[2], f[3]); w.z = cvt_pk_bf16(f[4], f[5]); w.w = cvt_pk_bf16(f[6], f[7]); return w; }
;     __device__ __forceinline__ void operator()(const f32x4 (&acc)[2][2][4][2], const Unit& u, int wr, int wc, int fr, int fq) const {
;     ...
;                     for (int m = 0; m < 4; ++m) if (rrow[ai][m] >= 0) {
;                         bf16* rp = dst + (size_t)rrow[ai][m] * D;
; #pragma unroll
;                         for (int bj = 0; bj < 2; ++bj) { float o[8];
; #pragma unroll
;                             for (int n = 0; n < 2; ++n)
; #pragma unroll
;                                 for (int j = 0; j < 4; ++j) o[n * 4 + j] = acc[ai][bj][m][n][j];
;                             *(v4u*)(rp + bj * 128) = pack8(o); }
;                     }
.LBB0_1114:
	v_mov_b32_e32 v143, v1
	v_lshlrev_b64 v[142:143], 11, v[142:143]
	v_lshl_add_u64 v[148:149], v[146:147], 0, v[142:143]
	v_cvt_pk_bf16_f32 v142, v106, v107
	v_cvt_pk_bf16_f32 v143, v108, v109
	v_cvt_pk_bf16_f32 v144, v98, v99
	v_cvt_pk_bf16_f32 v145, v100, v101
	global_store_dwordx4 v[148:149], v[142:145], off nt
	s_nop 1
	v_cvt_pk_bf16_f32 v142, v110, v111
	v_cvt_pk_bf16_f32 v143, v112, v113
	v_cvt_pk_bf16_f32 v144, v102, v103
	v_cvt_pk_bf16_f32 v145, v104, v105
	global_store_dwordx4 v[148:149], v[142:145], off offset:256 nt
	s_or_b64 exec, exec, s[0:1]
	v_cmp_lt_i32_e32 vcc, -1, v140
	s_and_saveexec_b64 s[0:1], vcc
	s_cbranch_execnz .LBB0_1108

; __device__ __forceinline__ v4u pack8(const float (&f)[8]) { v4u w; w.x = cvt_pk_bf16(f[0], f[1]); w.y = cvt_pk_bf16(f[2], f[3]); w.z = cvt_pk_bf16(f[4], f[5]); w.w = cvt_pk_bf16(f[6], f[7]); return w; }
;     __device__ __forceinline__ void operator()(const f32x4 (&acc)[2][2][4][2], const Unit& u, int wr, int wc, int fr, int fq) const {
;     ...
;                     for (int m = 0; m < 4; ++m) if (rrow[ai][m] >= 0) {
;                         bf16* rp = dst + (size_t)rrow[ai][m] * D;
; #pragma unroll
;                         for (int bj = 0; bj < 2; ++bj) { float o[8];
; #pragma unroll
;                             for (int n = 0; n < 2; ++n)
; #pragma unroll
;                                 for (int j = 0; j < 4; ++j) o[n * 4 + j] = acc[ai][bj][m][n][j];
;                             *(v4u*)(rp + bj * 128) = pack8(o); }
;                     }
.LBB0_1116:
	v_mov_b32_e32 v139, v1
	v_lshlrev_b64 v[138:139], 11, v[138:139]
	v_lshl_add_u64 v[142:143], v[146:147], 0, v[138:139]
	v_cvt_pk_bf16_f32 v138, v74, v75
	v_cvt_pk_bf16_f32 v139, v76, v77
	v_cvt_pk_bf16_f32 v140, v66, v67
	v_cvt_pk_bf16_f32 v141, v68, v69
	global_store_dwordx4 v[142:143], v[138:141], off nt
	s_nop 1
	v_cvt_pk_bf16_f32 v138, v78, v79
	v_cvt_pk_bf16_f32 v139, v80, v81
	v_cvt_pk_bf16_f32 v140, v70, v71
	v_cvt_pk_bf16_f32 v141, v72, v73
	global_store_dwordx4 v[142:143], v[138:141], off offset:256 nt
	s_or_b64 exec, exec, s[0:1]
	v_cmp_lt_i32_e32 vcc, -1, v136
	s_and_saveexec_b64 s[0:1], vcc
	s_cbranch_execnz .LBB0_1110

; __device__ __forceinline__ v4u pack8(const float (&f)[8]) { v4u w; w.x = cvt_pk_bf16(f[0], f[1]); w.y = cvt_pk_bf16(f[2], f[3]); w.z = cvt_pk_bf16(f[4], f[5]); w.w = cvt_pk_bf16(f[6], f[7]); return w; }
;     __device__ __forceinline__ void operator()(const f32x4 (&acc)[2][2][4][2], const Unit& u, int wr, int wc, int fr, int fq) const {
;     ...
;                     for (int m = 0; m < 4; ++m) if (rrow[ai][m] >= 0) {
;                         bf16* rp = dst + (size_t)rrow[ai][m] * D;
; #pragma unroll
;                         for (int bj = 0; bj < 2; ++bj) { float o[8];
; #pragma unroll
;                             for (int n = 0; n < 2; ++n)
; #pragma unroll
;                                 for (int j = 0; j < 4; ++j) o[n * 4 + j] = acc[ai][bj][m][n][j];
;                             *(v4u*)(rp + bj * 128) = pack8(o); }
;                     }
.LBB0_1118:
	v_mov_b32_e32 v135, v1
	v_lshlrev_b64 v[134:135], 11, v[134:135]
	v_lshl_add_u64 v[138:139], v[146:147], 0, v[134:135]
	v_cvt_pk_bf16_f32 v134, v42, v43
	v_cvt_pk_bf16_f32 v135, v44, v45
	v_cvt_pk_bf16_f32 v136, v34, v35
	v_cvt_pk_bf16_f32 v137, v36, v37
	global_store_dwordx4 v[138:139], v[134:137], off nt
	s_nop 1
	v_cvt_pk_bf16_f32 v134, v46, v47
	v_cvt_pk_bf16_f32 v135, v48, v49
	v_cvt_pk_bf16_f32 v136, v38, v39
	v_cvt_pk_bf16_f32 v137, v40, v41
	global_store_dwordx4 v[138:139], v[134:137], off offset:256 nt
	s_or_b64 exec, exec, s[0:1]
	v_cmp_lt_i32_e32 vcc, -1, v132
	s_and_saveexec_b64 s[0:1], vcc
	s_cbranch_execnz .LBB0_1112

; __device__ __forceinline__ v4u pack8(const float (&f)[8]) { v4u w; w.x = cvt_pk_bf16(f[0], f[1]); w.y = cvt_pk_bf16(f[2], f[3]); w.z = cvt_pk_bf16(f[4], f[5]); w.w = cvt_pk_bf16(f[6], f[7]); return w; }
;     __device__ __forceinline__ void operator()(const f32x4 (&acc)[2][2][4][2], const Unit& u, int wr, int wc, int fr, int fq) const {
;     ...
;                     for (int m = 0; m < 4; ++m) if (rrow[ai][m] >= 0) {
;                         bf16* rp = dst + (size_t)rrow[ai][m] * D;
; #pragma unroll
;                         for (int bj = 0; bj < 2; ++bj) { float o[8];
; #pragma unroll
;                             for (int n = 0; n < 2; ++n)
; #pragma unroll
;                                 for (int j = 0; j < 4; ++j) o[n * 4 + j] = acc[ai][bj][m][n][j];
;                             *(v4u*)(rp + bj * 128) = pack8(o); }
;                     }
.LBB0_1120:
	v_mov_b32_e32 v131, v1
	v_lshlrev_b64 v[130:131], 11, v[130:131]
	v_lshl_add_u64 v[134:135], v[146:147], 0, v[130:131]
	v_cvt_pk_bf16_f32 v130, v10, v11
	v_cvt_pk_bf16_f32 v131, v12, v13
	v_cvt_pk_bf16_f32 v132, v6, v7
	v_cvt_pk_bf16_f32 v133, v8, v9
	global_store_dwordx4 v[134:135], v[130:133], off nt
	s_nop 1
	v_cvt_pk_bf16_f32 v130, v14, v15
	v_cvt_pk_bf16_f32 v131, v16, v17
	v_cvt_pk_bf16_f32 v132, v2, v3
	v_cvt_pk_bf16_f32 v133, v4, v5
	global_store_dwordx4 v[134:135], v[130:133], off offset:256 nt

; __device__ __forceinline__ v4u pack8(const float (&f)[8]) { v4u w; w.x = cvt_pk_bf16(f[0], f[1]); w.y = cvt_pk_bf16(f[2], f[3]); w.z = cvt_pk_bf16(f[4], f[5]); w.w = cvt_pk_bf16(f[6], f[7]); return w; }
;     __device__ __forceinline__ void operator()(const f32x4 (&acc)[2][2][4][2], const Unit& u, int wr, int wc, int fr, int fq) const {
;     ...
;         } else if (GRP == 0) {
;             bf16* C = (bf16*)(ws + WS_L2);
;             const int col0 = u.pn * 256 + wc * 32 + 8 * fq;
; #pragma unroll
;             for (int ai = 0; ai < 2; ++ai)
; #pragma unroll
;                 for (int m = 0; m < 4; ++m) {
;                     bf16* rp = C + (size_t)(row0 + ai * 128 + m * 16) * NL2 + col0;
; #pragma unroll
;                     for (int bj = 0; bj < 2; ++bj) { float o[8];
; #pragma unroll
;                         for (int n = 0; n < 2; ++n)
; #pragma unroll
;                             for (int j = 0; j < 4; ++j) o[n * 4 + j] = acc[ai][bj][m][n][j];
;                         *(v4u*)(rp + bj * 128) = pack8(o); }
;                 }
.LBB0_1125:
	s_waitcnt lgkmcnt(0)
	v_lshl_or_b32 v130, s87, 8, v204
	v_readlane_b32 s0, v252, 32
	v_ashrrev_i32_e32 v131, 31, v130
	v_readlane_b32 s1, v252, 33
	v_ashrrev_i32_e32 v211, 31, v210
	v_cvt_pk_bf16_f32 v132, v122, v123
	v_cvt_pk_bf16_f32 v133, v124, v125
	v_cvt_pk_bf16_f32 v134, v114, v115
	v_cvt_pk_bf16_f32 v135, v116, v117
	s_nop 0
	v_lshl_add_u64 v[136:137], v[130:131], 1, s[0:1]
	v_lshlrev_b64 v[130:131], 13, v[210:211]
	v_lshl_add_u64 v[130:131], v[136:137], 0, v[130:131]
	global_store_dwordx4 v[130:131], v[132:135], off nt
	s_mov_b64 s[0:1], 0x100000
	s_nop 0
	v_cvt_pk_bf16_f32 v132, v126, v127
	v_cvt_pk_bf16_f32 v133, v128, v129
	v_cvt_pk_bf16_f32 v134, v118, v119
	v_cvt_pk_bf16_f32 v135, v120, v121
	global_store_dwordx4 v[130:131], v[132:135], off offset:256 nt
	s_nop 1
	v_or_b32_e32 v132, 16, v210
	v_ashrrev_i32_e32 v133, 31, v132
	v_lshlrev_b64 v[132:133], 13, v[132:133]
	v_lshl_add_u64 v[138:139], v[136:137], 0, v[132:133]
	v_cvt_pk_bf16_f32 v132, v106, v107
	v_cvt_pk_bf16_f32 v133, v108, v109
	v_cvt_pk_bf16_f32 v134, v98, v99
	v_cvt_pk_bf16_f32 v135, v100, v101
	global_store_dwordx4 v[138:139], v[132:135], off nt
	s_nop 1
	v_cvt_pk_bf16_f32 v132, v110, v111
	v_cvt_pk_bf16_f32 v133, v112, v113
	v_cvt_pk_bf16_f32 v134, v102, v103
	v_cvt_pk_bf16_f32 v135, v104, v105
	global_store_dwordx4 v[138:139], v[132:135], off offset:256 nt
	s_nop 1
	v_or_b32_e32 v132, 32, v210
	v_ashrrev_i32_e32 v133, 31, v132
	v_lshlrev_b64 v[132:133], 13, v[132:133]
	v_lshl_add_u64 v[138:139], v[136:137], 0, v[132:133]
	v_cvt_pk_bf16_f32 v132, v90, v91
	v_cvt_pk_bf16_f32 v133, v92, v93
	v_cvt_pk_bf16_f32 v134, v82, v83
	v_cvt_pk_bf16_f32 v135, v84, v85
	global_store_dwordx4 v[138:139], v[132:135], off nt
	s_nop 1
	v_cvt_pk_bf16_f32 v132, v94, v95
	v_cvt_pk_bf16_f32 v133, v96, v97
	v_cvt_pk_bf16_f32 v134, v86, v87
	v_cvt_pk_bf16_f32 v135, v88, v89
	global_store_dwordx4 v[138:139], v[132:135], off offset:256 nt
	s_nop 1
	v_or_b32_e32 v132, 48, v210
	v_ashrrev_i32_e32 v133, 31, v132
	v_lshlrev_b64 v[132:133], 13, v[132:133]
	v_lshl_add_u64 v[136:137], v[136:137], 0, v[132:133]
	v_cvt_pk_bf16_f32 v132, v74, v75
	v_cvt_pk_bf16_f32 v133, v76, v77
	v_cvt_pk_bf16_f32 v134, v66, v67
	v_cvt_pk_bf16_f32 v135, v68, v69
	global_store_dwordx4 v[136:137], v[132:135], off nt
	s_nop 1
	v_cvt_pk_bf16_f32 v132, v78, v79
	v_cvt_pk_bf16_f32 v133, v80, v81
	v_cvt_pk_bf16_f32 v134, v70, v71
	v_cvt_pk_bf16_f32 v135, v72, v73
	global_store_dwordx4 v[136:137], v[132:135], off offset:256 nt
	v_lshl_add_u64 v[136:137], v[130:131], 0, s[0:1]
	s_mov_b32 s0, 0x100000
	v_add_co_u32_e32 v138, vcc, s0, v130
	v_cvt_pk_bf16_f32 v132, v58, v59
	v_cvt_pk_bf16_f32 v133, v60, v61
	v_cvt_pk_bf16_f32 v134, v50, v51
	v_cvt_pk_bf16_f32 v135, v52, v53
	s_nop 1
	v_addc_co_u32_e32 v139, vcc, 0, v131, vcc
	s_mov_b64 s[0:1], 0x120000
	global_store_dwordx4 v[138:139], v[132:135], off nt
	s_nop 1
	v_cvt_pk_bf16_f32 v132, v62, v63
	v_cvt_pk_bf16_f32 v133, v64, v65
	v_cvt_pk_bf16_f32 v134, v54, v55
	v_cvt_pk_bf16_f32 v135, v56, v57
	global_store_dwordx4 v[136:137], v[132:135], off offset:256 nt
	v_lshl_add_u64 v[136:137], v[130:131], 0, s[0:1]
	s_mov_b32 s0, 0x120000
	v_add_co_u32_e32 v138, vcc, s0, v130
	v_cvt_pk_bf16_f32 v132, v42, v43
	v_cvt_pk_bf16_f32 v133, v44, v45
	v_cvt_pk_bf16_f32 v134, v34, v35
	v_cvt_pk_bf16_f32 v135, v36, v37
	s_nop 1
	v_addc_co_u32_e32 v139, vcc, 0, v131, vcc
	s_mov_b64 s[0:1], 0x140000
	global_store_dwordx4 v[138:139], v[132:135], off nt
	s_nop 1
	v_cvt_pk_bf16_f32 v132, v46, v47
	v_cvt_pk_bf16_f32 v133, v48, v49
	v_cvt_pk_bf16_f32 v134, v38, v39
	v_cvt_pk_bf16_f32 v135, v40, v41
	global_store_dwordx4 v[136:137], v[132:135], off offset:256 nt
	v_lshl_add_u64 v[136:137], v[130:131], 0, s[0:1]
	s_mov_b32 s0, 0x140000
	v_add_co_u32_e32 v138, vcc, s0, v130
	v_cvt_pk_bf16_f32 v132, v26, v27
	v_cvt_pk_bf16_f32 v133, v28, v29
	v_cvt_pk_bf16_f32 v134, v18, v19
	v_cvt_pk_bf16_f32 v135, v20, v21
	s_nop 1
	v_addc_co_u32_e32 v139, vcc, 0, v131, vcc
	s_mov_b64 s[0:1], 0x160000
	global_store_dwordx4 v[138:139], v[132:135], off nt
	s_nop 1
	v_cvt_pk_bf16_f32 v132, v30, v31
	v_cvt_pk_bf16_f32 v133, v32, v33
	v_cvt_pk_bf16_f32 v134, v22, v23
	v_cvt_pk_bf16_f32 v135, v24, v25
	global_store_dwordx4 v[136:137], v[132:135], off offset:256 nt
	v_lshl_add_u64 v[136:137], v[130:131], 0, s[0:1]
	s_mov_b32 s0, 0x160000
	v_add_co_u32_e32 v130, vcc, s0, v130
	v_cvt_pk_bf16_f32 v132, v10, v11
	v_cvt_pk_bf16_f32 v133, v12, v13
	v_cvt_pk_bf16_f32 v134, v6, v7
	v_cvt_pk_bf16_f32 v135, v8, v9
	s_nop 1
	v_addc_co_u32_e32 v131, vcc, 0, v131, vcc
	global_store_dwordx4 v[130:131], v[132:135], off nt
	v_cvt_pk_bf16_f32 v130, v14, v15
	v_cvt_pk_bf16_f32 v131, v16, v17
	s_nop 1
	v_cvt_pk_bf16_f32 v132, v2, v3
	v_cvt_pk_bf16_f32 v133, v4, v5
	global_store_dwordx4 v[136:137], v[130:133], off offset:256 nt
	s_cbranch_execz .LBB0_851

; __device__ __forceinline__ v4u pack8(const float (&f)[8]) { v4u w; w.x = cvt_pk_bf16(f[0], f[1]); w.y = cvt_pk_bf16(f[2], f[3]); w.z = cvt_pk_bf16(f[4], f[5]); w.w = cvt_pk_bf16(f[6], f[7]); return w; }
; __device__ __forceinline__ float siluf_(float x) { return x * rcpf_(1.f + __expf(-x)); }
;     __device__ __forceinline__ void operator()(const f32x4 (&acc)[2][2][4][2], const Unit& u, int wr, int wc, int fr, int fq) const {
;     ...
;             } else {
;                 const bool isg = u.pn >= 16;
;                 bf16* base = (isg ? SG : V) + ((u.pn - (isg ? 16 : 8)) * 256) + cw;
; #pragma unroll
;                 for (int ai = 0; ai < 2; ++ai)
; #pragma unroll
;                     for (int m = 0; m < 4; ++m) {
;                         bf16* rp = base + (size_t)(row0 + ai * 128 + m * 16) * 2048;
;                         const float rs = rtab[u.ord * 256 + (wr * 64 + fr + ai * 128 + m * 16)];
; #pragma unroll
;                         for (int bj = 0; bj < 2; ++bj) {
;                             float o[8];
; #pragma unroll
;                             for (int n = 0; n < 2; ++n)
; #pragma unroll
;                                 for (int j = 0; j < 4; ++j) { const float x = acc[ai][bj][m][n][j] * rs; o[n * 4 + j] = isg ? siluf_(x) : x; }
;                             *(v4u*)(rp + bj * 128) = pack8(o);
;                         }
;                     }
;             }
.LBB0_1127:
	v_or_b32_e32 v216, 16, v210
	v_or_b32_e32 v214, 32, v210
	v_or_b32_e32 v212, 48, v210
	s_mov_b64 s[0:1], -1
	s_cmp_gt_i32 s87, 7
	v_ashrrev_i32_e32 v211, 31, v210
	v_lshlrev_b32_e32 v0, 1, v204
	v_ashrrev_i32_e32 v217, 31, v216
	v_ashrrev_i32_e32 v215, 31, v214
	v_ashrrev_i32_e32 v213, 31, v212
	s_cbranch_scc0 .LBB0_1129
	v_lshl_add_u32 v138, s88, 10, v243
	ds_read2_b32 v[134:135], v138 offset1:16
	s_cmp_gt_u32 s87, 15
	s_cselect_b64 vcc, -1, 0
	s_and_b64 s[0:1], vcc, exec
	s_mov_b32 s0, 0x19000000
	s_waitcnt lgkmcnt(0)
	v_mul_f32_e32 v136, v122, v134
	v_mul_f32_e32 v137, 0xbfb8aa3b, v136
	v_exp_f32_e32 v137, v137
	v_readlane_b32 s20, v254, 38
	s_cselect_b32 s0, 0x1d100000, s0
	v_readlane_b32 s22, v254, 40
	v_add_f32_e32 v137, 1.0, v137
	v_rcp_f32_e32 v137, v137
	v_readlane_b32 s23, v254, 41
	s_add_u32 s2, s22, s0
	s_addc_u32 s3, s23, 0
	v_mul_f32_e32 v137, v136, v137
	v_cndmask_b32_e32 v136, v136, v137, vcc
	v_mul_f32_e32 v137, v123, v134
	v_mul_f32_e32 v139, 0xbfb8aa3b, v137
	v_exp_f32_e32 v139, v139
	s_and_b64 s[0:1], vcc, exec
	s_cselect_b32 s0, -16, -8
	s_add_i32 s0, s0, s87
	v_add_f32_e32 v139, 1.0, v139
	v_rcp_f32_e32 v139, v139
	s_lshl_b32 s0, s0, 8
	s_ashr_i32 s1, s0, 31
	s_lshl_b64 s[0:1], s[0:1], 1
	v_mul_f32_e32 v139, v137, v139
	v_cndmask_b32_e32 v137, v137, v139, vcc
	v_mul_f32_e32 v139, v124, v134
	v_mul_f32_e32 v140, 0xbfb8aa3b, v139
	v_exp_f32_e32 v140, v140
	s_add_u32 s0, s2, s0
	s_addc_u32 s1, s3, s1
	v_lshl_add_u64 v[132:133], s[0:1], 0, v[0:1]
	v_add_f32_e32 v140, 1.0, v140
	v_rcp_f32_e32 v140, v140
	v_lshlrev_b64 v[130:131], 12, v[210:211]
	v_lshl_add_u64 v[130:131], v[132:133], 0, v[130:131]
	s_mov_b64 s[0:1], 0x80000
	v_mul_f32_e32 v140, v139, v140
	v_cndmask_b32_e32 v139, v139, v140, vcc
	v_mul_f32_e32 v140, v125, v134
	v_mul_f32_e32 v141, 0xbfb8aa3b, v140
	v_exp_f32_e32 v141, v141
	v_readlane_b32 s21, v254, 39
	v_add_f32_e32 v141, 1.0, v141
	v_rcp_f32_e32 v141, v141
	s_nop 0
	v_mul_f32_e32 v141, v140, v141
	v_cndmask_b32_e32 v141, v140, v141, vcc
	v_mul_f32_e32 v140, v114, v134
	v_mul_f32_e32 v142, 0xbfb8aa3b, v140
	v_exp_f32_e32 v142, v142
	v_cvt_pk_bf16_f32 v141, v139, v141
	s_nop 0
	v_add_f32_e32 v142, 1.0, v142
	v_rcp_f32_e32 v142, v142
	s_nop 0
	v_mul_f32_e32 v142, v140, v142
	v_cndmask_b32_e32 v142, v140, v142, vcc
	v_mul_f32_e32 v140, v115, v134
	v_mul_f32_e32 v143, 0xbfb8aa3b, v140
	v_exp_f32_e32 v143, v143
	s_nop 0
	v_add_f32_e32 v143, 1.0, v143
	v_rcp_f32_e32 v143, v143
	s_nop 0
	v_mul_f32_e32 v143, v140, v143
	v_cndmask_b32_e32 v143, v140, v143, vcc
	v_mul_f32_e32 v140, v116, v134
	v_mul_f32_e32 v144, 0xbfb8aa3b, v140
	v_exp_f32_e32 v144, v144
	v_cvt_pk_bf16_f32 v142, v142, v143
	s_nop 0
	v_add_f32_e32 v144, 1.0, v144
	v_rcp_f32_e32 v144, v144
	s_nop 0
	v_mul_f32_e32 v144, v140, v144
	v_cndmask_b32_e32 v144, v140, v144, vcc
	v_mul_f32_e32 v140, v117, v134
	v_mul_f32_e32 v145, 0xbfb8aa3b, v140
	v_exp_f32_e32 v145, v145
	s_nop 0
	v_add_f32_e32 v145, 1.0, v145
	v_rcp_f32_e32 v145, v145
	s_nop 0
	v_mul_f32_e32 v145, v140, v145
	v_cndmask_b32_e32 v145, v140, v145, vcc
	v_cvt_pk_bf16_f32 v140, v136, v137
	v_mul_f32_e32 v136, v126, v134
	v_mul_f32_e32 v137, 0xbfb8aa3b, v136
	v_exp_f32_e32 v137, v137
	v_cvt_pk_bf16_f32 v143, v144, v145
	global_store_dwordx4 v[130:131], v[140:143], off nt
	v_add_f32_e32 v137, 1.0, v137
	v_rcp_f32_e32 v137, v137
	s_nop 0
	v_mul_f32_e32 v137, v136, v137
	v_cndmask_b32_e32 v136, v136, v137, vcc
	v_mul_f32_e32 v137, v127, v134
	v_mul_f32_e32 v139, 0xbfb8aa3b, v137
	v_exp_f32_e32 v139, v139
	s_nop 0
	v_add_f32_e32 v139, 1.0, v139
	v_rcp_f32_e32 v139, v139
	s_nop 0
	v_mul_f32_e32 v139, v137, v139
	v_cndmask_b32_e32 v137, v137, v139, vcc
	v_mul_f32_e32 v139, v128, v134
	v_mul_f32_e32 v140, 0xbfb8aa3b, v139
	v_exp_f32_e32 v140, v140
	s_nop 0
	v_add_f32_e32 v140, 1.0, v140
	v_rcp_f32_e32 v140, v140
	s_nop 0
	v_mul_f32_e32 v140, v139, v140
	v_cndmask_b32_e32 v139, v139, v140, vcc
	v_mul_f32_e32 v140, v129, v134
	v_mul_f32_e32 v141, 0xbfb8aa3b, v140
	v_exp_f32_e32 v141, v141
	s_nop 0
	v_add_f32_e32 v141, 1.0, v141
	v_rcp_f32_e32 v141, v141
	s_nop 0
	v_mul_f32_e32 v141, v140, v141
	v_cndmask_b32_e32 v141, v140, v141, vcc
	v_mul_f32_e32 v140, v118, v134
	v_mul_f32_e32 v142, 0xbfb8aa3b, v140
	v_exp_f32_e32 v142, v142
	v_cvt_pk_bf16_f32 v141, v139, v141
	s_nop 0
	v_add_f32_e32 v142, 1.0, v142
	v_rcp_f32_e32 v142, v142
	s_nop 0
	v_mul_f32_e32 v142, v140, v142
	v_cndmask_b32_e32 v142, v140, v142, vcc
	v_mul_f32_e32 v140, v119, v134
	v_mul_f32_e32 v143, 0xbfb8aa3b, v140
	v_exp_f32_e32 v143, v143
	s_nop 0
	v_add_f32_e32 v143, 1.0, v143
	v_rcp_f32_e32 v143, v143
	s_nop 0
	v_mul_f32_e32 v143, v140, v143
	v_cndmask_b32_e32 v143, v140, v143, vcc
	v_mul_f32_e32 v140, v120, v134
	v_mul_f32_e32 v144, 0xbfb8aa3b, v140
	v_exp_f32_e32 v144, v144
	v_mul_f32_e32 v134, v121, v134
	v_cvt_pk_bf16_f32 v142, v142, v143
	v_add_f32_e32 v144, 1.0, v144
	v_rcp_f32_e32 v144, v144
	s_nop 0
	v_mul_f32_e32 v144, v140, v144
	v_cndmask_b32_e32 v144, v140, v144, vcc
	v_mul_f32_e32 v140, 0xbfb8aa3b, v134
	v_exp_f32_e32 v140, v140
	s_nop 0
	v_add_f32_e32 v140, 1.0, v140
	v_rcp_f32_e32 v140, v140
	s_nop 0
	v_mul_f32_e32 v140, v134, v140
	v_cndmask_b32_e32 v134, v134, v140, vcc
	v_cvt_pk_bf16_f32 v143, v144, v134
	v_mul_f32_e32 v134, v106, v135
	v_mul_f32_e32 v139, 0xbfb8aa3b, v134
	v_exp_f32_e32 v139, v139
	v_cvt_pk_bf16_f32 v140, v136, v137
	global_store_dwordx4 v[130:131], v[140:143], off offset:256 nt
	v_lshlrev_b64 v[136:137], 12, v[216:217]
	v_add_f32_e32 v139, 1.0, v139
	v_rcp_f32_e32 v139, v139
	v_lshl_add_u64 v[136:137], v[132:133], 0, v[136:137]
	v_mul_f32_e32 v139, v134, v139
	v_cndmask_b32_e32 v134, v134, v139, vcc
; __device__ __forceinline__ v4u pack8(const float (&f)[8]) { v4u w; w.x = cvt_pk_bf16(f[0], f[1]); w.y = cvt_pk_bf16(f[2], f[3]); w.z = cvt_pk_bf16(f[4], f[5]); w.w = cvt_pk_bf16(f[6], f[7]); return w; }
; __device__ __forceinline__ float siluf_(float x) { return x * rcpf_(1.f + __expf(-x)); }
;     __device__ __forceinline__ void operator()(const f32x4 (&acc)[2][2][4][2], const Unit& u, int wr, int wc, int fr, int fq) const {
;     ...
;             } else {
;                 const bool isg = u.pn >= 16;
;                 bf16* base = (isg ? SG : V) + ((u.pn - (isg ? 16 : 8)) * 256) + cw;
; #pragma unroll
;                 for (int ai = 0; ai < 2; ++ai)
; #pragma unroll
;                     for (int m = 0; m < 4; ++m) {
;                         bf16* rp = base + (size_t)(row0 + ai * 128 + m * 16) * 2048;
;                         const float rs = rtab[u.ord * 256 + (wr * 64 + fr + ai * 128 + m * 16)];
; #pragma unroll
;                         for (int bj = 0; bj < 2; ++bj) {
;                             float o[8];
; #pragma unroll
;                             for (int n = 0; n < 2; ++n)
; #pragma unroll
;                                 for (int j = 0; j < 4; ++j) { const float x = acc[ai][bj][m][n][j] * rs; o[n * 4 + j] = isg ? siluf_(x) : x; }
;                             *(v4u*)(rp + bj * 128) = pack8(o);
;                         }
;                     }
;             }
	v_mul_f32_e32 v139, v107, v135
	v_mul_f32_e32 v140, 0xbfb8aa3b, v139
	v_exp_f32_e32 v140, v140
	s_nop 0
	v_add_f32_e32 v140, 1.0, v140
	v_rcp_f32_e32 v140, v140
	s_nop 0
	v_mul_f32_e32 v140, v139, v140
	v_cndmask_b32_e32 v139, v139, v140, vcc
	v_mul_f32_e32 v140, v108, v135
	v_mul_f32_e32 v141, 0xbfb8aa3b, v140
	v_exp_f32_e32 v141, v141
	s_nop 0
	v_add_f32_e32 v141, 1.0, v141
	v_rcp_f32_e32 v141, v141
	s_nop 0
	v_mul_f32_e32 v141, v140, v141
	v_cndmask_b32_e32 v141, v140, v141, vcc
	v_mul_f32_e32 v140, v109, v135
	v_mul_f32_e32 v142, 0xbfb8aa3b, v140
	v_exp_f32_e32 v142, v142
	s_nop 0
	v_add_f32_e32 v142, 1.0, v142
	v_rcp_f32_e32 v142, v142
	s_nop 0
	v_mul_f32_e32 v142, v140, v142
	v_cndmask_b32_e32 v142, v140, v142, vcc
	v_mul_f32_e32 v140, v98, v135
	v_mul_f32_e32 v143, 0xbfb8aa3b, v140
	v_exp_f32_e32 v143, v143
	v_cvt_pk_bf16_f32 v141, v141, v142
	s_nop 0
	v_add_f32_e32 v143, 1.0, v143
	v_rcp_f32_e32 v143, v143
	s_nop 0
	v_mul_f32_e32 v143, v140, v143
	v_cndmask_b32_e32 v143, v140, v143, vcc
	v_mul_f32_e32 v140, v99, v135
	v_mul_f32_e32 v144, 0xbfb8aa3b, v140
	v_exp_f32_e32 v144, v144
	s_nop 0
	v_add_f32_e32 v144, 1.0, v144
	v_rcp_f32_e32 v144, v144
	s_nop 0
	v_mul_f32_e32 v144, v140, v144
	v_cndmask_b32_e32 v144, v140, v144, vcc
	v_mul_f32_e32 v140, v100, v135
	v_mul_f32_e32 v145, 0xbfb8aa3b, v140
	v_exp_f32_e32 v145, v145
	v_cvt_pk_bf16_f32 v142, v143, v144
	s_nop 0
	v_add_f32_e32 v145, 1.0, v145
	v_rcp_f32_e32 v145, v145
	s_nop 0
	v_mul_f32_e32 v145, v140, v145
	v_cndmask_b32_e32 v145, v140, v145, vcc
	v_mul_f32_e32 v140, v101, v135
	v_mul_f32_e32 v146, 0xbfb8aa3b, v140
	v_exp_f32_e32 v146, v146
	s_nop 0
	v_add_f32_e32 v146, 1.0, v146
	v_rcp_f32_e32 v146, v146
	s_nop 0
	v_mul_f32_e32 v146, v140, v146
	v_cndmask_b32_e32 v146, v140, v146, vcc
	v_cvt_pk_bf16_f32 v140, v134, v139
	v_mul_f32_e32 v134, v110, v135
	v_mul_f32_e32 v139, 0xbfb8aa3b, v134
	v_exp_f32_e32 v139, v139
	v_cvt_pk_bf16_f32 v143, v145, v146
	global_store_dwordx4 v[136:137], v[140:143], off nt
	v_add_f32_e32 v139, 1.0, v139
	v_rcp_f32_e32 v139, v139
	s_nop 0
	v_mul_f32_e32 v139, v134, v139
	v_cndmask_b32_e32 v134, v134, v139, vcc
	v_mul_f32_e32 v139, v111, v135
	v_mul_f32_e32 v140, 0xbfb8aa3b, v139
	v_exp_f32_e32 v140, v140
	s_nop 0
	v_add_f32_e32 v140, 1.0, v140
	v_rcp_f32_e32 v140, v140
	s_nop 0
	v_mul_f32_e32 v140, v139, v140
	v_cndmask_b32_e32 v139, v139, v140, vcc
	v_mul_f32_e32 v140, v112, v135
	v_mul_f32_e32 v141, 0xbfb8aa3b, v140
	v_exp_f32_e32 v141, v141
	s_nop 0
	v_add_f32_e32 v141, 1.0, v141
	v_rcp_f32_e32 v141, v141
	s_nop 0
	v_mul_f32_e32 v141, v140, v141
	v_cndmask_b32_e32 v141, v140, v141, vcc
	v_mul_f32_e32 v140, v113, v135
	v_mul_f32_e32 v142, 0xbfb8aa3b, v140
	v_exp_f32_e32 v142, v142
	s_nop 0
	v_add_f32_e32 v142, 1.0, v142
	v_rcp_f32_e32 v142, v142
	s_nop 0
	v_mul_f32_e32 v142, v140, v142
	v_cndmask_b32_e32 v142, v140, v142, vcc
	v_mul_f32_e32 v140, v102, v135
	v_mul_f32_e32 v143, 0xbfb8aa3b, v140
	v_exp_f32_e32 v143, v143
	v_cvt_pk_bf16_f32 v141, v141, v142
	s_nop 0
	v_add_f32_e32 v143, 1.0, v143
	v_rcp_f32_e32 v143, v143
	s_nop 0
	v_mul_f32_e32 v143, v140, v143
	v_cndmask_b32_e32 v143, v140, v143, vcc
	v_mul_f32_e32 v140, v103, v135
	v_mul_f32_e32 v144, 0xbfb8aa3b, v140
	v_exp_f32_e32 v144, v144
	s_nop 0
	v_add_f32_e32 v144, 1.0, v144
	v_rcp_f32_e32 v144, v144
	s_nop 0
	v_mul_f32_e32 v144, v140, v144
	v_cndmask_b32_e32 v144, v140, v144, vcc
	v_mul_f32_e32 v140, v104, v135
	v_mul_f32_e32 v145, 0xbfb8aa3b, v140
	v_exp_f32_e32 v145, v145
	v_mul_f32_e32 v135, v105, v135
	v_cvt_pk_bf16_f32 v142, v143, v144
	v_add_f32_e32 v145, 1.0, v145
	v_rcp_f32_e32 v145, v145
	s_nop 0
	v_mul_f32_e32 v145, v140, v145
	v_cndmask_b32_e32 v145, v140, v145, vcc
	v_mul_f32_e32 v140, 0xbfb8aa3b, v135
	v_exp_f32_e32 v140, v140
	s_nop 0
	v_add_f32_e32 v140, 1.0, v140
	v_rcp_f32_e32 v140, v140
	s_nop 0
	v_mul_f32_e32 v140, v135, v140
	v_cndmask_b32_e32 v135, v135, v140, vcc
	v_cvt_pk_bf16_f32 v140, v134, v139
	v_cvt_pk_bf16_f32 v143, v145, v135
	v_lshlrev_b64 v[134:135], 12, v[214:215]
	global_store_dwordx4 v[136:137], v[140:143], off offset:256 nt
	v_lshl_add_u64 v[136:137], v[132:133], 0, v[134:135]
	ds_read2_b32 v[134:135], v138 offset0:32 offset1:48
	s_waitcnt lgkmcnt(0)
	v_mul_f32_e32 v139, v90, v134
	v_mul_f32_e32 v140, 0xbfb8aa3b, v139
	v_exp_f32_e32 v140, v140
	s_nop 0
	v_add_f32_e32 v140, 1.0, v140
	v_rcp_f32_e32 v140, v140
	s_nop 0
	v_mul_f32_e32 v140, v139, v140
	v_cndmask_b32_e32 v139, v139, v140, vcc
	v_mul_f32_e32 v140, v91, v134
	v_mul_f32_e32 v141, 0xbfb8aa3b, v140
	v_exp_f32_e32 v141, v141
	s_nop 0
	v_add_f32_e32 v141, 1.0, v141
	v_rcp_f32_e32 v141, v141
	s_nop 0
	v_mul_f32_e32 v141, v140, v141
	v_cndmask_b32_e32 v140, v140, v141, vcc
	v_mul_f32_e32 v141, v92, v134
	v_mul_f32_e32 v142, 0xbfb8aa3b, v141
	v_exp_f32_e32 v142, v142
	v_cvt_pk_bf16_f32 v140, v139, v140
	v_mul_f32_e32 v139, v94, v134
	v_add_f32_e32 v142, 1.0, v142
	v_rcp_f32_e32 v142, v142
	s_nop 0
	v_mul_f32_e32 v142, v141, v142
	v_cndmask_b32_e32 v141, v141, v142, vcc
	v_mul_f32_e32 v142, v93, v134
	v_mul_f32_e32 v143, 0xbfb8aa3b, v142
	v_exp_f32_e32 v143, v143
	s_nop 0
	v_add_f32_e32 v143, 1.0, v143
	v_rcp_f32_e32 v143, v143
	s_nop 0
	v_mul_f32_e32 v143, v142, v143
	v_cndmask_b32_e32 v142, v142, v143, vcc
	v_mul_f32_e32 v143, v82, v134
	v_mul_f32_e32 v144, 0xbfb8aa3b, v143
	v_exp_f32_e32 v144, v144
	v_cvt_pk_bf16_f32 v141, v141, v142
	s_nop 0
	v_add_f32_e32 v144, 1.0, v144
	v_rcp_f32_e32 v144, v144
	s_nop 0
	v_mul_f32_e32 v144, v143, v144
	v_cndmask_b32_e32 v143, v143, v144, vcc
	v_mul_f32_e32 v144, v83, v134
	v_mul_f32_e32 v145, 0xbfb8aa3b, v144
	v_exp_f32_e32 v145, v145
	s_nop 0
; __device__ __forceinline__ v4u pack8(const float (&f)[8]) { v4u w; w.x = cvt_pk_bf16(f[0], f[1]); w.y = cvt_pk_bf16(f[2], f[3]); w.z = cvt_pk_bf16(f[4], f[5]); w.w = cvt_pk_bf16(f[6], f[7]); return w; }
; __device__ __forceinline__ float siluf_(float x) { return x * rcpf_(1.f + __expf(-x)); }
;     __device__ __forceinline__ void operator()(const f32x4 (&acc)[2][2][4][2], const Unit& u, int wr, int wc, int fr, int fq) const {
;     ...
;             } else {
;                 const bool isg = u.pn >= 16;
;                 bf16* base = (isg ? SG : V) + ((u.pn - (isg ? 16 : 8)) * 256) + cw;
; #pragma unroll
;                 for (int ai = 0; ai < 2; ++ai)
; #pragma unroll
;                     for (int m = 0; m < 4; ++m) {
;                         bf16* rp = base + (size_t)(row0 + ai * 128 + m * 16) * 2048;
;                         const float rs = rtab[u.ord * 256 + (wr * 64 + fr + ai * 128 + m * 16)];
; #pragma unroll
;                         for (int bj = 0; bj < 2; ++bj) {
;                             float o[8];
; #pragma unroll
;                             for (int n = 0; n < 2; ++n)
; #pragma unroll
;                                 for (int j = 0; j < 4; ++j) { const float x = acc[ai][bj][m][n][j] * rs; o[n * 4 + j] = isg ? siluf_(x) : x; }
;                             *(v4u*)(rp + bj * 128) = pack8(o);
;                         }
;                     }
;             }
	v_add_f32_e32 v145, 1.0, v145
	v_rcp_f32_e32 v145, v145
	s_nop 0
	v_mul_f32_e32 v145, v144, v145
	v_cndmask_b32_e32 v144, v144, v145, vcc
	v_mul_f32_e32 v145, v84, v134
	v_mul_f32_e32 v146, 0xbfb8aa3b, v145
	v_exp_f32_e32 v146, v146
	v_cvt_pk_bf16_f32 v142, v143, v144
	s_nop 0
	v_add_f32_e32 v146, 1.0, v146
	v_rcp_f32_e32 v146, v146
	s_nop 0
	v_mul_f32_e32 v146, v145, v146
	v_cndmask_b32_e32 v145, v145, v146, vcc
	v_mul_f32_e32 v146, v85, v134
	v_mul_f32_e32 v147, 0xbfb8aa3b, v146
	v_exp_f32_e32 v147, v147
	s_nop 0
	v_add_f32_e32 v147, 1.0, v147
	v_rcp_f32_e32 v147, v147
	s_nop 0
	v_mul_f32_e32 v147, v146, v147
	v_cndmask_b32_e32 v146, v146, v147, vcc
	v_cvt_pk_bf16_f32 v143, v145, v146
	global_store_dwordx4 v[136:137], v[140:143], off nt
	s_nop 1
	v_mul_f32_e32 v140, 0xbfb8aa3b, v139
	v_exp_f32_e32 v140, v140
	s_nop 0
	v_add_f32_e32 v140, 1.0, v140
	v_rcp_f32_e32 v140, v140
	s_nop 0
	v_mul_f32_e32 v140, v139, v140
	v_cndmask_b32_e32 v139, v139, v140, vcc
	v_mul_f32_e32 v140, v95, v134
	v_mul_f32_e32 v141, 0xbfb8aa3b, v140
	v_exp_f32_e32 v141, v141
	s_nop 0
	v_add_f32_e32 v141, 1.0, v141
	v_rcp_f32_e32 v141, v141
	s_nop 0
	v_mul_f32_e32 v141, v140, v141
	v_cndmask_b32_e32 v140, v140, v141, vcc
	v_mul_f32_e32 v141, v96, v134
	v_mul_f32_e32 v142, 0xbfb8aa3b, v141
	v_exp_f32_e32 v142, v142
	v_cvt_pk_bf16_f32 v140, v139, v140
	s_nop 0
	v_add_f32_e32 v142, 1.0, v142
	v_rcp_f32_e32 v142, v142
	s_nop 0
	v_mul_f32_e32 v142, v141, v142
	v_cndmask_b32_e32 v141, v141, v142, vcc
	v_mul_f32_e32 v142, v97, v134
	v_mul_f32_e32 v143, 0xbfb8aa3b, v142
	v_exp_f32_e32 v143, v143
	s_nop 0
	v_add_f32_e32 v143, 1.0, v143
	v_rcp_f32_e32 v143, v143
	s_nop 0
	v_mul_f32_e32 v143, v142, v143
	v_cndmask_b32_e32 v142, v142, v143, vcc
	v_mul_f32_e32 v143, v86, v134
	v_mul_f32_e32 v144, 0xbfb8aa3b, v143
	v_exp_f32_e32 v144, v144
	v_cvt_pk_bf16_f32 v141, v141, v142
	s_nop 0
	v_add_f32_e32 v144, 1.0, v144
	v_rcp_f32_e32 v144, v144
	s_nop 0
	v_mul_f32_e32 v144, v143, v144
	v_cndmask_b32_e32 v143, v143, v144, vcc
	v_mul_f32_e32 v144, v87, v134
	v_mul_f32_e32 v145, 0xbfb8aa3b, v144
	v_exp_f32_e32 v145, v145
	s_nop 0
	v_add_f32_e32 v145, 1.0, v145
	v_rcp_f32_e32 v145, v145
	s_nop 0
	v_mul_f32_e32 v145, v144, v145
	v_cndmask_b32_e32 v144, v144, v145, vcc
	v_mul_f32_e32 v145, v88, v134
	v_mul_f32_e32 v146, 0xbfb8aa3b, v145
	v_exp_f32_e32 v146, v146
	v_mul_f32_e32 v134, v89, v134
	v_cvt_pk_bf16_f32 v142, v143, v144
	v_add_f32_e32 v146, 1.0, v146
	v_rcp_f32_e32 v146, v146
	s_nop 0
	v_mul_f32_e32 v146, v145, v146
	v_cndmask_b32_e32 v145, v145, v146, vcc
	v_mul_f32_e32 v146, 0xbfb8aa3b, v134
	v_exp_f32_e32 v146, v146
	s_nop 0
	v_add_f32_e32 v146, 1.0, v146
	v_rcp_f32_e32 v146, v146
	s_nop 0
	v_mul_f32_e32 v146, v134, v146
	v_cndmask_b32_e32 v134, v134, v146, vcc
	v_cvt_pk_bf16_f32 v143, v145, v134
	global_store_dwordx4 v[136:137], v[140:143], off offset:256 nt
	v_lshlrev_b64 v[136:137], 12, v[212:213]
	v_mul_f32_e32 v134, v74, v135
	v_lshl_add_u64 v[132:133], v[132:133], 0, v[136:137]
	v_mul_f32_e32 v136, 0xbfb8aa3b, v134
	v_exp_f32_e32 v136, v136
	s_nop 0
	v_add_f32_e32 v136, 1.0, v136
	v_rcp_f32_e32 v136, v136
	s_nop 0
	v_mul_f32_e32 v136, v134, v136
	v_cndmask_b32_e32 v134, v134, v136, vcc
	v_mul_f32_e32 v136, v75, v135
	v_mul_f32_e32 v137, 0xbfb8aa3b, v136
	v_exp_f32_e32 v137, v137
	s_nop 0
	v_add_f32_e32 v137, 1.0, v137
	v_rcp_f32_e32 v137, v137
	s_nop 0
	v_mul_f32_e32 v137, v136, v137
	v_cndmask_b32_e32 v136, v136, v137, vcc
	v_mul_f32_e32 v137, v76, v135
	v_mul_f32_e32 v139, 0xbfb8aa3b, v137
	v_exp_f32_e32 v139, v139
	s_nop 0
	v_add_f32_e32 v139, 1.0, v139
	v_rcp_f32_e32 v139, v139
	s_nop 0
	v_mul_f32_e32 v139, v137, v139
	v_cndmask_b32_e32 v137, v137, v139, vcc
	v_mul_f32_e32 v139, v77, v135
	v_mul_f32_e32 v140, 0xbfb8aa3b, v139
	v_exp_f32_e32 v140, v140
	s_nop 0
	v_add_f32_e32 v140, 1.0, v140
	v_rcp_f32_e32 v140, v140
	s_nop 0
	v_mul_f32_e32 v140, v139, v140
	v_cndmask_b32_e32 v139, v139, v140, vcc
	v_mul_f32_e32 v140, v66, v135
	v_mul_f32_e32 v141, 0xbfb8aa3b, v140
	v_exp_f32_e32 v141, v141
	s_nop 0
	v_add_f32_e32 v141, 1.0, v141
	v_rcp_f32_e32 v141, v141
	s_nop 0
	v_mul_f32_e32 v141, v140, v141
	v_cndmask_b32_e32 v142, v140, v141, vcc
	v_mul_f32_e32 v140, v67, v135
	v_mul_f32_e32 v141, 0xbfb8aa3b, v140
	v_exp_f32_e32 v141, v141
	s_nop 0
	v_add_f32_e32 v141, 1.0, v141
	v_rcp_f32_e32 v141, v141
	s_nop 0
	v_mul_f32_e32 v141, v140, v141
	v_cndmask_b32_e32 v143, v140, v141, vcc
	v_mul_f32_e32 v140, v68, v135
	v_mul_f32_e32 v141, 0xbfb8aa3b, v140
	v_exp_f32_e32 v141, v141
	v_cvt_pk_bf16_f32 v142, v142, v143
	s_nop 0
	v_add_f32_e32 v141, 1.0, v141
	v_rcp_f32_e32 v141, v141
	s_nop 0
	v_mul_f32_e32 v141, v140, v141
	v_cndmask_b32_e32 v144, v140, v141, vcc
	v_mul_f32_e32 v140, v69, v135
	v_mul_f32_e32 v141, 0xbfb8aa3b, v140
	v_exp_f32_e32 v141, v141
	s_nop 0
	v_add_f32_e32 v141, 1.0, v141
	v_rcp_f32_e32 v141, v141
	s_nop 0
	v_mul_f32_e32 v141, v140, v141
	v_cndmask_b32_e32 v145, v140, v141, vcc
	v_cvt_pk_bf16_f32 v140, v134, v136
	v_mul_f32_e32 v134, v78, v135
	v_mul_f32_e32 v136, 0xbfb8aa3b, v134
	v_exp_f32_e32 v136, v136
	v_cvt_pk_bf16_f32 v141, v137, v139
	v_cvt_pk_bf16_f32 v143, v144, v145
	global_store_dwordx4 v[132:133], v[140:143], off nt
	v_add_f32_e32 v136, 1.0, v136
	v_rcp_f32_e32 v136, v136
	s_nop 0
	v_mul_f32_e32 v136, v134, v136
	v_cndmask_b32_e32 v134, v134, v136, vcc
	v_mul_f32_e32 v136, v79, v135
	v_mul_f32_e32 v137, 0xbfb8aa3b, v136
	v_exp_f32_e32 v137, v137
	s_nop 0
	v_add_f32_e32 v137, 1.0, v137
	v_rcp_f32_e32 v137, v137
	s_nop 0
	v_mul_f32_e32 v137, v136, v137
	v_cndmask_b32_e32 v136, v136, v137, vcc
	v_mul_f32_e32 v137, v80, v135
	v_mul_f32_e32 v139, 0xbfb8aa3b, v137
; __device__ __forceinline__ v4u pack8(const float (&f)[8]) { v4u w; w.x = cvt_pk_bf16(f[0], f[1]); w.y = cvt_pk_bf16(f[2], f[3]); w.z = cvt_pk_bf16(f[4], f[5]); w.w = cvt_pk_bf16(f[6], f[7]); return w; }
; __device__ __forceinline__ float siluf_(float x) { return x * rcpf_(1.f + __expf(-x)); }
;     __device__ __forceinline__ void operator()(const f32x4 (&acc)[2][2][4][2], const Unit& u, int wr, int wc, int fr, int fq) const {
;     ...
;             } else {
;                 const bool isg = u.pn >= 16;
;                 bf16* base = (isg ? SG : V) + ((u.pn - (isg ? 16 : 8)) * 256) + cw;
; #pragma unroll
;                 for (int ai = 0; ai < 2; ++ai)
; #pragma unroll
;                     for (int m = 0; m < 4; ++m) {
;                         bf16* rp = base + (size_t)(row0 + ai * 128 + m * 16) * 2048;
;                         const float rs = rtab[u.ord * 256 + (wr * 64 + fr + ai * 128 + m * 16)];
; #pragma unroll
;                         for (int bj = 0; bj < 2; ++bj) {
;                             float o[8];
; #pragma unroll
;                             for (int n = 0; n < 2; ++n)
; #pragma unroll
;                                 for (int j = 0; j < 4; ++j) { const float x = acc[ai][bj][m][n][j] * rs; o[n * 4 + j] = isg ? siluf_(x) : x; }
;                             *(v4u*)(rp + bj * 128) = pack8(o);
;                         }
;                     }
;             }
	v_exp_f32_e32 v139, v139
	v_cvt_pk_bf16_f32 v134, v134, v136
	s_nop 0
	v_add_f32_e32 v139, 1.0, v139
	v_rcp_f32_e32 v139, v139
	s_nop 0
	v_mul_f32_e32 v139, v137, v139
	v_cndmask_b32_e32 v137, v137, v139, vcc
	v_mul_f32_e32 v139, v81, v135
	v_mul_f32_e32 v140, 0xbfb8aa3b, v139
	v_exp_f32_e32 v140, v140
	s_nop 0
	v_add_f32_e32 v140, 1.0, v140
	v_rcp_f32_e32 v140, v140
	s_nop 0
	v_mul_f32_e32 v140, v139, v140
	v_cndmask_b32_e32 v139, v139, v140, vcc
	v_mul_f32_e32 v140, v70, v135
	v_mul_f32_e32 v141, 0xbfb8aa3b, v140
	v_exp_f32_e32 v141, v141
	s_nop 0
	v_add_f32_e32 v141, 1.0, v141
	v_rcp_f32_e32 v141, v141
	s_nop 0
	v_mul_f32_e32 v141, v140, v141
	v_cndmask_b32_e32 v140, v140, v141, vcc
	v_mul_f32_e32 v141, v71, v135
	v_mul_f32_e32 v142, 0xbfb8aa3b, v141
	v_exp_f32_e32 v142, v142
	s_nop 0
	v_add_f32_e32 v142, 1.0, v142
	v_rcp_f32_e32 v142, v142
	s_nop 0
	v_mul_f32_e32 v142, v141, v142
	v_cndmask_b32_e32 v141, v141, v142, vcc
	v_mul_f32_e32 v142, v72, v135
	v_mul_f32_e32 v143, 0xbfb8aa3b, v142
	v_exp_f32_e32 v143, v143
	v_mul_f32_e32 v135, v73, v135
	v_cvt_pk_bf16_f32 v136, v140, v141
	v_add_f32_e32 v143, 1.0, v143
	v_rcp_f32_e32 v143, v143
	s_nop 0
	v_mul_f32_e32 v143, v142, v143
	v_cndmask_b32_e32 v142, v142, v143, vcc
	v_mul_f32_e32 v143, 0xbfb8aa3b, v135
	v_exp_f32_e32 v143, v143
	s_nop 0
	v_add_f32_e32 v143, 1.0, v143
	v_rcp_f32_e32 v143, v143
	s_nop 0
	v_mul_f32_e32 v143, v135, v143
	v_cndmask_b32_e32 v143, v135, v143, vcc
	v_cvt_pk_bf16_f32 v135, v137, v139
	v_cvt_pk_bf16_f32 v137, v142, v143
	global_store_dwordx4 v[132:133], v[134:137], off offset:256 nt
	ds_read2_b32 v[132:133], v138 offset0:128 offset1:144
	s_nop 0
	v_lshl_add_u64 v[134:135], v[130:131], 0, s[0:1]
	s_mov_b32 s0, 0x80000
	s_waitcnt lgkmcnt(0)
	v_mul_f32_e32 v136, v58, v132
	v_mul_f32_e32 v137, 0xbfb8aa3b, v136
	v_exp_f32_e32 v137, v137
	s_nop 0
	v_add_f32_e32 v137, 1.0, v137
	v_rcp_f32_e32 v137, v137
	s_nop 0
	v_mul_f32_e32 v137, v136, v137
	v_cndmask_b32_e32 v136, v136, v137, vcc
	v_mul_f32_e32 v137, v59, v132
	v_mul_f32_e32 v139, 0xbfb8aa3b, v137
	v_exp_f32_e32 v139, v139
	s_nop 0
	v_add_f32_e32 v139, 1.0, v139
	v_rcp_f32_e32 v139, v139
	s_nop 0
	v_mul_f32_e32 v139, v137, v139
	v_cndmask_b32_e32 v137, v137, v139, vcc
	v_mul_f32_e32 v139, v60, v132
	v_mul_f32_e32 v140, 0xbfb8aa3b, v139
	v_exp_f32_e32 v140, v140
	s_nop 0
	v_add_f32_e32 v140, 1.0, v140
	v_rcp_f32_e32 v140, v140
	s_nop 0
	v_mul_f32_e32 v140, v139, v140
	v_cndmask_b32_e32 v139, v139, v140, vcc
	v_mul_f32_e32 v140, v61, v132
	v_mul_f32_e32 v141, 0xbfb8aa3b, v140
	v_exp_f32_e32 v141, v141
	s_nop 0
	v_add_f32_e32 v141, 1.0, v141
	v_rcp_f32_e32 v141, v141
	s_nop 0
	v_mul_f32_e32 v141, v140, v141
	v_cndmask_b32_e32 v141, v140, v141, vcc
	v_mul_f32_e32 v140, v50, v132
	v_mul_f32_e32 v142, 0xbfb8aa3b, v140
	v_exp_f32_e32 v142, v142
	v_cvt_pk_bf16_f32 v141, v139, v141
	s_nop 0
	v_add_f32_e32 v142, 1.0, v142
	v_rcp_f32_e32 v142, v142
	s_nop 0
	v_mul_f32_e32 v142, v140, v142
	v_cndmask_b32_e32 v142, v140, v142, vcc
	v_mul_f32_e32 v140, v51, v132
	v_mul_f32_e32 v143, 0xbfb8aa3b, v140
	v_exp_f32_e32 v143, v143
	s_nop 0
	v_add_f32_e32 v143, 1.0, v143
	v_rcp_f32_e32 v143, v143
	s_nop 0
	v_mul_f32_e32 v143, v140, v143
	v_cndmask_b32_e32 v143, v140, v143, vcc
	v_mul_f32_e32 v140, v52, v132
	v_mul_f32_e32 v144, 0xbfb8aa3b, v140
	v_exp_f32_e32 v144, v144
	v_cvt_pk_bf16_f32 v142, v142, v143
	s_nop 0
	v_add_f32_e32 v144, 1.0, v144
	v_rcp_f32_e32 v144, v144
	s_nop 0
	v_mul_f32_e32 v144, v140, v144
	v_cndmask_b32_e32 v144, v140, v144, vcc
	v_mul_f32_e32 v140, v53, v132
	v_mul_f32_e32 v145, 0xbfb8aa3b, v140
	v_exp_f32_e32 v145, v145
	s_nop 0
	v_add_f32_e32 v145, 1.0, v145
	v_rcp_f32_e32 v145, v145
	s_nop 0
	v_mul_f32_e32 v145, v140, v145
	v_cndmask_b32_e32 v145, v140, v145, vcc
	v_cvt_pk_bf16_f32 v140, v136, v137
	v_add_co_u32_e64 v136, s[0:1], s0, v130
	v_cvt_pk_bf16_f32 v143, v144, v145
	s_nop 1
	v_addc_co_u32_e64 v137, s[0:1], 0, v131, s[0:1]
	global_store_dwordx4 v[136:137], v[140:143], off nt
	v_mul_f32_e32 v136, v62, v132
	v_mul_f32_e32 v137, 0xbfb8aa3b, v136
	v_exp_f32_e32 v137, v137
	s_mov_b64 s[0:1], 0x90000
	v_add_f32_e32 v137, 1.0, v137
	v_rcp_f32_e32 v137, v137
	s_nop 0
	v_mul_f32_e32 v137, v136, v137
	v_cndmask_b32_e32 v136, v136, v137, vcc
	v_mul_f32_e32 v137, v63, v132
	v_mul_f32_e32 v139, 0xbfb8aa3b, v137
	v_exp_f32_e32 v139, v139
	s_nop 0
	v_add_f32_e32 v139, 1.0, v139
	v_rcp_f32_e32 v139, v139
	s_nop 0
	v_mul_f32_e32 v139, v137, v139
	v_cndmask_b32_e32 v137, v137, v139, vcc
	v_mul_f32_e32 v139, v64, v132
	v_mul_f32_e32 v140, 0xbfb8aa3b, v139
	v_exp_f32_e32 v140, v140
	s_nop 0
	v_add_f32_e32 v140, 1.0, v140
	v_rcp_f32_e32 v140, v140
	s_nop 0
	v_mul_f32_e32 v140, v139, v140
	v_cndmask_b32_e32 v139, v139, v140, vcc
	v_mul_f32_e32 v140, v65, v132
	v_mul_f32_e32 v141, 0xbfb8aa3b, v140
	v_exp_f32_e32 v141, v141
	s_nop 0
	v_add_f32_e32 v141, 1.0, v141
	v_rcp_f32_e32 v141, v141
	s_nop 0
	v_mul_f32_e32 v141, v140, v141
	v_cndmask_b32_e32 v141, v140, v141, vcc
	v_mul_f32_e32 v140, v54, v132
	v_mul_f32_e32 v142, 0xbfb8aa3b, v140
	v_exp_f32_e32 v142, v142
	v_cvt_pk_bf16_f32 v141, v139, v141
	s_nop 0
	v_add_f32_e32 v142, 1.0, v142
	v_rcp_f32_e32 v142, v142
	s_nop 0
	v_mul_f32_e32 v142, v140, v142
	v_cndmask_b32_e32 v142, v140, v142, vcc
	v_mul_f32_e32 v140, v55, v132
	v_mul_f32_e32 v143, 0xbfb8aa3b, v140
	v_exp_f32_e32 v143, v143
	s_nop 0
	v_add_f32_e32 v143, 1.0, v143
	v_rcp_f32_e32 v143, v143
	s_nop 0
	v_mul_f32_e32 v143, v140, v143
	v_cndmask_b32_e32 v143, v140, v143, vcc
	v_mul_f32_e32 v140, v56, v132
	v_mul_f32_e32 v144, 0xbfb8aa3b, v140
	v_exp_f32_e32 v144, v144
	v_mul_f32_e32 v132, v57, v132
; __device__ __forceinline__ v4u pack8(const float (&f)[8]) { v4u w; w.x = cvt_pk_bf16(f[0], f[1]); w.y = cvt_pk_bf16(f[2], f[3]); w.z = cvt_pk_bf16(f[4], f[5]); w.w = cvt_pk_bf16(f[6], f[7]); return w; }
; __device__ __forceinline__ float siluf_(float x) { return x * rcpf_(1.f + __expf(-x)); }
;     __device__ __forceinline__ void operator()(const f32x4 (&acc)[2][2][4][2], const Unit& u, int wr, int wc, int fr, int fq) const {
;     ...
;             } else {
;                 const bool isg = u.pn >= 16;
;                 bf16* base = (isg ? SG : V) + ((u.pn - (isg ? 16 : 8)) * 256) + cw;
; #pragma unroll
;                 for (int ai = 0; ai < 2; ++ai)
; #pragma unroll
;                     for (int m = 0; m < 4; ++m) {
;                         bf16* rp = base + (size_t)(row0 + ai * 128 + m * 16) * 2048;
;                         const float rs = rtab[u.ord * 256 + (wr * 64 + fr + ai * 128 + m * 16)];
; #pragma unroll
;                         for (int bj = 0; bj < 2; ++bj) {
;                             float o[8];
; #pragma unroll
;                             for (int n = 0; n < 2; ++n)
; #pragma unroll
;                                 for (int j = 0; j < 4; ++j) { const float x = acc[ai][bj][m][n][j] * rs; o[n * 4 + j] = isg ? siluf_(x) : x; }
;                             *(v4u*)(rp + bj * 128) = pack8(o);
;                         }
;                     }
;             }
	v_cvt_pk_bf16_f32 v142, v142, v143
	v_add_f32_e32 v144, 1.0, v144
	v_rcp_f32_e32 v144, v144
	s_nop 0
	v_mul_f32_e32 v144, v140, v144
	v_cndmask_b32_e32 v144, v140, v144, vcc
	v_mul_f32_e32 v140, 0xbfb8aa3b, v132
	v_exp_f32_e32 v140, v140
	s_nop 0
	v_add_f32_e32 v140, 1.0, v140
	v_rcp_f32_e32 v140, v140
	s_nop 0
	v_mul_f32_e32 v140, v132, v140
	v_cndmask_b32_e32 v132, v132, v140, vcc
	v_cvt_pk_bf16_f32 v143, v144, v132
	v_mul_f32_e32 v132, v42, v133
	v_cvt_pk_bf16_f32 v140, v136, v137
	v_mul_f32_e32 v136, 0xbfb8aa3b, v132
	v_exp_f32_e32 v136, v136
	global_store_dwordx4 v[134:135], v[140:143], off offset:256 nt
	v_lshl_add_u64 v[134:135], v[130:131], 0, s[0:1]
	s_mov_b32 s0, 0x90000
	v_add_f32_e32 v136, 1.0, v136
	v_rcp_f32_e32 v136, v136
	s_nop 0
	v_mul_f32_e32 v136, v132, v136
	v_cndmask_b32_e32 v132, v132, v136, vcc
	v_mul_f32_e32 v136, v43, v133
	v_mul_f32_e32 v137, 0xbfb8aa3b, v136
	v_exp_f32_e32 v137, v137
	s_nop 0
	v_add_f32_e32 v137, 1.0, v137
	v_rcp_f32_e32 v137, v137
	s_nop 0
	v_mul_f32_e32 v137, v136, v137
	v_cndmask_b32_e32 v136, v136, v137, vcc
	v_mul_f32_e32 v137, v44, v133
	v_mul_f32_e32 v139, 0xbfb8aa3b, v137
	v_exp_f32_e32 v139, v139
	s_nop 0
	v_add_f32_e32 v139, 1.0, v139
	v_rcp_f32_e32 v139, v139
	s_nop 0
	v_mul_f32_e32 v139, v137, v139
	v_cndmask_b32_e32 v137, v137, v139, vcc
	v_mul_f32_e32 v139, v45, v133
	v_mul_f32_e32 v140, 0xbfb8aa3b, v139
	v_exp_f32_e32 v140, v140
	s_nop 0
	v_add_f32_e32 v140, 1.0, v140
	v_rcp_f32_e32 v140, v140
	s_nop 0
	v_mul_f32_e32 v140, v139, v140
	v_cndmask_b32_e32 v139, v139, v140, vcc
	v_mul_f32_e32 v140, v34, v133
	v_mul_f32_e32 v141, 0xbfb8aa3b, v140
	v_exp_f32_e32 v141, v141
	s_nop 0
	v_add_f32_e32 v141, 1.0, v141
	v_rcp_f32_e32 v141, v141
	s_nop 0
	v_mul_f32_e32 v141, v140, v141
	v_cndmask_b32_e32 v142, v140, v141, vcc
	v_mul_f32_e32 v140, v35, v133
	v_mul_f32_e32 v141, 0xbfb8aa3b, v140
	v_exp_f32_e32 v141, v141
	s_nop 0
	v_add_f32_e32 v141, 1.0, v141
	v_rcp_f32_e32 v141, v141
	s_nop 0
	v_mul_f32_e32 v141, v140, v141
	v_cndmask_b32_e32 v143, v140, v141, vcc
	v_mul_f32_e32 v140, v36, v133
	v_mul_f32_e32 v141, 0xbfb8aa3b, v140
	v_exp_f32_e32 v141, v141
	v_cvt_pk_bf16_f32 v142, v142, v143
	s_nop 0
	v_add_f32_e32 v141, 1.0, v141
	v_rcp_f32_e32 v141, v141
	s_nop 0
	v_mul_f32_e32 v141, v140, v141
	v_cndmask_b32_e32 v144, v140, v141, vcc
	v_mul_f32_e32 v140, v37, v133
	v_mul_f32_e32 v141, 0xbfb8aa3b, v140
	v_exp_f32_e32 v141, v141
	s_nop 0
	v_add_f32_e32 v141, 1.0, v141
	v_rcp_f32_e32 v141, v141
	s_nop 0
	v_mul_f32_e32 v141, v140, v141
	v_cndmask_b32_e32 v145, v140, v141, vcc
	v_cvt_pk_bf16_f32 v140, v132, v136
	v_add_co_u32_e64 v136, s[0:1], s0, v130
	v_cvt_pk_bf16_f32 v141, v137, v139
	v_mul_f32_e32 v132, v46, v133
	s_nop 0
	v_addc_co_u32_e64 v137, s[0:1], 0, v131, s[0:1]
	v_cvt_pk_bf16_f32 v143, v144, v145
	global_store_dwordx4 v[136:137], v[140:143], off nt
	v_mul_f32_e32 v136, 0xbfb8aa3b, v132
	v_exp_f32_e32 v136, v136
	s_mov_b64 s[0:1], 0xa0000
	v_add_f32_e32 v136, 1.0, v136
	v_rcp_f32_e32 v136, v136
	s_nop 0
	v_mul_f32_e32 v136, v132, v136
	v_cndmask_b32_e32 v132, v132, v136, vcc
	v_mul_f32_e32 v136, v47, v133
	v_mul_f32_e32 v137, 0xbfb8aa3b, v136
	v_exp_f32_e32 v137, v137
	s_nop 0
	v_add_f32_e32 v137, 1.0, v137
	v_rcp_f32_e32 v137, v137
	s_nop 0
	v_mul_f32_e32 v137, v136, v137
	v_cndmask_b32_e32 v136, v136, v137, vcc
	v_mul_f32_e32 v137, v48, v133
	v_mul_f32_e32 v139, 0xbfb8aa3b, v137
	v_exp_f32_e32 v139, v139
	s_nop 0
	v_add_f32_e32 v139, 1.0, v139
	v_rcp_f32_e32 v139, v139
	s_nop 0
	v_mul_f32_e32 v139, v137, v139
	v_cndmask_b32_e32 v137, v137, v139, vcc
	v_mul_f32_e32 v139, v49, v133
	v_mul_f32_e32 v140, 0xbfb8aa3b, v139
	v_exp_f32_e32 v140, v140
	s_nop 0
	v_add_f32_e32 v140, 1.0, v140
	v_rcp_f32_e32 v140, v140
	s_nop 0
	v_mul_f32_e32 v140, v139, v140
	v_cndmask_b32_e32 v139, v139, v140, vcc
	v_mul_f32_e32 v140, v38, v133
	v_mul_f32_e32 v141, 0xbfb8aa3b, v140
	v_exp_f32_e32 v141, v141
	s_nop 0
	v_add_f32_e32 v141, 1.0, v141
	v_rcp_f32_e32 v141, v141
	s_nop 0
	v_mul_f32_e32 v141, v140, v141
	v_cndmask_b32_e32 v142, v140, v141, vcc
	v_mul_f32_e32 v140, v39, v133
	v_mul_f32_e32 v141, 0xbfb8aa3b, v140
	v_exp_f32_e32 v141, v141
	s_nop 0
	v_add_f32_e32 v141, 1.0, v141
	v_rcp_f32_e32 v141, v141
	s_nop 0
	v_mul_f32_e32 v141, v140, v141
	v_cndmask_b32_e32 v143, v140, v141, vcc
	v_mul_f32_e32 v140, v40, v133
	v_mul_f32_e32 v141, 0xbfb8aa3b, v140
	v_exp_f32_e32 v141, v141
	v_mul_f32_e32 v133, v41, v133
	v_cvt_pk_bf16_f32 v142, v142, v143
	v_add_f32_e32 v141, 1.0, v141
	v_rcp_f32_e32 v141, v141
	s_nop 0
	v_mul_f32_e32 v141, v140, v141
	v_cndmask_b32_e32 v144, v140, v141, vcc
	v_mul_f32_e32 v140, 0xbfb8aa3b, v133
	v_exp_f32_e32 v140, v140
	v_cvt_pk_bf16_f32 v141, v137, v139
	s_nop 0
	v_add_f32_e32 v140, 1.0, v140
	v_rcp_f32_e32 v140, v140
	s_nop 0
	v_mul_f32_e32 v140, v133, v140
	v_cndmask_b32_e32 v133, v133, v140, vcc
	v_cvt_pk_bf16_f32 v140, v132, v136
	v_cvt_pk_bf16_f32 v143, v144, v133
	ds_read2_b32 v[132:133], v138 offset0:160 offset1:176
	global_store_dwordx4 v[134:135], v[140:143], off offset:256 nt
	v_lshl_add_u64 v[134:135], v[130:131], 0, s[0:1]
	s_mov_b32 s0, 0xa0000
	s_waitcnt lgkmcnt(0)
; __device__ __forceinline__ v4u pack8(const float (&f)[8]) { v4u w; w.x = cvt_pk_bf16(f[0], f[1]); w.y = cvt_pk_bf16(f[2], f[3]); w.z = cvt_pk_bf16(f[4], f[5]); w.w = cvt_pk_bf16(f[6], f[7]); return w; }
; __device__ __forceinline__ float siluf_(float x) { return x * rcpf_(1.f + __expf(-x)); }
;     __device__ __forceinline__ void operator()(const f32x4 (&acc)[2][2][4][2], const Unit& u, int wr, int wc, int fr, int fq) const {
;     ...
;             } else {
;                 const bool isg = u.pn >= 16;
;                 bf16* base = (isg ? SG : V) + ((u.pn - (isg ? 16 : 8)) * 256) + cw;
; #pragma unroll
;                 for (int ai = 0; ai < 2; ++ai)
; #pragma unroll
;                     for (int m = 0; m < 4; ++m) {
;                         bf16* rp = base + (size_t)(row0 + ai * 128 + m * 16) * 2048;
;                         const float rs = rtab[u.ord * 256 + (wr * 64 + fr + ai * 128 + m * 16)];
; #pragma unroll
;                         for (int bj = 0; bj < 2; ++bj) {
;                             float o[8];
; #pragma unroll
;                             for (int n = 0; n < 2; ++n)
; #pragma unroll
;                                 for (int j = 0; j < 4; ++j) { const float x = acc[ai][bj][m][n][j] * rs; o[n * 4 + j] = isg ? siluf_(x) : x; }
;                             *(v4u*)(rp + bj * 128) = pack8(o);
;                         }
;                     }
;             }
	v_mul_f32_e32 v136, v26, v132
	v_mul_f32_e32 v137, 0xbfb8aa3b, v136
	v_exp_f32_e32 v137, v137
	s_nop 0
	v_add_f32_e32 v137, 1.0, v137
	v_rcp_f32_e32 v137, v137
	s_nop 0
	v_mul_f32_e32 v137, v136, v137
	v_cndmask_b32_e32 v136, v136, v137, vcc
	v_mul_f32_e32 v137, v27, v132
	v_mul_f32_e32 v138, 0xbfb8aa3b, v137
	v_exp_f32_e32 v138, v138
	s_nop 0
	v_add_f32_e32 v138, 1.0, v138
	v_rcp_f32_e32 v138, v138
	s_nop 0
	v_mul_f32_e32 v138, v137, v138
	v_cndmask_b32_e32 v137, v137, v138, vcc
	v_mul_f32_e32 v138, v28, v132
	v_mul_f32_e32 v139, 0xbfb8aa3b, v138
	v_exp_f32_e32 v139, v139
	v_cvt_pk_bf16_f32 v136, v136, v137
	s_nop 0
	v_add_f32_e32 v139, 1.0, v139
	v_rcp_f32_e32 v139, v139
	s_nop 0
	v_mul_f32_e32 v139, v138, v139
	v_cndmask_b32_e32 v138, v138, v139, vcc
	v_mul_f32_e32 v139, v29, v132
	v_mul_f32_e32 v140, 0xbfb8aa3b, v139
	v_exp_f32_e32 v140, v140
	s_nop 0
	v_add_f32_e32 v140, 1.0, v140
	v_rcp_f32_e32 v140, v140
	s_nop 0
	v_mul_f32_e32 v140, v139, v140
	v_cndmask_b32_e32 v139, v139, v140, vcc
	v_mul_f32_e32 v140, v18, v132
	v_mul_f32_e32 v141, 0xbfb8aa3b, v140
	v_exp_f32_e32 v141, v141
	v_cvt_pk_bf16_f32 v137, v138, v139
	s_nop 0
	v_add_f32_e32 v141, 1.0, v141
	v_rcp_f32_e32 v141, v141
	s_nop 0
	v_mul_f32_e32 v141, v140, v141
	v_cndmask_b32_e32 v140, v140, v141, vcc
	v_mul_f32_e32 v141, v19, v132
	v_mul_f32_e32 v142, 0xbfb8aa3b, v141
	v_exp_f32_e32 v142, v142
	s_nop 0
	v_add_f32_e32 v142, 1.0, v142
	v_rcp_f32_e32 v142, v142
	s_nop 0
	v_mul_f32_e32 v142, v141, v142
	v_cndmask_b32_e32 v141, v141, v142, vcc
	v_mul_f32_e32 v142, v20, v132
	v_mul_f32_e32 v143, 0xbfb8aa3b, v142
	v_exp_f32_e32 v143, v143
	v_cvt_pk_bf16_f32 v138, v140, v141
	v_add_co_u32_e64 v140, s[0:1], s0, v130
	v_add_f32_e32 v143, 1.0, v143
	v_rcp_f32_e32 v143, v143
	v_addc_co_u32_e64 v141, s[0:1], 0, v131, s[0:1]
	s_mov_b64 s[0:1], 0xb0000
	v_mul_f32_e32 v143, v142, v143
	v_cndmask_b32_e32 v142, v142, v143, vcc
	v_mul_f32_e32 v143, v21, v132
	v_mul_f32_e32 v144, 0xbfb8aa3b, v143
	v_exp_f32_e32 v144, v144
	s_nop 0
	v_add_f32_e32 v144, 1.0, v144
	v_rcp_f32_e32 v144, v144
	s_nop 0
	v_mul_f32_e32 v144, v143, v144
	v_cndmask_b32_e32 v143, v143, v144, vcc
	v_cvt_pk_bf16_f32 v139, v142, v143
	global_store_dwordx4 v[140:141], v[136:139], off nt
	s_nop 1
	v_mul_f32_e32 v136, v30, v132
	v_mul_f32_e32 v137, 0xbfb8aa3b, v136
	v_exp_f32_e32 v137, v137
	s_nop 0
	v_add_f32_e32 v137, 1.0, v137
	v_rcp_f32_e32 v137, v137
	s_nop 0
	v_mul_f32_e32 v137, v136, v137
	v_cndmask_b32_e32 v136, v136, v137, vcc
	v_mul_f32_e32 v137, v31, v132
	v_mul_f32_e32 v138, 0xbfb8aa3b, v137
	v_exp_f32_e32 v138, v138
	s_nop 0
	v_add_f32_e32 v138, 1.0, v138
	v_rcp_f32_e32 v138, v138
	s_nop 0
	v_mul_f32_e32 v138, v137, v138
	v_cndmask_b32_e32 v137, v137, v138, vcc
	v_mul_f32_e32 v138, v32, v132
	v_mul_f32_e32 v139, 0xbfb8aa3b, v138
	v_exp_f32_e32 v139, v139
	v_cvt_pk_bf16_f32 v136, v136, v137
	s_nop 0
	v_add_f32_e32 v139, 1.0, v139
	v_rcp_f32_e32 v139, v139
	s_nop 0
	v_mul_f32_e32 v139, v138, v139
	v_cndmask_b32_e32 v138, v138, v139, vcc
	v_mul_f32_e32 v139, v33, v132
	v_mul_f32_e32 v140, 0xbfb8aa3b, v139
	v_exp_f32_e32 v140, v140
	s_nop 0
	v_add_f32_e32 v140, 1.0, v140
	v_rcp_f32_e32 v140, v140
	s_nop 0
	v_mul_f32_e32 v140, v139, v140
	v_cndmask_b32_e32 v139, v139, v140, vcc
	v_mul_f32_e32 v140, v22, v132
	v_mul_f32_e32 v141, 0xbfb8aa3b, v140
	v_exp_f32_e32 v141, v141
	v_cvt_pk_bf16_f32 v137, v138, v139
	s_nop 0
	v_add_f32_e32 v141, 1.0, v141
	v_rcp_f32_e32 v141, v141
	s_nop 0
	v_mul_f32_e32 v141, v140, v141
	v_cndmask_b32_e32 v140, v140, v141, vcc
	v_mul_f32_e32 v141, v23, v132
	v_mul_f32_e32 v142, 0xbfb8aa3b, v141
	v_exp_f32_e32 v142, v142
	s_nop 0
	v_add_f32_e32 v142, 1.0, v142
	v_rcp_f32_e32 v142, v142
	s_nop 0
	v_mul_f32_e32 v142, v141, v142
	v_cndmask_b32_e32 v141, v141, v142, vcc
	v_mul_f32_e32 v142, v24, v132
	v_mul_f32_e32 v143, 0xbfb8aa3b, v142
	v_exp_f32_e32 v143, v143
	v_mul_f32_e32 v132, v25, v132
	v_cvt_pk_bf16_f32 v138, v140, v141
	v_add_f32_e32 v143, 1.0, v143
	v_rcp_f32_e32 v143, v143
	s_nop 0
	v_mul_f32_e32 v143, v142, v143
	v_cndmask_b32_e32 v142, v142, v143, vcc
	v_mul_f32_e32 v143, 0xbfb8aa3b, v132
	v_exp_f32_e32 v143, v143
	s_nop 0
	v_add_f32_e32 v143, 1.0, v143
	v_rcp_f32_e32 v143, v143
	s_nop 0
	v_mul_f32_e32 v143, v132, v143
	v_cndmask_b32_e32 v132, v132, v143, vcc
	v_cvt_pk_bf16_f32 v139, v142, v132
	v_mul_f32_e32 v132, v10, v133
	global_store_dwordx4 v[134:135], v[136:139], off offset:256 nt
	v_lshl_add_u64 v[134:135], v[130:131], 0, s[0:1]
	s_mov_b32 s0, 0xb0000
	v_mul_f32_e32 v136, 0xbfb8aa3b, v132
	v_exp_f32_e32 v136, v136
	v_add_co_u32_e64 v130, s[0:1], s0, v130
	v_add_f32_e32 v136, 1.0, v136
	v_rcp_f32_e32 v136, v136
	v_addc_co_u32_e64 v131, s[0:1], 0, v131, s[0:1]
	s_mov_b64 s[0:1], 0
	v_mul_f32_e32 v136, v132, v136
	v_cndmask_b32_e32 v132, v132, v136, vcc
	v_mul_f32_e32 v136, v11, v133
	v_mul_f32_e32 v137, 0xbfb8aa3b, v136
	v_exp_f32_e32 v137, v137
	s_nop 0
	v_add_f32_e32 v137, 1.0, v137
	v_rcp_f32_e32 v137, v137
	s_nop 0
	v_mul_f32_e32 v137, v136, v137
	v_cndmask_b32_e32 v136, v136, v137, vcc
	v_mul_f32_e32 v137, v12, v133
	v_mul_f32_e32 v138, 0xbfb8aa3b, v137
	v_exp_f32_e32 v138, v138
	v_cvt_pk_bf16_f32 v136, v132, v136
	s_nop 0
	v_add_f32_e32 v138, 1.0, v138
	v_rcp_f32_e32 v138, v138
	s_nop 0
	v_mul_f32_e32 v138, v137, v138
	v_cndmask_b32_e32 v137, v137, v138, vcc
	v_mul_f32_e32 v138, v13, v133
	v_mul_f32_e32 v139, 0xbfb8aa3b, v138
	v_exp_f32_e32 v139, v139
	s_nop 0
	v_add_f32_e32 v139, 1.0, v139
	v_rcp_f32_e32 v139, v139
	s_nop 0
	v_mul_f32_e32 v139, v138, v139
	v_cndmask_b32_e32 v138, v138, v139, vcc
	v_mul_f32_e32 v139, v6, v133
	v_mul_f32_e32 v140, 0xbfb8aa3b, v139
; __device__ __forceinline__ v4u pack8(const float (&f)[8]) { v4u w; w.x = cvt_pk_bf16(f[0], f[1]); w.y = cvt_pk_bf16(f[2], f[3]); w.z = cvt_pk_bf16(f[4], f[5]); w.w = cvt_pk_bf16(f[6], f[7]); return w; }
; __device__ __forceinline__ float siluf_(float x) { return x * rcpf_(1.f + __expf(-x)); }
;     __device__ __forceinline__ void operator()(const f32x4 (&acc)[2][2][4][2], const Unit& u, int wr, int wc, int fr, int fq) const {
;     ...
;                     for (int m = 0; m < 4; ++m) { const int row = row0 + ai * 128 + m * 16; const int pi = row < MP ? row % TP : TP;
;                         const f32x4* cs = (const f32x4*)(CS + ((size_t)pi * 128 + cw) * 2);
; #pragma unroll
;                         for (int q4 = 0; q4 < 4; ++q4) tt[m][q4] = cs[q4]; }
;     ...
;             } else {
;                 const bool isg = u.pn >= 16;
;                 bf16* base = (isg ? SG : V) + ((u.pn - (isg ? 16 : 8)) * 256) + cw;
; #pragma unroll
;                 for (int ai = 0; ai < 2; ++ai)
; #pragma unroll
;                     for (int m = 0; m < 4; ++m) {
;                         bf16* rp = base + (size_t)(row0 + ai * 128 + m * 16) * 2048;
;                         const float rs = rtab[u.ord * 256 + (wr * 64 + fr + ai * 128 + m * 16)];
; #pragma unroll
;                         for (int bj = 0; bj < 2; ++bj) {
;                             float o[8];
; #pragma unroll
;                             for (int n = 0; n < 2; ++n)
; #pragma unroll
;                                 for (int j = 0; j < 4; ++j) { const float x = acc[ai][bj][m][n][j] * rs; o[n * 4 + j] = isg ? siluf_(x) : x; }
;                             *(v4u*)(rp + bj * 128) = pack8(o);
;                         }
;                     }
;             }
	v_exp_f32_e32 v140, v140
	v_cvt_pk_bf16_f32 v137, v137, v138
	s_nop 0
	v_add_f32_e32 v140, 1.0, v140
	v_rcp_f32_e32 v140, v140
	s_nop 0
	v_mul_f32_e32 v140, v139, v140
	v_cndmask_b32_e32 v139, v139, v140, vcc
	v_mul_f32_e32 v140, v7, v133
	v_mul_f32_e32 v141, 0xbfb8aa3b, v140
	v_exp_f32_e32 v141, v141
	s_nop 0
	v_add_f32_e32 v141, 1.0, v141
	v_rcp_f32_e32 v141, v141
	s_nop 0
	v_mul_f32_e32 v141, v140, v141
	v_cndmask_b32_e32 v140, v140, v141, vcc
	v_mul_f32_e32 v141, v8, v133
	v_mul_f32_e32 v142, 0xbfb8aa3b, v141
	v_exp_f32_e32 v142, v142
	v_cvt_pk_bf16_f32 v138, v139, v140
	s_nop 0
	v_add_f32_e32 v142, 1.0, v142
	v_rcp_f32_e32 v142, v142
	s_nop 0
	v_mul_f32_e32 v142, v141, v142
	v_cndmask_b32_e32 v141, v141, v142, vcc
	v_mul_f32_e32 v142, v9, v133
	v_mul_f32_e32 v143, 0xbfb8aa3b, v142
	v_exp_f32_e32 v143, v143
	s_nop 0
	v_add_f32_e32 v143, 1.0, v143
	v_rcp_f32_e32 v143, v143
	s_nop 0
	v_mul_f32_e32 v143, v142, v143
	v_cndmask_b32_e32 v142, v142, v143, vcc
	v_cvt_pk_bf16_f32 v139, v141, v142
	global_store_dwordx4 v[130:131], v[136:139], off nt
	v_mul_f32_e32 v130, v14, v133
	v_mul_f32_e32 v131, 0xbfb8aa3b, v130
	v_exp_f32_e32 v131, v131
	s_nop 0
	v_add_f32_e32 v131, 1.0, v131
	v_rcp_f32_e32 v131, v131
	s_nop 0
	v_mul_f32_e32 v131, v130, v131
	v_cndmask_b32_e32 v130, v130, v131, vcc
	v_mul_f32_e32 v131, v15, v133
	v_mul_f32_e32 v132, 0xbfb8aa3b, v131
	v_exp_f32_e32 v132, v132
	s_nop 0
	v_add_f32_e32 v132, 1.0, v132
	v_rcp_f32_e32 v132, v132
	s_nop 0
	v_mul_f32_e32 v132, v131, v132
	v_cndmask_b32_e32 v131, v131, v132, vcc
	v_mul_f32_e32 v132, v16, v133
	v_mul_f32_e32 v136, 0xbfb8aa3b, v132
	v_exp_f32_e32 v136, v136
	v_cvt_pk_bf16_f32 v130, v130, v131
	s_nop 0
	v_add_f32_e32 v136, 1.0, v136
	v_rcp_f32_e32 v136, v136
	s_nop 0
	v_mul_f32_e32 v136, v132, v136
	v_cndmask_b32_e32 v132, v132, v136, vcc
	v_mul_f32_e32 v136, v17, v133
	v_mul_f32_e32 v137, 0xbfb8aa3b, v136
	v_exp_f32_e32 v137, v137
	s_nop 0
	v_add_f32_e32 v137, 1.0, v137
	v_rcp_f32_e32 v137, v137
	s_nop 0
	v_mul_f32_e32 v137, v136, v137
	v_cndmask_b32_e32 v136, v136, v137, vcc
	v_mul_f32_e32 v137, v2, v133
	v_mul_f32_e32 v138, 0xbfb8aa3b, v137
	v_exp_f32_e32 v138, v138
	v_cvt_pk_bf16_f32 v131, v132, v136
	s_nop 0
	v_add_f32_e32 v138, 1.0, v138
	v_rcp_f32_e32 v138, v138
	s_nop 0
	v_mul_f32_e32 v138, v137, v138
	v_cndmask_b32_e32 v137, v137, v138, vcc
	v_mul_f32_e32 v138, v3, v133
	v_mul_f32_e32 v139, 0xbfb8aa3b, v138
	v_exp_f32_e32 v139, v139
	s_nop 0
	v_add_f32_e32 v139, 1.0, v139
	v_rcp_f32_e32 v139, v139
	s_nop 0
	v_mul_f32_e32 v139, v138, v139
	v_cndmask_b32_e32 v138, v138, v139, vcc
	v_mul_f32_e32 v139, v4, v133
	v_mul_f32_e32 v140, 0xbfb8aa3b, v139
	v_exp_f32_e32 v140, v140
	v_mul_f32_e32 v133, v5, v133
	v_cvt_pk_bf16_f32 v132, v137, v138
	v_add_f32_e32 v140, 1.0, v140
	v_rcp_f32_e32 v140, v140
	s_nop 0
	v_mul_f32_e32 v140, v139, v140
	v_cndmask_b32_e32 v139, v139, v140, vcc
	v_mul_f32_e32 v140, 0xbfb8aa3b, v133
	v_exp_f32_e32 v140, v140
	s_nop 0
	v_add_f32_e32 v140, 1.0, v140
	v_rcp_f32_e32 v140, v140
	s_nop 0
	v_mul_f32_e32 v140, v133, v140
	v_cndmask_b32_e32 v133, v133, v140, vcc
	v_cvt_pk_bf16_f32 v133, v139, v133
	global_store_dwordx4 v[134:135], v[130:133], off offset:256 nt
.LBB0_1129:
	s_andn2_b64 vcc, exec, s[0:1]
	s_cbranch_vccnz .LBB0_1147
	v_cmp_gt_i32_e32 vcc, s17, v210
	s_waitcnt lgkmcnt(0)
	v_mov_b64_e32 v[130:131], 0x40800
	v_mov_b64_e32 v[132:133], 0x40800
	s_and_saveexec_b64 s[0:1], vcc
	s_mov_b32 s2, 0xfe03f81
	v_mul_hi_i32 v132, v210, s2
	v_lshrrev_b32_e32 v133, 31, v132
	v_ashrrev_i32_e32 v132, 7, v132
	v_add_u32_e32 v132, v132, v133
	v_mul_lo_u32 v132, v132, s16
	v_sub_u32_e32 v132, v210, v132
	v_ashrrev_i32_e32 v133, 31, v132
	v_lshlrev_b64 v[132:133], 7, v[132:133]
	s_or_b64 exec, exec, s[0:1]
	v_readlane_b32 s0, v252, 28
	v_or_b32_e32 v132, v132, v204
	v_readlane_b32 s1, v252, 29
	v_cmp_gt_i32_e32 vcc, s17, v216
	s_nop 0
	v_lshl_add_u64 v[132:133], v[132:133], 3, s[0:1]
	global_load_dwordx4 v[178:181], v[132:133], off offset:48
	global_load_dwordx4 v[182:185], v[132:133], off offset:32
	global_load_dwordx4 v[186:189], v[132:133], off offset:16
	global_load_dwordx4 v[190:193], v[132:133], off
	s_and_saveexec_b64 s[0:1], vcc
	s_mov_b32 s2, 0xfe03f81
	v_mul_hi_i32 v130, v216, s2
	v_lshrrev_b32_e32 v131, 31, v130
	v_ashrrev_i32_e32 v130, 7, v130
	v_add_u32_e32 v130, v130, v131
	v_mul_lo_u32 v130, v130, s16
	v_sub_u32_e32 v130, v216, v130
	v_ashrrev_i32_e32 v131, 31, v130
	v_lshlrev_b64 v[130:131], 7, v[130:131]
	s_or_b64 exec, exec, s[0:1]
	v_readlane_b32 s0, v252, 28
	v_or_b32_e32 v130, v130, v204
	v_readlane_b32 s1, v252, 29
	v_cmp_gt_i32_e32 vcc, s17, v214
	v_mov_b64_e32 v[132:133], 0x40800
	v_lshl_add_u64 v[130:131], v[130:131], 3, s[0:1]
	global_load_dwordx4 v[162:165], v[130:131], off offset:48
	global_load_dwordx4 v[166:169], v[130:131], off offset:32
	global_load_dwordx4 v[170:173], v[130:131], off offset:16
	global_load_dwordx4 v[174:177], v[130:131], off
	v_mov_b64_e32 v[130:131], 0x40800
	s_and_saveexec_b64 s[0:1], vcc
	s_mov_b32 s2, 0xfe03f81
	v_mul_hi_i32 v132, v214, s2
	v_lshrrev_b32_e32 v133, 31, v132
	v_ashrrev_i32_e32 v132, 7, v132
	v_add_u32_e32 v132, v132, v133
	v_mul_lo_u32 v132, v132, s16
	v_sub_u32_e32 v132, v214, v132
	v_ashrrev_i32_e32 v133, 31, v132
	v_lshlrev_b64 v[132:133], 7, v[132:133]
	s_or_b64 exec, exec, s[0:1]
	v_readlane_b32 s0, v252, 28
	v_or_b32_e32 v132, v132, v204
	v_readlane_b32 s1, v252, 29
	v_cmp_gt_i32_e32 vcc, s17, v212
	s_nop 0
	v_lshl_add_u64 v[132:133], v[132:133], 3, s[0:1]
	global_load_dwordx4 v[138:141], v[132:133], off offset:48
	global_load_dwordx4 v[150:153], v[132:133], off offset:32
; __device__ __forceinline__ v4u pack8(const float (&f)[8]) { v4u w; w.x = cvt_pk_bf16(f[0], f[1]); w.y = cvt_pk_bf16(f[2], f[3]); w.z = cvt_pk_bf16(f[4], f[5]); w.w = cvt_pk_bf16(f[6], f[7]); return w; }
;     __device__ __forceinline__ void operator()(const f32x4 (&acc)[2][2][4][2], const Unit& u, int wr, int wc, int fr, int fq) const {
;     ...
;                     for (int m = 0; m < 4; ++m) { const int row = row0 + ai * 128 + m * 16; const int pi = row < MP ? row % TP : TP;
;                         const f32x4* cs = (const f32x4*)(CS + ((size_t)pi * 128 + cw) * 2);
; #pragma unroll
;                         for (int q4 = 0; q4 < 4; ++q4) tt[m][q4] = cs[q4]; }
; #pragma unroll
;                     for (int m = 0; m < 4; ++m) {
;                         const int row = row0 + ai * 128 + m * 16;
;                         const float rs = rtab[u.ord * 256 + (row - u.pm * 256)] * sc;
;                         const f32x4 t0 = tt[m][0], t1 = tt[m][1], t2 = tt[m][2], t3 = tt[m][3];
;                         const float c[8] = {t0.x, t0.z, t1.x, t1.z, t2.x, t2.z, t3.x, t3.z}, s[8] = {t0.y, t0.w, t1.y, t1.w, t2.y, t2.w, t3.y, t3.w};
;                         float o1[8], o2[8];
; #pragma unroll
;                         for (int n = 0; n < 2; ++n)
; #pragma unroll
;                             for (int j = 0; j < 4; ++j) {
;                                 const float x1 = acc[ai][0][m][n][j], x2 = acc[ai][1][m][n][j];
;                                 o1[n * 4 + j] = (x1 * c[n * 4 + j] - x2 * s[n * 4 + j]) * rs;
;                                 o2[n * 4 + j] = (x1 * s[n * 4 + j] + x2 * c[n * 4 + j]) * rs;
;                             }
;                         bf16* rp = base + (size_t)row * 2048;
;                         *(v4u*)rp = pack8(o1); *(v4u*)(rp + 128) = pack8(o2);
;                     }
	global_load_dwordx4 v[154:157], v[132:133], off offset:16
	global_load_dwordx4 v[158:161], v[132:133], off
	s_and_saveexec_b64 s[0:1], vcc
	s_mov_b32 s2, 0xfe03f81
	v_mul_hi_i32 v130, v212, s2
	v_lshrrev_b32_e32 v131, 31, v130
	v_ashrrev_i32_e32 v130, 7, v130
	v_add_u32_e32 v130, v130, v131
	v_mul_lo_u32 v130, v130, s16
	v_sub_u32_e32 v130, v212, v130
	v_ashrrev_i32_e32 v131, 31, v130
	v_lshlrev_b64 v[130:131], 7, v[130:131]
	s_or_b64 exec, exec, s[0:1]
	s_cmp_gt_i32 s87, 3
	s_cselect_b64 vcc, -1, 0
	s_and_b64 s[0:1], vcc, exec
	s_cselect_b32 s0, 0x800, 0
	v_readlane_b32 s2, v252, 30
	v_readlane_b32 s3, v252, 31
	s_add_u32 s0, s2, s0
	s_addc_u32 s1, s3, 0
	s_lshl_b32 s2, s87, 9
	s_and_b32 s2, s2, 0x600
	s_add_u32 s0, s0, s2
	s_addc_u32 s1, s1, 0
	v_lshl_add_u64 v[218:219], s[0:1], 0, v[0:1]
	v_readlane_b32 s0, v252, 28
	v_or_b32_e32 v130, v130, v204
	v_readlane_b32 s1, v252, 29
	v_mov_b32_e32 v132, 0x3d800000
	v_cndmask_b32_e32 v221, 1.0, v132, vcc
	v_lshl_add_u64 v[146:147], v[130:131], 3, s[0:1]
	global_load_dwordx4 v[130:133], v[146:147], off offset:48
	global_load_dwordx4 v[134:137], v[146:147], off offset:32
	global_load_dwordx4 v[142:145], v[146:147], off offset:16
	s_nop 0
	global_load_dwordx4 v[146:149], v[146:147], off
	s_lshl_b32 s0, s88, 10
	v_add_u32_e32 v0, s0, v245
	ds_read2_b32 v[234:235], v0 offset1:16
	v_mov_b32_e32 v236, v122
	v_mov_b32_e32 v237, v126
	v_mov_b32_e32 v248, v126
	v_mov_b32_e32 v249, v122
	v_mov_b32_e32 v126, v123
	v_mov_b32_e32 v122, v127
	s_waitcnt vmcnt(0)
	v_pk_mul_f32 v[236:237], v[236:237], v[190:191]
	v_pk_mul_f32 v[190:191], v[248:249], v[190:191]
	v_pk_mul_f32 v[248:249], v[126:127], v[192:193]
	v_pk_mul_f32 v[122:123], v[122:123], v[192:193]
	v_mov_b32_e32 v126, v124
	v_mov_b32_e32 v127, v128
	v_mov_b32_e32 v192, v128
	v_mov_b32_e32 v193, v124
	v_mov_b32_e32 v128, v125
	v_mov_b32_e32 v124, v129
	v_pk_mul_f32 v[126:127], v[126:127], v[186:187]
	v_pk_mul_f32 v[186:187], v[192:193], v[186:187]
	v_pk_mul_f32 v[192:193], v[128:129], v[188:189]
	v_pk_mul_f32 v[124:125], v[124:125], v[188:189]
	v_mov_b32_e32 v128, v114
	v_mov_b32_e32 v129, v118
	v_mov_b32_e32 v188, v118
	v_mov_b32_e32 v189, v114
	v_mov_b32_e32 v118, v115
	v_mov_b32_e32 v114, v119
	v_pk_mul_f32 v[128:129], v[128:129], v[182:183]
	v_pk_mul_f32 v[182:183], v[188:189], v[182:183]
	v_pk_mul_f32 v[188:189], v[118:119], v[184:185]
	v_pk_mul_f32 v[114:115], v[114:115], v[184:185]
	v_mov_b32_e32 v220, v116
	v_mov_b32_e32 v118, v178
	s_waitcnt lgkmcnt(0)
	v_mov_b32_e32 v119, v234
	v_pk_mul_f32 v[118:119], v[220:221], v[118:119]
	v_add_f32_e32 v114, v115, v114
	v_add_f32_e32 v124, v125, v124
	v_sub_f32_e32 v125, v128, v129
	v_add_f32_e32 v128, v183, v182
	v_mul_f32_e32 v182, v114, v119
	v_fma_f32 v114, -v120, v179, v118
	v_mul_f32_e32 v183, v114, v119
	v_mov_b32_e32 v114, v120
	v_mov_b32_e32 v115, v116
	v_pk_mul_f32 v[114:115], v[114:115], v[178:179]
	v_mov_b32_e32 v120, v117
	v_add_f32_e32 v114, v115, v114
	v_mul_f32_e32 v178, v114, v119
	v_pk_mul_f32 v[114:115], v[120:121], v[180:181]
	v_mov_b32_e32 v116, v121
	v_sub_f32_e32 v114, v114, v115
	v_mul_f32_e32 v120, v114, v119
	v_pk_mul_f32 v[114:115], v[116:117], v[180:181]
	v_sub_f32_e32 v184, v236, v237
	v_add_f32_e32 v114, v115, v114
	v_add_f32_e32 v185, v191, v190
	v_sub_f32_e32 v190, v248, v249
	v_add_f32_e32 v122, v123, v122
	v_sub_f32_e32 v123, v126, v127
	v_add_f32_e32 v126, v187, v186
	v_sub_f32_e32 v127, v192, v193
	v_sub_f32_e32 v129, v188, v189
	v_mul_f32_e32 v121, v114, v119
	v_lshlrev_b64 v[114:115], 12, v[210:211]
	v_mul_f32_e32 v184, v184, v119
	v_mul_f32_e32 v185, v185, v119
	v_mul_f32_e32 v190, v190, v119
	v_mul_f32_e32 v122, v122, v119
	v_mul_f32_e32 v123, v123, v119
	v_mul_f32_e32 v126, v126, v119
	v_mul_f32_e32 v127, v127, v119
	v_mul_f32_e32 v124, v124, v119
	v_mul_f32_e32 v125, v125, v119
	v_mul_f32_e32 v128, v128, v119
	v_mul_f32_e32 v129, v129, v119
	v_lshl_add_u64 v[118:119], v[218:219], 0, v[114:115]
	v_cvt_pk_bf16_f32 v115, v123, v127
	v_cvt_pk_bf16_f32 v116, v125, v129
	v_cvt_pk_bf16_f32 v114, v184, v190
	v_cvt_pk_bf16_f32 v117, v183, v120
	global_store_dwordx4 v[118:119], v[114:117], off nt
	v_mov_b32_e32 v120, v112
	v_mov_b32_e32 v125, v98
	v_cvt_pk_bf16_f32 v115, v126, v124
	v_cvt_pk_bf16_f32 v116, v128, v182
	v_cvt_pk_bf16_f32 v114, v185, v122
	v_cvt_pk_bf16_f32 v117, v178, v121
	global_store_dwordx4 v[118:119], v[114:117], off offset:256 nt
	v_mov_b32_e32 v121, v108
	v_mov_b32_e32 v124, v102
	v_mov_b32_e32 v115, v110
	v_mov_b32_e32 v116, v110
	v_mov_b32_e32 v110, v107
	v_mov_b32_e32 v114, v106
	v_mov_b32_e32 v117, v106
	v_pk_mul_f32 v[118:119], v[110:111], v[176:177]
	v_mov_b32_e32 v106, v111
	v_mov_b32_e32 v111, v112
	v_mov_b32_e32 v112, v109
	v_pk_mul_f32 v[122:123], v[112:113], v[172:173]
	v_mov_b32_e32 v112, v98
	v_mov_b32_e32 v98, v103
	v_mov_b32_e32 v110, v108
	v_mov_b32_e32 v108, v113
	v_mov_b32_e32 v113, v102
	v_mov_b32_e32 v102, v99
	v_pk_mul_f32 v[98:99], v[98:99], v[168:169]
	v_mov_b32_e32 v220, v100
	v_mov_b32_e32 v234, v162
	v_pk_mul_f32 v[114:115], v[114:115], v[174:175]
	v_pk_mul_f32 v[116:117], v[116:117], v[174:175]
	v_pk_mul_f32 v[126:127], v[102:103], v[168:169]
	v_pk_mul_f32 v[102:103], v[220:221], v[234:235]
	v_add_f32_e32 v98, v99, v98
	v_sub_f32_e32 v114, v114, v115
	v_add_f32_e32 v115, v117, v116
	v_mul_f32_e32 v117, v98, v103
	v_fma_f32 v98, -v104, v163, v102
	v_sub_f32_e32 v116, v118, v119
	v_mul_f32_e32 v118, v98, v103
	v_mov_b32_e32 v98, v104
	v_mov_b32_e32 v99, v100
	v_pk_mul_f32 v[98:99], v[98:99], v[162:163]
	v_mov_b32_e32 v104, v101
	v_add_f32_e32 v98, v99, v98
	v_mul_f32_e32 v119, v98, v103
	v_pk_mul_f32 v[98:99], v[104:105], v[164:165]
; __device__ __forceinline__ v4u pack8(const float (&f)[8]) { v4u w; w.x = cvt_pk_bf16(f[0], f[1]); w.y = cvt_pk_bf16(f[2], f[3]); w.z = cvt_pk_bf16(f[4], f[5]); w.w = cvt_pk_bf16(f[6], f[7]); return w; }
;     __device__ __forceinline__ void operator()(const f32x4 (&acc)[2][2][4][2], const Unit& u, int wr, int wc, int fr, int fq) const {
;     ...
;                     for (int m = 0; m < 4; ++m) {
;                         const int row = row0 + ai * 128 + m * 16;
;                         const float rs = rtab[u.ord * 256 + (row - u.pm * 256)] * sc;
;                         const f32x4 t0 = tt[m][0], t1 = tt[m][1], t2 = tt[m][2], t3 = tt[m][3];
;                         const float c[8] = {t0.x, t0.z, t1.x, t1.z, t2.x, t2.z, t3.x, t3.z}, s[8] = {t0.y, t0.w, t1.y, t1.w, t2.y, t2.w, t3.y, t3.w};
;                         float o1[8], o2[8];
; #pragma unroll
;                         for (int n = 0; n < 2; ++n)
; #pragma unroll
;                             for (int j = 0; j < 4; ++j) {
;                                 const float x1 = acc[ai][0][m][n][j], x2 = acc[ai][1][m][n][j];
;                                 o1[n * 4 + j] = (x1 * c[n * 4 + j] - x2 * s[n * 4 + j]) * rs;
;                                 o2[n * 4 + j] = (x1 * s[n * 4 + j] + x2 * c[n * 4 + j]) * rs;
;                             }
;                         bf16* rp = base + (size_t)row * 2048;
;                         *(v4u*)rp = pack8(o1); *(v4u*)(rp + 128) = pack8(o2);
;                     }
	v_mov_b32_e32 v100, v105
	v_sub_f32_e32 v98, v98, v99
	v_mul_f32_e32 v104, v98, v103
	v_pk_mul_f32 v[98:99], v[100:101], v[164:165]
	v_pk_mul_f32 v[106:107], v[106:107], v[176:177]
	v_pk_mul_f32 v[110:111], v[110:111], v[170:171]
	v_pk_mul_f32 v[120:121], v[120:121], v[170:171]
	v_pk_mul_f32 v[108:109], v[108:109], v[172:173]
	v_pk_mul_f32 v[112:113], v[112:113], v[166:167]
	v_pk_mul_f32 v[124:125], v[124:125], v[166:167]
	v_add_f32_e32 v98, v99, v98
	v_add_f32_e32 v106, v107, v106
	v_sub_f32_e32 v107, v110, v111
	v_add_f32_e32 v110, v121, v120
	v_sub_f32_e32 v111, v122, v123
	v_add_f32_e32 v108, v109, v108
	v_sub_f32_e32 v109, v112, v113
	v_add_f32_e32 v112, v125, v124
	v_sub_f32_e32 v113, v126, v127
	v_mul_f32_e32 v105, v98, v103
	v_lshlrev_b64 v[98:99], 12, v[216:217]
	v_mul_f32_e32 v114, v114, v103
	v_mul_f32_e32 v115, v115, v103
	v_mul_f32_e32 v116, v116, v103
	v_mul_f32_e32 v106, v106, v103
	v_mul_f32_e32 v107, v107, v103
	v_mul_f32_e32 v110, v110, v103
	v_mul_f32_e32 v111, v111, v103
	v_mul_f32_e32 v108, v108, v103
	v_mul_f32_e32 v109, v109, v103
	v_mul_f32_e32 v112, v112, v103
	v_mul_f32_e32 v113, v113, v103
	v_lshl_add_u64 v[102:103], v[218:219], 0, v[98:99]
	v_cvt_pk_bf16_f32 v98, v114, v116
	v_cvt_pk_bf16_f32 v99, v107, v111
	v_cvt_pk_bf16_f32 v100, v109, v113
	v_cvt_pk_bf16_f32 v101, v118, v104
	global_store_dwordx4 v[102:103], v[98:101], off nt
	v_mov_b32_e32 v107, v92
	v_mov_b32_e32 v111, v82
	v_cvt_pk_bf16_f32 v98, v115, v106
	v_cvt_pk_bf16_f32 v99, v110, v108
	v_cvt_pk_bf16_f32 v100, v112, v117
	v_cvt_pk_bf16_f32 v101, v119, v105
	global_store_dwordx4 v[102:103], v[98:101], off offset:256 nt
	ds_read2_b32 v[98:99], v0 offset0:32 offset1:48
	v_mov_b32_e32 v102, v94
	v_mov_b32_e32 v101, v94
	v_mov_b32_e32 v94, v91
	v_mov_b32_e32 v100, v90
	v_mov_b32_e32 v103, v90
	v_pk_mul_f32 v[104:105], v[94:95], v[160:161]
	v_mov_b32_e32 v90, v95
	v_mov_b32_e32 v95, v96
	v_mov_b32_e32 v106, v96
	v_mov_b32_e32 v96, v93
	v_mov_b32_e32 v94, v92
	v_pk_mul_f32 v[108:109], v[96:97], v[156:157]
	v_mov_b32_e32 v92, v97
	v_mov_b32_e32 v96, v82
	v_mov_b32_e32 v97, v86
	v_mov_b32_e32 v110, v86
	v_mov_b32_e32 v86, v83
	v_mov_b32_e32 v82, v87
	v_pk_mul_f32 v[112:113], v[86:87], v[152:153]
	v_pk_mul_f32 v[82:83], v[82:83], v[152:153]
	v_mov_b32_e32 v220, v84
	v_mov_b32_e32 v86, v138
	s_waitcnt lgkmcnt(0)
	v_mov_b32_e32 v87, v98
	v_pk_mul_f32 v[100:101], v[100:101], v[158:159]
	v_pk_mul_f32 v[102:103], v[102:103], v[158:159]
	v_pk_mul_f32 v[86:87], v[220:221], v[86:87]
	v_add_f32_e32 v82, v83, v82
	v_sub_f32_e32 v98, v100, v101
	v_add_f32_e32 v100, v103, v102
	v_mul_f32_e32 v102, v82, v87
	v_fma_f32 v82, -v88, v139, v86
	v_mul_f32_e32 v103, v82, v87
	v_mov_b32_e32 v82, v88
	v_mov_b32_e32 v83, v84
	v_pk_mul_f32 v[82:83], v[82:83], v[138:139]
	v_mov_b32_e32 v88, v85
	v_add_f32_e32 v82, v83, v82
	v_sub_f32_e32 v101, v104, v105
	v_mul_f32_e32 v104, v82, v87
	v_pk_mul_f32 v[82:83], v[88:89], v[140:141]
	v_mov_b32_e32 v84, v89
	v_sub_f32_e32 v82, v82, v83
	v_mul_f32_e32 v88, v82, v87
	v_pk_mul_f32 v[82:83], v[84:85], v[140:141]
	v_pk_mul_f32 v[90:91], v[90:91], v[160:161]
	v_pk_mul_f32 v[94:95], v[94:95], v[154:155]
	v_pk_mul_f32 v[106:107], v[106:107], v[154:155]
	v_pk_mul_f32 v[92:93], v[92:93], v[156:157]
	v_pk_mul_f32 v[96:97], v[96:97], v[150:151]
	v_pk_mul_f32 v[110:111], v[110:111], v[150:151]
	v_add_f32_e32 v82, v83, v82
	v_add_f32_e32 v90, v91, v90
	v_sub_f32_e32 v91, v94, v95
	v_add_f32_e32 v94, v107, v106
	v_sub_f32_e32 v95, v108, v109
	v_add_f32_e32 v92, v93, v92
	v_sub_f32_e32 v93, v96, v97
	v_add_f32_e32 v96, v111, v110
	v_sub_f32_e32 v97, v112, v113
	v_mul_f32_e32 v89, v82, v87
	v_lshlrev_b64 v[82:83], 12, v[214:215]
	v_mul_f32_e32 v98, v98, v87
	v_mul_f32_e32 v100, v100, v87
	v_mul_f32_e32 v101, v101, v87
	v_mul_f32_e32 v90, v90, v87
	v_mul_f32_e32 v91, v91, v87
	v_mul_f32_e32 v94, v94, v87
	v_mul_f32_e32 v95, v95, v87
	v_mul_f32_e32 v92, v92, v87
	v_mul_f32_e32 v93, v93, v87
	v_mul_f32_e32 v96, v96, v87
	v_mul_f32_e32 v97, v97, v87
	v_lshl_add_u64 v[86:87], v[218:219], 0, v[82:83]
	v_cvt_pk_bf16_f32 v83, v91, v95
	v_cvt_pk_bf16_f32 v84, v93, v97
	v_cvt_pk_bf16_f32 v82, v98, v101
	v_cvt_pk_bf16_f32 v85, v103, v88
	global_store_dwordx4 v[86:87], v[82:85], off nt
	v_mov_b32_e32 v88, v80
	v_mov_b32_e32 v93, v66
	v_cvt_pk_bf16_f32 v83, v94, v92
	v_cvt_pk_bf16_f32 v84, v96, v102
	v_cvt_pk_bf16_f32 v82, v100, v90
	v_cvt_pk_bf16_f32 v85, v104, v89
	global_store_dwordx4 v[86:87], v[82:85], off offset:256 nt
	v_mov_b32_e32 v89, v76
	v_mov_b32_e32 v92, v70
	v_mov_b32_e32 v83, v78
	v_mov_b32_e32 v84, v78
	v_mov_b32_e32 v78, v75
	v_mov_b32_e32 v82, v74
	v_mov_b32_e32 v85, v74
	v_pk_mul_f32 v[86:87], v[78:79], v[148:149]
	v_mov_b32_e32 v74, v79
	v_mov_b32_e32 v79, v80
	v_mov_b32_e32 v80, v77
	v_pk_mul_f32 v[90:91], v[80:81], v[144:145]
	v_mov_b32_e32 v80, v66
	v_mov_b32_e32 v66, v71
	v_mov_b32_e32 v78, v76
	v_mov_b32_e32 v76, v81
	v_mov_b32_e32 v81, v70
	v_mov_b32_e32 v70, v67
	v_pk_mul_f32 v[66:67], v[66:67], v[136:137]
	v_mov_b32_e32 v220, v68
	v_mov_b32_e32 v98, v130
	v_pk_mul_f32 v[82:83], v[82:83], v[146:147]
	v_pk_mul_f32 v[84:85], v[84:85], v[146:147]
	v_pk_mul_f32 v[94:95], v[70:71], v[136:137]
	v_pk_mul_f32 v[70:71], v[220:221], v[98:99]
	v_add_f32_e32 v66, v67, v66
	v_sub_f32_e32 v82, v82, v83
	v_add_f32_e32 v83, v85, v84
	v_mul_f32_e32 v85, v66, v71
	v_fma_f32 v66, -v72, v131, v70
	v_sub_f32_e32 v84, v86, v87
	v_mul_f32_e32 v86, v66, v71
	v_mov_b32_e32 v66, v72
	v_mov_b32_e32 v67, v68
	v_pk_mul_f32 v[66:67], v[66:67], v[130:131]
	v_mov_b32_e32 v72, v69
	v_add_f32_e32 v66, v67, v66
	v_mul_f32_e32 v87, v66, v71
	v_pk_mul_f32 v[66:67], v[72:73], v[132:133]
; __device__ __forceinline__ v4u pack8(const float (&f)[8]) { v4u w; w.x = cvt_pk_bf16(f[0], f[1]); w.y = cvt_pk_bf16(f[2], f[3]); w.z = cvt_pk_bf16(f[4], f[5]); w.w = cvt_pk_bf16(f[6], f[7]); return w; }
;     __device__ __forceinline__ void operator()(const f32x4 (&acc)[2][2][4][2], const Unit& u, int wr, int wc, int fr, int fq) const {
;     ...
;                     for (int m = 0; m < 4; ++m) { const int row = row0 + ai * 128 + m * 16; const int pi = row < MP ? row % TP : TP;
;                         const f32x4* cs = (const f32x4*)(CS + ((size_t)pi * 128 + cw) * 2);
; #pragma unroll
;                         for (int q4 = 0; q4 < 4; ++q4) tt[m][q4] = cs[q4]; }
;     ...
;                     for (int m = 0; m < 4; ++m) {
;                         const int row = row0 + ai * 128 + m * 16;
;                         const float rs = rtab[u.ord * 256 + (row - u.pm * 256)] * sc;
;                         const f32x4 t0 = tt[m][0], t1 = tt[m][1], t2 = tt[m][2], t3 = tt[m][3];
;                         const float c[8] = {t0.x, t0.z, t1.x, t1.z, t2.x, t2.z, t3.x, t3.z}, s[8] = {t0.y, t0.w, t1.y, t1.w, t2.y, t2.w, t3.y, t3.w};
;                         float o1[8], o2[8];
; #pragma unroll
;                         for (int n = 0; n < 2; ++n)
; #pragma unroll
;                             for (int j = 0; j < 4; ++j) {
;                                 const float x1 = acc[ai][0][m][n][j], x2 = acc[ai][1][m][n][j];
;                                 o1[n * 4 + j] = (x1 * c[n * 4 + j] - x2 * s[n * 4 + j]) * rs;
;                                 o2[n * 4 + j] = (x1 * s[n * 4 + j] + x2 * c[n * 4 + j]) * rs;
;                             }
;                         bf16* rp = base + (size_t)row * 2048;
;                         *(v4u*)rp = pack8(o1); *(v4u*)(rp + 128) = pack8(o2);
;                     }
	v_mov_b32_e32 v68, v73
	v_sub_f32_e32 v66, v66, v67
	v_mul_f32_e32 v72, v66, v71
	v_pk_mul_f32 v[66:67], v[68:69], v[132:133]
	v_pk_mul_f32 v[74:75], v[74:75], v[148:149]
	v_pk_mul_f32 v[78:79], v[78:79], v[142:143]
	v_pk_mul_f32 v[88:89], v[88:89], v[142:143]
	v_pk_mul_f32 v[76:77], v[76:77], v[144:145]
	v_pk_mul_f32 v[80:81], v[80:81], v[134:135]
	v_pk_mul_f32 v[92:93], v[92:93], v[134:135]
	v_add_f32_e32 v66, v67, v66
	v_add_f32_e32 v74, v75, v74
	v_sub_f32_e32 v75, v78, v79
	v_add_f32_e32 v78, v89, v88
	v_sub_f32_e32 v79, v90, v91
	v_add_f32_e32 v76, v77, v76
	v_sub_f32_e32 v77, v80, v81
	v_add_f32_e32 v80, v93, v92
	v_sub_f32_e32 v81, v94, v95
	v_mul_f32_e32 v73, v66, v71
	v_lshlrev_b64 v[66:67], 12, v[212:213]
	v_mul_f32_e32 v82, v82, v71
	v_mul_f32_e32 v83, v83, v71
	v_mul_f32_e32 v84, v84, v71
	v_mul_f32_e32 v74, v74, v71
	v_mul_f32_e32 v75, v75, v71
	v_mul_f32_e32 v78, v78, v71
	v_mul_f32_e32 v79, v79, v71
	v_mul_f32_e32 v76, v76, v71
	v_mul_f32_e32 v77, v77, v71
	v_mul_f32_e32 v80, v80, v71
	v_mul_f32_e32 v81, v81, v71
	v_lshl_add_u64 v[70:71], v[218:219], 0, v[66:67]
	v_cvt_pk_bf16_f32 v66, v82, v84
	v_cvt_pk_bf16_f32 v67, v75, v79
	v_cvt_pk_bf16_f32 v68, v77, v81
	v_cvt_pk_bf16_f32 v69, v86, v72
	global_store_dwordx4 v[70:71], v[66:69], off nt
	s_movk_i32 s0, 0x4000
	v_add_u32_e32 v136, 0x80, v210
	v_cvt_pk_bf16_f32 v66, v83, v74
	v_cvt_pk_bf16_f32 v67, v78, v76
	v_cvt_pk_bf16_f32 v68, v80, v85
	v_cvt_pk_bf16_f32 v69, v87, v73
	global_store_dwordx4 v[70:71], v[66:69], off offset:256 nt
	v_cmp_gt_i32_e32 vcc, s0, v210
	s_nop 0
	v_mov_b64_e32 v[66:67], 0x40800
	v_mov_b64_e32 v[68:69], 0x40800
	s_and_saveexec_b64 s[0:1], vcc
	s_mov_b32 s2, 0xfe03f81
	v_mul_hi_i32 v68, v136, s2
	v_lshrrev_b32_e32 v69, 31, v68
	v_ashrrev_i32_e32 v68, 7, v68
	v_add_u32_e32 v68, v68, v69
	v_mul_lo_u32 v68, v68, s16
	v_sub_u32_e32 v68, v136, v68
	v_ashrrev_i32_e32 v69, 31, v68
	v_lshlrev_b64 v[68:69], 7, v[68:69]
	s_or_b64 exec, exec, s[0:1]
	v_readlane_b32 s0, v252, 28
	v_or_b32_e32 v68, v68, v204
	v_readlane_b32 s1, v252, 29
	v_add_u32_e32 v134, 0x90, v210
	s_nop 0
	v_lshl_add_u64 v[68:69], v[68:69], 3, s[0:1]
	global_load_dwordx4 v[110:113], v[68:69], off offset:48
	global_load_dwordx4 v[118:121], v[68:69], off offset:32
	global_load_dwordx4 v[122:125], v[68:69], off offset:16
	global_load_dwordx4 v[126:129], v[68:69], off
	s_movk_i32 s0, 0x3ff0
	v_cmp_gt_i32_e32 vcc, s0, v210
	s_and_saveexec_b64 s[0:1], vcc
	s_mov_b32 s2, 0xfe03f81
	v_mul_hi_i32 v66, v134, s2
	v_lshrrev_b32_e32 v67, 31, v66
	v_ashrrev_i32_e32 v66, 7, v66
	v_add_u32_e32 v66, v66, v67
	v_mul_lo_u32 v66, v66, s16
	v_sub_u32_e32 v66, v134, v66
	v_ashrrev_i32_e32 v67, 31, v66
	v_lshlrev_b64 v[66:67], 7, v[66:67]
	s_or_b64 exec, exec, s[0:1]
	v_readlane_b32 s0, v252, 28
	v_or_b32_e32 v66, v66, v204
	v_readlane_b32 s1, v252, 29
	v_add_u32_e32 v132, 0xa0, v210
	v_mov_b64_e32 v[68:69], 0x40800
	v_lshl_add_u64 v[66:67], v[66:67], 3, s[0:1]
	global_load_dwordx4 v[98:101], v[66:67], off offset:48
	global_load_dwordx4 v[102:105], v[66:67], off offset:32
	global_load_dwordx4 v[106:109], v[66:67], off offset:16
	global_load_dwordx4 v[114:117], v[66:67], off
	s_movk_i32 s0, 0x3fe0
	v_cmp_gt_i32_e32 vcc, s0, v210
	v_mov_b64_e32 v[66:67], 0x40800
	s_and_saveexec_b64 s[0:1], vcc
	s_mov_b32 s2, 0xfe03f81
	v_mul_hi_i32 v68, v132, s2
	v_lshrrev_b32_e32 v69, 31, v68
	v_ashrrev_i32_e32 v68, 7, v68
	v_add_u32_e32 v68, v68, v69
	v_mul_lo_u32 v68, v68, s16
	v_sub_u32_e32 v68, v132, v68
	v_ashrrev_i32_e32 v69, 31, v68
	v_lshlrev_b64 v[68:69], 7, v[68:69]
	s_or_b64 exec, exec, s[0:1]
	v_readlane_b32 s0, v252, 28
	v_or_b32_e32 v68, v68, v204
	v_readlane_b32 s1, v252, 29
	v_add_u32_e32 v130, 0xb0, v210
	s_nop 0
	v_lshl_add_u64 v[68:69], v[68:69], 3, s[0:1]
	global_load_dwordx4 v[78:81], v[68:69], off offset:48
	global_load_dwordx4 v[86:89], v[68:69], off offset:32
	global_load_dwordx4 v[90:93], v[68:69], off offset:16
	global_load_dwordx4 v[94:97], v[68:69], off
	s_movk_i32 s0, 0x3fd0
	v_cmp_gt_i32_e32 vcc, s0, v210
	s_and_saveexec_b64 s[0:1], vcc
	s_mov_b32 s2, 0xfe03f81
	v_mul_hi_i32 v66, v130, s2
	v_lshrrev_b32_e32 v67, 31, v66
	v_ashrrev_i32_e32 v66, 7, v66
	v_add_u32_e32 v66, v66, v67
	v_mul_lo_u32 v66, v66, s16
	v_sub_u32_e32 v66, v130, v66
	v_ashrrev_i32_e32 v67, 31, v66
	v_lshlrev_b64 v[66:67], 7, v[66:67]
	s_or_b64 exec, exec, s[0:1]
	v_readlane_b32 s0, v252, 28
	v_or_b32_e32 v66, v66, v204
	v_readlane_b32 s1, v252, 29
	v_mov_b32_e32 v140, v58
	v_mov_b32_e32 v141, v62
	v_lshl_add_u64 v[82:83], v[66:67], 3, s[0:1]
	global_load_dwordx4 v[66:69], v[82:83], off offset:48
	global_load_dwordx4 v[70:73], v[82:83], off offset:32
	global_load_dwordx4 v[74:77], v[82:83], off offset:16
	s_nop 0
	global_load_dwordx4 v[82:85], v[82:83], off
	ds_read2_b32 v[138:139], v0 offset0:128 offset1:144
	v_mov_b32_e32 v142, v62
	v_mov_b32_e32 v143, v58
	v_mov_b32_e32 v62, v59
	v_mov_b32_e32 v58, v63
	s_waitcnt vmcnt(12)
	v_pk_mul_f32 v[140:141], v[140:141], v[126:127]
	v_pk_mul_f32 v[126:127], v[142:143], v[126:127]
	v_pk_mul_f32 v[142:143], v[62:63], v[128:129]
	v_pk_mul_f32 v[58:59], v[58:59], v[128:129]
	v_mov_b32_e32 v62, v60
	v_mov_b32_e32 v63, v64
	v_mov_b32_e32 v128, v64
	v_mov_b32_e32 v129, v60
	v_mov_b32_e32 v64, v61
	v_mov_b32_e32 v60, v65
	v_pk_mul_f32 v[62:63], v[62:63], v[122:123]
	v_pk_mul_f32 v[122:123], v[128:129], v[122:123]
	v_pk_mul_f32 v[128:129], v[64:65], v[124:125]
	v_pk_mul_f32 v[60:61], v[60:61], v[124:125]
	v_mov_b32_e32 v64, v50
	v_mov_b32_e32 v65, v54
	v_mov_b32_e32 v124, v54
	v_mov_b32_e32 v125, v50
	v_mov_b32_e32 v54, v51
	v_mov_b32_e32 v50, v55
	v_pk_mul_f32 v[64:65], v[64:65], v[118:119]
	v_pk_mul_f32 v[118:119], v[124:125], v[118:119]
	v_pk_mul_f32 v[124:125], v[54:55], v[120:121]
	v_pk_mul_f32 v[50:51], v[50:51], v[120:121]
	v_mov_b32_e32 v220, v52
	v_mov_b32_e32 v54, v110
	s_waitcnt lgkmcnt(0)
; __device__ __forceinline__ v4u pack8(const float (&f)[8]) { v4u w; w.x = cvt_pk_bf16(f[0], f[1]); w.y = cvt_pk_bf16(f[2], f[3]); w.z = cvt_pk_bf16(f[4], f[5]); w.w = cvt_pk_bf16(f[6], f[7]); return w; }
;     __device__ __forceinline__ void operator()(const f32x4 (&acc)[2][2][4][2], const Unit& u, int wr, int wc, int fr, int fq) const {
;     ...
;                     for (int m = 0; m < 4; ++m) {
;                         const int row = row0 + ai * 128 + m * 16;
;                         const float rs = rtab[u.ord * 256 + (row - u.pm * 256)] * sc;
;                         const f32x4 t0 = tt[m][0], t1 = tt[m][1], t2 = tt[m][2], t3 = tt[m][3];
;                         const float c[8] = {t0.x, t0.z, t1.x, t1.z, t2.x, t2.z, t3.x, t3.z}, s[8] = {t0.y, t0.w, t1.y, t1.w, t2.y, t2.w, t3.y, t3.w};
;                         float o1[8], o2[8];
; #pragma unroll
;                         for (int n = 0; n < 2; ++n)
; #pragma unroll
;                             for (int j = 0; j < 4; ++j) {
;                                 const float x1 = acc[ai][0][m][n][j], x2 = acc[ai][1][m][n][j];
;                                 o1[n * 4 + j] = (x1 * c[n * 4 + j] - x2 * s[n * 4 + j]) * rs;
;                                 o2[n * 4 + j] = (x1 * s[n * 4 + j] + x2 * c[n * 4 + j]) * rs;
;                             }
;                         bf16* rp = base + (size_t)row * 2048;
;                         *(v4u*)rp = pack8(o1); *(v4u*)(rp + 128) = pack8(o2);
;                     }
	v_mov_b32_e32 v55, v138
	v_pk_mul_f32 v[54:55], v[220:221], v[54:55]
	v_add_f32_e32 v50, v51, v50
	v_add_f32_e32 v60, v61, v60
	v_sub_f32_e32 v61, v64, v65
	v_add_f32_e32 v64, v119, v118
	v_mul_f32_e32 v118, v50, v55
	v_fma_f32 v50, -v56, v111, v54
	v_mul_f32_e32 v119, v50, v55
	v_mov_b32_e32 v50, v56
	v_mov_b32_e32 v51, v52
	v_pk_mul_f32 v[50:51], v[50:51], v[110:111]
	v_mov_b32_e32 v56, v53
	v_add_f32_e32 v50, v51, v50
	v_mul_f32_e32 v110, v50, v55
	v_pk_mul_f32 v[50:51], v[56:57], v[112:113]
	v_mov_b32_e32 v52, v57
	v_sub_f32_e32 v50, v50, v51
	v_mul_f32_e32 v56, v50, v55
	v_pk_mul_f32 v[50:51], v[52:53], v[112:113]
	v_ashrrev_i32_e32 v137, 31, v136
	v_add_f32_e32 v50, v51, v50
	v_sub_f32_e32 v120, v140, v141
	v_add_f32_e32 v121, v127, v126
	v_sub_f32_e32 v126, v142, v143
	v_add_f32_e32 v58, v59, v58
	v_sub_f32_e32 v59, v62, v63
	v_add_f32_e32 v62, v123, v122
	v_sub_f32_e32 v63, v128, v129
	v_sub_f32_e32 v65, v124, v125
	v_mul_f32_e32 v57, v50, v55
	v_lshlrev_b64 v[50:51], 12, v[136:137]
	v_mul_f32_e32 v120, v120, v55
	v_mul_f32_e32 v121, v121, v55
	v_mul_f32_e32 v126, v126, v55
	v_mul_f32_e32 v58, v58, v55
	v_mul_f32_e32 v59, v59, v55
	v_mul_f32_e32 v62, v62, v55
	v_mul_f32_e32 v63, v63, v55
	v_mul_f32_e32 v60, v60, v55
	v_mul_f32_e32 v61, v61, v55
	v_mul_f32_e32 v64, v64, v55
	v_mul_f32_e32 v65, v65, v55
	v_lshl_add_u64 v[54:55], v[218:219], 0, v[50:51]
	v_cvt_pk_bf16_f32 v51, v59, v63
	v_cvt_pk_bf16_f32 v52, v61, v65
	v_cvt_pk_bf16_f32 v50, v120, v126
	v_cvt_pk_bf16_f32 v53, v119, v56
	global_store_dwordx4 v[54:55], v[50:53], off nt
	v_mov_b32_e32 v56, v48
	v_mov_b32_e32 v61, v34
	v_cvt_pk_bf16_f32 v51, v62, v60
	v_cvt_pk_bf16_f32 v52, v64, v118
	v_cvt_pk_bf16_f32 v50, v121, v58
	v_cvt_pk_bf16_f32 v53, v110, v57
	global_store_dwordx4 v[54:55], v[50:53], off offset:256 nt
	v_mov_b32_e32 v57, v44
	v_mov_b32_e32 v60, v38
	v_mov_b32_e32 v51, v46
	v_mov_b32_e32 v52, v46
	v_mov_b32_e32 v46, v43
	v_mov_b32_e32 v50, v42
	v_mov_b32_e32 v53, v42
	s_waitcnt vmcnt(10)
	v_pk_mul_f32 v[54:55], v[46:47], v[116:117]
	v_mov_b32_e32 v42, v47
	v_mov_b32_e32 v47, v48
	v_mov_b32_e32 v48, v45
	v_pk_mul_f32 v[58:59], v[48:49], v[108:109]
	v_mov_b32_e32 v48, v34
	v_mov_b32_e32 v34, v39
	v_mov_b32_e32 v46, v44
	v_mov_b32_e32 v44, v49
	v_mov_b32_e32 v49, v38
	v_mov_b32_e32 v38, v35
	v_pk_mul_f32 v[34:35], v[34:35], v[104:105]
	v_mov_b32_e32 v220, v36
	v_mov_b32_e32 v138, v98
	v_pk_mul_f32 v[50:51], v[50:51], v[114:115]
	v_pk_mul_f32 v[52:53], v[52:53], v[114:115]
	v_pk_mul_f32 v[62:63], v[38:39], v[104:105]
	v_pk_mul_f32 v[38:39], v[220:221], v[138:139]
	v_add_f32_e32 v34, v35, v34
	v_sub_f32_e32 v50, v50, v51
	v_add_f32_e32 v51, v53, v52
	v_mul_f32_e32 v53, v34, v39
	v_fma_f32 v34, -v40, v99, v38
	v_sub_f32_e32 v52, v54, v55
	v_mul_f32_e32 v54, v34, v39
	v_mov_b32_e32 v34, v40
	v_mov_b32_e32 v35, v36
	v_pk_mul_f32 v[34:35], v[34:35], v[98:99]
	v_mov_b32_e32 v40, v37
	v_add_f32_e32 v34, v35, v34
	v_mul_f32_e32 v55, v34, v39
	v_pk_mul_f32 v[34:35], v[40:41], v[100:101]
	v_mov_b32_e32 v36, v41
	v_sub_f32_e32 v34, v34, v35
	v_mul_f32_e32 v40, v34, v39
	v_pk_mul_f32 v[34:35], v[36:37], v[100:101]
	v_pk_mul_f32 v[42:43], v[42:43], v[116:117]
	v_pk_mul_f32 v[46:47], v[46:47], v[106:107]
	v_pk_mul_f32 v[56:57], v[56:57], v[106:107]
	v_pk_mul_f32 v[44:45], v[44:45], v[108:109]
	v_pk_mul_f32 v[48:49], v[48:49], v[102:103]
	v_pk_mul_f32 v[60:61], v[60:61], v[102:103]
	v_add_f32_e32 v34, v35, v34
	v_ashrrev_i32_e32 v135, 31, v134
	v_add_f32_e32 v42, v43, v42
	v_sub_f32_e32 v43, v46, v47
	v_add_f32_e32 v46, v57, v56
	v_sub_f32_e32 v47, v58, v59
	v_add_f32_e32 v44, v45, v44
	v_sub_f32_e32 v45, v48, v49
	v_add_f32_e32 v48, v61, v60
	v_sub_f32_e32 v49, v62, v63
	v_mul_f32_e32 v41, v34, v39
	v_lshlrev_b64 v[34:35], 12, v[134:135]
	v_mul_f32_e32 v50, v50, v39
	v_mul_f32_e32 v51, v51, v39
	v_mul_f32_e32 v52, v52, v39
	v_mul_f32_e32 v42, v42, v39
	v_mul_f32_e32 v43, v43, v39
	v_mul_f32_e32 v46, v46, v39
	v_mul_f32_e32 v47, v47, v39
	v_mul_f32_e32 v44, v44, v39
	v_mul_f32_e32 v45, v45, v39
	v_mul_f32_e32 v48, v48, v39
	v_mul_f32_e32 v49, v49, v39
	v_lshl_add_u64 v[38:39], v[218:219], 0, v[34:35]
	v_cvt_pk_bf16_f32 v34, v50, v52
	v_cvt_pk_bf16_f32 v35, v43, v47
	v_cvt_pk_bf16_f32 v36, v45, v49
	v_cvt_pk_bf16_f32 v37, v54, v40
	global_store_dwordx4 v[38:39], v[34:37], off nt
	v_mov_b32_e32 v43, v28
	v_mov_b32_e32 v47, v18
	v_cvt_pk_bf16_f32 v34, v51, v42
	v_cvt_pk_bf16_f32 v35, v46, v44
	v_cvt_pk_bf16_f32 v36, v48, v53
	v_cvt_pk_bf16_f32 v37, v55, v41
	global_store_dwordx4 v[38:39], v[34:37], off offset:256 nt
	ds_read2_b32 v[34:35], v0 offset0:160 offset1:176
	v_mov_b32_e32 v38, v30
	v_mov_b32_e32 v37, v30
	v_mov_b32_e32 v30, v27
	v_mov_b32_e32 v36, v26
	v_mov_b32_e32 v39, v26
	s_waitcnt vmcnt(8)
; __device__ __forceinline__ v4u pack8(const float (&f)[8]) { v4u w; w.x = cvt_pk_bf16(f[0], f[1]); w.y = cvt_pk_bf16(f[2], f[3]); w.z = cvt_pk_bf16(f[4], f[5]); w.w = cvt_pk_bf16(f[6], f[7]); return w; }
;     __device__ __forceinline__ void operator()(const f32x4 (&acc)[2][2][4][2], const Unit& u, int wr, int wc, int fr, int fq) const {
;     ...
;                     for (int m = 0; m < 4; ++m) {
;                         const int row = row0 + ai * 128 + m * 16;
;                         const float rs = rtab[u.ord * 256 + (row - u.pm * 256)] * sc;
;                         const f32x4 t0 = tt[m][0], t1 = tt[m][1], t2 = tt[m][2], t3 = tt[m][3];
;                         const float c[8] = {t0.x, t0.z, t1.x, t1.z, t2.x, t2.z, t3.x, t3.z}, s[8] = {t0.y, t0.w, t1.y, t1.w, t2.y, t2.w, t3.y, t3.w};
;                         float o1[8], o2[8];
; #pragma unroll
;                         for (int n = 0; n < 2; ++n)
; #pragma unroll
;                             for (int j = 0; j < 4; ++j) {
;                                 const float x1 = acc[ai][0][m][n][j], x2 = acc[ai][1][m][n][j];
;                                 o1[n * 4 + j] = (x1 * c[n * 4 + j] - x2 * s[n * 4 + j]) * rs;
;                                 o2[n * 4 + j] = (x1 * s[n * 4 + j] + x2 * c[n * 4 + j]) * rs;
;                             }
;                         bf16* rp = base + (size_t)row * 2048;
;                         *(v4u*)rp = pack8(o1); *(v4u*)(rp + 128) = pack8(o2);
;                     }
	v_pk_mul_f32 v[40:41], v[30:31], v[96:97]
	v_mov_b32_e32 v26, v31
	v_mov_b32_e32 v31, v32
	v_mov_b32_e32 v42, v32
	v_mov_b32_e32 v32, v29
	v_mov_b32_e32 v30, v28
	v_pk_mul_f32 v[44:45], v[32:33], v[92:93]
	v_mov_b32_e32 v28, v33
	v_mov_b32_e32 v32, v18
	v_mov_b32_e32 v33, v22
	v_mov_b32_e32 v46, v22
	v_mov_b32_e32 v22, v19
	v_mov_b32_e32 v18, v23
	v_pk_mul_f32 v[48:49], v[22:23], v[88:89]
	v_pk_mul_f32 v[18:19], v[18:19], v[88:89]
	v_mov_b32_e32 v220, v20
	v_mov_b32_e32 v22, v78
	s_waitcnt lgkmcnt(0)
	v_mov_b32_e32 v23, v34
	v_pk_mul_f32 v[36:37], v[36:37], v[94:95]
	v_pk_mul_f32 v[22:23], v[220:221], v[22:23]
	v_add_f32_e32 v18, v19, v18
	v_pk_mul_f32 v[38:39], v[38:39], v[94:95]
	v_sub_f32_e32 v0, v36, v37
	v_mul_f32_e32 v37, v18, v23
	v_fma_f32 v18, -v24, v79, v22
	v_add_f32_e32 v34, v39, v38
	v_mul_f32_e32 v38, v18, v23
	v_mov_b32_e32 v18, v24
	v_mov_b32_e32 v19, v20
	v_pk_mul_f32 v[18:19], v[18:19], v[78:79]
	v_mov_b32_e32 v24, v21
	v_add_f32_e32 v18, v19, v18
	v_mul_f32_e32 v39, v18, v23
	v_pk_mul_f32 v[18:19], v[24:25], v[80:81]
	v_mov_b32_e32 v20, v25
	v_sub_f32_e32 v18, v18, v19
	v_mul_f32_e32 v24, v18, v23
	v_pk_mul_f32 v[18:19], v[20:21], v[80:81]
	v_pk_mul_f32 v[26:27], v[26:27], v[96:97]
	v_pk_mul_f32 v[30:31], v[30:31], v[90:91]
	v_pk_mul_f32 v[42:43], v[42:43], v[90:91]
	v_pk_mul_f32 v[28:29], v[28:29], v[92:93]
	v_pk_mul_f32 v[32:33], v[32:33], v[86:87]
	v_pk_mul_f32 v[46:47], v[46:47], v[86:87]
	v_add_f32_e32 v18, v19, v18
	v_ashrrev_i32_e32 v133, 31, v132
	v_sub_f32_e32 v36, v40, v41
	v_add_f32_e32 v26, v27, v26
	v_sub_f32_e32 v27, v30, v31
	v_add_f32_e32 v30, v43, v42
	v_sub_f32_e32 v31, v44, v45
	v_add_f32_e32 v28, v29, v28
	v_sub_f32_e32 v29, v32, v33
	v_add_f32_e32 v32, v47, v46
	v_sub_f32_e32 v33, v48, v49
	v_mul_f32_e32 v25, v18, v23
	v_lshlrev_b64 v[18:19], 12, v[132:133]
	v_mul_f32_e32 v0, v0, v23
	v_mul_f32_e32 v34, v34, v23
	v_mul_f32_e32 v36, v36, v23
	v_mul_f32_e32 v26, v26, v23
	v_mul_f32_e32 v27, v27, v23
	v_mul_f32_e32 v30, v30, v23
	v_mul_f32_e32 v31, v31, v23
	v_mul_f32_e32 v28, v28, v23
	v_mul_f32_e32 v29, v29, v23
	v_mul_f32_e32 v32, v32, v23
	v_mul_f32_e32 v33, v33, v23
	v_lshl_add_u64 v[22:23], v[218:219], 0, v[18:19]
	v_cvt_pk_bf16_f32 v19, v27, v31
	v_cvt_pk_bf16_f32 v20, v29, v33
	v_cvt_pk_bf16_f32 v18, v0, v36
	v_cvt_pk_bf16_f32 v21, v38, v24
	global_store_dwordx4 v[22:23], v[18:21], off nt
	v_mov_b32_e32 v24, v16
	v_mov_b32_e32 v29, v6
	v_cvt_pk_bf16_f32 v19, v30, v28
	v_cvt_pk_bf16_f32 v20, v32, v37
	v_cvt_pk_bf16_f32 v18, v34, v26
	v_cvt_pk_bf16_f32 v21, v39, v25
	global_store_dwordx4 v[22:23], v[18:21], off offset:256 nt
	v_mov_b32_e32 v25, v12
	v_mov_b32_e32 v28, v2
	v_mov_b32_e32 v19, v14
	v_mov_b32_e32 v20, v14
	v_mov_b32_e32 v14, v11
	v_mov_b32_e32 v18, v10
	v_mov_b32_e32 v21, v10
	s_waitcnt vmcnt(6)
	v_pk_mul_f32 v[22:23], v[14:15], v[84:85]
	v_mov_b32_e32 v10, v15
	v_mov_b32_e32 v15, v16
	v_mov_b32_e32 v16, v13
	v_mov_b32_e32 v14, v12
	v_pk_mul_f32 v[26:27], v[16:17], v[76:77]
	v_mov_b32_e32 v12, v17
	v_mov_b32_e32 v16, v6
	v_mov_b32_e32 v17, v2
	v_mov_b32_e32 v2, v7
	v_mov_b32_e32 v6, v3
	v_pk_mul_f32 v[30:31], v[2:3], v[72:73]
	v_pk_mul_f32 v[2:3], v[6:7], v[72:73]
	v_mov_b32_e32 v220, v8
	v_mov_b32_e32 v34, v66
	v_pk_mul_f32 v[18:19], v[18:19], v[82:83]
	v_pk_mul_f32 v[20:21], v[20:21], v[82:83]
	v_pk_mul_f32 v[6:7], v[220:221], v[34:35]
	v_add_f32_e32 v2, v3, v2
	v_sub_f32_e32 v0, v18, v19
	v_add_f32_e32 v18, v21, v20
	v_mul_f32_e32 v20, v2, v7
	v_fma_f32 v2, -v4, v67, v6
	v_mul_f32_e32 v21, v2, v7
	v_mov_b32_e32 v2, v4
	v_mov_b32_e32 v3, v8
	v_pk_mul_f32 v[2:3], v[2:3], v[66:67]
	v_mov_b32_e32 v4, v9
	v_add_f32_e32 v2, v3, v2
	v_sub_f32_e32 v19, v22, v23
	v_mul_f32_e32 v22, v2, v7
	v_pk_mul_f32 v[2:3], v[4:5], v[68:69]
	v_mov_b32_e32 v8, v5
	v_sub_f32_e32 v2, v2, v3
	v_mul_f32_e32 v23, v2, v7
	v_pk_mul_f32 v[2:3], v[8:9], v[68:69]
	v_pk_mul_f32 v[10:11], v[10:11], v[84:85]
	v_pk_mul_f32 v[14:15], v[14:15], v[74:75]
	v_pk_mul_f32 v[24:25], v[24:25], v[74:75]
	v_pk_mul_f32 v[12:13], v[12:13], v[76:77]
	v_pk_mul_f32 v[16:17], v[16:17], v[70:71]
	v_pk_mul_f32 v[28:29], v[28:29], v[70:71]
	v_add_f32_e32 v2, v3, v2
	v_ashrrev_i32_e32 v131, 31, v130
	v_add_f32_e32 v10, v11, v10
	v_sub_f32_e32 v11, v14, v15
	v_add_f32_e32 v14, v25, v24
	v_sub_f32_e32 v15, v26, v27
	v_add_f32_e32 v12, v13, v12
	v_sub_f32_e32 v13, v16, v17
	v_add_f32_e32 v16, v29, v28
	v_sub_f32_e32 v17, v30, v31
	v_mul_f32_e32 v8, v2, v7
	v_lshlrev_b64 v[2:3], 12, v[130:131]
	v_mul_f32_e32 v0, v0, v7
	v_mul_f32_e32 v18, v18, v7
	v_mul_f32_e32 v19, v19, v7
	v_mul_f32_e32 v10, v10, v7
	v_mul_f32_e32 v11, v11, v7
	v_mul_f32_e32 v14, v14, v7
	v_mul_f32_e32 v15, v15, v7
	v_mul_f32_e32 v12, v12, v7
	v_mul_f32_e32 v13, v13, v7
	v_mul_f32_e32 v16, v16, v7
	v_mul_f32_e32 v17, v17, v7
	v_lshl_add_u64 v[6:7], v[218:219], 0, v[2:3]
	v_cvt_pk_bf16_f32 v2, v0, v19
	v_cvt_pk_bf16_f32 v3, v11, v15
	v_cvt_pk_bf16_f32 v4, v13, v17
	v_cvt_pk_bf16_f32 v5, v21, v23
	global_store_dwordx4 v[6:7], v[2:5], off nt
	s_nop 1
	v_cvt_pk_bf16_f32 v2, v18, v10
	v_cvt_pk_bf16_f32 v3, v14, v12
	v_cvt_pk_bf16_f32 v4, v16, v20
	v_cvt_pk_bf16_f32 v5, v22, v8
	global_store_dwordx4 v[6:7], v[2:5], off offset:256 nt

;     __device__ __forceinline__ void operator()(const f32x4 (&acc)[2][2][4][2], const Unit& u, int wr, int wc, int fr, int fq) const {
;     ...
;             const int R0 = 254 * u.pm - 2, bq = (R0 + 2) / TP, tq = (R0 + 2) - bq * TP;
;             const bool plain = (R0 + 255 < MP) && tq >= 2 && tq + 253 < TP - 2;
;             if (plain) {
;     ...
;             for (int n = 0; n < 2; ++n) {
;                 const int f0 = u.pn * 128 + fl + 4 * n;
;                 const f32x4 w0 = *(const f32x4*)(cw + f0), w1 = *(const f32x4*)(cw + DFF + f0), w2 = *(const f32x4*)(cw + 2 * DFF + f0), bb = *(const f32x4*)(cb + f0);
;                 f32x4 prev = (f32x4){0.f, 0.f, 0.f, 0.f};
; #pragma unroll
;                 for (int ai = 0; ai < 2; ++ai)
; #pragma unroll
;                     for (int m = 0; m < 4; ++m) {
;                         const int l = 128 * ai + 64 * wr + 16 * m + frL, row = 254 * u.pm - 2 + l;
;                         const float rs = rt[l];
;                         const f32x4 cur = acc[ai][1][m][n] * rs, uu = acc[ai][0][m][n] * rs;
;                         if (m == 0) {
;                             const int B = 2 * ai + wr;
;                             prev = (f32x4){0.f, 0.f, 0.f, 0.f};
;                             if (B > 0 && frL >= 14) prev = *(const LAS f32x4*)(halo + ((B - 1) * 2 + (frL - 14)) * 128 + fl + 4 * n);
;                         }
;                         f32x4 g1, g2;
;                         {
;                             const float c1x = dpp_ror1(cur.x), c1y = dpp_ror1(cur.y), c1z = dpp_ror1(cur.z), c1w = dpp_ror1(cur.w);
;                             const float p1x = dpp_ror1(prev.x), p1y = dpp_ror1(prev.y), p1z = dpp_ror1(prev.z), p1w = dpp_ror1(prev.w);
;                             const float c2x = dpp_ror2(cur.x), c2y = dpp_ror2(cur.y), c2z = dpp_ror2(cur.z), c2w = dpp_ror2(cur.w);
;                             const float p2x = dpp_ror2(prev.x), p2y = dpp_ror2(prev.y), p2z = dpp_ror2(prev.z), p2w = dpp_ror2(prev.w);
;                             const bool s1 = frL >= 1, s2 = frL >= 2;
;                             g1.x = s1 ? c1x : p1x; g1.y = s1 ? c1y : p1y; g1.z = s1 ? c1z : p1z; g1.w = s1 ? c1w : p1w;
;                             g2.x = s2 ? c2x : p2x; g2.y = s2 ? c2y : p2y; g2.z = s2 ? c2z : p2z; g2.w = s2 ? c2w : p2w;
;                         }
;                         if (l >= 2 && row < M) {
.LBB0_1185:
	s_or_b64 exec, exec, s[0:1]
	s_mul_i32 s21, s10, 0xfe
	s_mul_hi_i32 s0, s21, 0xfe03f81
	s_lshr_b32 s1, s0, 31
	s_ashr_i32 s0, s0, 7
	s_add_i32 s0, s0, s1
	s_mulk_i32 s0, 0x810
	s_sub_i32 s7, s21, s0
	s_cmpk_lt_i32 s21, 0x3f83
	s_cselect_b64 s[0:1], -1, 0
	s_cmp_gt_i32 s7, 1
	s_cselect_b64 s[8:9], -1, 0
	s_and_b64 s[0:1], s[0:1], s[8:9]
	s_cmpk_lt_u32 s7, 0x711
	s_waitcnt lgkmcnt(0)
	s_barrier
	s_cselect_b64 s[8:9], -1, 0
	s_and_b64 s[8:9], s[0:1], s[8:9]
	v_add_u32_e32 v211, s19, v212
	s_mov_b64 s[0:1], -1
	s_andn2_b64 vcc, exec, s[8:9]
	v_cmp_gt_i32_e64 s[10:11], 14, v212
	v_lshl_add_u32 v184, s52, 7, v0
	v_lshl_add_u32 v209, v211, 2, s6
	s_cbranch_vccz .LBB0_1388
	v_ashrrev_i32_e32 v185, 31, v184
	v_lshlrev_b64 v[2:3], 2, v[184:185]
	v_lshl_add_u64 v[198:199], s[34:35], 0, v[2:3]
	v_lshl_add_u64 v[132:133], s[44:45], 0, v[2:3]
	v_lshl_add_u64 v[134:135], s[46:47], 0, v[2:3]
	v_lshl_add_u64 v[200:201], s[36:37], 0, v[2:3]
	global_load_dwordx4 v[140:143], v[198:199], off
	global_load_dwordx4 v[136:139], v[132:133], off
	s_nop 0
	global_load_dwordx4 v[132:135], v[134:135], off
	ds_read_b32 v166, v209
	global_load_dwordx4 v[144:147], v[200:201], off
	v_lshl_add_u32 v190, v212, 9, s82
	s_movk_i32 s0, 0xe000
	v_add3_u32 v220, v190, v210, s0
	s_nor_b64 s[52:53], s[28:29], s[10:11]
	v_mov_b32_e32 v152, 0
	v_mov_b32_e32 v153, 0
	v_mov_b32_e32 v154, 0
	v_mov_b32_e32 v155, 0
	s_and_saveexec_b64 s[0:1], s[52:53]
	ds_read_b128 v[152:155], v220
	s_or_b64 exec, exec, s[0:1]
	v_readlane_b32 s0, v252, 8
	v_readlane_b32 s1, v252, 9
	s_waitcnt lgkmcnt(0)
	v_mov_b32_e32 v167, v166
	v_lshl_add_u64 v[164:165], s[38:39], 0, v[2:3]
	v_lshl_add_u64 v[202:203], v[184:185], 1, s[0:1]
	v_add3_u32 v185, s21, -2, v211
	s_movk_i32 s0, 0x4100
	v_lshl_add_u64 v[162:163], s[42:43], 0, v[2:3]
	v_lshl_add_u64 v[160:161], s[40:41], 0, v[2:3]
	v_pk_mul_f32 v[150:151], v[130:131], v[166:167] op_sel_hi:[1,0]
	v_pk_mul_f32 v[148:149], v[128:129], v[166:167] op_sel_hi:[1,0]
	v_mov_b32_e32 v0, v1
	v_mov_b32_e32 v2, v1
	v_mov_b32_e32 v3, v1
	v_mov_b32_e32 v168, v1
	v_mov_b32_e32 v169, v1
	v_mov_b32_e32 v170, v1
	v_mov_b32_e32 v171, v1
	v_mov_b32_e32 v187, v1
	v_mov_b32_e32 v186, v1
	v_mov_b32_e32 v188, v1
	v_mov_b32_e32 v189, v1
	v_mov_b32_e32 v191, v1
	v_mov_b32_e32 v192, v1
	v_mov_b32_e32 v193, v1
	v_mov_b32_e32 v196, v1
	v_mov_b32_e32 v197, v1
	v_cmp_lt_i32_e32 vcc, 1, v211
	v_cmp_gt_i32_e64 s[0:1], s0, v185
	v_cmp_lt_i32_e64 s[8:9], 0, v212
	v_cmp_lt_i32_e64 s[6:7], 1, v212
	v_mov_b32_dpp v0, v148 row_ror:1 row_mask:0xf bank_mask:0xf
	v_mov_b32_dpp v2, v149 row_ror:1 row_mask:0xf bank_mask:0xf
	v_mov_b32_dpp v3, v150 row_ror:1 row_mask:0xf bank_mask:0xf
	v_mov_b32_dpp v168, v151 row_ror:1 row_mask:0xf bank_mask:0xf
	v_mov_b32_dpp v169, v152 row_ror:1 row_mask:0xf bank_mask:0xf
	v_mov_b32_dpp v170, v153 row_ror:1 row_mask:0xf bank_mask:0xf
	v_mov_b32_dpp v171, v154 row_ror:1 row_mask:0xf bank_mask:0xf
	v_mov_b32_dpp v187, v155 row_ror:1 row_mask:0xf bank_mask:0xf
	v_mov_b32_dpp v186, v148 row_ror:2 row_mask:0xf bank_mask:0xf
	v_mov_b32_dpp v188, v149 row_ror:2 row_mask:0xf bank_mask:0xf
	v_mov_b32_dpp v189, v150 row_ror:2 row_mask:0xf bank_mask:0xf
	v_mov_b32_dpp v191, v151 row_ror:2 row_mask:0xf bank_mask:0xf
	v_mov_b32_dpp v192, v152 row_ror:2 row_mask:0xf bank_mask:0xf
	v_mov_b32_dpp v193, v153 row_ror:2 row_mask:0xf bank_mask:0xf
	v_mov_b32_dpp v196, v154 row_ror:2 row_mask:0xf bank_mask:0xf
	v_mov_b32_dpp v197, v155 row_ror:2 row_mask:0xf bank_mask:0xf
	s_and_b64 s[54:55], vcc, s[0:1]
	s_and_saveexec_b64 s[0:1], s[54:55]
	s_cbranch_execz .LBB0_1200
	s_movk_i32 s14, 0x407f
	v_cmp_lt_i32_e32 vcc, s14, v185
	s_and_saveexec_b64 s[56:57], vcc
	s_xor_b64 s[56:57], exec, s[56:57]
	s_cbranch_execz .LBB0_1191
	v_add_u32_e32 v0, 0xffffbf80, v185
	s_movk_i32 s14, 0x5800
	v_mad_u64_u32 v[2:3], s[58:59], v0, s14, v[164:165]
	v_add_co_u32_e32 v152, vcc, 0x2000, v2
	s_nop 1
	v_addc_co_u32_e32 v153, vcc, 0, v3, vcc
	global_load_dwordx4 v[152:155], v[152:153], off offset:3072
	s_nop 0
	global_load_dwordx4 v[156:159], v[2:3], off
	v_mad_u64_u32 v[2:3], s[58:59], v0, s14, v[162:163]
	v_add_co_u32_e32 v168, vcc, 0x2000, v2
	s_nop 1
	v_addc_co_u32_e32 v169, vcc, 0, v3, vcc
	s_waitcnt vmcnt(0)
	global_store_dwordx4 v[2:3], v[152:155], off nt
	global_store_dwordx4 v[168:169], v[148:151], off offset:3072 nt

;     __device__ __forceinline__ void operator()(const f32x4 (&acc)[2][2][4][2], const Unit& u, int wr, int wc, int fr, int fq) const {
;     ...
;                         if (l >= 2 && row < M) {
;                             if (row < MP) {
;                                 const int b = row / TP, t = row - b * TP;
;                                 if (t < 2) { g2 = (f32x4){0.f, 0.f, 0.f, 0.f}; if (t == 0) g1 = g2; }
;                                 if (t >= TP - 2) *(f32x4*)(cvp + ((size_t)b * 2 + (t - (TP - 2))) * DFF + f0) = cur;
.LBB0_1196:
	s_or_b64 exec, exec, s[58:59]
	s_movk_i32 s14, 0x80d
	v_cmp_lt_i32_e32 vcc, s14, v170
	s_and_saveexec_b64 s[58:59], vcc
	s_cbranch_execz .LBB0_1198
	v_ashrrev_i32_e32 v169, 31, v168
	v_add_u32_e32 v0, 0xfffff7f2, v170
	v_lshl_add_u64 v[2:3], v[168:169], 1, v[0:1]
	s_movk_i32 s14, 0x2c00
	v_mad_u64_u32 v[168:169], s[60:61], v2, s14, v[160:161]
	v_mad_i32_i24 v169, v3, s14, v169
	global_store_dwordx4 v[168:169], v[148:151], off nt

; #define LAS __attribute__((address_space(3)))
;     __device__ __forceinline__ void operator()(const f32x4 (&acc)[2][2][4][2], const Unit& u, int wr, int wc, int fr, int fq) const {
;     ...
;                         const int l = 128 * ai + 64 * wr + 16 * m + frL, row = 254 * u.pm - 2 + l;
;                         const float rs = rt[l];
;                         const f32x4 cur = acc[ai][1][m][n] * rs, uu = acc[ai][0][m][n] * rs;
;                         if (m == 0) {
;                             const int B = 2 * ai + wr;
;                             prev = (f32x4){0.f, 0.f, 0.f, 0.f};
;                             if (B > 0 && frL >= 14) prev = *(const LAS f32x4*)(halo + ((B - 1) * 2 + (frL - 14)) * 128 + fl + 4 * n);
;                         }
;                         f32x4 g1, g2;
;                         {
;                             const float c1x = dpp_ror1(cur.x), c1y = dpp_ror1(cur.y), c1z = dpp_ror1(cur.z), c1w = dpp_ror1(cur.w);
;                             const float p1x = dpp_ror1(prev.x), p1y = dpp_ror1(prev.y), p1z = dpp_ror1(prev.z), p1w = dpp_ror1(prev.w);
;                             const float c2x = dpp_ror2(cur.x), c2y = dpp_ror2(cur.y), c2z = dpp_ror2(cur.z), c2w = dpp_ror2(cur.w);
;                             const float p2x = dpp_ror2(prev.x), p2y = dpp_ror2(prev.y), p2z = dpp_ror2(prev.z), p2w = dpp_ror2(prev.w);
;                             const bool s1 = frL >= 1, s2 = frL >= 2;
;                             g1.x = s1 ? c1x : p1x; g1.y = s1 ? c1y : p1y; g1.z = s1 ? c1z : p1z; g1.w = s1 ? c1w : p1w;
;                             g2.x = s2 ? c2x : p2x; g2.y = s2 ? c2y : p2y; g2.z = s2 ? c2z : p2z; g2.w = s2 ? c2w : p2w;
;                         }
;                         if (l >= 2 && row < M) {
;                             if (row < MP) {
;                                 const int b = row / TP, t = row - b * TP;
;                                 if (t < 2) { g2 = (f32x4){0.f, 0.f, 0.f, 0.f}; if (t == 0) g1 = g2; }
;                                 if (t >= TP - 2) *(f32x4*)(cvp + ((size_t)b * 2 + (t - (TP - 2))) * DFF + f0) = cur;
;                             } else {
;                                 const int s = row - MP;
;                                 const float* c0 = cst + ((size_t)s * 2 + 0) * DFF + f0;
;                                 g2 = *(const f32x4*)c0; g1 = *(const f32x4*)(c0 + DFF);
.LBB0_1199:
	s_or_b64 exec, exec, s[56:57]
	s_waitcnt vmcnt(0)
	v_pk_fma_f32 v[156:157], v[140:141], v[156:157], v[144:145]
	v_pk_fma_f32 v[158:159], v[142:143], v[158:159], v[146:147]
	v_pk_fma_f32 v[152:153], v[136:137], v[152:153], v[156:157]
	v_pk_fma_f32 v[154:155], v[138:139], v[154:155], v[158:159]
	v_pk_fma_f32 v[152:153], v[132:133], v[148:149], v[152:153]
	v_pk_fma_f32 v[154:155], v[134:135], v[150:151], v[154:155]
	v_mul_f32_e32 v0, 0xbfb8aa3b, v152
	v_mul_f32_e32 v156, 0xbfb8aa3b, v153
	v_exp_f32_e32 v0, v0
	v_exp_f32_e32 v156, v156
	v_pk_mul_f32 v[168:169], v[124:125], v[166:167]
	v_mov_b32_e32 v2, v166
	v_add_f32_e32 v0, 1.0, v0
	v_add_f32_e32 v156, 1.0, v156
	v_rcp_f32_e32 v0, v0
	v_rcp_f32_e32 v156, v156
	v_mov_b32_e32 v3, v166
	v_pk_mul_f32 v[2:3], v[126:127], v[2:3]
	v_mul_f32_e32 v0, v152, v0
	v_mul_f32_e32 v152, v153, v156
	v_mul_f32_e32 v153, 0xbfb8aa3b, v154
	v_exp_f32_e32 v153, v153
	v_mul_f32_e32 v156, 0xbfb8aa3b, v155
	v_exp_f32_e32 v156, v156
	v_mul_f32_e32 v0, v168, v0
	v_add_f32_e32 v153, 1.0, v153
	v_rcp_f32_e32 v153, v153
	v_add_f32_e32 v156, 1.0, v156
	v_rcp_f32_e32 v156, v156
	v_mul_f32_e32 v152, v169, v152
	v_cvt_pk_bf16_f32 v152, v0, v152
	v_mul_f32_e32 v0, v154, v153
	v_mul_f32_e32 v0, v2, v0
	v_mul_f32_e32 v2, v155, v156
	v_mul_f32_e32 v2, v3, v2
	s_movk_i32 s14, 0x1600
	v_cvt_pk_bf16_f32 v153, v0, v2
	v_mad_i64_i32 v[2:3], s[56:57], v185, s14, v[202:203]
	global_store_dwordx2 v[2:3], v[152:153], off nt
.LBB0_1200:
	s_or_b64 exec, exec, s[0:1]
	ds_read_b32 v168, v209 offset:64
	v_add_u32_e32 v156, 16, v211
	v_add3_u32 v213, s21, 14, v211
	s_movk_i32 s0, 0x4100
	v_mov_b32_e32 v0, v1
	s_waitcnt lgkmcnt(0)
	v_mov_b32_e32 v169, v168
	v_pk_mul_f32 v[154:155], v[114:115], v[168:169] op_sel_hi:[1,0]
	v_pk_mul_f32 v[152:153], v[112:113], v[168:169] op_sel_hi:[1,0]
	v_mov_b32_e32 v2, v1
	v_mov_b32_e32 v3, v1
	v_mov_b32_e32 v170, v1
	v_mov_b32_e32 v171, v1
	v_mov_b32_e32 v186, v1
	v_mov_b32_e32 v187, v1
	v_mov_b32_e32 v189, v1
	v_mov_b32_e32 v188, v1
	v_mov_b32_e32 v191, v1
	v_mov_b32_e32 v192, v1
	v_mov_b32_e32 v193, v1
	v_mov_b32_e32 v196, v1
	v_mov_b32_e32 v197, v1
	v_mov_b32_e32 v204, v1
	v_mov_b32_e32 v205, v1
	v_cmp_lt_i32_e32 vcc, 1, v156
	v_cmp_gt_i32_e64 s[0:1], s0, v213
	v_mov_b32_dpp v0, v152 row_ror:1 row_mask:0xf bank_mask:0xf
	v_mov_b32_dpp v2, v153 row_ror:1 row_mask:0xf bank_mask:0xf
	v_mov_b32_dpp v3, v154 row_ror:1 row_mask:0xf bank_mask:0xf
	v_mov_b32_dpp v170, v155 row_ror:1 row_mask:0xf bank_mask:0xf
	v_mov_b32_dpp v171, v148 row_ror:1 row_mask:0xf bank_mask:0xf
	v_mov_b32_dpp v186, v149 row_ror:1 row_mask:0xf bank_mask:0xf
	v_mov_b32_dpp v187, v150 row_ror:1 row_mask:0xf bank_mask:0xf
	v_mov_b32_dpp v189, v151 row_ror:1 row_mask:0xf bank_mask:0xf
	v_mov_b32_dpp v188, v152 row_ror:2 row_mask:0xf bank_mask:0xf
	v_mov_b32_dpp v191, v153 row_ror:2 row_mask:0xf bank_mask:0xf
	v_mov_b32_dpp v192, v154 row_ror:2 row_mask:0xf bank_mask:0xf
	v_mov_b32_dpp v193, v155 row_ror:2 row_mask:0xf bank_mask:0xf
	v_mov_b32_dpp v196, v148 row_ror:2 row_mask:0xf bank_mask:0xf
	v_mov_b32_dpp v197, v149 row_ror:2 row_mask:0xf bank_mask:0xf
	v_mov_b32_dpp v204, v150 row_ror:2 row_mask:0xf bank_mask:0xf
	v_mov_b32_dpp v205, v151 row_ror:2 row_mask:0xf bank_mask:0xf
	s_and_b64 s[56:57], vcc, s[0:1]
	s_and_saveexec_b64 s[0:1], s[56:57]
	s_cbranch_execz .LBB0_1212
	s_movk_i32 s14, 0x407f
	v_cmp_lt_i32_e32 vcc, s14, v213
	s_and_saveexec_b64 s[58:59], vcc
	s_xor_b64 s[58:59], exec, s[58:59]
	s_cbranch_execz .LBB0_1203
	v_add_u32_e32 v0, 0xffffbf80, v213
	s_movk_i32 s14, 0x5800
	v_mad_u64_u32 v[2:3], s[60:61], v0, s14, v[164:165]
	v_add_co_u32_e32 v148, vcc, 0x2000, v2
	s_nop 1
	v_addc_co_u32_e32 v149, vcc, 0, v3, vcc
	global_load_dwordx4 v[148:151], v[148:149], off offset:3072
	s_nop 0
	global_load_dwordx4 v[156:159], v[2:3], off
	v_mad_u64_u32 v[2:3], s[60:61], v0, s14, v[162:163]
	v_add_co_u32_e32 v170, vcc, 0x2000, v2
	s_nop 1
	v_addc_co_u32_e32 v171, vcc, 0, v3, vcc
	s_waitcnt vmcnt(0)
	global_store_dwordx4 v[2:3], v[148:151], off nt
	global_store_dwordx4 v[170:171], v[152:155], off offset:3072 nt

;     __device__ __forceinline__ void operator()(const f32x4 (&acc)[2][2][4][2], const Unit& u, int wr, int wc, int fr, int fq) const {
;     ...
;                         if (l >= 2 && row < M) {
;                             if (row < MP) {
;                                 const int b = row / TP, t = row - b * TP;
;                                 if (t < 2) { g2 = (f32x4){0.f, 0.f, 0.f, 0.f}; if (t == 0) g1 = g2; }
;                                 if (t >= TP - 2) *(f32x4*)(cvp + ((size_t)b * 2 + (t - (TP - 2))) * DFF + f0) = cur;
.LBB0_1208:
	s_or_b64 exec, exec, s[60:61]
	s_movk_i32 s14, 0x80d
	v_cmp_lt_i32_e32 vcc, s14, v186
	s_and_saveexec_b64 s[60:61], vcc
	s_cbranch_execz .LBB0_1210
	v_ashrrev_i32_e32 v171, 31, v170
	v_add_u32_e32 v0, 0xfffff7f2, v186
	v_lshl_add_u64 v[2:3], v[170:171], 1, v[0:1]
	s_movk_i32 s14, 0x2c00
	v_mad_u64_u32 v[170:171], s[62:63], v2, s14, v[160:161]
	v_mad_i32_i24 v171, v3, s14, v171
	global_store_dwordx4 v[170:171], v[152:155], off nt

; #define LAS __attribute__((address_space(3)))
;     __device__ __forceinline__ void operator()(const f32x4 (&acc)[2][2][4][2], const Unit& u, int wr, int wc, int fr, int fq) const {
;     ...
;                         const int l = 128 * ai + 64 * wr + 16 * m + frL, row = 254 * u.pm - 2 + l;
;                         const float rs = rt[l];
;                         const f32x4 cur = acc[ai][1][m][n] * rs, uu = acc[ai][0][m][n] * rs;
;                         if (m == 0) {
;                             const int B = 2 * ai + wr;
;                             prev = (f32x4){0.f, 0.f, 0.f, 0.f};
;                             if (B > 0 && frL >= 14) prev = *(const LAS f32x4*)(halo + ((B - 1) * 2 + (frL - 14)) * 128 + fl + 4 * n);
;                         }
;                         f32x4 g1, g2;
;                         {
;                             const float c1x = dpp_ror1(cur.x), c1y = dpp_ror1(cur.y), c1z = dpp_ror1(cur.z), c1w = dpp_ror1(cur.w);
;                             const float p1x = dpp_ror1(prev.x), p1y = dpp_ror1(prev.y), p1z = dpp_ror1(prev.z), p1w = dpp_ror1(prev.w);
;                             const float c2x = dpp_ror2(cur.x), c2y = dpp_ror2(cur.y), c2z = dpp_ror2(cur.z), c2w = dpp_ror2(cur.w);
;                             const float p2x = dpp_ror2(prev.x), p2y = dpp_ror2(prev.y), p2z = dpp_ror2(prev.z), p2w = dpp_ror2(prev.w);
;                             const bool s1 = frL >= 1, s2 = frL >= 2;
;                             g1.x = s1 ? c1x : p1x; g1.y = s1 ? c1y : p1y; g1.z = s1 ? c1z : p1z; g1.w = s1 ? c1w : p1w;
;                             g2.x = s2 ? c2x : p2x; g2.y = s2 ? c2y : p2y; g2.z = s2 ? c2z : p2z; g2.w = s2 ? c2w : p2w;
;                         }
;                         if (l >= 2 && row < M) {
;                             if (row < MP) {
;                                 const int b = row / TP, t = row - b * TP;
;                                 if (t < 2) { g2 = (f32x4){0.f, 0.f, 0.f, 0.f}; if (t == 0) g1 = g2; }
;                                 if (t >= TP - 2) *(f32x4*)(cvp + ((size_t)b * 2 + (t - (TP - 2))) * DFF + f0) = cur;
;                             } else {
;                                 const int s = row - MP;
;                                 const float* c0 = cst + ((size_t)s * 2 + 0) * DFF + f0;
;                                 g2 = *(const f32x4*)c0; g1 = *(const f32x4*)(c0 + DFF);
.LBB0_1211:
	s_or_b64 exec, exec, s[58:59]
	s_waitcnt vmcnt(0)
	v_pk_fma_f32 v[156:157], v[140:141], v[156:157], v[144:145]
	v_pk_fma_f32 v[158:159], v[142:143], v[158:159], v[146:147]
	v_pk_fma_f32 v[148:149], v[136:137], v[148:149], v[156:157]
	v_pk_fma_f32 v[150:151], v[138:139], v[150:151], v[158:159]
	v_pk_fma_f32 v[148:149], v[132:133], v[152:153], v[148:149]
	v_pk_fma_f32 v[150:151], v[134:135], v[154:155], v[150:151]
	v_mul_f32_e32 v0, 0xbfb8aa3b, v148
	v_mul_f32_e32 v156, 0xbfb8aa3b, v149
	v_exp_f32_e32 v0, v0
	v_exp_f32_e32 v156, v156
	v_pk_mul_f32 v[170:171], v[108:109], v[168:169]
	v_mov_b32_e32 v2, v168
	v_add_f32_e32 v0, 1.0, v0
	v_add_f32_e32 v156, 1.0, v156
	v_rcp_f32_e32 v0, v0
	v_rcp_f32_e32 v156, v156
	v_mov_b32_e32 v3, v168
	v_pk_mul_f32 v[2:3], v[110:111], v[2:3]
	v_mul_f32_e32 v0, v148, v0
	v_mul_f32_e32 v148, v149, v156
	v_mul_f32_e32 v149, 0xbfb8aa3b, v150
	v_exp_f32_e32 v149, v149
	v_mul_f32_e32 v156, 0xbfb8aa3b, v151
	v_exp_f32_e32 v156, v156
	v_mul_f32_e32 v0, v170, v0
	v_add_f32_e32 v149, 1.0, v149
	v_rcp_f32_e32 v149, v149
	v_add_f32_e32 v156, 1.0, v156
	v_rcp_f32_e32 v156, v156
	v_mul_f32_e32 v148, v171, v148
	v_cvt_pk_bf16_f32 v148, v0, v148
	v_mul_f32_e32 v0, v150, v149
	v_mul_f32_e32 v0, v2, v0
	v_mul_f32_e32 v2, v151, v156
	v_mul_f32_e32 v2, v3, v2
	s_movk_i32 s14, 0x1600
	v_cvt_pk_bf16_f32 v149, v0, v2
	v_mad_i64_i32 v[2:3], s[58:59], v213, s14, v[202:203]
	global_store_dwordx2 v[2:3], v[148:149], off nt
.LBB0_1212:
	s_or_b64 exec, exec, s[0:1]
	ds_read_b32 v186, v209 offset:128
	v_add_u32_e32 v156, 32, v211
	v_add3_u32 v214, s21, 30, v211
	s_movk_i32 s0, 0x4100
	v_mov_b32_e32 v0, v1
	s_waitcnt lgkmcnt(0)
	v_mov_b32_e32 v187, v186
	v_pk_mul_f32 v[150:151], v[98:99], v[186:187] op_sel_hi:[1,0]
	v_pk_mul_f32 v[148:149], v[96:97], v[186:187] op_sel_hi:[1,0]
	v_mov_b32_e32 v2, v1
	v_mov_b32_e32 v3, v1
	v_mov_b32_e32 v170, v1
	v_mov_b32_e32 v171, v1
	v_mov_b32_e32 v188, v1
	v_mov_b32_e32 v189, v1
	v_mov_b32_e32 v192, v1
	v_mov_b32_e32 v191, v1
	v_mov_b32_e32 v193, v1
	v_mov_b32_e32 v196, v1
	v_mov_b32_e32 v197, v1
	v_mov_b32_e32 v204, v1
	v_mov_b32_e32 v205, v1
	v_mov_b32_e32 v215, v1
	v_mov_b32_e32 v216, v1
	v_cmp_lt_i32_e32 vcc, 1, v156
	v_cmp_gt_i32_e64 s[0:1], s0, v214
	v_mov_b32_dpp v0, v148 row_ror:1 row_mask:0xf bank_mask:0xf
	v_mov_b32_dpp v2, v149 row_ror:1 row_mask:0xf bank_mask:0xf
	v_mov_b32_dpp v3, v150 row_ror:1 row_mask:0xf bank_mask:0xf
	v_mov_b32_dpp v170, v151 row_ror:1 row_mask:0xf bank_mask:0xf
	v_mov_b32_dpp v171, v152 row_ror:1 row_mask:0xf bank_mask:0xf
	v_mov_b32_dpp v188, v153 row_ror:1 row_mask:0xf bank_mask:0xf
	v_mov_b32_dpp v189, v154 row_ror:1 row_mask:0xf bank_mask:0xf
	v_mov_b32_dpp v192, v155 row_ror:1 row_mask:0xf bank_mask:0xf
	v_mov_b32_dpp v191, v148 row_ror:2 row_mask:0xf bank_mask:0xf
	v_mov_b32_dpp v193, v149 row_ror:2 row_mask:0xf bank_mask:0xf
	v_mov_b32_dpp v196, v150 row_ror:2 row_mask:0xf bank_mask:0xf
	v_mov_b32_dpp v197, v151 row_ror:2 row_mask:0xf bank_mask:0xf
	v_mov_b32_dpp v204, v152 row_ror:2 row_mask:0xf bank_mask:0xf
	v_mov_b32_dpp v205, v153 row_ror:2 row_mask:0xf bank_mask:0xf
	v_mov_b32_dpp v215, v154 row_ror:2 row_mask:0xf bank_mask:0xf
	v_mov_b32_dpp v216, v155 row_ror:2 row_mask:0xf bank_mask:0xf
	s_and_b64 s[58:59], vcc, s[0:1]
	s_and_saveexec_b64 s[0:1], s[58:59]
	s_cbranch_execz .LBB0_1224
	s_movk_i32 s14, 0x407f
	v_cmp_lt_i32_e32 vcc, s14, v214
	s_and_saveexec_b64 s[60:61], vcc
	s_xor_b64 s[60:61], exec, s[60:61]
	s_cbranch_execz .LBB0_1215
	v_add_u32_e32 v0, 0xffffbf80, v214
	s_movk_i32 s14, 0x5800
	v_mad_u64_u32 v[2:3], s[62:63], v0, s14, v[164:165]
	v_add_co_u32_e32 v152, vcc, 0x2000, v2
	s_nop 1
	v_addc_co_u32_e32 v153, vcc, 0, v3, vcc
	global_load_dwordx4 v[152:155], v[152:153], off offset:3072
	s_nop 0
	global_load_dwordx4 v[156:159], v[2:3], off
	v_mad_u64_u32 v[2:3], s[62:63], v0, s14, v[162:163]
	v_add_co_u32_e32 v170, vcc, 0x2000, v2
	s_nop 1
	v_addc_co_u32_e32 v171, vcc, 0, v3, vcc
	s_waitcnt vmcnt(0)
	global_store_dwordx4 v[2:3], v[152:155], off nt
	global_store_dwordx4 v[170:171], v[148:151], off offset:3072 nt

;     __device__ __forceinline__ void operator()(const f32x4 (&acc)[2][2][4][2], const Unit& u, int wr, int wc, int fr, int fq) const {
;     ...
;                         if (l >= 2 && row < M) {
;                             if (row < MP) {
;                                 const int b = row / TP, t = row - b * TP;
;                                 if (t < 2) { g2 = (f32x4){0.f, 0.f, 0.f, 0.f}; if (t == 0) g1 = g2; }
;                                 if (t >= TP - 2) *(f32x4*)(cvp + ((size_t)b * 2 + (t - (TP - 2))) * DFF + f0) = cur;
.LBB0_1220:
	s_or_b64 exec, exec, s[62:63]
	s_movk_i32 s14, 0x80d
	v_cmp_lt_i32_e32 vcc, s14, v188
	s_and_saveexec_b64 s[62:63], vcc
	s_cbranch_execz .LBB0_1222
	v_ashrrev_i32_e32 v171, 31, v170
	v_add_u32_e32 v0, 0xfffff7f2, v188
	v_lshl_add_u64 v[2:3], v[170:171], 1, v[0:1]
	s_movk_i32 s14, 0x2c00
	v_mad_u64_u32 v[170:171], s[64:65], v2, s14, v[160:161]
	v_mad_i32_i24 v171, v3, s14, v171
	global_store_dwordx4 v[170:171], v[148:151], off nt

; #define LAS __attribute__((address_space(3)))
;     __device__ __forceinline__ void operator()(const f32x4 (&acc)[2][2][4][2], const Unit& u, int wr, int wc, int fr, int fq) const {
;     ...
;                         const int l = 128 * ai + 64 * wr + 16 * m + frL, row = 254 * u.pm - 2 + l;
;                         const float rs = rt[l];
;                         const f32x4 cur = acc[ai][1][m][n] * rs, uu = acc[ai][0][m][n] * rs;
;                         if (m == 0) {
;                             const int B = 2 * ai + wr;
;                             prev = (f32x4){0.f, 0.f, 0.f, 0.f};
;                             if (B > 0 && frL >= 14) prev = *(const LAS f32x4*)(halo + ((B - 1) * 2 + (frL - 14)) * 128 + fl + 4 * n);
;                         }
;                         f32x4 g1, g2;
;                         {
;                             const float c1x = dpp_ror1(cur.x), c1y = dpp_ror1(cur.y), c1z = dpp_ror1(cur.z), c1w = dpp_ror1(cur.w);
;                             const float p1x = dpp_ror1(prev.x), p1y = dpp_ror1(prev.y), p1z = dpp_ror1(prev.z), p1w = dpp_ror1(prev.w);
;                             const float c2x = dpp_ror2(cur.x), c2y = dpp_ror2(cur.y), c2z = dpp_ror2(cur.z), c2w = dpp_ror2(cur.w);
;                             const float p2x = dpp_ror2(prev.x), p2y = dpp_ror2(prev.y), p2z = dpp_ror2(prev.z), p2w = dpp_ror2(prev.w);
;                             const bool s1 = frL >= 1, s2 = frL >= 2;
;                             g1.x = s1 ? c1x : p1x; g1.y = s1 ? c1y : p1y; g1.z = s1 ? c1z : p1z; g1.w = s1 ? c1w : p1w;
;                             g2.x = s2 ? c2x : p2x; g2.y = s2 ? c2y : p2y; g2.z = s2 ? c2z : p2z; g2.w = s2 ? c2w : p2w;
;                         }
;                         if (l >= 2 && row < M) {
;                             if (row < MP) {
;                                 const int b = row / TP, t = row - b * TP;
;                                 if (t < 2) { g2 = (f32x4){0.f, 0.f, 0.f, 0.f}; if (t == 0) g1 = g2; }
;                                 if (t >= TP - 2) *(f32x4*)(cvp + ((size_t)b * 2 + (t - (TP - 2))) * DFF + f0) = cur;
;                             } else {
;                                 const int s = row - MP;
;                                 const float* c0 = cst + ((size_t)s * 2 + 0) * DFF + f0;
;                                 g2 = *(const f32x4*)c0; g1 = *(const f32x4*)(c0 + DFF);
.LBB0_1223:
	s_or_b64 exec, exec, s[60:61]
	s_waitcnt vmcnt(0)
	v_pk_fma_f32 v[156:157], v[140:141], v[156:157], v[144:145]
	v_pk_fma_f32 v[158:159], v[142:143], v[158:159], v[146:147]
	v_pk_fma_f32 v[152:153], v[136:137], v[152:153], v[156:157]
	v_pk_fma_f32 v[154:155], v[138:139], v[154:155], v[158:159]
	v_pk_fma_f32 v[152:153], v[132:133], v[148:149], v[152:153]
	v_pk_fma_f32 v[154:155], v[134:135], v[150:151], v[154:155]
	v_mul_f32_e32 v0, 0xbfb8aa3b, v152
	v_mul_f32_e32 v156, 0xbfb8aa3b, v153
	v_exp_f32_e32 v0, v0
	v_exp_f32_e32 v156, v156
	v_pk_mul_f32 v[170:171], v[92:93], v[186:187]
	v_mov_b32_e32 v2, v186
	v_add_f32_e32 v0, 1.0, v0
	v_add_f32_e32 v156, 1.0, v156
	v_rcp_f32_e32 v0, v0
	v_rcp_f32_e32 v156, v156
	v_mov_b32_e32 v3, v186
	v_pk_mul_f32 v[2:3], v[94:95], v[2:3]
	v_mul_f32_e32 v0, v152, v0
	v_mul_f32_e32 v152, v153, v156
	v_mul_f32_e32 v153, 0xbfb8aa3b, v154
	v_exp_f32_e32 v153, v153
	v_mul_f32_e32 v156, 0xbfb8aa3b, v155
	v_exp_f32_e32 v156, v156
	v_mul_f32_e32 v0, v170, v0
	v_add_f32_e32 v153, 1.0, v153
	v_rcp_f32_e32 v153, v153
	v_add_f32_e32 v156, 1.0, v156
	v_rcp_f32_e32 v156, v156
	v_mul_f32_e32 v152, v171, v152
	v_cvt_pk_bf16_f32 v152, v0, v152
	v_mul_f32_e32 v0, v154, v153
	v_mul_f32_e32 v0, v2, v0
	v_mul_f32_e32 v2, v155, v156
	v_mul_f32_e32 v2, v3, v2
	s_movk_i32 s14, 0x1600
	v_cvt_pk_bf16_f32 v153, v0, v2
	v_mad_i64_i32 v[2:3], s[60:61], v214, s14, v[202:203]
	global_store_dwordx2 v[2:3], v[152:153], off nt
.LBB0_1224:
	s_or_b64 exec, exec, s[0:1]
	ds_read_b32 v188, v209 offset:192
	v_add_u32_e32 v156, 48, v211
	v_add3_u32 v215, s21, 46, v211
	s_movk_i32 s0, 0x4100
	v_mov_b32_e32 v0, v1
	s_waitcnt lgkmcnt(0)
	v_mov_b32_e32 v189, v188
	v_pk_mul_f32 v[154:155], v[82:83], v[188:189] op_sel_hi:[1,0]
	v_pk_mul_f32 v[152:153], v[80:81], v[188:189] op_sel_hi:[1,0]
	v_mov_b32_e32 v2, v1
	v_mov_b32_e32 v3, v1
	v_mov_b32_e32 v170, v1
	v_mov_b32_e32 v171, v1
	v_mov_b32_e32 v191, v1
	v_mov_b32_e32 v192, v1
	v_mov_b32_e32 v196, v1
	v_mov_b32_e32 v193, v1
	v_mov_b32_e32 v197, v1
	v_mov_b32_e32 v204, v1
	v_mov_b32_e32 v205, v1
	v_mov_b32_e32 v216, v1
	v_mov_b32_e32 v217, v1
	v_mov_b32_e32 v218, v1
	v_mov_b32_e32 v219, v1
	v_cmp_lt_i32_e32 vcc, 1, v156
	v_cmp_gt_i32_e64 s[0:1], s0, v215
	v_mov_b32_dpp v0, v152 row_ror:1 row_mask:0xf bank_mask:0xf
	v_mov_b32_dpp v2, v153 row_ror:1 row_mask:0xf bank_mask:0xf
	v_mov_b32_dpp v3, v154 row_ror:1 row_mask:0xf bank_mask:0xf
	v_mov_b32_dpp v170, v155 row_ror:1 row_mask:0xf bank_mask:0xf
	v_mov_b32_dpp v171, v148 row_ror:1 row_mask:0xf bank_mask:0xf
	v_mov_b32_dpp v191, v149 row_ror:1 row_mask:0xf bank_mask:0xf
	v_mov_b32_dpp v192, v150 row_ror:1 row_mask:0xf bank_mask:0xf
	v_mov_b32_dpp v196, v151 row_ror:1 row_mask:0xf bank_mask:0xf
	v_mov_b32_dpp v193, v152 row_ror:2 row_mask:0xf bank_mask:0xf
	v_mov_b32_dpp v197, v153 row_ror:2 row_mask:0xf bank_mask:0xf
	v_mov_b32_dpp v204, v154 row_ror:2 row_mask:0xf bank_mask:0xf
	v_mov_b32_dpp v205, v155 row_ror:2 row_mask:0xf bank_mask:0xf
	v_mov_b32_dpp v216, v148 row_ror:2 row_mask:0xf bank_mask:0xf
	v_mov_b32_dpp v217, v149 row_ror:2 row_mask:0xf bank_mask:0xf
	v_mov_b32_dpp v218, v150 row_ror:2 row_mask:0xf bank_mask:0xf
	v_mov_b32_dpp v219, v151 row_ror:2 row_mask:0xf bank_mask:0xf
	s_and_b64 s[60:61], vcc, s[0:1]
	s_and_saveexec_b64 s[0:1], s[60:61]
	s_cbranch_execz .LBB0_1236
	s_movk_i32 s14, 0x407f
	v_cmp_lt_i32_e32 vcc, s14, v215
	s_and_saveexec_b64 s[62:63], vcc
	s_xor_b64 s[62:63], exec, s[62:63]
	s_cbranch_execz .LBB0_1227
	v_add_u32_e32 v0, 0xffffbf80, v215
	s_movk_i32 s14, 0x5800
	v_mad_u64_u32 v[2:3], s[64:65], v0, s14, v[164:165]
	v_add_co_u32_e32 v148, vcc, 0x2000, v2
	s_nop 1
	v_addc_co_u32_e32 v149, vcc, 0, v3, vcc
	global_load_dwordx4 v[148:151], v[148:149], off offset:3072
	s_nop 0
	global_load_dwordx4 v[156:159], v[2:3], off
	v_mad_u64_u32 v[2:3], s[64:65], v0, s14, v[162:163]
	v_add_co_u32_e32 v170, vcc, 0x2000, v2
	s_nop 1
	v_addc_co_u32_e32 v171, vcc, 0, v3, vcc
	s_waitcnt vmcnt(0)
	global_store_dwordx4 v[2:3], v[148:151], off nt
	global_store_dwordx4 v[170:171], v[152:155], off offset:3072 nt

;     __device__ __forceinline__ void operator()(const f32x4 (&acc)[2][2][4][2], const Unit& u, int wr, int wc, int fr, int fq) const {
;     ...
;                         if (l >= 2 && row < M) {
;                             if (row < MP) {
;                                 const int b = row / TP, t = row - b * TP;
;                                 if (t < 2) { g2 = (f32x4){0.f, 0.f, 0.f, 0.f}; if (t == 0) g1 = g2; }
;                                 if (t >= TP - 2) *(f32x4*)(cvp + ((size_t)b * 2 + (t - (TP - 2))) * DFF + f0) = cur;
.LBB0_1232:
	s_or_b64 exec, exec, s[64:65]
	s_movk_i32 s14, 0x80d
	v_cmp_lt_i32_e32 vcc, s14, v191
	s_and_saveexec_b64 s[64:65], vcc
	s_cbranch_execz .LBB0_1234
	v_ashrrev_i32_e32 v171, 31, v170
	v_add_u32_e32 v0, 0xfffff7f2, v191
	v_lshl_add_u64 v[2:3], v[170:171], 1, v[0:1]
	s_movk_i32 s14, 0x2c00
	v_mad_u64_u32 v[170:171], s[66:67], v2, s14, v[160:161]
	v_mad_i32_i24 v171, v3, s14, v171
	global_store_dwordx4 v[170:171], v[152:155], off nt

; #define LAS __attribute__((address_space(3)))
;     __device__ __forceinline__ void operator()(const f32x4 (&acc)[2][2][4][2], const Unit& u, int wr, int wc, int fr, int fq) const {
;     ...
;                         const int l = 128 * ai + 64 * wr + 16 * m + frL, row = 254 * u.pm - 2 + l;
;                         const float rs = rt[l];
;                         const f32x4 cur = acc[ai][1][m][n] * rs, uu = acc[ai][0][m][n] * rs;
;                         if (m == 0) {
;                             const int B = 2 * ai + wr;
;                             prev = (f32x4){0.f, 0.f, 0.f, 0.f};
;                             if (B > 0 && frL >= 14) prev = *(const LAS f32x4*)(halo + ((B - 1) * 2 + (frL - 14)) * 128 + fl + 4 * n);
;                         }
;                         f32x4 g1, g2;
;                         {
;                             const float c1x = dpp_ror1(cur.x), c1y = dpp_ror1(cur.y), c1z = dpp_ror1(cur.z), c1w = dpp_ror1(cur.w);
;                             const float p1x = dpp_ror1(prev.x), p1y = dpp_ror1(prev.y), p1z = dpp_ror1(prev.z), p1w = dpp_ror1(prev.w);
;                             const float c2x = dpp_ror2(cur.x), c2y = dpp_ror2(cur.y), c2z = dpp_ror2(cur.z), c2w = dpp_ror2(cur.w);
;                             const float p2x = dpp_ror2(prev.x), p2y = dpp_ror2(prev.y), p2z = dpp_ror2(prev.z), p2w = dpp_ror2(prev.w);
;                             const bool s1 = frL >= 1, s2 = frL >= 2;
;                             g1.x = s1 ? c1x : p1x; g1.y = s1 ? c1y : p1y; g1.z = s1 ? c1z : p1z; g1.w = s1 ? c1w : p1w;
;                             g2.x = s2 ? c2x : p2x; g2.y = s2 ? c2y : p2y; g2.z = s2 ? c2z : p2z; g2.w = s2 ? c2w : p2w;
;                         }
;                         if (l >= 2 && row < M) {
;                             if (row < MP) {
;                                 const int b = row / TP, t = row - b * TP;
;                                 if (t < 2) { g2 = (f32x4){0.f, 0.f, 0.f, 0.f}; if (t == 0) g1 = g2; }
;                                 if (t >= TP - 2) *(f32x4*)(cvp + ((size_t)b * 2 + (t - (TP - 2))) * DFF + f0) = cur;
;                             } else {
;                                 const int s = row - MP;
;                                 const float* c0 = cst + ((size_t)s * 2 + 0) * DFF + f0;
;                                 g2 = *(const f32x4*)c0; g1 = *(const f32x4*)(c0 + DFF);
.LBB0_1235:
	s_or_b64 exec, exec, s[62:63]
	s_waitcnt vmcnt(0)
	v_pk_fma_f32 v[156:157], v[140:141], v[156:157], v[144:145]
	v_pk_fma_f32 v[158:159], v[142:143], v[158:159], v[146:147]
	v_pk_fma_f32 v[148:149], v[136:137], v[148:149], v[156:157]
	v_pk_fma_f32 v[150:151], v[138:139], v[150:151], v[158:159]
	v_pk_fma_f32 v[148:149], v[132:133], v[152:153], v[148:149]
	v_pk_fma_f32 v[150:151], v[134:135], v[154:155], v[150:151]
	v_mul_f32_e32 v0, 0xbfb8aa3b, v148
	v_mul_f32_e32 v152, 0xbfb8aa3b, v149
	v_exp_f32_e32 v0, v0
	v_exp_f32_e32 v152, v152
	v_pk_mul_f32 v[170:171], v[76:77], v[188:189]
	v_mov_b32_e32 v2, v188
	v_add_f32_e32 v0, 1.0, v0
	v_add_f32_e32 v152, 1.0, v152
	v_rcp_f32_e32 v0, v0
	v_rcp_f32_e32 v152, v152
	v_mov_b32_e32 v3, v188
	v_pk_mul_f32 v[2:3], v[78:79], v[2:3]
	v_mul_f32_e32 v0, v148, v0
	v_mul_f32_e32 v148, v149, v152
	v_mul_f32_e32 v149, 0xbfb8aa3b, v150
	v_exp_f32_e32 v149, v149
	v_mul_f32_e32 v152, 0xbfb8aa3b, v151
	v_exp_f32_e32 v152, v152
	v_mul_f32_e32 v0, v170, v0
	v_add_f32_e32 v149, 1.0, v149
	v_rcp_f32_e32 v149, v149
	v_add_f32_e32 v152, 1.0, v152
	v_rcp_f32_e32 v152, v152
	v_mul_f32_e32 v148, v171, v148
	v_cvt_pk_bf16_f32 v148, v0, v148
	v_mul_f32_e32 v0, v150, v149
	v_mul_f32_e32 v0, v2, v0
	v_mul_f32_e32 v2, v151, v152
	v_mul_f32_e32 v2, v3, v2
	s_movk_i32 s14, 0x1600
	v_cvt_pk_bf16_f32 v149, v0, v2
	v_mad_i64_i32 v[2:3], s[62:63], v215, s14, v[202:203]
	global_store_dwordx2 v[2:3], v[148:149], off nt
.LBB0_1236:
	s_or_b64 exec, exec, s[0:1]
	ds_read_b32 v170, v209 offset:512
	s_movk_i32 s0, 0xe800
	v_add3_u32 v221, v190, v210, s0
	s_nor_b64 s[10:11], s[30:31], s[10:11]
	v_mov_b32_e32 v152, 0
	v_mov_b32_e32 v153, 0
	v_mov_b32_e32 v154, 0
	v_mov_b32_e32 v155, 0
	s_and_saveexec_b64 s[0:1], s[10:11]
	ds_read_b128 v[152:155], v221
	s_or_b64 exec, exec, s[0:1]
	s_add_i32 s0, s21, 0x7e
	v_add_u32_e32 v156, 0x80, v211
	v_add_u32_e32 v216, s0, v211
	s_waitcnt lgkmcnt(0)
	v_mov_b32_e32 v171, v170
	s_movk_i32 s0, 0x4100
	v_pk_mul_f32 v[150:151], v[66:67], v[170:171] op_sel_hi:[1,0]
	v_pk_mul_f32 v[148:149], v[64:65], v[170:171] op_sel_hi:[1,0]
	v_mov_b32_e32 v0, v1
	v_mov_b32_e32 v2, v1
	v_mov_b32_e32 v3, v1
	v_mov_b32_e32 v190, v1
	v_mov_b32_e32 v191, v1
	v_mov_b32_e32 v192, v1
	v_mov_b32_e32 v193, v1
	v_mov_b32_e32 v197, v1
	v_mov_b32_e32 v196, v1
	v_mov_b32_e32 v204, v1
	v_mov_b32_e32 v205, v1
	v_mov_b32_e32 v217, v1
	v_mov_b32_e32 v218, v1
	v_mov_b32_e32 v219, v1
	v_mov_b32_e32 v239, v1
	v_mov_b32_e32 v240, v1
	v_cmp_lt_i32_e32 vcc, 1, v156
	v_cmp_gt_i32_e64 s[0:1], s0, v216
	v_mov_b32_dpp v0, v148 row_ror:1 row_mask:0xf bank_mask:0xf
	v_mov_b32_dpp v2, v149 row_ror:1 row_mask:0xf bank_mask:0xf
	v_mov_b32_dpp v3, v150 row_ror:1 row_mask:0xf bank_mask:0xf
	v_mov_b32_dpp v190, v151 row_ror:1 row_mask:0xf bank_mask:0xf
	v_mov_b32_dpp v191, v152 row_ror:1 row_mask:0xf bank_mask:0xf
	v_mov_b32_dpp v192, v153 row_ror:1 row_mask:0xf bank_mask:0xf
	v_mov_b32_dpp v193, v154 row_ror:1 row_mask:0xf bank_mask:0xf
	v_mov_b32_dpp v197, v155 row_ror:1 row_mask:0xf bank_mask:0xf
	v_mov_b32_dpp v196, v148 row_ror:2 row_mask:0xf bank_mask:0xf
	v_mov_b32_dpp v204, v149 row_ror:2 row_mask:0xf bank_mask:0xf
	v_mov_b32_dpp v205, v150 row_ror:2 row_mask:0xf bank_mask:0xf
	v_mov_b32_dpp v217, v151 row_ror:2 row_mask:0xf bank_mask:0xf
	v_mov_b32_dpp v218, v152 row_ror:2 row_mask:0xf bank_mask:0xf
	v_mov_b32_dpp v219, v153 row_ror:2 row_mask:0xf bank_mask:0xf
	v_mov_b32_dpp v239, v154 row_ror:2 row_mask:0xf bank_mask:0xf
	v_mov_b32_dpp v240, v155 row_ror:2 row_mask:0xf bank_mask:0xf
	s_and_b64 s[62:63], vcc, s[0:1]
	s_and_saveexec_b64 s[0:1], s[62:63]
	s_cbranch_execz .LBB0_1250
	s_movk_i32 s14, 0x407f
	v_cmp_lt_i32_e32 vcc, s14, v216
	s_and_saveexec_b64 s[64:65], vcc
	s_xor_b64 s[64:65], exec, s[64:65]
	s_cbranch_execz .LBB0_1241
	v_add_u32_e32 v0, 0xffffbf80, v216
	s_movk_i32 s14, 0x5800
	v_mad_u64_u32 v[2:3], s[66:67], v0, s14, v[164:165]
	v_add_co_u32_e32 v152, vcc, 0x2000, v2
	s_nop 1
	v_addc_co_u32_e32 v153, vcc, 0, v3, vcc
	global_load_dwordx4 v[152:155], v[152:153], off offset:3072
	s_nop 0
	global_load_dwordx4 v[156:159], v[2:3], off
	v_mad_u64_u32 v[2:3], s[66:67], v0, s14, v[162:163]
	v_add_co_u32_e32 v190, vcc, 0x2000, v2
	s_nop 1
	v_addc_co_u32_e32 v191, vcc, 0, v3, vcc
	s_waitcnt vmcnt(0)
	global_store_dwordx4 v[2:3], v[152:155], off nt
	global_store_dwordx4 v[190:191], v[148:151], off offset:3072 nt

;     __device__ __forceinline__ void operator()(const f32x4 (&acc)[2][2][4][2], const Unit& u, int wr, int wc, int fr, int fq) const {
;     ...
;                         if (l >= 2 && row < M) {
;                             if (row < MP) {
;                                 const int b = row / TP, t = row - b * TP;
;                                 if (t < 2) { g2 = (f32x4){0.f, 0.f, 0.f, 0.f}; if (t == 0) g1 = g2; }
;                                 if (t >= TP - 2) *(f32x4*)(cvp + ((size_t)b * 2 + (t - (TP - 2))) * DFF + f0) = cur;
.LBB0_1246:
	s_or_b64 exec, exec, s[66:67]
	s_movk_i32 s14, 0x80d
	v_cmp_lt_i32_e32 vcc, s14, v192
	s_and_saveexec_b64 s[66:67], vcc
	s_cbranch_execz .LBB0_1248
	v_ashrrev_i32_e32 v191, 31, v190
	v_add_u32_e32 v0, 0xfffff7f2, v192
	v_lshl_add_u64 v[2:3], v[190:191], 1, v[0:1]
	s_movk_i32 s14, 0x2c00
	v_mad_u64_u32 v[190:191], s[68:69], v2, s14, v[160:161]
	v_mad_i32_i24 v191, v3, s14, v191
	global_store_dwordx4 v[190:191], v[148:151], off nt

; #define LAS __attribute__((address_space(3)))
;     __device__ __forceinline__ void operator()(const f32x4 (&acc)[2][2][4][2], const Unit& u, int wr, int wc, int fr, int fq) const {
;     ...
;                         const int l = 128 * ai + 64 * wr + 16 * m + frL, row = 254 * u.pm - 2 + l;
;                         const float rs = rt[l];
;                         const f32x4 cur = acc[ai][1][m][n] * rs, uu = acc[ai][0][m][n] * rs;
;                         if (m == 0) {
;                             const int B = 2 * ai + wr;
;                             prev = (f32x4){0.f, 0.f, 0.f, 0.f};
;                             if (B > 0 && frL >= 14) prev = *(const LAS f32x4*)(halo + ((B - 1) * 2 + (frL - 14)) * 128 + fl + 4 * n);
;                         }
;                         f32x4 g1, g2;
;                         {
;                             const float c1x = dpp_ror1(cur.x), c1y = dpp_ror1(cur.y), c1z = dpp_ror1(cur.z), c1w = dpp_ror1(cur.w);
;                             const float p1x = dpp_ror1(prev.x), p1y = dpp_ror1(prev.y), p1z = dpp_ror1(prev.z), p1w = dpp_ror1(prev.w);
;                             const float c2x = dpp_ror2(cur.x), c2y = dpp_ror2(cur.y), c2z = dpp_ror2(cur.z), c2w = dpp_ror2(cur.w);
;                             const float p2x = dpp_ror2(prev.x), p2y = dpp_ror2(prev.y), p2z = dpp_ror2(prev.z), p2w = dpp_ror2(prev.w);
;                             const bool s1 = frL >= 1, s2 = frL >= 2;
;                             g1.x = s1 ? c1x : p1x; g1.y = s1 ? c1y : p1y; g1.z = s1 ? c1z : p1z; g1.w = s1 ? c1w : p1w;
;                             g2.x = s2 ? c2x : p2x; g2.y = s2 ? c2y : p2y; g2.z = s2 ? c2z : p2z; g2.w = s2 ? c2w : p2w;
;                         }
;                         if (l >= 2 && row < M) {
;                             if (row < MP) {
;                                 const int b = row / TP, t = row - b * TP;
;                                 if (t < 2) { g2 = (f32x4){0.f, 0.f, 0.f, 0.f}; if (t == 0) g1 = g2; }
;                                 if (t >= TP - 2) *(f32x4*)(cvp + ((size_t)b * 2 + (t - (TP - 2))) * DFF + f0) = cur;
;                             } else {
;                                 const int s = row - MP;
;                                 const float* c0 = cst + ((size_t)s * 2 + 0) * DFF + f0;
;                                 g2 = *(const f32x4*)c0; g1 = *(const f32x4*)(c0 + DFF);
.LBB0_1249:
	s_or_b64 exec, exec, s[64:65]
	s_waitcnt vmcnt(0)
	v_pk_fma_f32 v[156:157], v[140:141], v[156:157], v[144:145]
	v_pk_fma_f32 v[158:159], v[142:143], v[158:159], v[146:147]
	v_pk_fma_f32 v[152:153], v[136:137], v[152:153], v[156:157]
	v_pk_fma_f32 v[154:155], v[138:139], v[154:155], v[158:159]
	v_pk_fma_f32 v[152:153], v[132:133], v[148:149], v[152:153]
	v_pk_fma_f32 v[154:155], v[134:135], v[150:151], v[154:155]
	v_mul_f32_e32 v0, 0xbfb8aa3b, v152
	v_mul_f32_e32 v156, 0xbfb8aa3b, v153
	v_exp_f32_e32 v0, v0
	v_exp_f32_e32 v156, v156
	v_pk_mul_f32 v[190:191], v[60:61], v[170:171]
	v_mov_b32_e32 v2, v170
	v_add_f32_e32 v0, 1.0, v0
	v_add_f32_e32 v156, 1.0, v156
	v_rcp_f32_e32 v0, v0
	v_rcp_f32_e32 v156, v156
	v_mov_b32_e32 v3, v170
	v_pk_mul_f32 v[2:3], v[62:63], v[2:3]
	v_mul_f32_e32 v0, v152, v0
	v_mul_f32_e32 v152, v153, v156
	v_mul_f32_e32 v153, 0xbfb8aa3b, v154
	v_exp_f32_e32 v153, v153
	v_mul_f32_e32 v156, 0xbfb8aa3b, v155
	v_exp_f32_e32 v156, v156
	v_mul_f32_e32 v0, v190, v0
	v_add_f32_e32 v153, 1.0, v153
	v_rcp_f32_e32 v153, v153
	v_add_f32_e32 v156, 1.0, v156
	v_rcp_f32_e32 v156, v156
	v_mul_f32_e32 v152, v191, v152
	v_cvt_pk_bf16_f32 v152, v0, v152
	v_mul_f32_e32 v0, v154, v153
	v_mul_f32_e32 v0, v2, v0
	v_mul_f32_e32 v2, v155, v156
	v_mul_f32_e32 v2, v3, v2
	s_movk_i32 s14, 0x1600
	v_cvt_pk_bf16_f32 v153, v0, v2
	v_mad_i64_i32 v[2:3], s[64:65], v216, s14, v[202:203]
	global_store_dwordx2 v[2:3], v[152:153], off nt
.LBB0_1250:
	s_or_b64 exec, exec, s[0:1]
	ds_read_b32 v190, v209 offset:576
	s_add_i32 s0, s21, 0x8e
	v_add_u32_e32 v156, 0x90, v211
	v_add_u32_e32 v217, s0, v211
	s_movk_i32 s0, 0x4100
	s_waitcnt lgkmcnt(0)
	v_mov_b32_e32 v191, v190
	v_pk_mul_f32 v[154:155], v[50:51], v[190:191] op_sel_hi:[1,0]
	v_pk_mul_f32 v[152:153], v[48:49], v[190:191] op_sel_hi:[1,0]
	v_mov_b32_e32 v0, v1
	v_mov_b32_e32 v2, v1
	v_mov_b32_e32 v3, v1
	v_mov_b32_e32 v192, v1
	v_mov_b32_e32 v193, v1
	v_mov_b32_e32 v196, v1
	v_mov_b32_e32 v197, v1
	v_mov_b32_e32 v205, v1
	v_mov_b32_e32 v204, v1
	v_mov_b32_e32 v218, v1
	v_mov_b32_e32 v219, v1
	v_mov_b32_e32 v239, v1
	v_mov_b32_e32 v240, v1
	v_mov_b32_e32 v241, v1
	v_mov_b32_e32 v242, v1
	v_mov_b32_e32 v243, v1
	v_cmp_lt_i32_e32 vcc, 1, v156
	v_cmp_gt_i32_e64 s[0:1], s0, v217
	v_mov_b32_dpp v0, v152 row_ror:1 row_mask:0xf bank_mask:0xf
	v_mov_b32_dpp v2, v153 row_ror:1 row_mask:0xf bank_mask:0xf
	v_mov_b32_dpp v3, v154 row_ror:1 row_mask:0xf bank_mask:0xf
	v_mov_b32_dpp v192, v155 row_ror:1 row_mask:0xf bank_mask:0xf
	v_mov_b32_dpp v193, v148 row_ror:1 row_mask:0xf bank_mask:0xf
	v_mov_b32_dpp v196, v149 row_ror:1 row_mask:0xf bank_mask:0xf
	v_mov_b32_dpp v197, v150 row_ror:1 row_mask:0xf bank_mask:0xf
	v_mov_b32_dpp v205, v151 row_ror:1 row_mask:0xf bank_mask:0xf
	v_mov_b32_dpp v204, v152 row_ror:2 row_mask:0xf bank_mask:0xf
	v_mov_b32_dpp v218, v153 row_ror:2 row_mask:0xf bank_mask:0xf
	v_mov_b32_dpp v219, v154 row_ror:2 row_mask:0xf bank_mask:0xf
	v_mov_b32_dpp v239, v155 row_ror:2 row_mask:0xf bank_mask:0xf
	v_mov_b32_dpp v240, v148 row_ror:2 row_mask:0xf bank_mask:0xf
	v_mov_b32_dpp v241, v149 row_ror:2 row_mask:0xf bank_mask:0xf
	v_mov_b32_dpp v242, v150 row_ror:2 row_mask:0xf bank_mask:0xf
	v_mov_b32_dpp v243, v151 row_ror:2 row_mask:0xf bank_mask:0xf
	s_and_b64 s[64:65], vcc, s[0:1]
	s_and_saveexec_b64 s[0:1], s[64:65]
	s_cbranch_execz .LBB0_1262
	s_movk_i32 s14, 0x407f
	v_cmp_lt_i32_e32 vcc, s14, v217
	s_and_saveexec_b64 s[66:67], vcc
	s_xor_b64 s[66:67], exec, s[66:67]
	s_cbranch_execz .LBB0_1253
	v_add_u32_e32 v0, 0xffffbf80, v217
	s_movk_i32 s14, 0x5800
	v_mad_u64_u32 v[2:3], s[68:69], v0, s14, v[164:165]
	v_add_co_u32_e32 v148, vcc, 0x2000, v2
	s_nop 1
	v_addc_co_u32_e32 v149, vcc, 0, v3, vcc
	global_load_dwordx4 v[148:151], v[148:149], off offset:3072
	s_nop 0
	global_load_dwordx4 v[156:159], v[2:3], off
	v_mad_u64_u32 v[2:3], s[68:69], v0, s14, v[162:163]
	v_add_co_u32_e32 v192, vcc, 0x2000, v2
	s_nop 1
	v_addc_co_u32_e32 v193, vcc, 0, v3, vcc
	s_waitcnt vmcnt(0)
	global_store_dwordx4 v[2:3], v[148:151], off nt
	global_store_dwordx4 v[192:193], v[152:155], off offset:3072 nt

;     __device__ __forceinline__ void operator()(const f32x4 (&acc)[2][2][4][2], const Unit& u, int wr, int wc, int fr, int fq) const {
;     ...
;                         if (l >= 2 && row < M) {
;                             if (row < MP) {
;                                 const int b = row / TP, t = row - b * TP;
;                                 if (t < 2) { g2 = (f32x4){0.f, 0.f, 0.f, 0.f}; if (t == 0) g1 = g2; }
;                                 if (t >= TP - 2) *(f32x4*)(cvp + ((size_t)b * 2 + (t - (TP - 2))) * DFF + f0) = cur;
.LBB0_1258:
	s_or_b64 exec, exec, s[68:69]
	s_movk_i32 s14, 0x80d
	v_cmp_lt_i32_e32 vcc, s14, v196
	s_and_saveexec_b64 s[68:69], vcc
	s_cbranch_execz .LBB0_1260
	v_ashrrev_i32_e32 v193, 31, v192
	v_add_u32_e32 v0, 0xfffff7f2, v196
	v_lshl_add_u64 v[2:3], v[192:193], 1, v[0:1]
	s_movk_i32 s14, 0x2c00
	v_mad_u64_u32 v[192:193], s[70:71], v2, s14, v[160:161]
	v_mad_i32_i24 v193, v3, s14, v193
	global_store_dwordx4 v[192:193], v[152:155], off nt

; #define LAS __attribute__((address_space(3)))
;     __device__ __forceinline__ void operator()(const f32x4 (&acc)[2][2][4][2], const Unit& u, int wr, int wc, int fr, int fq) const {
;     ...
;                         const int l = 128 * ai + 64 * wr + 16 * m + frL, row = 254 * u.pm - 2 + l;
;                         const float rs = rt[l];
;                         const f32x4 cur = acc[ai][1][m][n] * rs, uu = acc[ai][0][m][n] * rs;
;                         if (m == 0) {
;                             const int B = 2 * ai + wr;
;                             prev = (f32x4){0.f, 0.f, 0.f, 0.f};
;                             if (B > 0 && frL >= 14) prev = *(const LAS f32x4*)(halo + ((B - 1) * 2 + (frL - 14)) * 128 + fl + 4 * n);
;                         }
;                         f32x4 g1, g2;
;                         {
;                             const float c1x = dpp_ror1(cur.x), c1y = dpp_ror1(cur.y), c1z = dpp_ror1(cur.z), c1w = dpp_ror1(cur.w);
;                             const float p1x = dpp_ror1(prev.x), p1y = dpp_ror1(prev.y), p1z = dpp_ror1(prev.z), p1w = dpp_ror1(prev.w);
;                             const float c2x = dpp_ror2(cur.x), c2y = dpp_ror2(cur.y), c2z = dpp_ror2(cur.z), c2w = dpp_ror2(cur.w);
;                             const float p2x = dpp_ror2(prev.x), p2y = dpp_ror2(prev.y), p2z = dpp_ror2(prev.z), p2w = dpp_ror2(prev.w);
;                             const bool s1 = frL >= 1, s2 = frL >= 2;
;                             g1.x = s1 ? c1x : p1x; g1.y = s1 ? c1y : p1y; g1.z = s1 ? c1z : p1z; g1.w = s1 ? c1w : p1w;
;                             g2.x = s2 ? c2x : p2x; g2.y = s2 ? c2y : p2y; g2.z = s2 ? c2z : p2z; g2.w = s2 ? c2w : p2w;
;                         }
;                         if (l >= 2 && row < M) {
;                             if (row < MP) {
;                                 const int b = row / TP, t = row - b * TP;
;                                 if (t < 2) { g2 = (f32x4){0.f, 0.f, 0.f, 0.f}; if (t == 0) g1 = g2; }
;                                 if (t >= TP - 2) *(f32x4*)(cvp + ((size_t)b * 2 + (t - (TP - 2))) * DFF + f0) = cur;
;                             } else {
;                                 const int s = row - MP;
;                                 const float* c0 = cst + ((size_t)s * 2 + 0) * DFF + f0;
;                                 g2 = *(const f32x4*)c0; g1 = *(const f32x4*)(c0 + DFF);
.LBB0_1261:
	s_or_b64 exec, exec, s[66:67]
	s_waitcnt vmcnt(0)
	v_pk_fma_f32 v[156:157], v[140:141], v[156:157], v[144:145]
	v_pk_fma_f32 v[158:159], v[142:143], v[158:159], v[146:147]
	v_pk_fma_f32 v[148:149], v[136:137], v[148:149], v[156:157]
	v_pk_fma_f32 v[150:151], v[138:139], v[150:151], v[158:159]
	v_pk_fma_f32 v[148:149], v[132:133], v[152:153], v[148:149]
	v_pk_fma_f32 v[150:151], v[134:135], v[154:155], v[150:151]
	v_mul_f32_e32 v0, 0xbfb8aa3b, v148
	v_mul_f32_e32 v156, 0xbfb8aa3b, v149
	v_exp_f32_e32 v0, v0
	v_exp_f32_e32 v156, v156
	v_pk_mul_f32 v[192:193], v[44:45], v[190:191]
	v_mov_b32_e32 v2, v190
	v_add_f32_e32 v0, 1.0, v0
	v_add_f32_e32 v156, 1.0, v156
	v_rcp_f32_e32 v0, v0
	v_rcp_f32_e32 v156, v156
	v_mov_b32_e32 v3, v190
	v_pk_mul_f32 v[2:3], v[46:47], v[2:3]
	v_mul_f32_e32 v0, v148, v0
	v_mul_f32_e32 v148, v149, v156
	v_mul_f32_e32 v149, 0xbfb8aa3b, v150
	v_exp_f32_e32 v149, v149
	v_mul_f32_e32 v156, 0xbfb8aa3b, v151
	v_exp_f32_e32 v156, v156
	v_mul_f32_e32 v0, v192, v0
	v_add_f32_e32 v149, 1.0, v149
	v_rcp_f32_e32 v149, v149
	v_add_f32_e32 v156, 1.0, v156
	v_rcp_f32_e32 v156, v156
	v_mul_f32_e32 v148, v193, v148
	v_cvt_pk_bf16_f32 v148, v0, v148
	v_mul_f32_e32 v0, v150, v149
	v_mul_f32_e32 v0, v2, v0
	v_mul_f32_e32 v2, v151, v156
	v_mul_f32_e32 v2, v3, v2
	s_movk_i32 s14, 0x1600
	v_cvt_pk_bf16_f32 v149, v0, v2
	v_mad_i64_i32 v[2:3], s[66:67], v217, s14, v[202:203]
	global_store_dwordx2 v[2:3], v[148:149], off nt
.LBB0_1262:
	s_or_b64 exec, exec, s[0:1]
	ds_read_b32 v192, v209 offset:640
	s_add_i32 s0, s21, 0x9e
	v_add_u32_e32 v156, 0xa0, v211
	v_add_u32_e32 v218, s0, v211
	s_movk_i32 s0, 0x4100
	s_waitcnt lgkmcnt(0)
	v_mov_b32_e32 v193, v192
	v_pk_mul_f32 v[150:151], v[34:35], v[192:193] op_sel_hi:[1,0]
	v_pk_mul_f32 v[148:149], v[32:33], v[192:193] op_sel_hi:[1,0]
	v_mov_b32_e32 v0, v1
	v_mov_b32_e32 v2, v1
	v_mov_b32_e32 v3, v1
	v_mov_b32_e32 v196, v1
	v_mov_b32_e32 v197, v1
	v_mov_b32_e32 v204, v1
	v_mov_b32_e32 v205, v1
	v_mov_b32_e32 v239, v1
	v_mov_b32_e32 v219, v1
	v_mov_b32_e32 v240, v1
	v_mov_b32_e32 v241, v1
	v_mov_b32_e32 v242, v1
	v_mov_b32_e32 v243, v1
	v_mov_b32_e32 v244, v1
	v_mov_b32_e32 v245, v1
	v_mov_b32_e32 v246, v1
	v_cmp_lt_i32_e32 vcc, 1, v156
	v_cmp_gt_i32_e64 s[0:1], s0, v218
	v_mov_b32_dpp v0, v148 row_ror:1 row_mask:0xf bank_mask:0xf
	v_mov_b32_dpp v2, v149 row_ror:1 row_mask:0xf bank_mask:0xf
	v_mov_b32_dpp v3, v150 row_ror:1 row_mask:0xf bank_mask:0xf
	v_mov_b32_dpp v196, v151 row_ror:1 row_mask:0xf bank_mask:0xf
	v_mov_b32_dpp v197, v152 row_ror:1 row_mask:0xf bank_mask:0xf
	v_mov_b32_dpp v204, v153 row_ror:1 row_mask:0xf bank_mask:0xf
	v_mov_b32_dpp v205, v154 row_ror:1 row_mask:0xf bank_mask:0xf
	v_mov_b32_dpp v239, v155 row_ror:1 row_mask:0xf bank_mask:0xf
	v_mov_b32_dpp v219, v148 row_ror:2 row_mask:0xf bank_mask:0xf
	v_mov_b32_dpp v240, v149 row_ror:2 row_mask:0xf bank_mask:0xf
	v_mov_b32_dpp v241, v150 row_ror:2 row_mask:0xf bank_mask:0xf
	v_mov_b32_dpp v242, v151 row_ror:2 row_mask:0xf bank_mask:0xf
	v_mov_b32_dpp v243, v152 row_ror:2 row_mask:0xf bank_mask:0xf
	v_mov_b32_dpp v244, v153 row_ror:2 row_mask:0xf bank_mask:0xf
	v_mov_b32_dpp v245, v154 row_ror:2 row_mask:0xf bank_mask:0xf
	v_mov_b32_dpp v246, v155 row_ror:2 row_mask:0xf bank_mask:0xf
	s_and_b64 s[66:67], vcc, s[0:1]
	s_and_saveexec_b64 s[0:1], s[66:67]
	s_cbranch_execz .LBB0_1274
	s_movk_i32 s14, 0x407f
	v_cmp_lt_i32_e32 vcc, s14, v218
	s_and_saveexec_b64 s[68:69], vcc
	s_xor_b64 s[68:69], exec, s[68:69]
	s_cbranch_execz .LBB0_1265
	v_add_u32_e32 v0, 0xffffbf80, v218
	s_movk_i32 s14, 0x5800
	v_mad_u64_u32 v[2:3], s[70:71], v0, s14, v[164:165]
	v_add_co_u32_e32 v152, vcc, 0x2000, v2
	s_nop 1
	v_addc_co_u32_e32 v153, vcc, 0, v3, vcc
	global_load_dwordx4 v[152:155], v[152:153], off offset:3072
	s_nop 0
	global_load_dwordx4 v[156:159], v[2:3], off
	v_mad_u64_u32 v[2:3], s[70:71], v0, s14, v[162:163]
	v_add_co_u32_e32 v196, vcc, 0x2000, v2
	s_nop 1
	v_addc_co_u32_e32 v197, vcc, 0, v3, vcc
	s_waitcnt vmcnt(0)
	global_store_dwordx4 v[2:3], v[152:155], off nt
	global_store_dwordx4 v[196:197], v[148:151], off offset:3072 nt

;     __device__ __forceinline__ void operator()(const f32x4 (&acc)[2][2][4][2], const Unit& u, int wr, int wc, int fr, int fq) const {
;     ...
;                         if (l >= 2 && row < M) {
;                             if (row < MP) {
;                                 const int b = row / TP, t = row - b * TP;
;                                 if (t < 2) { g2 = (f32x4){0.f, 0.f, 0.f, 0.f}; if (t == 0) g1 = g2; }
;                                 if (t >= TP - 2) *(f32x4*)(cvp + ((size_t)b * 2 + (t - (TP - 2))) * DFF + f0) = cur;
.LBB0_1270:
	s_or_b64 exec, exec, s[70:71]
	s_movk_i32 s14, 0x80d
	v_cmp_lt_i32_e32 vcc, s14, v204
	s_and_saveexec_b64 s[70:71], vcc
	s_cbranch_execz .LBB0_1272
	v_ashrrev_i32_e32 v197, 31, v196
	v_add_u32_e32 v0, 0xfffff7f2, v204
	v_lshl_add_u64 v[2:3], v[196:197], 1, v[0:1]
	s_movk_i32 s14, 0x2c00
	v_mad_u64_u32 v[196:197], s[72:73], v2, s14, v[160:161]
	v_mad_i32_i24 v197, v3, s14, v197
	global_store_dwordx4 v[196:197], v[148:151], off nt

; #define LAS __attribute__((address_space(3)))
;     __device__ __forceinline__ void operator()(const f32x4 (&acc)[2][2][4][2], const Unit& u, int wr, int wc, int fr, int fq) const {
;     ...
;                         const int l = 128 * ai + 64 * wr + 16 * m + frL, row = 254 * u.pm - 2 + l;
;                         const float rs = rt[l];
;                         const f32x4 cur = acc[ai][1][m][n] * rs, uu = acc[ai][0][m][n] * rs;
;                         if (m == 0) {
;                             const int B = 2 * ai + wr;
;                             prev = (f32x4){0.f, 0.f, 0.f, 0.f};
;                             if (B > 0 && frL >= 14) prev = *(const LAS f32x4*)(halo + ((B - 1) * 2 + (frL - 14)) * 128 + fl + 4 * n);
;                         }
;                         f32x4 g1, g2;
;                         {
;                             const float c1x = dpp_ror1(cur.x), c1y = dpp_ror1(cur.y), c1z = dpp_ror1(cur.z), c1w = dpp_ror1(cur.w);
;                             const float p1x = dpp_ror1(prev.x), p1y = dpp_ror1(prev.y), p1z = dpp_ror1(prev.z), p1w = dpp_ror1(prev.w);
;                             const float c2x = dpp_ror2(cur.x), c2y = dpp_ror2(cur.y), c2z = dpp_ror2(cur.z), c2w = dpp_ror2(cur.w);
;                             const float p2x = dpp_ror2(prev.x), p2y = dpp_ror2(prev.y), p2z = dpp_ror2(prev.z), p2w = dpp_ror2(prev.w);
;                             const bool s1 = frL >= 1, s2 = frL >= 2;
;                             g1.x = s1 ? c1x : p1x; g1.y = s1 ? c1y : p1y; g1.z = s1 ? c1z : p1z; g1.w = s1 ? c1w : p1w;
;                             g2.x = s2 ? c2x : p2x; g2.y = s2 ? c2y : p2y; g2.z = s2 ? c2z : p2z; g2.w = s2 ? c2w : p2w;
;                         }
;                         if (l >= 2 && row < M) {
;                             if (row < MP) {
;                                 const int b = row / TP, t = row - b * TP;
;                                 if (t < 2) { g2 = (f32x4){0.f, 0.f, 0.f, 0.f}; if (t == 0) g1 = g2; }
;                                 if (t >= TP - 2) *(f32x4*)(cvp + ((size_t)b * 2 + (t - (TP - 2))) * DFF + f0) = cur;
;                             } else {
;                                 const int s = row - MP;
;                                 const float* c0 = cst + ((size_t)s * 2 + 0) * DFF + f0;
;                                 g2 = *(const f32x4*)c0; g1 = *(const f32x4*)(c0 + DFF);
.LBB0_1273:
	s_or_b64 exec, exec, s[68:69]
	s_waitcnt vmcnt(0)
	v_pk_fma_f32 v[156:157], v[140:141], v[156:157], v[144:145]
	v_pk_fma_f32 v[158:159], v[142:143], v[158:159], v[146:147]
	v_pk_fma_f32 v[152:153], v[136:137], v[152:153], v[156:157]
	v_pk_fma_f32 v[154:155], v[138:139], v[154:155], v[158:159]
	v_pk_fma_f32 v[152:153], v[132:133], v[148:149], v[152:153]
	v_pk_fma_f32 v[154:155], v[134:135], v[150:151], v[154:155]
	v_mul_f32_e32 v0, 0xbfb8aa3b, v152
	v_mul_f32_e32 v156, 0xbfb8aa3b, v153
	v_exp_f32_e32 v0, v0
	v_exp_f32_e32 v156, v156
	v_pk_mul_f32 v[196:197], v[28:29], v[192:193]
	v_mov_b32_e32 v2, v192
	v_add_f32_e32 v0, 1.0, v0
	v_add_f32_e32 v156, 1.0, v156
	v_rcp_f32_e32 v0, v0
	v_rcp_f32_e32 v156, v156
	v_mov_b32_e32 v3, v192
	v_pk_mul_f32 v[2:3], v[30:31], v[2:3]
	v_mul_f32_e32 v0, v152, v0
	v_mul_f32_e32 v152, v153, v156
	v_mul_f32_e32 v153, 0xbfb8aa3b, v154
	v_exp_f32_e32 v153, v153
	v_mul_f32_e32 v156, 0xbfb8aa3b, v155
	v_exp_f32_e32 v156, v156
	v_mul_f32_e32 v0, v196, v0
	v_add_f32_e32 v153, 1.0, v153
	v_rcp_f32_e32 v153, v153
	v_add_f32_e32 v156, 1.0, v156
	v_rcp_f32_e32 v156, v156
	v_mul_f32_e32 v152, v197, v152
	v_cvt_pk_bf16_f32 v152, v0, v152
	v_mul_f32_e32 v0, v154, v153
	v_mul_f32_e32 v0, v2, v0
	v_mul_f32_e32 v2, v155, v156
	v_mul_f32_e32 v2, v3, v2
	s_movk_i32 s14, 0x1600
	v_cvt_pk_bf16_f32 v153, v0, v2
	v_mad_i64_i32 v[2:3], s[68:69], v218, s14, v[202:203]
	global_store_dwordx2 v[2:3], v[152:153], off nt
.LBB0_1274:
	s_or_b64 exec, exec, s[0:1]
	ds_read_b32 v196, v209 offset:704
	s_add_i32 s0, s21, 0xae
	v_add_u32_e32 v156, 0xb0, v211
	v_add_u32_e32 v219, s0, v211
	s_movk_i32 s0, 0x4100
	s_waitcnt lgkmcnt(0)
	v_mov_b32_e32 v197, v196
	v_pk_mul_f32 v[154:155], v[18:19], v[196:197] op_sel_hi:[1,0]
	v_pk_mul_f32 v[152:153], v[16:17], v[196:197] op_sel_hi:[1,0]
	v_mov_b32_e32 v0, v1
	v_mov_b32_e32 v2, v1
	v_mov_b32_e32 v3, v1
	v_mov_b32_e32 v204, v1
	v_mov_b32_e32 v205, v1
	v_mov_b32_e32 v239, v1
	v_mov_b32_e32 v240, v1
	v_mov_b32_e32 v242, v1
	v_mov_b32_e32 v241, v1
	v_mov_b32_e32 v243, v1
	v_mov_b32_e32 v244, v1
	v_mov_b32_e32 v245, v1
	v_mov_b32_e32 v246, v1
	v_mov_b32_e32 v247, v1
	v_mov_b32_e32 v248, v1
	v_mov_b32_e32 v249, v1
	v_cmp_lt_i32_e32 vcc, 1, v156
	v_cmp_gt_i32_e64 s[0:1], s0, v219
	v_mov_b32_dpp v0, v152 row_ror:1 row_mask:0xf bank_mask:0xf
	v_mov_b32_dpp v2, v153 row_ror:1 row_mask:0xf bank_mask:0xf
	v_mov_b32_dpp v3, v154 row_ror:1 row_mask:0xf bank_mask:0xf
	v_mov_b32_dpp v204, v155 row_ror:1 row_mask:0xf bank_mask:0xf
	v_mov_b32_dpp v205, v148 row_ror:1 row_mask:0xf bank_mask:0xf
	v_mov_b32_dpp v239, v149 row_ror:1 row_mask:0xf bank_mask:0xf
	v_mov_b32_dpp v240, v150 row_ror:1 row_mask:0xf bank_mask:0xf
	v_mov_b32_dpp v242, v151 row_ror:1 row_mask:0xf bank_mask:0xf
	v_mov_b32_dpp v241, v152 row_ror:2 row_mask:0xf bank_mask:0xf
	v_mov_b32_dpp v243, v153 row_ror:2 row_mask:0xf bank_mask:0xf
	v_mov_b32_dpp v244, v154 row_ror:2 row_mask:0xf bank_mask:0xf
	v_mov_b32_dpp v245, v155 row_ror:2 row_mask:0xf bank_mask:0xf
	v_mov_b32_dpp v246, v148 row_ror:2 row_mask:0xf bank_mask:0xf
	v_mov_b32_dpp v247, v149 row_ror:2 row_mask:0xf bank_mask:0xf
	v_mov_b32_dpp v248, v150 row_ror:2 row_mask:0xf bank_mask:0xf
	v_mov_b32_dpp v249, v151 row_ror:2 row_mask:0xf bank_mask:0xf
	s_and_b64 s[0:1], vcc, s[0:1]
	s_and_saveexec_b64 s[68:69], s[0:1]
	s_cbranch_execz .LBB0_1286
	s_movk_i32 s14, 0x407f
	v_cmp_lt_i32_e32 vcc, s14, v219
	s_and_saveexec_b64 s[70:71], vcc
	s_xor_b64 s[70:71], exec, s[70:71]
	s_cbranch_execz .LBB0_1277
	v_add_u32_e32 v0, 0xffffbf80, v219
	s_movk_i32 s14, 0x5800
	v_mad_u64_u32 v[2:3], s[72:73], v0, s14, v[164:165]
	v_add_co_u32_e32 v148, vcc, 0x2000, v2
	s_nop 1
	v_addc_co_u32_e32 v149, vcc, 0, v3, vcc
	global_load_dwordx4 v[148:151], v[148:149], off offset:3072
	s_nop 0
	global_load_dwordx4 v[156:159], v[2:3], off
	v_mad_u64_u32 v[2:3], s[72:73], v0, s14, v[162:163]
	v_add_co_u32_e32 v204, vcc, 0x2000, v2
	s_nop 1
	v_addc_co_u32_e32 v205, vcc, 0, v3, vcc
	s_waitcnt vmcnt(0)
	global_store_dwordx4 v[2:3], v[148:151], off nt
	global_store_dwordx4 v[204:205], v[152:155], off offset:3072 nt

;     __device__ __forceinline__ void operator()(const f32x4 (&acc)[2][2][4][2], const Unit& u, int wr, int wc, int fr, int fq) const {
;     ...
;                         if (l >= 2 && row < M) {
;                             if (row < MP) {
;                                 const int b = row / TP, t = row - b * TP;
;                                 if (t < 2) { g2 = (f32x4){0.f, 0.f, 0.f, 0.f}; if (t == 0) g1 = g2; }
;                                 if (t >= TP - 2) *(f32x4*)(cvp + ((size_t)b * 2 + (t - (TP - 2))) * DFF + f0) = cur;
.LBB0_1282:
	s_or_b64 exec, exec, s[72:73]
	s_movk_i32 s14, 0x80d
	v_cmp_lt_i32_e32 vcc, s14, v239
	s_and_saveexec_b64 s[72:73], vcc
	s_cbranch_execz .LBB0_1284
	v_ashrrev_i32_e32 v205, 31, v204
	v_add_u32_e32 v0, 0xfffff7f2, v239
	v_lshl_add_u64 v[2:3], v[204:205], 1, v[0:1]
	s_movk_i32 s14, 0x2c00
	v_mad_u64_u32 v[204:205], s[74:75], v2, s14, v[160:161]
	v_mad_i32_i24 v205, v3, s14, v205
	global_store_dwordx4 v[204:205], v[152:155], off nt

; #define LAS __attribute__((address_space(3)))
;     __device__ __forceinline__ void operator()(const f32x4 (&acc)[2][2][4][2], const Unit& u, int wr, int wc, int fr, int fq) const {
;     ...
;                         const int l = 128 * ai + 64 * wr + 16 * m + frL, row = 254 * u.pm - 2 + l;
;                         const float rs = rt[l];
;                         const f32x4 cur = acc[ai][1][m][n] * rs, uu = acc[ai][0][m][n] * rs;
;                         if (m == 0) {
;                             const int B = 2 * ai + wr;
;                             prev = (f32x4){0.f, 0.f, 0.f, 0.f};
;                             if (B > 0 && frL >= 14) prev = *(const LAS f32x4*)(halo + ((B - 1) * 2 + (frL - 14)) * 128 + fl + 4 * n);
;                         }
;                         f32x4 g1, g2;
;                         {
;                             const float c1x = dpp_ror1(cur.x), c1y = dpp_ror1(cur.y), c1z = dpp_ror1(cur.z), c1w = dpp_ror1(cur.w);
;                             const float p1x = dpp_ror1(prev.x), p1y = dpp_ror1(prev.y), p1z = dpp_ror1(prev.z), p1w = dpp_ror1(prev.w);
;                             const float c2x = dpp_ror2(cur.x), c2y = dpp_ror2(cur.y), c2z = dpp_ror2(cur.z), c2w = dpp_ror2(cur.w);
;                             const float p2x = dpp_ror2(prev.x), p2y = dpp_ror2(prev.y), p2z = dpp_ror2(prev.z), p2w = dpp_ror2(prev.w);
;                             const bool s1 = frL >= 1, s2 = frL >= 2;
;                             g1.x = s1 ? c1x : p1x; g1.y = s1 ? c1y : p1y; g1.z = s1 ? c1z : p1z; g1.w = s1 ? c1w : p1w;
;                             g2.x = s2 ? c2x : p2x; g2.y = s2 ? c2y : p2y; g2.z = s2 ? c2z : p2z; g2.w = s2 ? c2w : p2w;
;                         }
;                         if (l >= 2 && row < M) {
;                             if (row < MP) {
;                                 const int b = row / TP, t = row - b * TP;
;                                 if (t < 2) { g2 = (f32x4){0.f, 0.f, 0.f, 0.f}; if (t == 0) g1 = g2; }
;                                 if (t >= TP - 2) *(f32x4*)(cvp + ((size_t)b * 2 + (t - (TP - 2))) * DFF + f0) = cur;
;                             } else {
;                                 const int s = row - MP;
;                                 const float* c0 = cst + ((size_t)s * 2 + 0) * DFF + f0;
;                                 g2 = *(const f32x4*)c0; g1 = *(const f32x4*)(c0 + DFF);
.LBB0_1285:
	s_or_b64 exec, exec, s[70:71]
	s_waitcnt vmcnt(0)
	v_pk_fma_f32 v[140:141], v[140:141], v[156:157], v[144:145]
	v_pk_fma_f32 v[142:143], v[142:143], v[158:159], v[146:147]
	v_pk_fma_f32 v[136:137], v[136:137], v[148:149], v[140:141]
	v_pk_mul_f32 v[204:205], v[12:13], v[196:197]
	v_pk_fma_f32 v[132:133], v[132:133], v[152:153], v[136:137]
	v_mov_b32_e32 v2, v196
	v_mul_f32_e32 v0, 0xbfb8aa3b, v132
	v_mul_f32_e32 v136, 0xbfb8aa3b, v133
	v_exp_f32_e32 v0, v0
	v_exp_f32_e32 v140, v136
	v_pk_fma_f32 v[136:137], v[138:139], v[150:151], v[142:143]
	v_mov_b32_e32 v3, v196
	v_add_f32_e32 v0, 1.0, v0
	v_add_f32_e32 v138, 1.0, v140
	v_rcp_f32_e32 v0, v0
	v_rcp_f32_e32 v138, v138
	v_pk_fma_f32 v[134:135], v[134:135], v[154:155], v[136:137]
	v_pk_mul_f32 v[2:3], v[14:15], v[2:3]
	v_mul_f32_e32 v0, v132, v0
	v_mul_f32_e32 v132, v133, v138
	v_mul_f32_e32 v133, 0xbfb8aa3b, v134
	v_exp_f32_e32 v133, v133
	v_mul_f32_e32 v136, 0xbfb8aa3b, v135
	v_exp_f32_e32 v136, v136
	v_mul_f32_e32 v0, v204, v0
	v_add_f32_e32 v133, 1.0, v133
	v_rcp_f32_e32 v133, v133
	v_add_f32_e32 v136, 1.0, v136
	v_rcp_f32_e32 v136, v136
	v_mul_f32_e32 v132, v205, v132
	v_cvt_pk_bf16_f32 v132, v0, v132
	v_mul_f32_e32 v0, v134, v133
	v_mul_f32_e32 v0, v2, v0
	v_mul_f32_e32 v2, v135, v136
	v_mul_f32_e32 v2, v3, v2
	s_movk_i32 s14, 0x1600
	v_cvt_pk_bf16_f32 v133, v0, v2
	v_mad_i64_i32 v[2:3], s[70:71], v219, s14, v[202:203]
	global_store_dwordx2 v[2:3], v[132:133], off nt
.LBB0_1286:
	s_or_b64 exec, exec, s[68:69]
	v_or_b32_e32 v202, 4, v184
	v_ashrrev_i32_e32 v203, 31, v202
	v_lshlrev_b64 v[2:3], 2, v[202:203]
	s_waitcnt vmcnt(0)
	v_lshl_add_u64 v[132:133], s[44:45], 0, v[2:3]
	global_load_dwordx4 v[140:143], v[198:199], off offset:16
	v_lshl_add_u64 v[2:3], s[46:47], 0, v[2:3]
	global_load_dwordx4 v[136:139], v[132:133], off
	s_nop 0
	global_load_dwordx4 v[132:135], v[2:3], off
	global_load_dwordx4 v[144:147], v[200:201], off offset:16
	v_mov_b32_e32 v152, 0
	v_mov_b32_e32 v153, 0
	v_mov_b32_e32 v154, 0
	v_mov_b32_e32 v155, 0
	s_and_saveexec_b64 s[68:69], s[52:53]
	ds_read_b128 v[152:155], v220 offset:16
	s_or_b64 exec, exec, s[68:69]
	v_mov_b32_e32 v2, v166
	v_mov_b32_e32 v3, v166
	v_pk_mul_f32 v[150:151], v[122:123], v[2:3]
	v_pk_mul_f32 v[148:149], v[120:121], v[166:167]
	v_mov_b32_e32 v0, v1
	v_mov_b32_e32 v2, v1
	v_mov_b32_e32 v3, v1
	v_mov_b32_e32 v198, v1
	v_mov_b32_e32 v199, v1
	v_mov_b32_e32 v200, v1
	v_mov_b32_e32 v201, v1
	v_mov_b32_e32 v205, v1
	v_mov_b32_e32 v204, v1
	v_mov_b32_e32 v220, v1
	v_mov_b32_e32 v239, v1
	v_mov_b32_e32 v240, v1
	v_mov_b32_e32 v241, v1
	v_mov_b32_e32 v242, v1
	v_mov_b32_e32 v243, v1
	v_mov_b32_e32 v244, v1
	v_mov_b32_dpp v0, v148 row_ror:1 row_mask:0xf bank_mask:0xf
	v_mov_b32_dpp v2, v149 row_ror:1 row_mask:0xf bank_mask:0xf
	v_mov_b32_dpp v3, v150 row_ror:1 row_mask:0xf bank_mask:0xf
	v_mov_b32_dpp v198, v151 row_ror:1 row_mask:0xf bank_mask:0xf
	s_waitcnt lgkmcnt(0)
	v_mov_b32_dpp v199, v152 row_ror:1 row_mask:0xf bank_mask:0xf
	v_mov_b32_dpp v200, v153 row_ror:1 row_mask:0xf bank_mask:0xf
	v_mov_b32_dpp v201, v154 row_ror:1 row_mask:0xf bank_mask:0xf
	v_mov_b32_dpp v205, v155 row_ror:1 row_mask:0xf bank_mask:0xf
	v_mov_b32_dpp v204, v148 row_ror:2 row_mask:0xf bank_mask:0xf
	v_mov_b32_dpp v220, v149 row_ror:2 row_mask:0xf bank_mask:0xf
	v_mov_b32_dpp v239, v150 row_ror:2 row_mask:0xf bank_mask:0xf
	v_mov_b32_dpp v240, v151 row_ror:2 row_mask:0xf bank_mask:0xf
	v_mov_b32_dpp v241, v152 row_ror:2 row_mask:0xf bank_mask:0xf
	v_mov_b32_dpp v242, v153 row_ror:2 row_mask:0xf bank_mask:0xf
	v_mov_b32_dpp v243, v154 row_ror:2 row_mask:0xf bank_mask:0xf
	v_mov_b32_dpp v244, v155 row_ror:2 row_mask:0xf bank_mask:0xf
	s_and_saveexec_b64 s[52:53], s[54:55]
	s_cbranch_execz .LBB0_1300
	s_movk_i32 s14, 0x407f
	v_cmp_lt_i32_e32 vcc, s14, v185
	s_and_saveexec_b64 s[54:55], vcc
	s_xor_b64 s[54:55], exec, s[54:55]
	s_cbranch_execz .LBB0_1291
	v_add_u32_e32 v0, 0xffffbf80, v185
	s_movk_i32 s14, 0x5800
	v_mad_u64_u32 v[2:3], s[68:69], v0, s14, v[164:165]
	v_add_co_u32_e32 v152, vcc, 0x2000, v2
	s_nop 1
	v_addc_co_u32_e32 v153, vcc, 0, v3, vcc
	global_load_dwordx4 v[152:155], v[152:153], off offset:3088
	s_nop 0
	global_load_dwordx4 v[156:159], v[2:3], off offset:16
	v_mad_u64_u32 v[2:3], s[68:69], v0, s14, v[162:163]
	v_add_co_u32_e32 v198, vcc, 0x2000, v2
	s_nop 1
	v_addc_co_u32_e32 v199, vcc, 0, v3, vcc
	s_waitcnt vmcnt(1)
	global_store_dwordx4 v[2:3], v[152:155], off offset:16 nt
	global_store_dwordx4 v[198:199], v[148:151], off offset:3088 nt

;     __device__ __forceinline__ void operator()(const f32x4 (&acc)[2][2][4][2], const Unit& u, int wr, int wc, int fr, int fq) const {
;     ...
;                         if (l >= 2 && row < M) {
;                             if (row < MP) {
;                                 const int b = row / TP, t = row - b * TP;
;                                 if (t < 2) { g2 = (f32x4){0.f, 0.f, 0.f, 0.f}; if (t == 0) g1 = g2; }
;                                 if (t >= TP - 2) *(f32x4*)(cvp + ((size_t)b * 2 + (t - (TP - 2))) * DFF + f0) = cur;
.LBB0_1296:
	s_or_b64 exec, exec, s[68:69]
	s_movk_i32 s14, 0x80d
	v_cmp_lt_i32_e32 vcc, s14, v200
	s_and_saveexec_b64 s[68:69], vcc
	s_cbranch_execz .LBB0_1298
	v_ashrrev_i32_e32 v199, 31, v198
	v_add_u32_e32 v0, 0xfffff7f2, v200
	v_lshl_add_u64 v[2:3], v[198:199], 1, v[0:1]
	s_movk_i32 s14, 0x2c00
	v_mad_u64_u32 v[198:199], s[70:71], v2, s14, v[160:161]
	v_mad_i32_i24 v199, v3, s14, v199
	global_store_dwordx4 v[198:199], v[148:151], off offset:16 nt

; #define LAS __attribute__((address_space(3)))
;     __device__ __forceinline__ void operator()(const f32x4 (&acc)[2][2][4][2], const Unit& u, int wr, int wc, int fr, int fq) const {
;     ...
;                         const int l = 128 * ai + 64 * wr + 16 * m + frL, row = 254 * u.pm - 2 + l;
;                         const float rs = rt[l];
;                         const f32x4 cur = acc[ai][1][m][n] * rs, uu = acc[ai][0][m][n] * rs;
;                         if (m == 0) {
;                             const int B = 2 * ai + wr;
;                             prev = (f32x4){0.f, 0.f, 0.f, 0.f};
;                             if (B > 0 && frL >= 14) prev = *(const LAS f32x4*)(halo + ((B - 1) * 2 + (frL - 14)) * 128 + fl + 4 * n);
;                         }
;                         f32x4 g1, g2;
;                         {
;                             const float c1x = dpp_ror1(cur.x), c1y = dpp_ror1(cur.y), c1z = dpp_ror1(cur.z), c1w = dpp_ror1(cur.w);
;                             const float p1x = dpp_ror1(prev.x), p1y = dpp_ror1(prev.y), p1z = dpp_ror1(prev.z), p1w = dpp_ror1(prev.w);
;                             const float c2x = dpp_ror2(cur.x), c2y = dpp_ror2(cur.y), c2z = dpp_ror2(cur.z), c2w = dpp_ror2(cur.w);
;                             const float p2x = dpp_ror2(prev.x), p2y = dpp_ror2(prev.y), p2z = dpp_ror2(prev.z), p2w = dpp_ror2(prev.w);
;                             const bool s1 = frL >= 1, s2 = frL >= 2;
;                             g1.x = s1 ? c1x : p1x; g1.y = s1 ? c1y : p1y; g1.z = s1 ? c1z : p1z; g1.w = s1 ? c1w : p1w;
;                             g2.x = s2 ? c2x : p2x; g2.y = s2 ? c2y : p2y; g2.z = s2 ? c2z : p2z; g2.w = s2 ? c2w : p2w;
;                         }
;                         if (l >= 2 && row < M) {
;                             if (row < MP) {
;                                 const int b = row / TP, t = row - b * TP;
;                                 if (t < 2) { g2 = (f32x4){0.f, 0.f, 0.f, 0.f}; if (t == 0) g1 = g2; }
;                                 if (t >= TP - 2) *(f32x4*)(cvp + ((size_t)b * 2 + (t - (TP - 2))) * DFF + f0) = cur;
;                             } else {
;                                 const int s = row - MP;
;                                 const float* c0 = cst + ((size_t)s * 2 + 0) * DFF + f0;
;                                 g2 = *(const f32x4*)c0; g1 = *(const f32x4*)(c0 + DFF);
.LBB0_1299:
	s_or_b64 exec, exec, s[54:55]
	s_waitcnt vmcnt(0)
	v_pk_fma_f32 v[156:157], v[140:141], v[156:157], v[144:145]
	v_pk_fma_f32 v[158:159], v[142:143], v[158:159], v[146:147]
	v_pk_fma_f32 v[152:153], v[136:137], v[152:153], v[156:157]
	v_pk_fma_f32 v[154:155], v[138:139], v[154:155], v[158:159]
	v_pk_fma_f32 v[152:153], v[148:149], v[132:133], v[152:153]
	v_pk_fma_f32 v[154:155], v[150:151], v[134:135], v[154:155]
	v_mul_f32_e32 v0, 0xbfb8aa3b, v152
	v_mul_f32_e32 v156, 0xbfb8aa3b, v153
	v_exp_f32_e32 v0, v0
	v_exp_f32_e32 v156, v156
	v_mov_b32_e32 v2, v166
	v_mov_b32_e32 v3, v166
	v_add_f32_e32 v0, 1.0, v0
	v_add_f32_e32 v156, 1.0, v156
	v_rcp_f32_e32 v0, v0
	v_rcp_f32_e32 v156, v156
	v_pk_mul_f32 v[166:167], v[116:117], v[166:167]
	v_pk_mul_f32 v[2:3], v[118:119], v[2:3]
	v_mul_f32_e32 v0, v152, v0
	v_mul_f32_e32 v152, v153, v156
	v_mul_f32_e32 v153, 0xbfb8aa3b, v154
	v_exp_f32_e32 v153, v153
	v_mul_f32_e32 v156, 0xbfb8aa3b, v155
	v_exp_f32_e32 v156, v156
	v_mul_f32_e32 v0, v166, v0
	v_add_f32_e32 v153, 1.0, v153
	v_rcp_f32_e32 v153, v153
	v_add_f32_e32 v156, 1.0, v156
	v_rcp_f32_e32 v156, v156
	v_mul_f32_e32 v152, v167, v152
	v_cvt_pk_bf16_f32 v152, v0, v152
	v_mul_f32_e32 v0, v154, v153
	v_mul_f32_e32 v0, v2, v0
	v_mul_f32_e32 v2, v155, v156
	v_readlane_b32 s54, v252, 8
	v_mul_f32_e32 v2, v3, v2
	v_readlane_b32 s55, v252, 9
	v_cvt_pk_bf16_f32 v153, v0, v2
	s_movk_i32 s14, 0x1600
	s_nop 0
	v_mov_b64_e32 v[2:3], s[54:55]
	v_mad_i64_i32 v[2:3], s[54:55], v185, s14, v[2:3]
	v_lshl_add_u64 v[2:3], v[202:203], 1, v[2:3]
	global_store_dwordx2 v[2:3], v[152:153], off nt
.LBB0_1300:
	s_or_b64 exec, exec, s[52:53]
	v_mov_b32_e32 v2, v168
	v_mov_b32_e32 v3, v168
	v_pk_mul_f32 v[154:155], v[106:107], v[2:3]
	v_pk_mul_f32 v[152:153], v[104:105], v[168:169]
	v_mov_b32_e32 v0, v1
	v_mov_b32_e32 v2, v1
	v_mov_b32_e32 v3, v1
	v_mov_b32_e32 v166, v1
	v_mov_b32_e32 v167, v1
	v_mov_b32_e32 v185, v1
	v_mov_b32_e32 v198, v1
	v_mov_b32_e32 v200, v1
	v_mov_b32_e32 v199, v1
	v_mov_b32_e32 v201, v1
	v_mov_b32_e32 v204, v1
	v_mov_b32_e32 v205, v1
	v_mov_b32_e32 v220, v1
	v_mov_b32_e32 v239, v1
	v_mov_b32_e32 v240, v1
	v_mov_b32_e32 v241, v1
	v_mov_b32_dpp v0, v152 row_ror:1 row_mask:0xf bank_mask:0xf
	v_mov_b32_dpp v2, v153 row_ror:1 row_mask:0xf bank_mask:0xf
	v_mov_b32_dpp v3, v154 row_ror:1 row_mask:0xf bank_mask:0xf
	v_mov_b32_dpp v166, v155 row_ror:1 row_mask:0xf bank_mask:0xf
	v_mov_b32_dpp v167, v148 row_ror:1 row_mask:0xf bank_mask:0xf
	v_mov_b32_dpp v185, v149 row_ror:1 row_mask:0xf bank_mask:0xf
	v_mov_b32_dpp v198, v150 row_ror:1 row_mask:0xf bank_mask:0xf
	v_mov_b32_dpp v200, v151 row_ror:1 row_mask:0xf bank_mask:0xf
	v_mov_b32_dpp v199, v152 row_ror:2 row_mask:0xf bank_mask:0xf
	v_mov_b32_dpp v201, v153 row_ror:2 row_mask:0xf bank_mask:0xf
	v_mov_b32_dpp v204, v154 row_ror:2 row_mask:0xf bank_mask:0xf
	v_mov_b32_dpp v205, v155 row_ror:2 row_mask:0xf bank_mask:0xf
	v_mov_b32_dpp v220, v148 row_ror:2 row_mask:0xf bank_mask:0xf
	v_mov_b32_dpp v239, v149 row_ror:2 row_mask:0xf bank_mask:0xf
	v_mov_b32_dpp v240, v150 row_ror:2 row_mask:0xf bank_mask:0xf
	v_mov_b32_dpp v241, v151 row_ror:2 row_mask:0xf bank_mask:0xf
	s_and_saveexec_b64 s[52:53], s[56:57]
	s_cbranch_execz .LBB0_1312
	s_movk_i32 s14, 0x407f
	v_cmp_lt_i32_e32 vcc, s14, v213
	s_and_saveexec_b64 s[54:55], vcc
	s_xor_b64 s[54:55], exec, s[54:55]
	s_cbranch_execz .LBB0_1303
	v_add_u32_e32 v0, 0xffffbf80, v213
	s_movk_i32 s14, 0x5800
	v_mad_u64_u32 v[2:3], s[56:57], v0, s14, v[164:165]
	v_add_co_u32_e32 v148, vcc, 0x2000, v2
	s_nop 1
	v_addc_co_u32_e32 v149, vcc, 0, v3, vcc
	global_load_dwordx4 v[148:151], v[148:149], off offset:3088
	s_nop 0
	global_load_dwordx4 v[156:159], v[2:3], off offset:16
	v_mad_u64_u32 v[2:3], s[56:57], v0, s14, v[162:163]
	v_add_co_u32_e32 v166, vcc, 0x2000, v2
	s_nop 1
	v_addc_co_u32_e32 v167, vcc, 0, v3, vcc
	s_waitcnt vmcnt(1)
	global_store_dwordx4 v[2:3], v[148:151], off offset:16 nt
	global_store_dwordx4 v[166:167], v[152:155], off offset:3088 nt

;     __device__ __forceinline__ void operator()(const f32x4 (&acc)[2][2][4][2], const Unit& u, int wr, int wc, int fr, int fq) const {
;     ...
;                         if (l >= 2 && row < M) {
;                             if (row < MP) {
;                                 const int b = row / TP, t = row - b * TP;
;                                 if (t < 2) { g2 = (f32x4){0.f, 0.f, 0.f, 0.f}; if (t == 0) g1 = g2; }
;                                 if (t >= TP - 2) *(f32x4*)(cvp + ((size_t)b * 2 + (t - (TP - 2))) * DFF + f0) = cur;
.LBB0_1308:
	s_or_b64 exec, exec, s[56:57]
	s_movk_i32 s14, 0x80d
	v_cmp_lt_i32_e32 vcc, s14, v185
	s_and_saveexec_b64 s[56:57], vcc
	s_cbranch_execz .LBB0_1310
	v_ashrrev_i32_e32 v167, 31, v166
	v_add_u32_e32 v0, 0xfffff7f2, v185
	v_lshl_add_u64 v[2:3], v[166:167], 1, v[0:1]
	s_movk_i32 s14, 0x2c00
	v_mad_u64_u32 v[166:167], s[68:69], v2, s14, v[160:161]
	v_mad_i32_i24 v167, v3, s14, v167
	global_store_dwordx4 v[166:167], v[152:155], off offset:16 nt

; #define LAS __attribute__((address_space(3)))
;     __device__ __forceinline__ void operator()(const f32x4 (&acc)[2][2][4][2], const Unit& u, int wr, int wc, int fr, int fq) const {
;     ...
;                         const int l = 128 * ai + 64 * wr + 16 * m + frL, row = 254 * u.pm - 2 + l;
;                         const float rs = rt[l];
;                         const f32x4 cur = acc[ai][1][m][n] * rs, uu = acc[ai][0][m][n] * rs;
;                         if (m == 0) {
;                             const int B = 2 * ai + wr;
;                             prev = (f32x4){0.f, 0.f, 0.f, 0.f};
;                             if (B > 0 && frL >= 14) prev = *(const LAS f32x4*)(halo + ((B - 1) * 2 + (frL - 14)) * 128 + fl + 4 * n);
;                         }
;                         f32x4 g1, g2;
;                         {
;                             const float c1x = dpp_ror1(cur.x), c1y = dpp_ror1(cur.y), c1z = dpp_ror1(cur.z), c1w = dpp_ror1(cur.w);
;                             const float p1x = dpp_ror1(prev.x), p1y = dpp_ror1(prev.y), p1z = dpp_ror1(prev.z), p1w = dpp_ror1(prev.w);
;                             const float c2x = dpp_ror2(cur.x), c2y = dpp_ror2(cur.y), c2z = dpp_ror2(cur.z), c2w = dpp_ror2(cur.w);
;                             const float p2x = dpp_ror2(prev.x), p2y = dpp_ror2(prev.y), p2z = dpp_ror2(prev.z), p2w = dpp_ror2(prev.w);
;                             const bool s1 = frL >= 1, s2 = frL >= 2;
;                             g1.x = s1 ? c1x : p1x; g1.y = s1 ? c1y : p1y; g1.z = s1 ? c1z : p1z; g1.w = s1 ? c1w : p1w;
;                             g2.x = s2 ? c2x : p2x; g2.y = s2 ? c2y : p2y; g2.z = s2 ? c2z : p2z; g2.w = s2 ? c2w : p2w;
;                         }
;                         if (l >= 2 && row < M) {
;                             if (row < MP) {
;                                 const int b = row / TP, t = row - b * TP;
;                                 if (t < 2) { g2 = (f32x4){0.f, 0.f, 0.f, 0.f}; if (t == 0) g1 = g2; }
;                                 if (t >= TP - 2) *(f32x4*)(cvp + ((size_t)b * 2 + (t - (TP - 2))) * DFF + f0) = cur;
;                             } else {
;                                 const int s = row - MP;
;                                 const float* c0 = cst + ((size_t)s * 2 + 0) * DFF + f0;
;                                 g2 = *(const f32x4*)c0; g1 = *(const f32x4*)(c0 + DFF);
.LBB0_1311:
	s_or_b64 exec, exec, s[54:55]
	s_waitcnt vmcnt(0)
	v_pk_fma_f32 v[156:157], v[140:141], v[156:157], v[144:145]
	v_pk_fma_f32 v[158:159], v[142:143], v[158:159], v[146:147]
	v_pk_fma_f32 v[148:149], v[136:137], v[148:149], v[156:157]
	v_pk_fma_f32 v[150:151], v[138:139], v[150:151], v[158:159]
	v_pk_fma_f32 v[148:149], v[152:153], v[132:133], v[148:149]
	v_pk_fma_f32 v[150:151], v[154:155], v[134:135], v[150:151]
	v_mul_f32_e32 v0, 0xbfb8aa3b, v148
	v_mul_f32_e32 v156, 0xbfb8aa3b, v149
	v_exp_f32_e32 v0, v0
	v_exp_f32_e32 v156, v156
	v_pk_mul_f32 v[166:167], v[100:101], v[168:169]
	v_mov_b32_e32 v2, v168
	v_add_f32_e32 v0, 1.0, v0
	v_add_f32_e32 v156, 1.0, v156
	v_rcp_f32_e32 v0, v0
	v_rcp_f32_e32 v156, v156
	v_mov_b32_e32 v3, v168
	v_pk_mul_f32 v[2:3], v[102:103], v[2:3]
	v_mul_f32_e32 v0, v148, v0
	v_mul_f32_e32 v148, v149, v156
	v_mul_f32_e32 v149, 0xbfb8aa3b, v150
	v_exp_f32_e32 v149, v149
	v_mul_f32_e32 v156, 0xbfb8aa3b, v151
	v_exp_f32_e32 v156, v156
	v_mul_f32_e32 v0, v166, v0
	v_add_f32_e32 v149, 1.0, v149
	v_rcp_f32_e32 v149, v149
	v_add_f32_e32 v156, 1.0, v156
	v_rcp_f32_e32 v156, v156
	v_mul_f32_e32 v148, v167, v148
	v_cvt_pk_bf16_f32 v148, v0, v148
	v_mul_f32_e32 v0, v150, v149
	v_mul_f32_e32 v0, v2, v0
	v_mul_f32_e32 v2, v151, v156
	v_readlane_b32 s54, v252, 8
	v_mul_f32_e32 v2, v3, v2
	v_readlane_b32 s55, v252, 9
	v_cvt_pk_bf16_f32 v149, v0, v2
	s_movk_i32 s14, 0x1600
	s_nop 0
	v_mov_b64_e32 v[2:3], s[54:55]
	v_mad_i64_i32 v[2:3], s[54:55], v213, s14, v[2:3]
	v_lshl_add_u64 v[2:3], v[202:203], 1, v[2:3]
	global_store_dwordx2 v[2:3], v[148:149], off nt
.LBB0_1312:
	s_or_b64 exec, exec, s[52:53]
	v_mov_b32_e32 v2, v186
	v_mov_b32_e32 v3, v186
	v_pk_mul_f32 v[150:151], v[90:91], v[2:3]
	v_pk_mul_f32 v[148:149], v[88:89], v[186:187]
	v_mov_b32_e32 v0, v1
	v_mov_b32_e32 v2, v1
	v_mov_b32_e32 v3, v1
	v_mov_b32_e32 v166, v1
	v_mov_b32_e32 v167, v1
	v_mov_b32_e32 v168, v1
	v_mov_b32_e32 v169, v1
	v_mov_b32_e32 v198, v1
	v_mov_b32_e32 v185, v1
	v_mov_b32_e32 v199, v1
	v_mov_b32_e32 v200, v1
	v_mov_b32_e32 v201, v1
	v_mov_b32_e32 v204, v1
	v_mov_b32_e32 v205, v1
	v_mov_b32_e32 v213, v1
	v_mov_b32_e32 v220, v1
	v_mov_b32_dpp v0, v148 row_ror:1 row_mask:0xf bank_mask:0xf
	v_mov_b32_dpp v2, v149 row_ror:1 row_mask:0xf bank_mask:0xf
	v_mov_b32_dpp v3, v150 row_ror:1 row_mask:0xf bank_mask:0xf
	v_mov_b32_dpp v166, v151 row_ror:1 row_mask:0xf bank_mask:0xf
	v_mov_b32_dpp v167, v152 row_ror:1 row_mask:0xf bank_mask:0xf
	v_mov_b32_dpp v168, v153 row_ror:1 row_mask:0xf bank_mask:0xf
	v_mov_b32_dpp v169, v154 row_ror:1 row_mask:0xf bank_mask:0xf
	v_mov_b32_dpp v198, v155 row_ror:1 row_mask:0xf bank_mask:0xf
	v_mov_b32_dpp v185, v148 row_ror:2 row_mask:0xf bank_mask:0xf
	v_mov_b32_dpp v199, v149 row_ror:2 row_mask:0xf bank_mask:0xf
	v_mov_b32_dpp v200, v150 row_ror:2 row_mask:0xf bank_mask:0xf
	v_mov_b32_dpp v201, v151 row_ror:2 row_mask:0xf bank_mask:0xf
	v_mov_b32_dpp v204, v152 row_ror:2 row_mask:0xf bank_mask:0xf
	v_mov_b32_dpp v205, v153 row_ror:2 row_mask:0xf bank_mask:0xf
	v_mov_b32_dpp v213, v154 row_ror:2 row_mask:0xf bank_mask:0xf
	v_mov_b32_dpp v220, v155 row_ror:2 row_mask:0xf bank_mask:0xf
	s_and_saveexec_b64 s[52:53], s[58:59]
	s_cbranch_execz .LBB0_1324
	s_movk_i32 s14, 0x407f
	v_cmp_lt_i32_e32 vcc, s14, v214
	s_and_saveexec_b64 s[54:55], vcc
	s_xor_b64 s[54:55], exec, s[54:55]
	s_cbranch_execz .LBB0_1315
	v_add_u32_e32 v0, 0xffffbf80, v214
	s_movk_i32 s14, 0x5800
	v_mad_u64_u32 v[2:3], s[56:57], v0, s14, v[164:165]
	v_add_co_u32_e32 v152, vcc, 0x2000, v2
	s_nop 1
	v_addc_co_u32_e32 v153, vcc, 0, v3, vcc
	global_load_dwordx4 v[152:155], v[152:153], off offset:3088
	s_nop 0
	global_load_dwordx4 v[156:159], v[2:3], off offset:16
	v_mad_u64_u32 v[2:3], s[56:57], v0, s14, v[162:163]
	v_add_co_u32_e32 v166, vcc, 0x2000, v2
	s_nop 1
	v_addc_co_u32_e32 v167, vcc, 0, v3, vcc
	s_waitcnt vmcnt(1)
	global_store_dwordx4 v[2:3], v[152:155], off offset:16 nt
	global_store_dwordx4 v[166:167], v[148:151], off offset:3088 nt

;     __device__ __forceinline__ void operator()(const f32x4 (&acc)[2][2][4][2], const Unit& u, int wr, int wc, int fr, int fq) const {
;     ...
;                             if (row < MP) {
;                                 const int b = row / TP, t = row - b * TP;
;                                 if (t < 2) { g2 = (f32x4){0.f, 0.f, 0.f, 0.f}; if (t == 0) g1 = g2; }
;                                 if (t >= TP - 2) *(f32x4*)(cvp + ((size_t)b * 2 + (t - (TP - 2))) * DFF + f0) = cur;
.LBB0_1320:
	s_or_b64 exec, exec, s[56:57]
	s_movk_i32 s14, 0x80d
	v_cmp_lt_i32_e32 vcc, s14, v168
	s_and_saveexec_b64 s[56:57], vcc
	s_cbranch_execz .LBB0_1322
	v_ashrrev_i32_e32 v167, 31, v166
	v_add_u32_e32 v0, 0xfffff7f2, v168
	v_lshl_add_u64 v[2:3], v[166:167], 1, v[0:1]
	s_movk_i32 s14, 0x2c00
	v_mad_u64_u32 v[166:167], s[58:59], v2, s14, v[160:161]
	v_mad_i32_i24 v167, v3, s14, v167
	global_store_dwordx4 v[166:167], v[148:151], off offset:16 nt

; #define LAS __attribute__((address_space(3)))
;     __device__ __forceinline__ void operator()(const f32x4 (&acc)[2][2][4][2], const Unit& u, int wr, int wc, int fr, int fq) const {
;     ...
;                         const int l = 128 * ai + 64 * wr + 16 * m + frL, row = 254 * u.pm - 2 + l;
;                         const float rs = rt[l];
;                         const f32x4 cur = acc[ai][1][m][n] * rs, uu = acc[ai][0][m][n] * rs;
;                         if (m == 0) {
;                             const int B = 2 * ai + wr;
;                             prev = (f32x4){0.f, 0.f, 0.f, 0.f};
;                             if (B > 0 && frL >= 14) prev = *(const LAS f32x4*)(halo + ((B - 1) * 2 + (frL - 14)) * 128 + fl + 4 * n);
;                         }
;                         f32x4 g1, g2;
;                         {
;                             const float c1x = dpp_ror1(cur.x), c1y = dpp_ror1(cur.y), c1z = dpp_ror1(cur.z), c1w = dpp_ror1(cur.w);
;                             const float p1x = dpp_ror1(prev.x), p1y = dpp_ror1(prev.y), p1z = dpp_ror1(prev.z), p1w = dpp_ror1(prev.w);
;                             const float c2x = dpp_ror2(cur.x), c2y = dpp_ror2(cur.y), c2z = dpp_ror2(cur.z), c2w = dpp_ror2(cur.w);
;                             const float p2x = dpp_ror2(prev.x), p2y = dpp_ror2(prev.y), p2z = dpp_ror2(prev.z), p2w = dpp_ror2(prev.w);
;                             const bool s1 = frL >= 1, s2 = frL >= 2;
;                             g1.x = s1 ? c1x : p1x; g1.y = s1 ? c1y : p1y; g1.z = s1 ? c1z : p1z; g1.w = s1 ? c1w : p1w;
;                             g2.x = s2 ? c2x : p2x; g2.y = s2 ? c2y : p2y; g2.z = s2 ? c2z : p2z; g2.w = s2 ? c2w : p2w;
;                         }
;                         if (l >= 2 && row < M) {
;                             if (row < MP) {
;                                 const int b = row / TP, t = row - b * TP;
;                                 if (t < 2) { g2 = (f32x4){0.f, 0.f, 0.f, 0.f}; if (t == 0) g1 = g2; }
;                                 if (t >= TP - 2) *(f32x4*)(cvp + ((size_t)b * 2 + (t - (TP - 2))) * DFF + f0) = cur;
;                             } else {
;                                 const int s = row - MP;
;                                 const float* c0 = cst + ((size_t)s * 2 + 0) * DFF + f0;
;                                 g2 = *(const f32x4*)c0; g1 = *(const f32x4*)(c0 + DFF);
.LBB0_1323:
	s_or_b64 exec, exec, s[54:55]
	s_waitcnt vmcnt(0)
	v_pk_fma_f32 v[156:157], v[140:141], v[156:157], v[144:145]
	v_pk_fma_f32 v[158:159], v[142:143], v[158:159], v[146:147]
	v_pk_fma_f32 v[152:153], v[136:137], v[152:153], v[156:157]
	v_pk_fma_f32 v[154:155], v[138:139], v[154:155], v[158:159]
	v_pk_fma_f32 v[152:153], v[148:149], v[132:133], v[152:153]
	v_pk_fma_f32 v[154:155], v[150:151], v[134:135], v[154:155]
	v_mul_f32_e32 v0, 0xbfb8aa3b, v152
	v_mul_f32_e32 v156, 0xbfb8aa3b, v153
	v_exp_f32_e32 v0, v0
	v_exp_f32_e32 v156, v156
	v_pk_mul_f32 v[166:167], v[84:85], v[186:187]
	v_mov_b32_e32 v2, v186
	v_add_f32_e32 v0, 1.0, v0
	v_add_f32_e32 v156, 1.0, v156
	v_rcp_f32_e32 v0, v0
	v_rcp_f32_e32 v156, v156
	v_mov_b32_e32 v3, v186
	v_pk_mul_f32 v[2:3], v[86:87], v[2:3]
	v_mul_f32_e32 v0, v152, v0
	v_mul_f32_e32 v152, v153, v156
	v_mul_f32_e32 v153, 0xbfb8aa3b, v154
	v_exp_f32_e32 v153, v153
	v_mul_f32_e32 v156, 0xbfb8aa3b, v155
	v_exp_f32_e32 v156, v156
	v_mul_f32_e32 v0, v166, v0
	v_add_f32_e32 v153, 1.0, v153
	v_rcp_f32_e32 v153, v153
	v_add_f32_e32 v156, 1.0, v156
	v_rcp_f32_e32 v156, v156
	v_mul_f32_e32 v152, v167, v152
	v_cvt_pk_bf16_f32 v152, v0, v152
	v_mul_f32_e32 v0, v154, v153
	v_mul_f32_e32 v0, v2, v0
	v_mul_f32_e32 v2, v155, v156
	v_readlane_b32 s54, v252, 8
	v_mul_f32_e32 v2, v3, v2
	v_readlane_b32 s55, v252, 9
	v_cvt_pk_bf16_f32 v153, v0, v2
	s_movk_i32 s14, 0x1600
	s_nop 0
	v_mov_b64_e32 v[2:3], s[54:55]
	v_mad_i64_i32 v[2:3], s[54:55], v214, s14, v[2:3]
	v_lshl_add_u64 v[2:3], v[202:203], 1, v[2:3]
	global_store_dwordx2 v[2:3], v[152:153], off nt
.LBB0_1324:
	s_or_b64 exec, exec, s[52:53]
	v_mov_b32_e32 v2, v188
	v_mov_b32_e32 v3, v188
	v_pk_mul_f32 v[154:155], v[74:75], v[2:3]
	v_pk_mul_f32 v[152:153], v[72:73], v[188:189]
	v_mov_b32_e32 v0, v1
	v_mov_b32_e32 v2, v1
	v_mov_b32_e32 v3, v1
	v_mov_b32_e32 v166, v1
	v_mov_b32_e32 v167, v1
	v_mov_b32_e32 v168, v1
	v_mov_b32_e32 v169, v1
	v_mov_b32_e32 v186, v1
	v_mov_b32_e32 v185, v1
	v_mov_b32_e32 v187, v1
	v_mov_b32_e32 v198, v1
	v_mov_b32_e32 v199, v1
	v_mov_b32_e32 v200, v1
	v_mov_b32_e32 v201, v1
	v_mov_b32_e32 v204, v1
	v_mov_b32_e32 v205, v1
	v_mov_b32_dpp v0, v152 row_ror:1 row_mask:0xf bank_mask:0xf
	v_mov_b32_dpp v2, v153 row_ror:1 row_mask:0xf bank_mask:0xf
	v_mov_b32_dpp v3, v154 row_ror:1 row_mask:0xf bank_mask:0xf
	v_mov_b32_dpp v166, v155 row_ror:1 row_mask:0xf bank_mask:0xf
	v_mov_b32_dpp v167, v148 row_ror:1 row_mask:0xf bank_mask:0xf
	v_mov_b32_dpp v168, v149 row_ror:1 row_mask:0xf bank_mask:0xf
	v_mov_b32_dpp v169, v150 row_ror:1 row_mask:0xf bank_mask:0xf
	v_mov_b32_dpp v186, v151 row_ror:1 row_mask:0xf bank_mask:0xf
	v_mov_b32_dpp v185, v152 row_ror:2 row_mask:0xf bank_mask:0xf
	v_mov_b32_dpp v187, v153 row_ror:2 row_mask:0xf bank_mask:0xf
	v_mov_b32_dpp v198, v154 row_ror:2 row_mask:0xf bank_mask:0xf
	v_mov_b32_dpp v199, v155 row_ror:2 row_mask:0xf bank_mask:0xf
	v_mov_b32_dpp v200, v148 row_ror:2 row_mask:0xf bank_mask:0xf
	v_mov_b32_dpp v201, v149 row_ror:2 row_mask:0xf bank_mask:0xf
	v_mov_b32_dpp v204, v150 row_ror:2 row_mask:0xf bank_mask:0xf
	v_mov_b32_dpp v205, v151 row_ror:2 row_mask:0xf bank_mask:0xf
	s_and_saveexec_b64 s[52:53], s[60:61]
	s_cbranch_execz .LBB0_1336
	s_movk_i32 s14, 0x407f
	v_cmp_lt_i32_e32 vcc, s14, v215
	s_and_saveexec_b64 s[54:55], vcc
	s_xor_b64 s[54:55], exec, s[54:55]
	s_cbranch_execz .LBB0_1327
	v_add_u32_e32 v0, 0xffffbf80, v215
	s_movk_i32 s14, 0x5800
	v_mad_u64_u32 v[2:3], s[56:57], v0, s14, v[164:165]
	v_add_co_u32_e32 v148, vcc, 0x2000, v2
	s_nop 1
	v_addc_co_u32_e32 v149, vcc, 0, v3, vcc
	global_load_dwordx4 v[148:151], v[148:149], off offset:3088
	s_nop 0
	global_load_dwordx4 v[156:159], v[2:3], off offset:16
	v_mad_u64_u32 v[2:3], s[56:57], v0, s14, v[162:163]
	v_add_co_u32_e32 v166, vcc, 0x2000, v2
	s_nop 1
	v_addc_co_u32_e32 v167, vcc, 0, v3, vcc
	s_waitcnt vmcnt(1)
	global_store_dwordx4 v[2:3], v[148:151], off offset:16 nt
	global_store_dwordx4 v[166:167], v[152:155], off offset:3088 nt

;     __device__ __forceinline__ void operator()(const f32x4 (&acc)[2][2][4][2], const Unit& u, int wr, int wc, int fr, int fq) const {
;     ...
;                             if (row < MP) {
;                                 const int b = row / TP, t = row - b * TP;
;                                 if (t < 2) { g2 = (f32x4){0.f, 0.f, 0.f, 0.f}; if (t == 0) g1 = g2; }
;                                 if (t >= TP - 2) *(f32x4*)(cvp + ((size_t)b * 2 + (t - (TP - 2))) * DFF + f0) = cur;
.LBB0_1332:
	s_or_b64 exec, exec, s[56:57]
	s_movk_i32 s14, 0x80d
	v_cmp_lt_i32_e32 vcc, s14, v168
	s_and_saveexec_b64 s[56:57], vcc
	s_cbranch_execz .LBB0_1334
	v_ashrrev_i32_e32 v167, 31, v166
	v_add_u32_e32 v0, 0xfffff7f2, v168
	v_lshl_add_u64 v[2:3], v[166:167], 1, v[0:1]
	s_movk_i32 s14, 0x2c00
	v_mad_u64_u32 v[166:167], s[58:59], v2, s14, v[160:161]
	v_mad_i32_i24 v167, v3, s14, v167
	global_store_dwordx4 v[166:167], v[152:155], off offset:16 nt

; #define LAS __attribute__((address_space(3)))
;     __device__ __forceinline__ void operator()(const f32x4 (&acc)[2][2][4][2], const Unit& u, int wr, int wc, int fr, int fq) const {
;     ...
;                         const int l = 128 * ai + 64 * wr + 16 * m + frL, row = 254 * u.pm - 2 + l;
;                         const float rs = rt[l];
;                         const f32x4 cur = acc[ai][1][m][n] * rs, uu = acc[ai][0][m][n] * rs;
;                         if (m == 0) {
;                             const int B = 2 * ai + wr;
;                             prev = (f32x4){0.f, 0.f, 0.f, 0.f};
;                             if (B > 0 && frL >= 14) prev = *(const LAS f32x4*)(halo + ((B - 1) * 2 + (frL - 14)) * 128 + fl + 4 * n);
;                         }
;                         f32x4 g1, g2;
;                         {
;                             const float c1x = dpp_ror1(cur.x), c1y = dpp_ror1(cur.y), c1z = dpp_ror1(cur.z), c1w = dpp_ror1(cur.w);
;                             const float p1x = dpp_ror1(prev.x), p1y = dpp_ror1(prev.y), p1z = dpp_ror1(prev.z), p1w = dpp_ror1(prev.w);
;                             const float c2x = dpp_ror2(cur.x), c2y = dpp_ror2(cur.y), c2z = dpp_ror2(cur.z), c2w = dpp_ror2(cur.w);
;                             const float p2x = dpp_ror2(prev.x), p2y = dpp_ror2(prev.y), p2z = dpp_ror2(prev.z), p2w = dpp_ror2(prev.w);
;                             const bool s1 = frL >= 1, s2 = frL >= 2;
;                             g1.x = s1 ? c1x : p1x; g1.y = s1 ? c1y : p1y; g1.z = s1 ? c1z : p1z; g1.w = s1 ? c1w : p1w;
;                             g2.x = s2 ? c2x : p2x; g2.y = s2 ? c2y : p2y; g2.z = s2 ? c2z : p2z; g2.w = s2 ? c2w : p2w;
;                         }
;                         if (l >= 2 && row < M) {
;                             if (row < MP) {
;                                 const int b = row / TP, t = row - b * TP;
;                                 if (t < 2) { g2 = (f32x4){0.f, 0.f, 0.f, 0.f}; if (t == 0) g1 = g2; }
;                                 if (t >= TP - 2) *(f32x4*)(cvp + ((size_t)b * 2 + (t - (TP - 2))) * DFF + f0) = cur;
;                             } else {
;                                 const int s = row - MP;
;                                 const float* c0 = cst + ((size_t)s * 2 + 0) * DFF + f0;
;                                 g2 = *(const f32x4*)c0; g1 = *(const f32x4*)(c0 + DFF);
.LBB0_1335:
	s_or_b64 exec, exec, s[54:55]
	s_waitcnt vmcnt(0)
	v_pk_fma_f32 v[156:157], v[140:141], v[156:157], v[144:145]
	v_pk_fma_f32 v[158:159], v[142:143], v[158:159], v[146:147]
	v_pk_fma_f32 v[148:149], v[136:137], v[148:149], v[156:157]
	v_pk_fma_f32 v[150:151], v[138:139], v[150:151], v[158:159]
	v_pk_fma_f32 v[148:149], v[152:153], v[132:133], v[148:149]
	v_pk_fma_f32 v[150:151], v[154:155], v[134:135], v[150:151]
	v_mul_f32_e32 v0, 0xbfb8aa3b, v148
	v_mul_f32_e32 v152, 0xbfb8aa3b, v149
	v_exp_f32_e32 v0, v0
	v_exp_f32_e32 v152, v152
	v_pk_mul_f32 v[166:167], v[68:69], v[188:189]
	v_mov_b32_e32 v2, v188
	v_add_f32_e32 v0, 1.0, v0
	v_add_f32_e32 v152, 1.0, v152
	v_rcp_f32_e32 v0, v0
	v_rcp_f32_e32 v152, v152
	v_mov_b32_e32 v3, v188
	v_pk_mul_f32 v[2:3], v[70:71], v[2:3]
	v_mul_f32_e32 v0, v148, v0
	v_mul_f32_e32 v148, v149, v152
	v_mul_f32_e32 v149, 0xbfb8aa3b, v150
	v_exp_f32_e32 v149, v149
	v_mul_f32_e32 v152, 0xbfb8aa3b, v151
	v_exp_f32_e32 v152, v152
	v_mul_f32_e32 v0, v166, v0
	v_add_f32_e32 v149, 1.0, v149
	v_rcp_f32_e32 v149, v149
	v_add_f32_e32 v152, 1.0, v152
	v_rcp_f32_e32 v152, v152
	v_mul_f32_e32 v148, v167, v148
	v_cvt_pk_bf16_f32 v148, v0, v148
	v_mul_f32_e32 v0, v150, v149
	v_mul_f32_e32 v0, v2, v0
	v_mul_f32_e32 v2, v151, v152
	v_readlane_b32 s54, v252, 8
	v_mul_f32_e32 v2, v3, v2
	v_readlane_b32 s55, v252, 9
	v_cvt_pk_bf16_f32 v149, v0, v2
	s_movk_i32 s14, 0x1600
	s_nop 0
	v_mov_b64_e32 v[2:3], s[54:55]
	v_mad_i64_i32 v[2:3], s[54:55], v215, s14, v[2:3]
	v_lshl_add_u64 v[2:3], v[202:203], 1, v[2:3]
	global_store_dwordx2 v[2:3], v[148:149], off nt
.LBB0_1336:
	s_or_b64 exec, exec, s[52:53]
	v_mov_b32_e32 v152, 0
	v_mov_b32_e32 v153, 0
	v_mov_b32_e32 v154, 0
	v_mov_b32_e32 v155, 0
	s_and_saveexec_b64 s[52:53], s[10:11]
	ds_read_b128 v[152:155], v221 offset:16
	s_or_b64 exec, exec, s[52:53]
	v_mov_b32_e32 v2, v170
	v_mov_b32_e32 v3, v170
	v_pk_mul_f32 v[150:151], v[58:59], v[2:3]
	v_pk_mul_f32 v[148:149], v[56:57], v[170:171]
	v_mov_b32_e32 v0, v1
	v_mov_b32_e32 v2, v1
	v_mov_b32_e32 v3, v1
	v_mov_b32_e32 v166, v1
	v_mov_b32_e32 v167, v1
	v_mov_b32_e32 v168, v1
	v_mov_b32_e32 v169, v1
	v_mov_b32_e32 v186, v1
	v_mov_b32_e32 v185, v1
	v_mov_b32_e32 v187, v1
	v_mov_b32_e32 v188, v1
	v_mov_b32_e32 v189, v1
	v_mov_b32_e32 v198, v1
	v_mov_b32_e32 v199, v1
	v_mov_b32_e32 v200, v1
	v_mov_b32_e32 v201, v1
	v_mov_b32_dpp v0, v148 row_ror:1 row_mask:0xf bank_mask:0xf
	v_mov_b32_dpp v2, v149 row_ror:1 row_mask:0xf bank_mask:0xf
	v_mov_b32_dpp v3, v150 row_ror:1 row_mask:0xf bank_mask:0xf
	v_mov_b32_dpp v166, v151 row_ror:1 row_mask:0xf bank_mask:0xf
	s_waitcnt lgkmcnt(0)
	v_mov_b32_dpp v167, v152 row_ror:1 row_mask:0xf bank_mask:0xf
	v_mov_b32_dpp v168, v153 row_ror:1 row_mask:0xf bank_mask:0xf
	v_mov_b32_dpp v169, v154 row_ror:1 row_mask:0xf bank_mask:0xf
	v_mov_b32_dpp v186, v155 row_ror:1 row_mask:0xf bank_mask:0xf
	v_mov_b32_dpp v185, v148 row_ror:2 row_mask:0xf bank_mask:0xf
	v_mov_b32_dpp v187, v149 row_ror:2 row_mask:0xf bank_mask:0xf
	v_mov_b32_dpp v188, v150 row_ror:2 row_mask:0xf bank_mask:0xf
	v_mov_b32_dpp v189, v151 row_ror:2 row_mask:0xf bank_mask:0xf
	v_mov_b32_dpp v198, v152 row_ror:2 row_mask:0xf bank_mask:0xf
	v_mov_b32_dpp v199, v153 row_ror:2 row_mask:0xf bank_mask:0xf
	v_mov_b32_dpp v200, v154 row_ror:2 row_mask:0xf bank_mask:0xf
	v_mov_b32_dpp v201, v155 row_ror:2 row_mask:0xf bank_mask:0xf
	s_and_saveexec_b64 s[10:11], s[62:63]
	s_cbranch_execz .LBB0_1350
	s_movk_i32 s14, 0x407f
	v_cmp_lt_i32_e32 vcc, s14, v216
	s_and_saveexec_b64 s[52:53], vcc
	s_xor_b64 s[52:53], exec, s[52:53]
	s_cbranch_execz .LBB0_1341
	v_add_u32_e32 v0, 0xffffbf80, v216
	s_movk_i32 s14, 0x5800
	v_mad_u64_u32 v[2:3], s[54:55], v0, s14, v[164:165]
	v_add_co_u32_e32 v152, vcc, 0x2000, v2
	s_nop 1
	v_addc_co_u32_e32 v153, vcc, 0, v3, vcc
	global_load_dwordx4 v[152:155], v[152:153], off offset:3088
	s_nop 0
	global_load_dwordx4 v[156:159], v[2:3], off offset:16
	v_mad_u64_u32 v[2:3], s[54:55], v0, s14, v[162:163]
	v_add_co_u32_e32 v166, vcc, 0x2000, v2
	s_nop 1
	v_addc_co_u32_e32 v167, vcc, 0, v3, vcc
	s_waitcnt vmcnt(1)
	global_store_dwordx4 v[2:3], v[152:155], off offset:16 nt
	global_store_dwordx4 v[166:167], v[148:151], off offset:3088 nt

;     __device__ __forceinline__ void operator()(const f32x4 (&acc)[2][2][4][2], const Unit& u, int wr, int wc, int fr, int fq) const {
;     ...
;                             if (row < MP) {
;                                 const int b = row / TP, t = row - b * TP;
;                                 if (t < 2) { g2 = (f32x4){0.f, 0.f, 0.f, 0.f}; if (t == 0) g1 = g2; }
;                                 if (t >= TP - 2) *(f32x4*)(cvp + ((size_t)b * 2 + (t - (TP - 2))) * DFF + f0) = cur;
.LBB0_1346:
	s_or_b64 exec, exec, s[54:55]
	s_movk_i32 s14, 0x80d
	v_cmp_lt_i32_e32 vcc, s14, v168
	s_and_saveexec_b64 s[54:55], vcc
	s_cbranch_execz .LBB0_1348
	v_ashrrev_i32_e32 v167, 31, v166
	v_add_u32_e32 v0, 0xfffff7f2, v168
	v_lshl_add_u64 v[2:3], v[166:167], 1, v[0:1]
	s_movk_i32 s14, 0x2c00
	v_mad_u64_u32 v[166:167], s[56:57], v2, s14, v[160:161]
	v_mad_i32_i24 v167, v3, s14, v167
	global_store_dwordx4 v[166:167], v[148:151], off offset:16 nt

; #define LAS __attribute__((address_space(3)))
;     __device__ __forceinline__ void operator()(const f32x4 (&acc)[2][2][4][2], const Unit& u, int wr, int wc, int fr, int fq) const {
;     ...
;                         const int l = 128 * ai + 64 * wr + 16 * m + frL, row = 254 * u.pm - 2 + l;
;                         const float rs = rt[l];
;                         const f32x4 cur = acc[ai][1][m][n] * rs, uu = acc[ai][0][m][n] * rs;
;                         if (m == 0) {
;                             const int B = 2 * ai + wr;
;                             prev = (f32x4){0.f, 0.f, 0.f, 0.f};
;                             if (B > 0 && frL >= 14) prev = *(const LAS f32x4*)(halo + ((B - 1) * 2 + (frL - 14)) * 128 + fl + 4 * n);
;                         }
;                         f32x4 g1, g2;
;                         {
;                             const float c1x = dpp_ror1(cur.x), c1y = dpp_ror1(cur.y), c1z = dpp_ror1(cur.z), c1w = dpp_ror1(cur.w);
;                             const float p1x = dpp_ror1(prev.x), p1y = dpp_ror1(prev.y), p1z = dpp_ror1(prev.z), p1w = dpp_ror1(prev.w);
;                             const float c2x = dpp_ror2(cur.x), c2y = dpp_ror2(cur.y), c2z = dpp_ror2(cur.z), c2w = dpp_ror2(cur.w);
;                             const float p2x = dpp_ror2(prev.x), p2y = dpp_ror2(prev.y), p2z = dpp_ror2(prev.z), p2w = dpp_ror2(prev.w);
;                             const bool s1 = frL >= 1, s2 = frL >= 2;
;                             g1.x = s1 ? c1x : p1x; g1.y = s1 ? c1y : p1y; g1.z = s1 ? c1z : p1z; g1.w = s1 ? c1w : p1w;
;                             g2.x = s2 ? c2x : p2x; g2.y = s2 ? c2y : p2y; g2.z = s2 ? c2z : p2z; g2.w = s2 ? c2w : p2w;
;                         }
;                         if (l >= 2 && row < M) {
;                             if (row < MP) {
;                                 const int b = row / TP, t = row - b * TP;
;                                 if (t < 2) { g2 = (f32x4){0.f, 0.f, 0.f, 0.f}; if (t == 0) g1 = g2; }
;                                 if (t >= TP - 2) *(f32x4*)(cvp + ((size_t)b * 2 + (t - (TP - 2))) * DFF + f0) = cur;
;                             } else {
;                                 const int s = row - MP;
;                                 const float* c0 = cst + ((size_t)s * 2 + 0) * DFF + f0;
;                                 g2 = *(const f32x4*)c0; g1 = *(const f32x4*)(c0 + DFF);
.LBB0_1349:
	s_or_b64 exec, exec, s[52:53]
	s_waitcnt vmcnt(0)
	v_pk_fma_f32 v[156:157], v[140:141], v[156:157], v[144:145]
	v_pk_fma_f32 v[158:159], v[142:143], v[158:159], v[146:147]
	v_pk_fma_f32 v[152:153], v[136:137], v[152:153], v[156:157]
	v_pk_fma_f32 v[154:155], v[138:139], v[154:155], v[158:159]
	v_pk_fma_f32 v[152:153], v[148:149], v[132:133], v[152:153]
	v_pk_fma_f32 v[154:155], v[150:151], v[134:135], v[154:155]
	v_mul_f32_e32 v0, 0xbfb8aa3b, v152
	v_mul_f32_e32 v156, 0xbfb8aa3b, v153
	v_exp_f32_e32 v0, v0
	v_exp_f32_e32 v156, v156
	v_pk_mul_f32 v[166:167], v[52:53], v[170:171]
	v_mov_b32_e32 v2, v170
	v_add_f32_e32 v0, 1.0, v0
	v_add_f32_e32 v156, 1.0, v156
	v_rcp_f32_e32 v0, v0
	v_rcp_f32_e32 v156, v156
	v_mov_b32_e32 v3, v170
	v_pk_mul_f32 v[2:3], v[54:55], v[2:3]
	v_mul_f32_e32 v0, v152, v0
	v_mul_f32_e32 v152, v153, v156
	v_mul_f32_e32 v153, 0xbfb8aa3b, v154
	v_exp_f32_e32 v153, v153
	v_mul_f32_e32 v156, 0xbfb8aa3b, v155
	v_exp_f32_e32 v156, v156
	v_mul_f32_e32 v0, v166, v0
	v_add_f32_e32 v153, 1.0, v153
	v_rcp_f32_e32 v153, v153
	v_add_f32_e32 v156, 1.0, v156
	v_rcp_f32_e32 v156, v156
	v_mul_f32_e32 v152, v167, v152
	v_cvt_pk_bf16_f32 v152, v0, v152
	v_mul_f32_e32 v0, v154, v153
	v_mul_f32_e32 v0, v2, v0
	v_mul_f32_e32 v2, v155, v156
	v_readlane_b32 s52, v252, 8
	v_mul_f32_e32 v2, v3, v2
	v_readlane_b32 s53, v252, 9
	v_cvt_pk_bf16_f32 v153, v0, v2
	s_movk_i32 s14, 0x1600
	s_nop 0
	v_mov_b64_e32 v[2:3], s[52:53]
	v_mad_i64_i32 v[2:3], s[52:53], v216, s14, v[2:3]
	v_lshl_add_u64 v[2:3], v[202:203], 1, v[2:3]
	global_store_dwordx2 v[2:3], v[152:153], off nt
.LBB0_1350:
	s_or_b64 exec, exec, s[10:11]
	v_mov_b32_e32 v2, v190
	v_mov_b32_e32 v3, v190
	v_pk_mul_f32 v[154:155], v[42:43], v[2:3]
	v_pk_mul_f32 v[152:153], v[40:41], v[190:191]
	v_mov_b32_e32 v0, v1
	v_mov_b32_e32 v2, v1
	v_mov_b32_e32 v3, v1
	v_mov_b32_e32 v166, v1
	v_mov_b32_e32 v167, v1
	v_mov_b32_e32 v168, v1
	v_mov_b32_e32 v169, v1
	v_mov_b32_e32 v171, v1
	v_mov_b32_e32 v170, v1
	v_mov_b32_e32 v185, v1
	v_mov_b32_e32 v186, v1
	v_mov_b32_e32 v187, v1
	v_mov_b32_e32 v188, v1
	v_mov_b32_e32 v189, v1
	v_mov_b32_e32 v198, v1
	v_mov_b32_e32 v199, v1
	v_mov_b32_dpp v0, v152 row_ror:1 row_mask:0xf bank_mask:0xf
	v_mov_b32_dpp v2, v153 row_ror:1 row_mask:0xf bank_mask:0xf
	v_mov_b32_dpp v3, v154 row_ror:1 row_mask:0xf bank_mask:0xf
	v_mov_b32_dpp v166, v155 row_ror:1 row_mask:0xf bank_mask:0xf
	v_mov_b32_dpp v167, v148 row_ror:1 row_mask:0xf bank_mask:0xf
	v_mov_b32_dpp v168, v149 row_ror:1 row_mask:0xf bank_mask:0xf
	v_mov_b32_dpp v169, v150 row_ror:1 row_mask:0xf bank_mask:0xf
	v_mov_b32_dpp v171, v151 row_ror:1 row_mask:0xf bank_mask:0xf
	v_mov_b32_dpp v170, v152 row_ror:2 row_mask:0xf bank_mask:0xf
	v_mov_b32_dpp v185, v153 row_ror:2 row_mask:0xf bank_mask:0xf
	v_mov_b32_dpp v186, v154 row_ror:2 row_mask:0xf bank_mask:0xf
	v_mov_b32_dpp v187, v155 row_ror:2 row_mask:0xf bank_mask:0xf
	v_mov_b32_dpp v188, v148 row_ror:2 row_mask:0xf bank_mask:0xf
	v_mov_b32_dpp v189, v149 row_ror:2 row_mask:0xf bank_mask:0xf
	v_mov_b32_dpp v198, v150 row_ror:2 row_mask:0xf bank_mask:0xf
	v_mov_b32_dpp v199, v151 row_ror:2 row_mask:0xf bank_mask:0xf
	s_and_saveexec_b64 s[10:11], s[64:65]
	s_cbranch_execz .LBB0_1362
	s_movk_i32 s14, 0x407f
	v_cmp_lt_i32_e32 vcc, s14, v217
	s_and_saveexec_b64 s[52:53], vcc
	s_xor_b64 s[52:53], exec, s[52:53]
	s_cbranch_execz .LBB0_1353
	v_add_u32_e32 v0, 0xffffbf80, v217
	s_movk_i32 s14, 0x5800
	v_mad_u64_u32 v[2:3], s[54:55], v0, s14, v[164:165]
	v_add_co_u32_e32 v148, vcc, 0x2000, v2
	s_nop 1
	v_addc_co_u32_e32 v149, vcc, 0, v3, vcc
	global_load_dwordx4 v[148:151], v[148:149], off offset:3088
	s_nop 0
	global_load_dwordx4 v[156:159], v[2:3], off offset:16
	v_mad_u64_u32 v[2:3], s[54:55], v0, s14, v[162:163]
	v_add_co_u32_e32 v166, vcc, 0x2000, v2
	s_nop 1
	v_addc_co_u32_e32 v167, vcc, 0, v3, vcc
	s_waitcnt vmcnt(1)
	global_store_dwordx4 v[2:3], v[148:151], off offset:16 nt
	global_store_dwordx4 v[166:167], v[152:155], off offset:3088 nt

;     __device__ __forceinline__ void operator()(const f32x4 (&acc)[2][2][4][2], const Unit& u, int wr, int wc, int fr, int fq) const {
;     ...
;                             if (row < MP) {
;                                 const int b = row / TP, t = row - b * TP;
;                                 if (t < 2) { g2 = (f32x4){0.f, 0.f, 0.f, 0.f}; if (t == 0) g1 = g2; }
;                                 if (t >= TP - 2) *(f32x4*)(cvp + ((size_t)b * 2 + (t - (TP - 2))) * DFF + f0) = cur;
.LBB0_1358:
	s_or_b64 exec, exec, s[54:55]
	s_movk_i32 s14, 0x80d
	v_cmp_lt_i32_e32 vcc, s14, v168
	s_and_saveexec_b64 s[54:55], vcc
	s_cbranch_execz .LBB0_1360
	v_ashrrev_i32_e32 v167, 31, v166
	v_add_u32_e32 v0, 0xfffff7f2, v168
	v_lshl_add_u64 v[2:3], v[166:167], 1, v[0:1]
	s_movk_i32 s14, 0x2c00
	v_mad_u64_u32 v[166:167], s[56:57], v2, s14, v[160:161]
	v_mad_i32_i24 v167, v3, s14, v167
	global_store_dwordx4 v[166:167], v[152:155], off offset:16 nt

; #define LAS __attribute__((address_space(3)))
;     __device__ __forceinline__ void operator()(const f32x4 (&acc)[2][2][4][2], const Unit& u, int wr, int wc, int fr, int fq) const {
;     ...
;                         const int l = 128 * ai + 64 * wr + 16 * m + frL, row = 254 * u.pm - 2 + l;
;                         const float rs = rt[l];
;                         const f32x4 cur = acc[ai][1][m][n] * rs, uu = acc[ai][0][m][n] * rs;
;                         if (m == 0) {
;                             const int B = 2 * ai + wr;
;                             prev = (f32x4){0.f, 0.f, 0.f, 0.f};
;                             if (B > 0 && frL >= 14) prev = *(const LAS f32x4*)(halo + ((B - 1) * 2 + (frL - 14)) * 128 + fl + 4 * n);
;                         }
;                         f32x4 g1, g2;
;                         {
;                             const float c1x = dpp_ror1(cur.x), c1y = dpp_ror1(cur.y), c1z = dpp_ror1(cur.z), c1w = dpp_ror1(cur.w);
;                             const float p1x = dpp_ror1(prev.x), p1y = dpp_ror1(prev.y), p1z = dpp_ror1(prev.z), p1w = dpp_ror1(prev.w);
;                             const float c2x = dpp_ror2(cur.x), c2y = dpp_ror2(cur.y), c2z = dpp_ror2(cur.z), c2w = dpp_ror2(cur.w);
;                             const float p2x = dpp_ror2(prev.x), p2y = dpp_ror2(prev.y), p2z = dpp_ror2(prev.z), p2w = dpp_ror2(prev.w);
;                             const bool s1 = frL >= 1, s2 = frL >= 2;
;                             g1.x = s1 ? c1x : p1x; g1.y = s1 ? c1y : p1y; g1.z = s1 ? c1z : p1z; g1.w = s1 ? c1w : p1w;
;                             g2.x = s2 ? c2x : p2x; g2.y = s2 ? c2y : p2y; g2.z = s2 ? c2z : p2z; g2.w = s2 ? c2w : p2w;
;                         }
;                         if (l >= 2 && row < M) {
;                             if (row < MP) {
;                                 const int b = row / TP, t = row - b * TP;
;                                 if (t < 2) { g2 = (f32x4){0.f, 0.f, 0.f, 0.f}; if (t == 0) g1 = g2; }
;                                 if (t >= TP - 2) *(f32x4*)(cvp + ((size_t)b * 2 + (t - (TP - 2))) * DFF + f0) = cur;
;                             } else {
;                                 const int s = row - MP;
;                                 const float* c0 = cst + ((size_t)s * 2 + 0) * DFF + f0;
;                                 g2 = *(const f32x4*)c0; g1 = *(const f32x4*)(c0 + DFF);
.LBB0_1361:
	s_or_b64 exec, exec, s[52:53]
	s_waitcnt vmcnt(0)
	v_pk_fma_f32 v[156:157], v[140:141], v[156:157], v[144:145]
	v_pk_fma_f32 v[158:159], v[142:143], v[158:159], v[146:147]
	v_pk_fma_f32 v[148:149], v[136:137], v[148:149], v[156:157]
	v_pk_fma_f32 v[150:151], v[138:139], v[150:151], v[158:159]
	v_pk_fma_f32 v[148:149], v[152:153], v[132:133], v[148:149]
	v_pk_fma_f32 v[150:151], v[154:155], v[134:135], v[150:151]
	v_mul_f32_e32 v0, 0xbfb8aa3b, v148
	v_mul_f32_e32 v156, 0xbfb8aa3b, v149
	v_exp_f32_e32 v0, v0
	v_exp_f32_e32 v156, v156
	v_pk_mul_f32 v[166:167], v[36:37], v[190:191]
	v_mov_b32_e32 v2, v190
	v_add_f32_e32 v0, 1.0, v0
	v_add_f32_e32 v156, 1.0, v156
	v_rcp_f32_e32 v0, v0
	v_rcp_f32_e32 v156, v156
	v_mov_b32_e32 v3, v190
	v_pk_mul_f32 v[2:3], v[38:39], v[2:3]
	v_mul_f32_e32 v0, v148, v0
	v_mul_f32_e32 v148, v149, v156
	v_mul_f32_e32 v149, 0xbfb8aa3b, v150
	v_exp_f32_e32 v149, v149
	v_mul_f32_e32 v156, 0xbfb8aa3b, v151
	v_exp_f32_e32 v156, v156
	v_mul_f32_e32 v0, v166, v0
	v_add_f32_e32 v149, 1.0, v149
	v_rcp_f32_e32 v149, v149
	v_add_f32_e32 v156, 1.0, v156
	v_rcp_f32_e32 v156, v156
	v_mul_f32_e32 v148, v167, v148
	v_cvt_pk_bf16_f32 v148, v0, v148
	v_mul_f32_e32 v0, v150, v149
	v_mul_f32_e32 v0, v2, v0
	v_mul_f32_e32 v2, v151, v156
	v_readlane_b32 s52, v252, 8
	v_mul_f32_e32 v2, v3, v2
	v_readlane_b32 s53, v252, 9
	v_cvt_pk_bf16_f32 v149, v0, v2
	s_movk_i32 s14, 0x1600
	s_nop 0
	v_mov_b64_e32 v[2:3], s[52:53]
	v_mad_i64_i32 v[2:3], s[52:53], v217, s14, v[2:3]
	v_lshl_add_u64 v[2:3], v[202:203], 1, v[2:3]
	global_store_dwordx2 v[2:3], v[148:149], off nt
.LBB0_1362:
	s_or_b64 exec, exec, s[10:11]
	v_mov_b32_e32 v2, v192
	v_mov_b32_e32 v3, v192
	v_pk_mul_f32 v[150:151], v[26:27], v[2:3]
	v_pk_mul_f32 v[148:149], v[24:25], v[192:193]
	v_mov_b32_e32 v0, v1
	v_mov_b32_e32 v2, v1
	v_mov_b32_e32 v3, v1
	v_mov_b32_e32 v166, v1
	v_mov_b32_e32 v167, v1
	v_mov_b32_e32 v168, v1
	v_mov_b32_e32 v169, v1
	v_mov_b32_e32 v171, v1
	v_mov_b32_e32 v170, v1
	v_mov_b32_e32 v185, v1
	v_mov_b32_e32 v186, v1
	v_mov_b32_e32 v187, v1
	v_mov_b32_e32 v188, v1
	v_mov_b32_e32 v189, v1
	v_mov_b32_e32 v190, v1
	v_mov_b32_e32 v191, v1
	v_mov_b32_dpp v0, v148 row_ror:1 row_mask:0xf bank_mask:0xf
	v_mov_b32_dpp v2, v149 row_ror:1 row_mask:0xf bank_mask:0xf
	v_mov_b32_dpp v3, v150 row_ror:1 row_mask:0xf bank_mask:0xf
	v_mov_b32_dpp v166, v151 row_ror:1 row_mask:0xf bank_mask:0xf
	v_mov_b32_dpp v167, v152 row_ror:1 row_mask:0xf bank_mask:0xf
	v_mov_b32_dpp v168, v153 row_ror:1 row_mask:0xf bank_mask:0xf
	v_mov_b32_dpp v169, v154 row_ror:1 row_mask:0xf bank_mask:0xf
	v_mov_b32_dpp v171, v155 row_ror:1 row_mask:0xf bank_mask:0xf
	v_mov_b32_dpp v170, v148 row_ror:2 row_mask:0xf bank_mask:0xf
	v_mov_b32_dpp v185, v149 row_ror:2 row_mask:0xf bank_mask:0xf
	v_mov_b32_dpp v186, v150 row_ror:2 row_mask:0xf bank_mask:0xf
	v_mov_b32_dpp v187, v151 row_ror:2 row_mask:0xf bank_mask:0xf
	v_mov_b32_dpp v188, v152 row_ror:2 row_mask:0xf bank_mask:0xf
	v_mov_b32_dpp v189, v153 row_ror:2 row_mask:0xf bank_mask:0xf
	v_mov_b32_dpp v190, v154 row_ror:2 row_mask:0xf bank_mask:0xf
	v_mov_b32_dpp v191, v155 row_ror:2 row_mask:0xf bank_mask:0xf
	s_and_saveexec_b64 s[10:11], s[66:67]
	s_cbranch_execz .LBB0_1374
	s_movk_i32 s14, 0x407f
	v_cmp_lt_i32_e32 vcc, s14, v218
	s_and_saveexec_b64 s[52:53], vcc
	s_xor_b64 s[52:53], exec, s[52:53]
	s_cbranch_execz .LBB0_1365
	v_add_u32_e32 v0, 0xffffbf80, v218
	s_movk_i32 s14, 0x5800
	v_mad_u64_u32 v[2:3], s[54:55], v0, s14, v[164:165]
	v_add_co_u32_e32 v152, vcc, 0x2000, v2
	s_nop 1
	v_addc_co_u32_e32 v153, vcc, 0, v3, vcc
	global_load_dwordx4 v[152:155], v[152:153], off offset:3088
	s_nop 0
	global_load_dwordx4 v[156:159], v[2:3], off offset:16
	v_mad_u64_u32 v[2:3], s[54:55], v0, s14, v[162:163]
	v_add_co_u32_e32 v166, vcc, 0x2000, v2
	s_nop 1
	v_addc_co_u32_e32 v167, vcc, 0, v3, vcc
	s_waitcnt vmcnt(1)
	global_store_dwordx4 v[2:3], v[152:155], off offset:16 nt
	global_store_dwordx4 v[166:167], v[148:151], off offset:3088 nt

; #define LAS __attribute__((address_space(3)))
;     __device__ __forceinline__ void operator()(const f32x4 (&acc)[2][2][4][2], const Unit& u, int wr, int wc, int fr, int fq) const {
;     ...
;                         const int l = 128 * ai + 64 * wr + 16 * m + frL, row = 254 * u.pm - 2 + l;
;                         const float rs = rt[l];
;                         const f32x4 cur = acc[ai][1][m][n] * rs, uu = acc[ai][0][m][n] * rs;
;                         if (m == 0) {
;                             const int B = 2 * ai + wr;
;                             prev = (f32x4){0.f, 0.f, 0.f, 0.f};
;                             if (B > 0 && frL >= 14) prev = *(const LAS f32x4*)(halo + ((B - 1) * 2 + (frL - 14)) * 128 + fl + 4 * n);
;                         }
;                         f32x4 g1, g2;
;                         {
;                             const float c1x = dpp_ror1(cur.x), c1y = dpp_ror1(cur.y), c1z = dpp_ror1(cur.z), c1w = dpp_ror1(cur.w);
;                             const float p1x = dpp_ror1(prev.x), p1y = dpp_ror1(prev.y), p1z = dpp_ror1(prev.z), p1w = dpp_ror1(prev.w);
;                             const float c2x = dpp_ror2(cur.x), c2y = dpp_ror2(cur.y), c2z = dpp_ror2(cur.z), c2w = dpp_ror2(cur.w);
;                             const float p2x = dpp_ror2(prev.x), p2y = dpp_ror2(prev.y), p2z = dpp_ror2(prev.z), p2w = dpp_ror2(prev.w);
;                             const bool s1 = frL >= 1, s2 = frL >= 2;
;                             g1.x = s1 ? c1x : p1x; g1.y = s1 ? c1y : p1y; g1.z = s1 ? c1z : p1z; g1.w = s1 ? c1w : p1w;
;                             g2.x = s2 ? c2x : p2x; g2.y = s2 ? c2y : p2y; g2.z = s2 ? c2z : p2z; g2.w = s2 ? c2w : p2w;
;                         }
;                         if (l >= 2 && row < M) {
;                             if (row < MP) {
;                                 const int b = row / TP, t = row - b * TP;
;                                 if (t < 2) { g2 = (f32x4){0.f, 0.f, 0.f, 0.f}; if (t == 0) g1 = g2; }
;                                 if (t >= TP - 2) *(f32x4*)(cvp + ((size_t)b * 2 + (t - (TP - 2))) * DFF + f0) = cur;
;                             } else {
;                                 const int s = row - MP;
;                                 const float* c0 = cst + ((size_t)s * 2 + 0) * DFF + f0;
;                                 g2 = *(const f32x4*)c0; g1 = *(const f32x4*)(c0 + DFF);
.LBB0_1373:
	s_or_b64 exec, exec, s[52:53]
	s_waitcnt vmcnt(0)
	v_pk_fma_f32 v[156:157], v[140:141], v[156:157], v[144:145]
	v_pk_fma_f32 v[158:159], v[142:143], v[158:159], v[146:147]
	v_pk_fma_f32 v[152:153], v[136:137], v[152:153], v[156:157]
	v_pk_fma_f32 v[154:155], v[138:139], v[154:155], v[158:159]
	v_pk_fma_f32 v[152:153], v[148:149], v[132:133], v[152:153]
	v_pk_fma_f32 v[154:155], v[150:151], v[134:135], v[154:155]
	v_mul_f32_e32 v0, 0xbfb8aa3b, v152
	v_mul_f32_e32 v156, 0xbfb8aa3b, v153
	v_exp_f32_e32 v0, v0
	v_exp_f32_e32 v156, v156
	v_pk_mul_f32 v[166:167], v[20:21], v[192:193]
	v_mov_b32_e32 v2, v192
	v_add_f32_e32 v0, 1.0, v0
	v_add_f32_e32 v156, 1.0, v156
	v_rcp_f32_e32 v0, v0
	v_rcp_f32_e32 v156, v156
	v_mov_b32_e32 v3, v192
	v_pk_mul_f32 v[2:3], v[22:23], v[2:3]
	v_mul_f32_e32 v0, v152, v0
	v_mul_f32_e32 v152, v153, v156
	v_mul_f32_e32 v153, 0xbfb8aa3b, v154
	v_exp_f32_e32 v153, v153
	v_mul_f32_e32 v156, 0xbfb8aa3b, v155
	v_exp_f32_e32 v156, v156
	v_mul_f32_e32 v0, v166, v0
	v_add_f32_e32 v153, 1.0, v153
	v_rcp_f32_e32 v153, v153
	v_add_f32_e32 v156, 1.0, v156
	v_rcp_f32_e32 v156, v156
	v_mul_f32_e32 v152, v167, v152
	v_cvt_pk_bf16_f32 v152, v0, v152
	v_mul_f32_e32 v0, v154, v153
	v_mul_f32_e32 v0, v2, v0
	v_mul_f32_e32 v2, v155, v156
	v_readlane_b32 s52, v252, 8
	v_mul_f32_e32 v2, v3, v2
	v_readlane_b32 s53, v252, 9
	v_cvt_pk_bf16_f32 v153, v0, v2
	s_movk_i32 s14, 0x1600
	s_nop 0
	v_mov_b64_e32 v[2:3], s[52:53]
	v_mad_i64_i32 v[2:3], s[52:53], v218, s14, v[2:3]
	v_lshl_add_u64 v[2:3], v[202:203], 1, v[2:3]
	global_store_dwordx2 v[2:3], v[152:153], off nt
.LBB0_1374:
	s_or_b64 exec, exec, s[10:11]
	v_mov_b32_e32 v2, v196
	v_mov_b32_e32 v3, v196
	v_pk_mul_f32 v[154:155], v[10:11], v[2:3]
	v_pk_mul_f32 v[152:153], v[8:9], v[196:197]
	v_mov_b32_e32 v0, v1
	v_mov_b32_e32 v2, v1
	v_mov_b32_e32 v3, v1
	v_mov_b32_e32 v166, v1
	v_mov_b32_e32 v167, v1
	v_mov_b32_e32 v168, v1
	v_mov_b32_e32 v169, v1
	v_mov_b32_e32 v171, v1
	v_mov_b32_e32 v170, v1
	v_mov_b32_e32 v185, v1
	v_mov_b32_e32 v186, v1
	v_mov_b32_e32 v187, v1
	v_mov_b32_e32 v188, v1
	v_mov_b32_e32 v189, v1
	v_mov_b32_e32 v190, v1
	v_mov_b32_e32 v191, v1
	v_mov_b32_dpp v0, v152 row_ror:1 row_mask:0xf bank_mask:0xf
	v_mov_b32_dpp v2, v153 row_ror:1 row_mask:0xf bank_mask:0xf
	v_mov_b32_dpp v3, v154 row_ror:1 row_mask:0xf bank_mask:0xf
	v_mov_b32_dpp v166, v155 row_ror:1 row_mask:0xf bank_mask:0xf
	v_mov_b32_dpp v167, v148 row_ror:1 row_mask:0xf bank_mask:0xf
	v_mov_b32_dpp v168, v149 row_ror:1 row_mask:0xf bank_mask:0xf
	v_mov_b32_dpp v169, v150 row_ror:1 row_mask:0xf bank_mask:0xf
	v_mov_b32_dpp v171, v151 row_ror:1 row_mask:0xf bank_mask:0xf
	v_mov_b32_dpp v170, v152 row_ror:2 row_mask:0xf bank_mask:0xf
	v_mov_b32_dpp v185, v153 row_ror:2 row_mask:0xf bank_mask:0xf
	v_mov_b32_dpp v186, v154 row_ror:2 row_mask:0xf bank_mask:0xf
	v_mov_b32_dpp v187, v155 row_ror:2 row_mask:0xf bank_mask:0xf
	v_mov_b32_dpp v188, v148 row_ror:2 row_mask:0xf bank_mask:0xf
	v_mov_b32_dpp v189, v149 row_ror:2 row_mask:0xf bank_mask:0xf
	v_mov_b32_dpp v190, v150 row_ror:2 row_mask:0xf bank_mask:0xf
	v_mov_b32_dpp v191, v151 row_ror:2 row_mask:0xf bank_mask:0xf
	s_and_saveexec_b64 s[10:11], s[0:1]
	s_cbranch_execz .LBB0_1386
	s_movk_i32 s0, 0x407f
	v_cmp_lt_i32_e32 vcc, s0, v219
	s_and_saveexec_b64 s[0:1], vcc
	s_xor_b64 s[0:1], exec, s[0:1]
	s_cbranch_execz .LBB0_1377
	v_add_u32_e32 v0, 0xffffbf80, v219
	s_movk_i32 s14, 0x5800
	v_mad_u64_u32 v[2:3], s[52:53], v0, s14, v[164:165]
	v_add_co_u32_e32 v148, vcc, 0x2000, v2
	s_nop 1
	v_addc_co_u32_e32 v149, vcc, 0, v3, vcc
	global_load_dwordx4 v[148:151], v[148:149], off offset:3088
	s_nop 0
	global_load_dwordx4 v[156:159], v[2:3], off offset:16
	v_mad_u64_u32 v[2:3], s[52:53], v0, s14, v[162:163]
	v_add_co_u32_e32 v160, vcc, 0x2000, v2
	s_nop 1
	v_addc_co_u32_e32 v161, vcc, 0, v3, vcc
	s_waitcnt vmcnt(1)
	global_store_dwordx4 v[2:3], v[148:151], off offset:16 nt
	global_store_dwordx4 v[160:161], v[152:155], off offset:3088 nt

;     __device__ __forceinline__ void operator()(const f32x4 (&acc)[2][2][4][2], const Unit& u, int wr, int wc, int fr, int fq) const {
;     ...
;                             if (row < MP) {
;                                 const int b = row / TP, t = row - b * TP;
;                                 if (t < 2) { g2 = (f32x4){0.f, 0.f, 0.f, 0.f}; if (t == 0) g1 = g2; }
;                                 if (t >= TP - 2) *(f32x4*)(cvp + ((size_t)b * 2 + (t - (TP - 2))) * DFF + f0) = cur;
.LBB0_1382:
	s_or_b64 exec, exec, s[6:7]
	s_movk_i32 s6, 0x80d
	v_cmp_lt_i32_e32 vcc, s6, v164
	s_and_saveexec_b64 s[6:7], vcc
	s_cbranch_execz .LBB0_1384
	v_ashrrev_i32_e32 v163, 31, v162
	v_add_u32_e32 v0, 0xfffff7f2, v164
	v_lshl_add_u64 v[2:3], v[162:163], 1, v[0:1]
	s_movk_i32 s14, 0x2c00
	v_mad_u64_u32 v[160:161], s[8:9], v2, s14, v[160:161]
	v_mad_i32_i24 v161, v3, s14, v161
	global_store_dwordx4 v[160:161], v[152:155], off offset:16 nt

; __device__ __forceinline__ unsigned cvt_pk_bf16(float lo, float hi) { unsigned r; asm("v_cvt_pk_bf16_f32 %0, %1, %2" : "=v"(r) : "v"(lo), "v"(hi)); return r; }
; __device__ __forceinline__ float siluf_(float x) { return x * rcpf_(1.f + __expf(-x)); }
;     __device__ __forceinline__ void operator()(const f32x4 (&acc)[2][2][4][2], const Unit& u, int wr, int wc, int fr, int fq) const {
;     ...
;                             const f32x4 cv = bb + w0 * g2 + w1 * g1 + w2 * cur;
;                             v2u w; w.x = cvt_pk_bf16(siluf_(cv.x) * uu.x, siluf_(cv.y) * uu.y); w.y = cvt_pk_bf16(siluf_(cv.z) * uu.z, siluf_(cv.w) * uu.w);
;                             *(v2u*)(ACT + (size_t)row * DFF + f0) = w;
.LBB0_1385:
	s_or_b64 exec, exec, s[0:1]
	s_waitcnt vmcnt(0)
	v_pk_fma_f32 v[140:141], v[140:141], v[156:157], v[144:145]
	v_pk_fma_f32 v[142:143], v[142:143], v[158:159], v[146:147]
	v_pk_fma_f32 v[136:137], v[136:137], v[148:149], v[140:141]
	v_pk_mul_f32 v[160:161], v[4:5], v[196:197]
	v_pk_fma_f32 v[132:133], v[152:153], v[132:133], v[136:137]
	v_mov_b32_e32 v2, v196
	v_mul_f32_e32 v0, 0xbfb8aa3b, v132
	v_mul_f32_e32 v136, 0xbfb8aa3b, v133
	v_exp_f32_e32 v0, v0
	v_exp_f32_e32 v140, v136
	v_pk_fma_f32 v[136:137], v[138:139], v[150:151], v[142:143]
	v_mov_b32_e32 v3, v196
	v_add_f32_e32 v0, 1.0, v0
	v_add_f32_e32 v138, 1.0, v140
	v_rcp_f32_e32 v0, v0
	v_rcp_f32_e32 v138, v138
	v_pk_fma_f32 v[134:135], v[154:155], v[134:135], v[136:137]
	v_pk_mul_f32 v[2:3], v[6:7], v[2:3]
	v_mul_f32_e32 v0, v132, v0
	v_mul_f32_e32 v132, v133, v138
	v_mul_f32_e32 v133, 0xbfb8aa3b, v134
	v_exp_f32_e32 v133, v133
	v_mul_f32_e32 v136, 0xbfb8aa3b, v135
	v_exp_f32_e32 v136, v136
	v_mul_f32_e32 v0, v160, v0
	v_add_f32_e32 v133, 1.0, v133
	v_rcp_f32_e32 v133, v133
	v_add_f32_e32 v136, 1.0, v136
	v_rcp_f32_e32 v136, v136
	v_mul_f32_e32 v132, v161, v132
	v_cvt_pk_bf16_f32 v132, v0, v132
	v_mul_f32_e32 v0, v134, v133
	v_mul_f32_e32 v0, v2, v0
	v_mul_f32_e32 v2, v135, v136
	v_readlane_b32 s0, v252, 8
	v_mul_f32_e32 v2, v3, v2
	v_readlane_b32 s1, v252, 9
	v_cvt_pk_bf16_f32 v133, v0, v2
	s_nop 1
	v_mov_b64_e32 v[2:3], s[0:1]
	s_movk_i32 s0, 0x1600
	v_mad_i64_i32 v[2:3], s[0:1], v219, s0, v[2:3]
	v_lshl_add_u64 v[2:3], v[202:203], 1, v[2:3]
	global_store_dwordx2 v[2:3], v[132:133], off nt

; #define LAS __attribute__((address_space(3)))
; __device__ __forceinline__ unsigned cvt_pk_bf16(float lo, float hi) { unsigned r; asm("v_cvt_pk_bf16_f32 %0, %1, %2" : "=v"(r) : "v"(lo), "v"(hi)); return r; }
;     __device__ __forceinline__ void operator()(const f32x4 (&acc)[2][2][4][2], const Unit& u, int wr, int wc, int fr, int fq) const {
;     ...
;                 for (int ai = 0; ai < 2; ++ai)
; #pragma unroll
;                     for (int m = 0; m < 4; ++m) {
;                         const int l = 128 * ai + 64 * wr + 16 * m + frL;
;                         const float rs = rt[l];
;                         if (m == 0) {
;                             const int B = 2 * ai + wr;
;                             prevA = (f32x4){0.f, 0.f, 0.f, 0.f}; prevB = prevA;
;                             if (B > 0 && frL >= 14) { const LAS float* hp = halo + ((B - 1) * 2 + (frL - 14)) * 128 + fl; prevA = *(const LAS f32x4*)hp; prevB = *(const LAS f32x4*)(hp + 4); }
;                         }
;                         unsigned wv[4];
; #pragma unroll
;                         for (int n = 0; n < 2; ++n) {
;                             const f32x4 w0 = n ? Wb0 : Wa0, w1 = n ? Wb1 : Wa1, w2 = n ? Wb2 : Wa2, bb = n ? Wbb : Wab;
;                             const f32x4 cur = acc[ai][1][m][n] * rs, uu = acc[ai][0][m][n] * rs, prev = n ? prevB : prevA;
;                             float ov[4];
; #pragma unroll
;                             for (int e = 0; e < 4; ++e) {
;                                 const float ce = cur[e], pe = prev[e];
;                                 const float g1 = dpp_mv<0x121>(k15 ? pe : ce), g2 = dpp_mv<0x122>(k14 ? pe : ce);
;                                 const float cv = fmaf(w0[e], g2, fmaf(w1[e], g1, fmaf(w2[e], ce, bb[e])));
;                                 ov[e] = siluf_(cv) * uu[e];
;                             }
;                             wv[2 * n] = cvt_pk_bf16(ov[0], ov[1]); wv[2 * n + 1] = cvt_pk_bf16(ov[2], ov[3]);
;                             if (n) prevB = cur; else prevA = cur;
;                         }
;                         if (ai > 0 || m > 0 || l >= 2) *(v4u*)((unsigned char*)ACT + (ob + (unsigned)((128 * ai + 16 * m) * DFF * 2))) = (v4u){wv[0], wv[1], wv[2], wv[3]};
;                         __builtin_amdgcn_sched_barrier(0);
;                     }
.LBB0_1391:
	s_or_b64 exec, exec, s[0:1]
	v_readlane_b32 s0, v255, 12
	s_add_i32 s0, s0, s21
	v_cmp_eq_u32_e64 s[6:7], 15, v212
	v_add_u32_e32 v2, s0, v212
	s_movk_i32 s0, 0xb00
	v_mul_lo_u32 v2, v2, s0
	s_waitcnt lgkmcnt(0)
	v_pk_mul_f32 v[128:129], v[128:129], v[0:1] op_sel_hi:[1,0]
	v_add_lshl_u32 v184, v184, v2, 1
	v_pk_mul_f32 v[2:3], v[130:131], v[0:1] op_sel_hi:[1,0]
	v_cndmask_b32_e64 v130, v128, v168, s[6:7]
	v_cndmask_b32_e32 v131, v168, v128, vcc
	s_waitcnt vmcnt(0)
	v_fma_f32 v168, v160, v128, v148
	v_mov_b32_dpp v130, v130 row_ror:1 row_mask:0xf bank_mask:0xf bound_ctrl:1
	v_mov_b32_dpp v131, v131 row_ror:2 row_mask:0xf bank_mask:0xf bound_ctrl:1
	v_fmac_f32_e32 v168, v156, v130
	v_fmac_f32_e32 v168, v152, v131
	v_mul_f32_e32 v130, 0xbfb8aa3b, v168
	v_exp_f32_e32 v130, v130
	v_mul_f32_e32 v124, v124, v0
	v_cndmask_b32_e32 v131, v169, v129, vcc
	v_mul_f32_e32 v125, v125, v0
	v_add_f32_e32 v130, 1.0, v130
	v_rcp_f32_e32 v130, v130
	v_mov_b32_dpp v131, v131 row_ror:2 row_mask:0xf bank_mask:0xf bound_ctrl:1
	v_mul_f32_e32 v126, v126, v0
	v_mul_f32_e32 v127, v127, v0
	v_mul_f32_e32 v130, v168, v130
	v_mul_f32_e32 v124, v124, v130
	v_cndmask_b32_e64 v130, v129, v169, s[6:7]
	v_fma_f32 v168, v161, v129, v149
	v_pk_mul_f32 v[120:121], v[120:121], v[0:1] op_sel_hi:[1,0]
	v_mov_b32_dpp v130, v130 row_ror:1 row_mask:0xf bank_mask:0xf bound_ctrl:1
	v_fmac_f32_e32 v168, v157, v130
	v_fmac_f32_e32 v168, v153, v131
	v_mul_f32_e32 v130, 0xbfb8aa3b, v168
	v_exp_f32_e32 v130, v130
	v_cndmask_b32_e32 v131, v170, v2, vcc
	v_mul_f32_e32 v116, v116, v0
	v_pk_mul_f32 v[122:123], v[122:123], v[0:1] op_sel_hi:[1,0]
	v_add_f32_e32 v130, 1.0, v130
	v_rcp_f32_e32 v130, v130
	v_mov_b32_dpp v131, v131 row_ror:2 row_mask:0xf bank_mask:0xf bound_ctrl:1
	v_mul_f32_e32 v117, v117, v0
	v_mul_f32_e32 v118, v118, v0
	v_mul_f32_e32 v130, v168, v130
	v_mul_f32_e32 v125, v125, v130
	v_cndmask_b32_e64 v130, v2, v170, s[6:7]
	v_fma_f32 v168, v162, v2, v150
	v_cvt_pk_bf16_f32 v124, v124, v125
	v_mul_f32_e32 v0, v119, v0
	v_mov_b32_dpp v130, v130 row_ror:1 row_mask:0xf bank_mask:0xf bound_ctrl:1
	v_fmac_f32_e32 v168, v158, v130
	v_fmac_f32_e32 v168, v154, v131
	v_mul_f32_e32 v130, 0xbfb8aa3b, v168
	v_exp_f32_e32 v130, v130
	v_cndmask_b32_e32 v131, v171, v3, vcc
	v_cmp_lt_i32_e64 s[0:1], 1, v211
	v_add_f32_e32 v130, 1.0, v130
	v_rcp_f32_e32 v130, v130
	v_mov_b32_dpp v131, v131 row_ror:2 row_mask:0xf bank_mask:0xf bound_ctrl:1
	v_mul_f32_e32 v130, v168, v130
	v_mul_f32_e32 v126, v126, v130
	v_cndmask_b32_e64 v130, v3, v171, s[6:7]
	v_fma_f32 v168, v163, v3, v151
	s_nop 0
	v_mov_b32_dpp v130, v130 row_ror:1 row_mask:0xf bank_mask:0xf bound_ctrl:1
	v_fmac_f32_e32 v168, v159, v130
	v_fmac_f32_e32 v168, v155, v131
	v_mul_f32_e32 v130, 0xbfb8aa3b, v168
	v_exp_f32_e32 v130, v130
	s_nop 0
	v_add_f32_e32 v130, 1.0, v130
	v_rcp_f32_e32 v130, v130
	s_nop 0
	v_mul_f32_e32 v130, v168, v130
	v_mul_f32_e32 v127, v127, v130
	v_cvt_pk_bf16_f32 v125, v126, v127
	v_cndmask_b32_e64 v126, v120, v164, s[6:7]
	v_cndmask_b32_e32 v127, v164, v120, vcc
	v_fma_f32 v130, v144, v120, v132
	v_mov_b32_dpp v126, v126 row_ror:1 row_mask:0xf bank_mask:0xf bound_ctrl:1
	v_mov_b32_dpp v127, v127 row_ror:2 row_mask:0xf bank_mask:0xf bound_ctrl:1
	v_fmac_f32_e32 v130, v140, v126
	v_fmac_f32_e32 v130, v136, v127
	v_mul_f32_e32 v126, 0xbfb8aa3b, v130
	v_exp_f32_e32 v126, v126
	v_cndmask_b32_e32 v127, v165, v121, vcc
	v_add_f32_e32 v126, 1.0, v126
	v_rcp_f32_e32 v126, v126
	v_mov_b32_dpp v127, v127 row_ror:2 row_mask:0xf bank_mask:0xf bound_ctrl:1
	v_mul_f32_e32 v126, v130, v126
	v_mul_f32_e32 v116, v116, v126
	v_cndmask_b32_e64 v126, v121, v165, s[6:7]
	v_fma_f32 v130, v145, v121, v133
	s_nop 0
	v_mov_b32_dpp v126, v126 row_ror:1 row_mask:0xf bank_mask:0xf bound_ctrl:1
	v_fmac_f32_e32 v130, v141, v126
	v_fmac_f32_e32 v130, v137, v127
	v_mul_f32_e32 v126, 0xbfb8aa3b, v130
	v_exp_f32_e32 v126, v126
	v_cndmask_b32_e32 v127, v166, v122, vcc
	v_add_f32_e32 v126, 1.0, v126
	v_rcp_f32_e32 v126, v126
	v_mov_b32_dpp v127, v127 row_ror:2 row_mask:0xf bank_mask:0xf bound_ctrl:1
	v_mul_f32_e32 v126, v130, v126
	v_mul_f32_e32 v117, v117, v126
	v_cndmask_b32_e64 v126, v122, v166, s[6:7]
	v_fma_f32 v130, v146, v122, v134
	s_nop 0
	v_mov_b32_dpp v126, v126 row_ror:1 row_mask:0xf bank_mask:0xf bound_ctrl:1
	v_fmac_f32_e32 v130, v142, v126
	v_fmac_f32_e32 v130, v138, v127
	v_mul_f32_e32 v126, 0xbfb8aa3b, v130
	v_exp_f32_e32 v126, v126
	v_cndmask_b32_e32 v127, v167, v123, vcc
	v_add_f32_e32 v126, 1.0, v126
	v_rcp_f32_e32 v126, v126
	v_mov_b32_dpp v127, v127 row_ror:2 row_mask:0xf bank_mask:0xf bound_ctrl:1
	v_mul_f32_e32 v126, v130, v126
	v_mul_f32_e32 v118, v118, v126
	v_cndmask_b32_e64 v126, v123, v167, s[6:7]
	v_fma_f32 v130, v147, v123, v135
	s_nop 0
	v_mov_b32_dpp v126, v126 row_ror:1 row_mask:0xf bank_mask:0xf bound_ctrl:1
	v_fmac_f32_e32 v130, v143, v126
	v_fmac_f32_e32 v130, v139, v127
	v_mul_f32_e32 v126, 0xbfb8aa3b, v130
	v_exp_f32_e32 v126, v126
	s_nop 0
	v_add_f32_e32 v126, 1.0, v126
	v_rcp_f32_e32 v126, v126
	s_nop 0
	v_mul_f32_e32 v126, v130, v126
	v_mul_f32_e32 v0, v0, v126
	v_cvt_pk_bf16_f32 v126, v116, v117
	v_cvt_pk_bf16_f32 v127, v118, v0
	s_and_saveexec_b64 s[8:9], s[0:1]
	s_cbranch_execz .LBB0_1393
	v_readlane_b32 s0, v252, 8
	v_readlane_b32 s1, v252, 9
	s_nop 4
	global_store_dwordx4 v184, v[124:127], s[0:1] nt
; #define LAS __attribute__((address_space(3)))
; __device__ __forceinline__ unsigned cvt_pk_bf16(float lo, float hi) { unsigned r; asm("v_cvt_pk_bf16_f32 %0, %1, %2" : "=v"(r) : "v"(lo), "v"(hi)); return r; }
;     __device__ __forceinline__ void operator()(const f32x4 (&acc)[2][2][4][2], const Unit& u, int wr, int wc, int fr, int fq) const {
;     ...
;                 for (int ai = 0; ai < 2; ++ai)
; #pragma unroll
;                     for (int m = 0; m < 4; ++m) {
;                         const int l = 128 * ai + 64 * wr + 16 * m + frL;
;                         const float rs = rt[l];
;                         if (m == 0) {
;                             const int B = 2 * ai + wr;
;                             prevA = (f32x4){0.f, 0.f, 0.f, 0.f}; prevB = prevA;
;                             if (B > 0 && frL >= 14) { const LAS float* hp = halo + ((B - 1) * 2 + (frL - 14)) * 128 + fl; prevA = *(const LAS f32x4*)hp; prevB = *(const LAS f32x4*)(hp + 4); }
;                         }
;                         unsigned wv[4];
; #pragma unroll
;                         for (int n = 0; n < 2; ++n) {
;                             const f32x4 w0 = n ? Wb0 : Wa0, w1 = n ? Wb1 : Wa1, w2 = n ? Wb2 : Wa2, bb = n ? Wbb : Wab;
;                             const f32x4 cur = acc[ai][1][m][n] * rs, uu = acc[ai][0][m][n] * rs, prev = n ? prevB : prevA;
;                             float ov[4];
; #pragma unroll
;                             for (int e = 0; e < 4; ++e) {
;                                 const float ce = cur[e], pe = prev[e];
;                                 const float g1 = dpp_mv<0x121>(k15 ? pe : ce), g2 = dpp_mv<0x122>(k14 ? pe : ce);
;                                 const float cv = fmaf(w0[e], g2, fmaf(w1[e], g1, fmaf(w2[e], ce, bb[e])));
;                                 ov[e] = siluf_(cv) * uu[e];
;                             }
;                             wv[2 * n] = cvt_pk_bf16(ov[0], ov[1]); wv[2 * n + 1] = cvt_pk_bf16(ov[2], ov[3]);
;                             if (n) prevB = cur; else prevA = cur;
;                         }
;                         if (ai > 0 || m > 0 || l >= 2) *(v4u*)((unsigned char*)ACT + (ob + (unsigned)((128 * ai + 16 * m) * DFF * 2))) = (v4u){wv[0], wv[1], wv[2], wv[3]};
;                         __builtin_amdgcn_sched_barrier(0);
;                     }
.LBB0_1393:
	s_or_b64 exec, exec, s[8:9]
	ds_read_b32 v116, v209 offset:64
	v_mov_b32_e32 v118, v108
	v_readlane_b32 s0, v252, 8
	v_readlane_b32 s1, v252, 9
	s_waitcnt lgkmcnt(0)
	v_pk_mul_f32 v[112:113], v[112:113], v[116:117] op_sel_hi:[1,0]
	s_nop 0
	v_cndmask_b32_e64 v0, v112, v128, s[6:7]
	v_pk_mul_f32 v[114:115], v[114:115], v[116:117] op_sel_hi:[1,0]
	v_cndmask_b32_e32 v117, v128, v112, vcc
	v_mov_b32_dpp v0, v0 row_ror:1 row_mask:0xf bank_mask:0xf bound_ctrl:1
	v_fma_f32 v119, v160, v112, v148
	v_mov_b32_dpp v117, v117 row_ror:2 row_mask:0xf bank_mask:0xf bound_ctrl:1
	v_fmac_f32_e32 v119, v156, v0
	v_fmac_f32_e32 v119, v152, v117
	v_mul_f32_e32 v0, 0xbfb8aa3b, v119
	v_exp_f32_e32 v0, v0
	v_cndmask_b32_e64 v108, v113, v129, s[6:7]
	v_add_f32_e32 v0, 1.0, v0
	v_rcp_f32_e32 v117, v0
	v_mov_b32_dpp v108, v108 row_ror:1 row_mask:0xf bank_mask:0xf bound_ctrl:1
	v_pk_mul_f32 v[118:119], v[118:119], v[116:117]
	s_nop 0
	v_mul_f32_e32 v0, v118, v119
	v_cndmask_b32_e32 v117, v129, v113, vcc
	v_fma_f32 v119, v161, v113, v149
	v_fmac_f32_e32 v119, v157, v108
	v_mov_b32_dpp v117, v117 row_ror:2 row_mask:0xf bank_mask:0xf bound_ctrl:1
	v_fmac_f32_e32 v119, v153, v117
	v_mul_f32_e32 v108, 0xbfb8aa3b, v119
	v_exp_f32_e32 v108, v108
	v_mov_b32_e32 v118, v109
	v_add_f32_e32 v108, 1.0, v108
	v_rcp_f32_e32 v117, v108
	s_nop 0
	v_pk_mul_f32 v[108:109], v[118:119], v[116:117]
	s_nop 0
	v_mul_f32_e32 v118, v108, v109
	v_cndmask_b32_e64 v108, v114, v2, s[6:7]
	v_cndmask_b32_e32 v2, v2, v114, vcc
	v_fma_f32 v109, v162, v114, v150
	v_mov_b32_dpp v108, v108 row_ror:1 row_mask:0xf bank_mask:0xf bound_ctrl:1
	v_mov_b32_dpp v2, v2 row_ror:2 row_mask:0xf bank_mask:0xf bound_ctrl:1
	v_fmac_f32_e32 v109, v158, v108
	v_fmac_f32_e32 v109, v154, v2
	v_mul_f32_e32 v2, 0xbfb8aa3b, v109
	v_exp_f32_e32 v2, v2
	v_mov_b32_e32 v108, v110
	v_add_f32_e32 v2, 1.0, v2
	v_rcp_f32_e32 v117, v2
	v_cndmask_b32_e64 v2, v115, v3, s[6:7]
	v_cndmask_b32_e32 v3, v3, v115, vcc
	v_pk_mul_f32 v[108:109], v[108:109], v[116:117]
	s_nop 0
	v_mul_f32_e32 v109, v108, v109
	v_mov_b32_dpp v2, v2 row_ror:1 row_mask:0xf bank_mask:0xf bound_ctrl:1
	v_mov_b32_dpp v108, v3 row_ror:2 row_mask:0xf bank_mask:0xf bound_ctrl:1
	v_fma_f32 v3, v163, v115, v151
	v_fmac_f32_e32 v3, v159, v2
	v_fmac_f32_e32 v3, v155, v108
	v_mul_f32_e32 v2, 0xbfb8aa3b, v3
	v_exp_f32_e32 v2, v2
	v_cvt_pk_bf16_f32 v108, v0, v118
	s_nop 0
	v_add_f32_e32 v2, 1.0, v2
	v_rcp_f32_e32 v117, v2
	v_mov_b32_e32 v2, v111
	v_pk_mul_f32 v[2:3], v[2:3], v[116:117]
	v_pk_mul_f32 v[104:105], v[104:105], v[116:117] op_sel_hi:[1,0]
	v_mul_f32_e32 v2, v2, v3
	v_cndmask_b32_e64 v0, v104, v120, s[6:7]
	v_cvt_pk_bf16_f32 v109, v109, v2
	v_pk_mul_f32 v[2:3], v[106:107], v[116:117] op_sel_hi:[1,0]
	v_cndmask_b32_e32 v106, v120, v104, vcc
	v_mov_b32_dpp v0, v0 row_ror:1 row_mask:0xf bank_mask:0xf bound_ctrl:1
	v_fma_f32 v107, v144, v104, v132
	v_mov_b32_dpp v106, v106 row_ror:2 row_mask:0xf bank_mask:0xf bound_ctrl:1
	v_fmac_f32_e32 v107, v140, v0
	v_fmac_f32_e32 v107, v136, v106
	v_mul_f32_e32 v0, 0xbfb8aa3b, v107
	v_exp_f32_e32 v0, v0
	v_mov_b32_e32 v106, v100
	v_cndmask_b32_e64 v100, v105, v121, s[6:7]
	v_add_f32_e32 v0, 1.0, v0
	v_rcp_f32_e32 v117, v0
	v_mov_b32_dpp v100, v100 row_ror:1 row_mask:0xf bank_mask:0xf bound_ctrl:1
	v_pk_mul_f32 v[106:107], v[106:107], v[116:117]
	s_nop 0
	v_mul_f32_e32 v0, v106, v107
	v_cndmask_b32_e32 v106, v121, v105, vcc
	v_fma_f32 v107, v145, v105, v133
	v_fmac_f32_e32 v107, v141, v100
	v_mov_b32_dpp v106, v106 row_ror:2 row_mask:0xf bank_mask:0xf bound_ctrl:1
	v_fmac_f32_e32 v107, v137, v106
	v_mul_f32_e32 v100, 0xbfb8aa3b, v107
	v_exp_f32_e32 v100, v100
	v_mov_b32_e32 v106, v101
	v_add_f32_e32 v100, 1.0, v100
	v_rcp_f32_e32 v117, v100
	s_nop 0
	v_pk_mul_f32 v[100:101], v[106:107], v[116:117]
	s_nop 0
	v_mul_f32_e32 v106, v100, v101
	v_cndmask_b32_e64 v100, v2, v122, s[6:7]
	v_cndmask_b32_e32 v101, v122, v2, vcc
	v_cvt_pk_bf16_f32 v110, v0, v106
	v_add_u32_e32 v0, 0x16000, v184
	v_mov_b32_dpp v100, v100 row_ror:1 row_mask:0xf bank_mask:0xf bound_ctrl:1
	v_mov_b32_dpp v107, v101 row_ror:2 row_mask:0xf bank_mask:0xf bound_ctrl:1
	v_fma_f32 v101, v146, v2, v134
	v_fmac_f32_e32 v101, v142, v100
	v_fmac_f32_e32 v101, v138, v107
	v_mul_f32_e32 v100, 0xbfb8aa3b, v101
	v_exp_f32_e32 v100, v100
	s_nop 0
	v_add_f32_e32 v100, 1.0, v100
	v_rcp_f32_e32 v117, v100
	v_mov_b32_e32 v100, v102
	v_pk_mul_f32 v[100:101], v[100:101], v[116:117]
	s_nop 0
	v_mul_f32_e32 v102, v100, v101
	v_cndmask_b32_e64 v100, v3, v123, s[6:7]
	v_cndmask_b32_e32 v101, v123, v3, vcc
	s_nop 0
	v_mov_b32_dpp v100, v100 row_ror:1 row_mask:0xf bank_mask:0xf bound_ctrl:1
	v_mov_b32_dpp v107, v101 row_ror:2 row_mask:0xf bank_mask:0xf bound_ctrl:1
	v_fma_f32 v101, v147, v3, v135
	v_fmac_f32_e32 v101, v143, v100
	v_fmac_f32_e32 v101, v139, v107
	v_mul_f32_e32 v100, 0xbfb8aa3b, v101
	v_exp_f32_e32 v100, v100
	s_nop 0
	v_add_f32_e32 v100, 1.0, v100
	v_rcp_f32_e32 v117, v100
	v_mov_b32_e32 v100, v103
	v_pk_mul_f32 v[100:101], v[100:101], v[116:117]
	s_nop 0
	v_mul_f32_e32 v100, v100, v101
	v_cvt_pk_bf16_f32 v111, v102, v100
	global_store_dwordx4 v0, v[108:111], s[0:1] nt
	ds_read_b32 v100, v209 offset:128
	v_mov_b32_e32 v102, v92
	s_waitcnt lgkmcnt(0)
; #define LAS __attribute__((address_space(3)))
; __device__ __forceinline__ unsigned cvt_pk_bf16(float lo, float hi) { unsigned r; asm("v_cvt_pk_bf16_f32 %0, %1, %2" : "=v"(r) : "v"(lo), "v"(hi)); return r; }
;     __device__ __forceinline__ void operator()(const f32x4 (&acc)[2][2][4][2], const Unit& u, int wr, int wc, int fr, int fq) const {
;     ...
;                 for (int ai = 0; ai < 2; ++ai)
; #pragma unroll
;                     for (int m = 0; m < 4; ++m) {
;                         const int l = 128 * ai + 64 * wr + 16 * m + frL;
;                         const float rs = rt[l];
;                         if (m == 0) {
;                             const int B = 2 * ai + wr;
;                             prevA = (f32x4){0.f, 0.f, 0.f, 0.f}; prevB = prevA;
;                             if (B > 0 && frL >= 14) { const LAS float* hp = halo + ((B - 1) * 2 + (frL - 14)) * 128 + fl; prevA = *(const LAS f32x4*)hp; prevB = *(const LAS f32x4*)(hp + 4); }
;                         }
;                         unsigned wv[4];
; #pragma unroll
;                         for (int n = 0; n < 2; ++n) {
;                             const f32x4 w0 = n ? Wb0 : Wa0, w1 = n ? Wb1 : Wa1, w2 = n ? Wb2 : Wa2, bb = n ? Wbb : Wab;
;                             const f32x4 cur = acc[ai][1][m][n] * rs, uu = acc[ai][0][m][n] * rs, prev = n ? prevB : prevA;
;                             float ov[4];
; #pragma unroll
;                             for (int e = 0; e < 4; ++e) {
;                                 const float ce = cur[e], pe = prev[e];
;                                 const float g1 = dpp_mv<0x121>(k15 ? pe : ce), g2 = dpp_mv<0x122>(k14 ? pe : ce);
;                                 const float cv = fmaf(w0[e], g2, fmaf(w1[e], g1, fmaf(w2[e], ce, bb[e])));
;                                 ov[e] = siluf_(cv) * uu[e];
;                             }
;                             wv[2 * n] = cvt_pk_bf16(ov[0], ov[1]); wv[2 * n + 1] = cvt_pk_bf16(ov[2], ov[3]);
;                             if (n) prevB = cur; else prevA = cur;
;                         }
;                         if (ai > 0 || m > 0 || l >= 2) *(v4u*)((unsigned char*)ACT + (ob + (unsigned)((128 * ai + 16 * m) * DFF * 2))) = (v4u){wv[0], wv[1], wv[2], wv[3]};
;                         __builtin_amdgcn_sched_barrier(0);
;                     }
	v_pk_mul_f32 v[96:97], v[96:97], v[100:101] op_sel_hi:[1,0]
	s_nop 0
	v_cndmask_b32_e64 v0, v96, v112, s[6:7]
	v_pk_mul_f32 v[98:99], v[98:99], v[100:101] op_sel_hi:[1,0]
	v_cndmask_b32_e32 v101, v112, v96, vcc
	v_mov_b32_dpp v0, v0 row_ror:1 row_mask:0xf bank_mask:0xf bound_ctrl:1
	v_fma_f32 v103, v160, v96, v148
	v_mov_b32_dpp v101, v101 row_ror:2 row_mask:0xf bank_mask:0xf bound_ctrl:1
	v_fmac_f32_e32 v103, v156, v0
	v_fmac_f32_e32 v103, v152, v101
	v_mul_f32_e32 v0, 0xbfb8aa3b, v103
	v_exp_f32_e32 v0, v0
	v_cndmask_b32_e64 v92, v97, v113, s[6:7]
	v_add_f32_e32 v0, 1.0, v0
	v_rcp_f32_e32 v101, v0
	v_mov_b32_dpp v92, v92 row_ror:1 row_mask:0xf bank_mask:0xf bound_ctrl:1
	v_pk_mul_f32 v[102:103], v[102:103], v[100:101]
	s_nop 0
	v_mul_f32_e32 v0, v102, v103
	v_cndmask_b32_e32 v101, v113, v97, vcc
	v_fma_f32 v103, v161, v97, v149
	v_fmac_f32_e32 v103, v157, v92
	v_mov_b32_dpp v101, v101 row_ror:2 row_mask:0xf bank_mask:0xf bound_ctrl:1
	v_fmac_f32_e32 v103, v153, v101
	v_mul_f32_e32 v92, 0xbfb8aa3b, v103
	v_exp_f32_e32 v92, v92
	v_mov_b32_e32 v102, v93
	v_add_f32_e32 v92, 1.0, v92
	v_rcp_f32_e32 v101, v92
	s_nop 0
	v_pk_mul_f32 v[92:93], v[102:103], v[100:101]
	s_nop 0
	v_mul_f32_e32 v102, v92, v93
	v_cndmask_b32_e64 v92, v98, v114, s[6:7]
	v_cndmask_b32_e32 v93, v114, v98, vcc
	s_nop 0
	v_mov_b32_dpp v92, v92 row_ror:1 row_mask:0xf bank_mask:0xf bound_ctrl:1
	v_mov_b32_dpp v101, v93 row_ror:2 row_mask:0xf bank_mask:0xf bound_ctrl:1
	v_fma_f32 v93, v162, v98, v150
	v_fmac_f32_e32 v93, v158, v92
	v_fmac_f32_e32 v93, v154, v101
	v_mul_f32_e32 v92, 0xbfb8aa3b, v93
	v_exp_f32_e32 v92, v92
	s_nop 0
	v_add_f32_e32 v92, 1.0, v92
	v_rcp_f32_e32 v101, v92
	v_mov_b32_e32 v92, v94
	v_pk_mul_f32 v[92:93], v[92:93], v[100:101]
	s_nop 0
	v_mul_f32_e32 v94, v92, v93
	v_cndmask_b32_e64 v92, v99, v115, s[6:7]
	v_cndmask_b32_e32 v93, v115, v99, vcc
	s_nop 0
	v_mov_b32_dpp v92, v92 row_ror:1 row_mask:0xf bank_mask:0xf bound_ctrl:1
	v_mov_b32_dpp v101, v93 row_ror:2 row_mask:0xf bank_mask:0xf bound_ctrl:1
	v_fma_f32 v93, v163, v99, v151
	v_fmac_f32_e32 v93, v159, v92
	v_fmac_f32_e32 v93, v155, v101
	v_mul_f32_e32 v92, 0xbfb8aa3b, v93
	v_exp_f32_e32 v92, v92
	s_nop 0
	v_add_f32_e32 v92, 1.0, v92
	v_rcp_f32_e32 v101, v92
	v_mov_b32_e32 v92, v95
	v_pk_mul_f32 v[92:93], v[92:93], v[100:101]
	v_pk_mul_f32 v[88:89], v[88:89], v[100:101] op_sel_hi:[1,0]
	v_mul_f32_e32 v93, v92, v93
	v_cvt_pk_bf16_f32 v92, v0, v102
	v_cndmask_b32_e64 v0, v88, v104, s[6:7]
	v_cvt_pk_bf16_f32 v93, v94, v93
	v_cndmask_b32_e32 v94, v104, v88, vcc
	v_fma_f32 v95, v144, v88, v132
	v_mov_b32_dpp v0, v0 row_ror:1 row_mask:0xf bank_mask:0xf bound_ctrl:1
	v_mov_b32_dpp v94, v94 row_ror:2 row_mask:0xf bank_mask:0xf bound_ctrl:1
	v_fmac_f32_e32 v95, v140, v0
	v_fmac_f32_e32 v95, v136, v94
	v_mul_f32_e32 v0, 0xbfb8aa3b, v95
	v_exp_f32_e32 v0, v0
	v_pk_mul_f32 v[90:91], v[90:91], v[100:101] op_sel_hi:[1,0]
	v_mov_b32_e32 v94, v84
	v_cndmask_b32_e64 v84, v89, v105, s[6:7]
	v_add_f32_e32 v0, 1.0, v0
	v_rcp_f32_e32 v101, v0
	v_mov_b32_dpp v84, v84 row_ror:1 row_mask:0xf bank_mask:0xf bound_ctrl:1
	v_pk_mul_f32 v[94:95], v[94:95], v[100:101]
	s_nop 0
	v_mul_f32_e32 v0, v94, v95
	v_cndmask_b32_e32 v94, v105, v89, vcc
	v_fma_f32 v95, v145, v89, v133
	v_fmac_f32_e32 v95, v141, v84
	v_mov_b32_dpp v94, v94 row_ror:2 row_mask:0xf bank_mask:0xf bound_ctrl:1
	v_fmac_f32_e32 v95, v137, v94
	v_mul_f32_e32 v84, 0xbfb8aa3b, v95
	v_exp_f32_e32 v84, v84
	v_mov_b32_e32 v94, v85
	v_add_f32_e32 v84, 1.0, v84
	v_rcp_f32_e32 v101, v84
	s_nop 0
	v_pk_mul_f32 v[84:85], v[94:95], v[100:101]
	s_nop 0
	v_mul_f32_e32 v94, v84, v85
	v_cndmask_b32_e64 v84, v90, v2, s[6:7]
	v_cndmask_b32_e32 v2, v2, v90, vcc
	v_fma_f32 v85, v146, v90, v134
	v_mov_b32_dpp v84, v84 row_ror:1 row_mask:0xf bank_mask:0xf bound_ctrl:1
	v_mov_b32_dpp v2, v2 row_ror:2 row_mask:0xf bank_mask:0xf bound_ctrl:1
	v_fmac_f32_e32 v85, v142, v84
	v_fmac_f32_e32 v85, v138, v2
	v_mul_f32_e32 v2, 0xbfb8aa3b, v85
	v_exp_f32_e32 v2, v2
	v_mov_b32_e32 v84, v86
	v_cvt_pk_bf16_f32 v94, v0, v94
	v_add_u32_e32 v0, 0x2c000, v184
	v_add_f32_e32 v2, 1.0, v2
	v_rcp_f32_e32 v101, v2
	v_cndmask_b32_e64 v2, v91, v3, s[6:7]
	v_cndmask_b32_e32 v3, v3, v91, vcc
	v_pk_mul_f32 v[84:85], v[84:85], v[100:101]
	s_nop 0
	v_mul_f32_e32 v84, v84, v85
	v_mov_b32_dpp v2, v2 row_ror:1 row_mask:0xf bank_mask:0xf bound_ctrl:1
	v_mov_b32_dpp v85, v3 row_ror:2 row_mask:0xf bank_mask:0xf bound_ctrl:1
	v_fma_f32 v3, v147, v91, v135
	v_fmac_f32_e32 v3, v143, v2
	v_fmac_f32_e32 v3, v139, v85
	v_mul_f32_e32 v2, 0xbfb8aa3b, v3
	v_exp_f32_e32 v2, v2
	s_nop 0
	v_add_f32_e32 v2, 1.0, v2
	v_rcp_f32_e32 v101, v2
	v_mov_b32_e32 v2, v87
	v_pk_mul_f32 v[2:3], v[2:3], v[100:101]
	s_nop 0
	v_mul_f32_e32 v2, v2, v3
	v_cvt_pk_bf16_f32 v95, v84, v2
	global_store_dwordx4 v0, v[92:95], s[0:1] nt
	ds_read_b32 v2, v209 offset:192
	v_mov_b32_e32 v86, v78
	s_waitcnt lgkmcnt(0)
; #define LAS __attribute__((address_space(3)))
; __device__ __forceinline__ unsigned cvt_pk_bf16(float lo, float hi) { unsigned r; asm("v_cvt_pk_bf16_f32 %0, %1, %2" : "=v"(r) : "v"(lo), "v"(hi)); return r; }
;     __device__ __forceinline__ void operator()(const f32x4 (&acc)[2][2][4][2], const Unit& u, int wr, int wc, int fr, int fq) const {
;     ...
;                 for (int ai = 0; ai < 2; ++ai)
; #pragma unroll
;                     for (int m = 0; m < 4; ++m) {
;                         const int l = 128 * ai + 64 * wr + 16 * m + frL;
;                         const float rs = rt[l];
;                         if (m == 0) {
;                             const int B = 2 * ai + wr;
;                             prevA = (f32x4){0.f, 0.f, 0.f, 0.f}; prevB = prevA;
;                             if (B > 0 && frL >= 14) { const LAS float* hp = halo + ((B - 1) * 2 + (frL - 14)) * 128 + fl; prevA = *(const LAS f32x4*)hp; prevB = *(const LAS f32x4*)(hp + 4); }
;                         }
;                         unsigned wv[4];
; #pragma unroll
;                         for (int n = 0; n < 2; ++n) {
;                             const f32x4 w0 = n ? Wb0 : Wa0, w1 = n ? Wb1 : Wa1, w2 = n ? Wb2 : Wa2, bb = n ? Wbb : Wab;
;                             const f32x4 cur = acc[ai][1][m][n] * rs, uu = acc[ai][0][m][n] * rs, prev = n ? prevB : prevA;
;                             float ov[4];
; #pragma unroll
;                             for (int e = 0; e < 4; ++e) {
;                                 const float ce = cur[e], pe = prev[e];
;                                 const float g1 = dpp_mv<0x121>(k15 ? pe : ce), g2 = dpp_mv<0x122>(k14 ? pe : ce);
;                                 const float cv = fmaf(w0[e], g2, fmaf(w1[e], g1, fmaf(w2[e], ce, bb[e])));
;                                 ov[e] = siluf_(cv) * uu[e];
;                             }
;                             wv[2 * n] = cvt_pk_bf16(ov[0], ov[1]); wv[2 * n + 1] = cvt_pk_bf16(ov[2], ov[3]);
;                             if (n) prevB = cur; else prevA = cur;
;                         }
;                         if (ai > 0 || m > 0 || l >= 2) *(v4u*)((unsigned char*)ACT + (ob + (unsigned)((128 * ai + 16 * m) * DFF * 2))) = (v4u){wv[0], wv[1], wv[2], wv[3]};
;                         __builtin_amdgcn_sched_barrier(0);
;                     }
	v_pk_mul_f32 v[80:81], v[80:81], v[2:3] op_sel_hi:[1,0]
	s_nop 0
	v_cndmask_b32_e64 v0, v80, v96, s[6:7]
	v_pk_mul_f32 v[82:83], v[82:83], v[2:3] op_sel_hi:[1,0]
	v_cndmask_b32_e32 v3, v96, v80, vcc
	v_fma_f32 v85, v160, v80, v148
	v_mov_b32_dpp v0, v0 row_ror:1 row_mask:0xf bank_mask:0xf bound_ctrl:1
	v_mov_b32_dpp v3, v3 row_ror:2 row_mask:0xf bank_mask:0xf bound_ctrl:1
	v_fmac_f32_e32 v85, v156, v0
	v_fmac_f32_e32 v85, v152, v3
	v_mul_f32_e32 v0, 0xbfb8aa3b, v85
	v_exp_f32_e32 v0, v0
	v_cndmask_b32_e64 v3, v81, v97, s[6:7]
	v_cndmask_b32_e32 v80, v97, v81, vcc
	v_fma_f32 v81, v161, v81, v149
	v_mov_b32_dpp v84, v3 row_ror:1 row_mask:0xf bank_mask:0xf bound_ctrl:1
	v_add_f32_e32 v0, 1.0, v0
	v_rcp_f32_e32 v3, v0
	v_fmac_f32_e32 v81, v157, v84
	v_mov_b32_dpp v0, v80 row_ror:2 row_mask:0xf bank_mask:0xf bound_ctrl:1
	v_fmac_f32_e32 v81, v153, v0
	v_mul_f32_e32 v0, 0xbfb8aa3b, v81
	v_exp_f32_e32 v0, v0
	v_mov_b32_e32 v84, v76
	v_pk_mul_f32 v[84:85], v[84:85], v[2:3]
	v_cndmask_b32_e32 v76, v98, v82, vcc
	v_add_f32_e32 v0, 1.0, v0
	v_rcp_f32_e32 v3, v0
	v_cndmask_b32_e64 v0, v82, v98, s[6:7]
	v_fma_f32 v87, v162, v82, v150
	v_mov_b32_dpp v76, v76 row_ror:2 row_mask:0xf bank_mask:0xf bound_ctrl:1
	v_mov_b32_dpp v0, v0 row_ror:1 row_mask:0xf bank_mask:0xf bound_ctrl:1
	v_fmac_f32_e32 v87, v158, v0
	v_fmac_f32_e32 v87, v154, v76
	v_mul_f32_e32 v0, 0xbfb8aa3b, v87
	v_exp_f32_e32 v0, v0
	v_mov_b32_e32 v80, v77
	v_pk_mul_f32 v[76:77], v[80:81], v[2:3]
	v_cndmask_b32_e32 v80, v99, v83, vcc
	v_add_f32_e32 v0, 1.0, v0
	v_rcp_f32_e32 v3, v0
	v_cndmask_b32_e64 v0, v83, v99, s[6:7]
	v_fma_f32 v81, v163, v83, v151
	v_mov_b32_dpp v80, v80 row_ror:2 row_mask:0xf bank_mask:0xf bound_ctrl:1
	v_mov_b32_dpp v0, v0 row_ror:1 row_mask:0xf bank_mask:0xf bound_ctrl:1
	v_fmac_f32_e32 v81, v159, v0
	v_fmac_f32_e32 v81, v155, v80
	v_mul_f32_e32 v0, 0xbfb8aa3b, v81
	v_exp_f32_e32 v0, v0
	v_pk_mul_f32 v[82:83], v[86:87], v[2:3]
	v_mov_b32_e32 v80, v79
	v_mul_f32_e32 v84, v84, v85
	v_add_f32_e32 v0, 1.0, v0
	v_rcp_f32_e32 v3, v0
	v_mul_f32_e32 v0, v76, v77
	v_mul_f32_e32 v82, v82, v83
	v_pk_mul_f32 v[72:73], v[72:73], v[2:3] op_sel_hi:[1,0]
	s_nop 0
	v_cndmask_b32_e64 v76, v72, v88, s[6:7]
	v_cndmask_b32_e32 v77, v88, v72, vcc
	v_pk_mul_f32 v[74:75], v[74:75], v[2:3] op_sel_hi:[1,0]
	v_mov_b32_dpp v76, v76 row_ror:1 row_mask:0xf bank_mask:0xf bound_ctrl:1
	v_mov_b32_dpp v78, v77 row_ror:2 row_mask:0xf bank_mask:0xf bound_ctrl:1
	v_fma_f32 v77, v144, v72, v132
	v_fmac_f32_e32 v77, v140, v76
	v_fmac_f32_e32 v77, v136, v78
	v_mul_f32_e32 v72, 0xbfb8aa3b, v77
	v_exp_f32_e32 v72, v72
	v_pk_mul_f32 v[78:79], v[80:81], v[2:3]
	v_cndmask_b32_e32 v76, v89, v73, vcc
	v_mul_f32_e32 v78, v78, v79
	v_add_f32_e32 v3, 1.0, v72
	v_cndmask_b32_e64 v72, v73, v89, s[6:7]
	v_fma_f32 v79, v145, v73, v133
	v_mov_b32_dpp v76, v76 row_ror:2 row_mask:0xf bank_mask:0xf bound_ctrl:1
	v_mov_b32_dpp v72, v72 row_ror:1 row_mask:0xf bank_mask:0xf bound_ctrl:1
	v_fmac_f32_e32 v79, v141, v72
	v_fmac_f32_e32 v79, v137, v76
	v_mul_f32_e32 v72, 0xbfb8aa3b, v79
	v_exp_f32_e32 v73, v72
	v_rcp_f32_e32 v3, v3
	v_cvt_pk_bf16_f32 v72, v84, v0
	v_mov_b32_e32 v76, v68
	v_add_f32_e32 v0, 1.0, v73
	v_pk_mul_f32 v[76:77], v[76:77], v[2:3]
	v_rcp_f32_e32 v3, v0
	v_cndmask_b32_e64 v0, v74, v90, s[6:7]
	v_cndmask_b32_e32 v68, v90, v74, vcc
	v_fma_f32 v81, v146, v74, v134
	v_mov_b32_dpp v0, v0 row_ror:1 row_mask:0xf bank_mask:0xf bound_ctrl:1
	v_mov_b32_dpp v68, v68 row_ror:2 row_mask:0xf bank_mask:0xf bound_ctrl:1
	v_fmac_f32_e32 v81, v142, v0
	v_fmac_f32_e32 v81, v138, v68
	v_mul_f32_e32 v0, 0xbfb8aa3b, v81
	v_exp_f32_e32 v0, v0
	v_cvt_pk_bf16_f32 v73, v82, v78
	v_mov_b32_e32 v78, v69
	v_pk_mul_f32 v[68:69], v[78:79], v[2:3]
	v_add_f32_e32 v0, 1.0, v0
	v_rcp_f32_e32 v3, v0
	v_cndmask_b32_e64 v0, v75, v91, s[6:7]
	v_cndmask_b32_e32 v74, v91, v75, vcc
	v_fma_f32 v75, v147, v75, v135
	v_mov_b32_dpp v0, v0 row_ror:1 row_mask:0xf bank_mask:0xf bound_ctrl:1
	v_mov_b32_dpp v74, v74 row_ror:2 row_mask:0xf bank_mask:0xf bound_ctrl:1
	v_fmac_f32_e32 v75, v143, v0
	v_fmac_f32_e32 v75, v139, v74
	v_mul_f32_e32 v0, 0xbfb8aa3b, v75
	v_exp_f32_e32 v0, v0
	v_mov_b32_e32 v80, v70
	v_mul_f32_e32 v78, v76, v77
	v_pk_mul_f32 v[76:77], v[80:81], v[2:3]
	v_add_f32_e32 v0, 1.0, v0
	v_rcp_f32_e32 v3, v0
	v_mul_f32_e32 v0, v68, v69
	v_mov_b32_e32 v74, v71
	v_mul_f32_e32 v68, v76, v77
	v_pk_mul_f32 v[2:3], v[74:75], v[2:3]
	v_cvt_pk_bf16_f32 v74, v78, v0
	v_add_u32_e32 v0, 0x42000, v184
	v_mul_f32_e32 v2, v2, v3
	v_cvt_pk_bf16_f32 v75, v68, v2
	global_store_dwordx4 v0, v[72:75], s[0:1] nt
	ds_read_b32 v76, v209 offset:512
	s_nor_b64 s[8:9], s[30:31], vcc
	v_mov_b32_e32 v68, 0
	v_mov_b32_e32 v69, 0
	v_mov_b32_e32 v70, 0
	v_mov_b32_e32 v71, 0
	v_mov_b32_e32 v72, 0
	v_mov_b32_e32 v73, 0
	v_mov_b32_e32 v74, 0
	v_mov_b32_e32 v75, 0
	s_and_saveexec_b64 s[0:1], s[8:9]
	s_cbranch_execz .LBB0_1395
	s_movk_i32 s8, 0xe800
	v_add3_u32 v0, v185, v210, s8
	ds_read_b128 v[72:75], v0
	ds_read_b128 v[68:71], v0 offset:16
; #define LAS __attribute__((address_space(3)))
; __device__ __forceinline__ unsigned cvt_pk_bf16(float lo, float hi) { unsigned r; asm("v_cvt_pk_bf16_f32 %0, %1, %2" : "=v"(r) : "v"(lo), "v"(hi)); return r; }
;     __device__ __forceinline__ void operator()(const f32x4 (&acc)[2][2][4][2], const Unit& u, int wr, int wc, int fr, int fq) const {
;     ...
;                 for (int ai = 0; ai < 2; ++ai)
; #pragma unroll
;                     for (int m = 0; m < 4; ++m) {
;                         const int l = 128 * ai + 64 * wr + 16 * m + frL;
;                         const float rs = rt[l];
;                         if (m == 0) {
;                             const int B = 2 * ai + wr;
;                             prevA = (f32x4){0.f, 0.f, 0.f, 0.f}; prevB = prevA;
;                             if (B > 0 && frL >= 14) { const LAS float* hp = halo + ((B - 1) * 2 + (frL - 14)) * 128 + fl; prevA = *(const LAS f32x4*)hp; prevB = *(const LAS f32x4*)(hp + 4); }
;                         }
;                         unsigned wv[4];
; #pragma unroll
;                         for (int n = 0; n < 2; ++n) {
;                             const f32x4 w0 = n ? Wb0 : Wa0, w1 = n ? Wb1 : Wa1, w2 = n ? Wb2 : Wa2, bb = n ? Wbb : Wab;
;                             const f32x4 cur = acc[ai][1][m][n] * rs, uu = acc[ai][0][m][n] * rs, prev = n ? prevB : prevA;
;                             float ov[4];
; #pragma unroll
;                             for (int e = 0; e < 4; ++e) {
;                                 const float ce = cur[e], pe = prev[e];
;                                 const float g1 = dpp_mv<0x121>(k15 ? pe : ce), g2 = dpp_mv<0x122>(k14 ? pe : ce);
;                                 const float cv = fmaf(w0[e], g2, fmaf(w1[e], g1, fmaf(w2[e], ce, bb[e])));
;                                 ov[e] = siluf_(cv) * uu[e];
;                             }
;                             wv[2 * n] = cvt_pk_bf16(ov[0], ov[1]); wv[2 * n + 1] = cvt_pk_bf16(ov[2], ov[3]);
;                             if (n) prevB = cur; else prevA = cur;
;                         }
;                         if (ai > 0 || m > 0 || l >= 2) *(v4u*)((unsigned char*)ACT + (ob + (unsigned)((128 * ai + 16 * m) * DFF * 2))) = (v4u){wv[0], wv[1], wv[2], wv[3]};
;                         __builtin_amdgcn_sched_barrier(0);
;                     }
.LBB0_1395:
	s_or_b64 exec, exec, s[0:1]
	s_waitcnt lgkmcnt(0)
	v_pk_mul_f32 v[64:65], v[64:65], v[76:77] op_sel_hi:[1,0]
	v_pk_mul_f32 v[66:67], v[66:67], v[76:77] op_sel_hi:[1,0]
	v_cndmask_b32_e64 v0, v64, v72, s[6:7]
	v_cndmask_b32_e32 v2, v72, v64, vcc
	v_fma_f32 v3, v160, v64, v148
	v_mov_b32_dpp v0, v0 row_ror:1 row_mask:0xf bank_mask:0xf bound_ctrl:1
	v_mov_b32_dpp v2, v2 row_ror:2 row_mask:0xf bank_mask:0xf bound_ctrl:1
	v_fmac_f32_e32 v3, v156, v0
	v_fmac_f32_e32 v3, v152, v2
	v_mul_f32_e32 v0, 0xbfb8aa3b, v3
	v_exp_f32_e32 v0, v0
	v_mov_b32_e32 v2, v60
	v_readlane_b32 s0, v252, 8
	v_readlane_b32 s1, v252, 9
	v_add_f32_e32 v0, 1.0, v0
	v_rcp_f32_e32 v77, v0
	s_nop 0
	v_pk_mul_f32 v[2:3], v[2:3], v[76:77]
	s_nop 0
	v_mul_f32_e32 v0, v2, v3
	v_cndmask_b32_e64 v2, v65, v73, s[6:7]
	v_cndmask_b32_e32 v3, v73, v65, vcc
	s_nop 0
	v_mov_b32_dpp v2, v2 row_ror:1 row_mask:0xf bank_mask:0xf bound_ctrl:1
	v_mov_b32_dpp v60, v3 row_ror:2 row_mask:0xf bank_mask:0xf bound_ctrl:1
	v_fma_f32 v3, v161, v65, v149
	v_fmac_f32_e32 v3, v157, v2
	v_fmac_f32_e32 v3, v153, v60
	v_mul_f32_e32 v2, 0xbfb8aa3b, v3
	v_exp_f32_e32 v2, v2
	s_nop 0
	v_add_f32_e32 v2, 1.0, v2
	v_rcp_f32_e32 v77, v2
	v_mov_b32_e32 v2, v61
	v_pk_mul_f32 v[2:3], v[2:3], v[76:77]
	s_nop 0
	v_mul_f32_e32 v60, v2, v3
	v_cndmask_b32_e64 v2, v66, v74, s[6:7]
	v_cndmask_b32_e32 v3, v74, v66, vcc
	v_cvt_pk_bf16_f32 v60, v0, v60
	s_nop 0
	v_mov_b32_dpp v2, v2 row_ror:1 row_mask:0xf bank_mask:0xf bound_ctrl:1
	v_mov_b32_dpp v61, v3 row_ror:2 row_mask:0xf bank_mask:0xf bound_ctrl:1
	v_fma_f32 v3, v162, v66, v150
	v_fmac_f32_e32 v3, v158, v2
	v_fmac_f32_e32 v3, v154, v61
	v_mul_f32_e32 v2, 0xbfb8aa3b, v3
	v_exp_f32_e32 v2, v2
	s_nop 0
	v_add_f32_e32 v2, 1.0, v2
	v_rcp_f32_e32 v77, v2
	v_mov_b32_e32 v2, v62
	v_pk_mul_f32 v[2:3], v[2:3], v[76:77]
	s_nop 0
	v_mul_f32_e32 v61, v2, v3
	v_cndmask_b32_e64 v2, v67, v75, s[6:7]
	v_cndmask_b32_e32 v3, v75, v67, vcc
	s_nop 0
	v_mov_b32_dpp v2, v2 row_ror:1 row_mask:0xf bank_mask:0xf bound_ctrl:1
	v_mov_b32_dpp v62, v3 row_ror:2 row_mask:0xf bank_mask:0xf bound_ctrl:1
	v_fma_f32 v3, v163, v67, v151
	v_fmac_f32_e32 v3, v159, v2
	v_fmac_f32_e32 v3, v155, v62
	v_mul_f32_e32 v2, 0xbfb8aa3b, v3
	v_exp_f32_e32 v2, v2
	s_nop 0
	v_add_f32_e32 v2, 1.0, v2
	v_rcp_f32_e32 v77, v2
	v_mov_b32_e32 v2, v63
	v_pk_mul_f32 v[2:3], v[2:3], v[76:77]
	v_pk_mul_f32 v[56:57], v[56:57], v[76:77] op_sel_hi:[1,0]
	v_mul_f32_e32 v2, v2, v3
	v_cndmask_b32_e64 v0, v56, v68, s[6:7]
	v_cvt_pk_bf16_f32 v61, v61, v2
	v_pk_mul_f32 v[2:3], v[58:59], v[76:77] op_sel_hi:[1,0]
	v_cndmask_b32_e32 v58, v68, v56, vcc
	v_mov_b32_dpp v0, v0 row_ror:1 row_mask:0xf bank_mask:0xf bound_ctrl:1
	v_fma_f32 v59, v144, v56, v132
	v_mov_b32_dpp v58, v58 row_ror:2 row_mask:0xf bank_mask:0xf bound_ctrl:1
	v_fmac_f32_e32 v59, v140, v0
	v_fmac_f32_e32 v59, v136, v58
	v_mul_f32_e32 v0, 0xbfb8aa3b, v59
	v_exp_f32_e32 v0, v0
	v_mov_b32_e32 v58, v52
	v_cndmask_b32_e64 v52, v57, v69, s[6:7]
	v_add_f32_e32 v0, 1.0, v0
	v_rcp_f32_e32 v77, v0
	v_mov_b32_dpp v52, v52 row_ror:1 row_mask:0xf bank_mask:0xf bound_ctrl:1
	v_pk_mul_f32 v[58:59], v[58:59], v[76:77]
	s_nop 0
	v_mul_f32_e32 v0, v58, v59
	v_cndmask_b32_e32 v58, v69, v57, vcc
	v_fma_f32 v59, v145, v57, v133
	v_fmac_f32_e32 v59, v141, v52
	v_mov_b32_dpp v58, v58 row_ror:2 row_mask:0xf bank_mask:0xf bound_ctrl:1
	v_fmac_f32_e32 v59, v137, v58
	v_mul_f32_e32 v52, 0xbfb8aa3b, v59
	v_exp_f32_e32 v52, v52
	v_mov_b32_e32 v58, v53
	v_add_f32_e32 v52, 1.0, v52
	v_rcp_f32_e32 v77, v52
	s_nop 0
	v_pk_mul_f32 v[52:53], v[58:59], v[76:77]
	s_nop 0
	v_mul_f32_e32 v58, v52, v53
	v_cndmask_b32_e64 v52, v2, v70, s[6:7]
	v_cndmask_b32_e32 v53, v70, v2, vcc
	v_cvt_pk_bf16_f32 v62, v0, v58
	v_add_u32_e32 v0, 0xb0000, v184
	v_mov_b32_dpp v52, v52 row_ror:1 row_mask:0xf bank_mask:0xf bound_ctrl:1
	v_mov_b32_dpp v59, v53 row_ror:2 row_mask:0xf bank_mask:0xf bound_ctrl:1
	v_fma_f32 v53, v146, v2, v134
	v_fmac_f32_e32 v53, v142, v52
	v_fmac_f32_e32 v53, v138, v59
	v_mul_f32_e32 v52, 0xbfb8aa3b, v53
	v_exp_f32_e32 v52, v52
	s_nop 0
	v_add_f32_e32 v52, 1.0, v52
	v_rcp_f32_e32 v77, v52
	v_mov_b32_e32 v52, v54
	v_pk_mul_f32 v[52:53], v[52:53], v[76:77]
	s_nop 0
	v_mul_f32_e32 v54, v52, v53
	v_cndmask_b32_e64 v52, v3, v71, s[6:7]
	v_cndmask_b32_e32 v53, v71, v3, vcc
	s_nop 0
	v_mov_b32_dpp v52, v52 row_ror:1 row_mask:0xf bank_mask:0xf bound_ctrl:1
	v_mov_b32_dpp v59, v53 row_ror:2 row_mask:0xf bank_mask:0xf bound_ctrl:1
	v_fma_f32 v53, v147, v3, v135
	v_fmac_f32_e32 v53, v143, v52
	v_fmac_f32_e32 v53, v139, v59
	v_mul_f32_e32 v52, 0xbfb8aa3b, v53
	v_exp_f32_e32 v52, v52
	s_nop 0
	v_add_f32_e32 v52, 1.0, v52
	v_rcp_f32_e32 v77, v52
	v_mov_b32_e32 v52, v55
	v_pk_mul_f32 v[52:53], v[52:53], v[76:77]
	s_nop 0
	v_mul_f32_e32 v52, v52, v53
	v_cvt_pk_bf16_f32 v63, v54, v52
	global_store_dwordx4 v0, v[60:63], s[0:1] nt
	ds_read_b32 v52, v209 offset:576
	v_mov_b32_e32 v54, v44
	s_waitcnt lgkmcnt(0)
; #define LAS __attribute__((address_space(3)))
; __device__ __forceinline__ unsigned cvt_pk_bf16(float lo, float hi) { unsigned r; asm("v_cvt_pk_bf16_f32 %0, %1, %2" : "=v"(r) : "v"(lo), "v"(hi)); return r; }
;     __device__ __forceinline__ void operator()(const f32x4 (&acc)[2][2][4][2], const Unit& u, int wr, int wc, int fr, int fq) const {
;     ...
;                 for (int ai = 0; ai < 2; ++ai)
; #pragma unroll
;                     for (int m = 0; m < 4; ++m) {
;                         const int l = 128 * ai + 64 * wr + 16 * m + frL;
;                         const float rs = rt[l];
;                         if (m == 0) {
;                             const int B = 2 * ai + wr;
;                             prevA = (f32x4){0.f, 0.f, 0.f, 0.f}; prevB = prevA;
;                             if (B > 0 && frL >= 14) { const LAS float* hp = halo + ((B - 1) * 2 + (frL - 14)) * 128 + fl; prevA = *(const LAS f32x4*)hp; prevB = *(const LAS f32x4*)(hp + 4); }
;                         }
;                         unsigned wv[4];
; #pragma unroll
;                         for (int n = 0; n < 2; ++n) {
;                             const f32x4 w0 = n ? Wb0 : Wa0, w1 = n ? Wb1 : Wa1, w2 = n ? Wb2 : Wa2, bb = n ? Wbb : Wab;
;                             const f32x4 cur = acc[ai][1][m][n] * rs, uu = acc[ai][0][m][n] * rs, prev = n ? prevB : prevA;
;                             float ov[4];
; #pragma unroll
;                             for (int e = 0; e < 4; ++e) {
;                                 const float ce = cur[e], pe = prev[e];
;                                 const float g1 = dpp_mv<0x121>(k15 ? pe : ce), g2 = dpp_mv<0x122>(k14 ? pe : ce);
;                                 const float cv = fmaf(w0[e], g2, fmaf(w1[e], g1, fmaf(w2[e], ce, bb[e])));
;                                 ov[e] = siluf_(cv) * uu[e];
;                             }
;                             wv[2 * n] = cvt_pk_bf16(ov[0], ov[1]); wv[2 * n + 1] = cvt_pk_bf16(ov[2], ov[3]);
;                             if (n) prevB = cur; else prevA = cur;
;                         }
;                         if (ai > 0 || m > 0 || l >= 2) *(v4u*)((unsigned char*)ACT + (ob + (unsigned)((128 * ai + 16 * m) * DFF * 2))) = (v4u){wv[0], wv[1], wv[2], wv[3]};
;                         __builtin_amdgcn_sched_barrier(0);
;                     }
	v_pk_mul_f32 v[48:49], v[48:49], v[52:53] op_sel_hi:[1,0]
	s_nop 0
	v_cndmask_b32_e64 v0, v48, v64, s[6:7]
	v_pk_mul_f32 v[50:51], v[50:51], v[52:53] op_sel_hi:[1,0]
	v_cndmask_b32_e32 v53, v64, v48, vcc
	v_mov_b32_dpp v0, v0 row_ror:1 row_mask:0xf bank_mask:0xf bound_ctrl:1
	v_fma_f32 v55, v160, v48, v148
	v_mov_b32_dpp v53, v53 row_ror:2 row_mask:0xf bank_mask:0xf bound_ctrl:1
	v_fmac_f32_e32 v55, v156, v0
	v_fmac_f32_e32 v55, v152, v53
	v_mul_f32_e32 v0, 0xbfb8aa3b, v55
	v_exp_f32_e32 v0, v0
	v_cndmask_b32_e64 v44, v49, v65, s[6:7]
	v_add_f32_e32 v0, 1.0, v0
	v_rcp_f32_e32 v53, v0
	v_mov_b32_dpp v44, v44 row_ror:1 row_mask:0xf bank_mask:0xf bound_ctrl:1
	v_pk_mul_f32 v[54:55], v[54:55], v[52:53]
	s_nop 0
	v_mul_f32_e32 v0, v54, v55
	v_cndmask_b32_e32 v53, v65, v49, vcc
	v_fma_f32 v55, v161, v49, v149
	v_fmac_f32_e32 v55, v157, v44
	v_mov_b32_dpp v53, v53 row_ror:2 row_mask:0xf bank_mask:0xf bound_ctrl:1
	v_fmac_f32_e32 v55, v153, v53
	v_mul_f32_e32 v44, 0xbfb8aa3b, v55
	v_exp_f32_e32 v44, v44
	v_mov_b32_e32 v54, v45
	v_add_f32_e32 v44, 1.0, v44
	v_rcp_f32_e32 v53, v44
	s_nop 0
	v_pk_mul_f32 v[44:45], v[54:55], v[52:53]
	s_nop 0
	v_mul_f32_e32 v54, v44, v45
	v_cndmask_b32_e64 v44, v50, v66, s[6:7]
	v_cndmask_b32_e32 v45, v66, v50, vcc
	s_nop 0
	v_mov_b32_dpp v44, v44 row_ror:1 row_mask:0xf bank_mask:0xf bound_ctrl:1
	v_mov_b32_dpp v53, v45 row_ror:2 row_mask:0xf bank_mask:0xf bound_ctrl:1
	v_fma_f32 v45, v162, v50, v150
	v_fmac_f32_e32 v45, v158, v44
	v_fmac_f32_e32 v45, v154, v53
	v_mul_f32_e32 v44, 0xbfb8aa3b, v45
	v_exp_f32_e32 v44, v44
	s_nop 0
	v_add_f32_e32 v44, 1.0, v44
	v_rcp_f32_e32 v53, v44
	v_mov_b32_e32 v44, v46
	v_pk_mul_f32 v[44:45], v[44:45], v[52:53]
	s_nop 0
	v_mul_f32_e32 v46, v44, v45
	v_cndmask_b32_e64 v44, v51, v67, s[6:7]
	v_cndmask_b32_e32 v45, v67, v51, vcc
	s_nop 0
	v_mov_b32_dpp v44, v44 row_ror:1 row_mask:0xf bank_mask:0xf bound_ctrl:1
	v_mov_b32_dpp v53, v45 row_ror:2 row_mask:0xf bank_mask:0xf bound_ctrl:1
	v_fma_f32 v45, v163, v51, v151
	v_fmac_f32_e32 v45, v159, v44
	v_fmac_f32_e32 v45, v155, v53
	v_mul_f32_e32 v44, 0xbfb8aa3b, v45
	v_exp_f32_e32 v44, v44
	s_nop 0
	v_add_f32_e32 v44, 1.0, v44
	v_rcp_f32_e32 v53, v44
	v_mov_b32_e32 v44, v47
	v_pk_mul_f32 v[44:45], v[44:45], v[52:53]
	v_pk_mul_f32 v[40:41], v[40:41], v[52:53] op_sel_hi:[1,0]
	v_mul_f32_e32 v45, v44, v45
	v_cvt_pk_bf16_f32 v44, v0, v54
	v_cndmask_b32_e64 v0, v40, v56, s[6:7]
	v_cvt_pk_bf16_f32 v45, v46, v45
	v_cndmask_b32_e32 v46, v56, v40, vcc
	v_fma_f32 v47, v144, v40, v132
	v_mov_b32_dpp v0, v0 row_ror:1 row_mask:0xf bank_mask:0xf bound_ctrl:1
	v_mov_b32_dpp v46, v46 row_ror:2 row_mask:0xf bank_mask:0xf bound_ctrl:1
	v_fmac_f32_e32 v47, v140, v0
	v_fmac_f32_e32 v47, v136, v46
	v_mul_f32_e32 v0, 0xbfb8aa3b, v47
	v_exp_f32_e32 v0, v0
	v_pk_mul_f32 v[42:43], v[42:43], v[52:53] op_sel_hi:[1,0]
	v_mov_b32_e32 v46, v36
	v_cndmask_b32_e64 v36, v41, v57, s[6:7]
	v_add_f32_e32 v0, 1.0, v0
	v_rcp_f32_e32 v53, v0
	v_mov_b32_dpp v36, v36 row_ror:1 row_mask:0xf bank_mask:0xf bound_ctrl:1
	v_pk_mul_f32 v[46:47], v[46:47], v[52:53]
	s_nop 0
	v_mul_f32_e32 v0, v46, v47
	v_cndmask_b32_e32 v46, v57, v41, vcc
	v_fma_f32 v47, v145, v41, v133
	v_fmac_f32_e32 v47, v141, v36
	v_mov_b32_dpp v46, v46 row_ror:2 row_mask:0xf bank_mask:0xf bound_ctrl:1
	v_fmac_f32_e32 v47, v137, v46
	v_mul_f32_e32 v36, 0xbfb8aa3b, v47
	v_exp_f32_e32 v36, v36
	v_mov_b32_e32 v46, v37
	v_add_f32_e32 v36, 1.0, v36
	v_rcp_f32_e32 v53, v36
	s_nop 0
	v_pk_mul_f32 v[36:37], v[46:47], v[52:53]
	s_nop 0
	v_mul_f32_e32 v46, v36, v37
	v_cndmask_b32_e64 v36, v42, v2, s[6:7]
	v_cndmask_b32_e32 v2, v2, v42, vcc
	v_fma_f32 v37, v146, v42, v134
	v_mov_b32_dpp v36, v36 row_ror:1 row_mask:0xf bank_mask:0xf bound_ctrl:1
	v_mov_b32_dpp v2, v2 row_ror:2 row_mask:0xf bank_mask:0xf bound_ctrl:1
	v_fmac_f32_e32 v37, v142, v36
	v_fmac_f32_e32 v37, v138, v2
	v_mul_f32_e32 v2, 0xbfb8aa3b, v37
	v_exp_f32_e32 v2, v2
	v_mov_b32_e32 v36, v38
	v_cvt_pk_bf16_f32 v46, v0, v46
	v_add_u32_e32 v0, 0xc6000, v184
	v_add_f32_e32 v2, 1.0, v2
	v_rcp_f32_e32 v53, v2
	v_cndmask_b32_e64 v2, v43, v3, s[6:7]
	v_cndmask_b32_e32 v3, v3, v43, vcc
	v_pk_mul_f32 v[36:37], v[36:37], v[52:53]
	s_nop 0
	v_mul_f32_e32 v36, v36, v37
	v_mov_b32_dpp v2, v2 row_ror:1 row_mask:0xf bank_mask:0xf bound_ctrl:1
	v_mov_b32_dpp v37, v3 row_ror:2 row_mask:0xf bank_mask:0xf bound_ctrl:1
	v_fma_f32 v3, v147, v43, v135
	v_fmac_f32_e32 v3, v143, v2
	v_fmac_f32_e32 v3, v139, v37
	v_mul_f32_e32 v2, 0xbfb8aa3b, v3
	v_exp_f32_e32 v2, v2
	s_nop 0
	v_add_f32_e32 v2, 1.0, v2
	v_rcp_f32_e32 v53, v2
	v_mov_b32_e32 v2, v39
	v_pk_mul_f32 v[2:3], v[2:3], v[52:53]
	s_nop 0
	v_mul_f32_e32 v2, v2, v3
	v_cvt_pk_bf16_f32 v47, v36, v2
	global_store_dwordx4 v0, v[44:47], s[0:1] nt
	ds_read_b32 v36, v209 offset:640
	s_waitcnt lgkmcnt(0)
; #define LAS __attribute__((address_space(3)))
; __device__ __forceinline__ unsigned cvt_pk_bf16(float lo, float hi) { unsigned r; asm("v_cvt_pk_bf16_f32 %0, %1, %2" : "=v"(r) : "v"(lo), "v"(hi)); return r; }
;     __device__ __forceinline__ void operator()(const f32x4 (&acc)[2][2][4][2], const Unit& u, int wr, int wc, int fr, int fq) const {
;     ...
;                 for (int ai = 0; ai < 2; ++ai)
; #pragma unroll
;                     for (int m = 0; m < 4; ++m) {
;                         const int l = 128 * ai + 64 * wr + 16 * m + frL;
;                         const float rs = rt[l];
;                         if (m == 0) {
;                             const int B = 2 * ai + wr;
;                             prevA = (f32x4){0.f, 0.f, 0.f, 0.f}; prevB = prevA;
;                             if (B > 0 && frL >= 14) { const LAS float* hp = halo + ((B - 1) * 2 + (frL - 14)) * 128 + fl; prevA = *(const LAS f32x4*)hp; prevB = *(const LAS f32x4*)(hp + 4); }
;                         }
;                         unsigned wv[4];
; #pragma unroll
;                         for (int n = 0; n < 2; ++n) {
;                             const f32x4 w0 = n ? Wb0 : Wa0, w1 = n ? Wb1 : Wa1, w2 = n ? Wb2 : Wa2, bb = n ? Wbb : Wab;
;                             const f32x4 cur = acc[ai][1][m][n] * rs, uu = acc[ai][0][m][n] * rs, prev = n ? prevB : prevA;
;                             float ov[4];
; #pragma unroll
;                             for (int e = 0; e < 4; ++e) {
;                                 const float ce = cur[e], pe = prev[e];
;                                 const float g1 = dpp_mv<0x121>(k15 ? pe : ce), g2 = dpp_mv<0x122>(k14 ? pe : ce);
;                                 const float cv = fmaf(w0[e], g2, fmaf(w1[e], g1, fmaf(w2[e], ce, bb[e])));
;                                 ov[e] = siluf_(cv) * uu[e];
;                             }
;                             wv[2 * n] = cvt_pk_bf16(ov[0], ov[1]); wv[2 * n + 1] = cvt_pk_bf16(ov[2], ov[3]);
;                             if (n) prevB = cur; else prevA = cur;
;                         }
;                         if (ai > 0 || m > 0 || l >= 2) *(v4u*)((unsigned char*)ACT + (ob + (unsigned)((128 * ai + 16 * m) * DFF * 2))) = (v4u){wv[0], wv[1], wv[2], wv[3]};
;                         __builtin_amdgcn_sched_barrier(0);
;                     }
	v_pk_mul_f32 v[32:33], v[32:33], v[36:37] op_sel_hi:[1,0]
	s_nop 0
	v_cndmask_b32_e64 v0, v32, v48, s[6:7]
	v_pk_mul_f32 v[2:3], v[34:35], v[36:37] op_sel_hi:[1,0]
	v_cndmask_b32_e32 v34, v48, v32, vcc
	v_mov_b32_dpp v0, v0 row_ror:1 row_mask:0xf bank_mask:0xf bound_ctrl:1
	v_fma_f32 v35, v160, v32, v148
	v_mov_b32_dpp v34, v34 row_ror:2 row_mask:0xf bank_mask:0xf bound_ctrl:1
	v_fmac_f32_e32 v35, v156, v0
	v_fmac_f32_e32 v35, v152, v34
	v_mul_f32_e32 v0, 0xbfb8aa3b, v35
	v_exp_f32_e32 v0, v0
	v_mov_b32_e32 v34, v28
	v_cndmask_b32_e64 v28, v33, v49, s[6:7]
	v_add_f32_e32 v0, 1.0, v0
	v_rcp_f32_e32 v37, v0
	v_mov_b32_dpp v28, v28 row_ror:1 row_mask:0xf bank_mask:0xf bound_ctrl:1
	v_pk_mul_f32 v[34:35], v[34:35], v[36:37]
	s_nop 0
	v_mul_f32_e32 v0, v34, v35
	v_cndmask_b32_e32 v34, v49, v33, vcc
	v_fma_f32 v35, v161, v33, v149
	v_fmac_f32_e32 v35, v157, v28
	v_mov_b32_dpp v34, v34 row_ror:2 row_mask:0xf bank_mask:0xf bound_ctrl:1
	v_fmac_f32_e32 v35, v153, v34
	v_mul_f32_e32 v28, 0xbfb8aa3b, v35
	v_exp_f32_e32 v28, v28
	v_mov_b32_e32 v34, v29
	v_add_f32_e32 v28, 1.0, v28
	v_rcp_f32_e32 v37, v28
	s_nop 0
	v_pk_mul_f32 v[28:29], v[34:35], v[36:37]
	s_nop 0
	v_mul_f32_e32 v34, v28, v29
	v_cndmask_b32_e64 v28, v2, v50, s[6:7]
	v_cndmask_b32_e32 v29, v50, v2, vcc
	s_nop 0
	v_mov_b32_dpp v28, v28 row_ror:1 row_mask:0xf bank_mask:0xf bound_ctrl:1
	v_mov_b32_dpp v35, v29 row_ror:2 row_mask:0xf bank_mask:0xf bound_ctrl:1
	v_fma_f32 v29, v162, v2, v150
	v_fmac_f32_e32 v29, v158, v28
	v_fmac_f32_e32 v29, v154, v35
	v_mul_f32_e32 v28, 0xbfb8aa3b, v29
	v_exp_f32_e32 v28, v28
	s_nop 0
	v_add_f32_e32 v28, 1.0, v28
	v_rcp_f32_e32 v37, v28
	v_mov_b32_e32 v28, v30
	v_pk_mul_f32 v[28:29], v[28:29], v[36:37]
	s_nop 0
	v_mul_f32_e32 v30, v28, v29
	v_cndmask_b32_e64 v28, v3, v51, s[6:7]
	v_cndmask_b32_e32 v29, v51, v3, vcc
	s_nop 0
	v_mov_b32_dpp v28, v28 row_ror:1 row_mask:0xf bank_mask:0xf bound_ctrl:1
	v_mov_b32_dpp v35, v29 row_ror:2 row_mask:0xf bank_mask:0xf bound_ctrl:1
	v_fma_f32 v29, v163, v3, v151
	v_fmac_f32_e32 v29, v159, v28
	v_fmac_f32_e32 v29, v155, v35
	v_mul_f32_e32 v28, 0xbfb8aa3b, v29
	v_exp_f32_e32 v28, v28
	s_nop 0
	v_add_f32_e32 v28, 1.0, v28
	v_rcp_f32_e32 v37, v28
	v_mov_b32_e32 v28, v31
	v_pk_mul_f32 v[28:29], v[28:29], v[36:37]
	v_pk_mul_f32 v[24:25], v[24:25], v[36:37] op_sel_hi:[1,0]
	v_mul_f32_e32 v29, v28, v29
	v_cvt_pk_bf16_f32 v28, v0, v34
	v_cndmask_b32_e64 v0, v24, v40, s[6:7]
	v_cvt_pk_bf16_f32 v29, v30, v29
	v_cndmask_b32_e32 v30, v40, v24, vcc
	v_fma_f32 v31, v144, v24, v132
	v_mov_b32_dpp v0, v0 row_ror:1 row_mask:0xf bank_mask:0xf bound_ctrl:1
	v_mov_b32_dpp v30, v30 row_ror:2 row_mask:0xf bank_mask:0xf bound_ctrl:1
	v_fmac_f32_e32 v31, v140, v0
	v_fmac_f32_e32 v31, v136, v30
	v_mul_f32_e32 v0, 0xbfb8aa3b, v31
	v_exp_f32_e32 v0, v0
	v_pk_mul_f32 v[26:27], v[26:27], v[36:37] op_sel_hi:[1,0]
	v_mov_b32_e32 v30, v20
	v_cndmask_b32_e64 v20, v25, v41, s[6:7]
	v_add_f32_e32 v0, 1.0, v0
	v_rcp_f32_e32 v37, v0
	v_mov_b32_dpp v20, v20 row_ror:1 row_mask:0xf bank_mask:0xf bound_ctrl:1
	v_pk_mul_f32 v[30:31], v[30:31], v[36:37]
	s_nop 0
	v_mul_f32_e32 v0, v30, v31
	v_cndmask_b32_e32 v30, v41, v25, vcc
	v_fma_f32 v31, v145, v25, v133
	v_fmac_f32_e32 v31, v141, v20
	v_mov_b32_dpp v30, v30 row_ror:2 row_mask:0xf bank_mask:0xf bound_ctrl:1
	v_fmac_f32_e32 v31, v137, v30
	v_mul_f32_e32 v20, 0xbfb8aa3b, v31
	v_exp_f32_e32 v20, v20
	v_mov_b32_e32 v30, v21
	v_add_f32_e32 v20, 1.0, v20
	v_rcp_f32_e32 v37, v20
	s_nop 0
	v_pk_mul_f32 v[20:21], v[30:31], v[36:37]
	s_nop 0
	v_mul_f32_e32 v30, v20, v21
	v_cndmask_b32_e64 v20, v26, v42, s[6:7]
	v_cndmask_b32_e32 v21, v42, v26, vcc
	v_cvt_pk_bf16_f32 v30, v0, v30
	v_add_u32_e32 v0, 0xdc000, v184
	v_mov_b32_dpp v20, v20 row_ror:1 row_mask:0xf bank_mask:0xf bound_ctrl:1
	v_mov_b32_dpp v31, v21 row_ror:2 row_mask:0xf bank_mask:0xf bound_ctrl:1
	v_fma_f32 v21, v146, v26, v134
	v_fmac_f32_e32 v21, v142, v20
	v_fmac_f32_e32 v21, v138, v31
	v_mul_f32_e32 v20, 0xbfb8aa3b, v21
	v_exp_f32_e32 v20, v20
	s_nop 0
	v_add_f32_e32 v20, 1.0, v20
	v_rcp_f32_e32 v37, v20
	v_mov_b32_e32 v20, v22
	v_pk_mul_f32 v[20:21], v[20:21], v[36:37]
	s_nop 0
	v_mul_f32_e32 v22, v20, v21
	v_cndmask_b32_e64 v20, v27, v43, s[6:7]
	v_cndmask_b32_e32 v21, v43, v27, vcc
	s_nop 0
	v_mov_b32_dpp v20, v20 row_ror:1 row_mask:0xf bank_mask:0xf bound_ctrl:1
	v_mov_b32_dpp v31, v21 row_ror:2 row_mask:0xf bank_mask:0xf bound_ctrl:1
	v_fma_f32 v21, v147, v27, v135
	v_fmac_f32_e32 v21, v143, v20
	v_fmac_f32_e32 v21, v139, v31
	v_mul_f32_e32 v20, 0xbfb8aa3b, v21
	v_exp_f32_e32 v20, v20
	s_nop 0
	v_add_f32_e32 v20, 1.0, v20
	v_rcp_f32_e32 v37, v20
	v_mov_b32_e32 v20, v23
	v_pk_mul_f32 v[20:21], v[20:21], v[36:37]
	s_nop 0
	v_mul_f32_e32 v20, v20, v21
	v_cvt_pk_bf16_f32 v31, v22, v20
	global_store_dwordx4 v0, v[28:31], s[0:1] nt
	ds_read_b32 v20, v209 offset:704
	s_nop 0
	v_mov_b32_e32 v28, v14
	s_waitcnt lgkmcnt(0)
; #define LAS __attribute__((address_space(3)))
; __device__ __forceinline__ unsigned cvt_pk_bf16(float lo, float hi) { unsigned r; asm("v_cvt_pk_bf16_f32 %0, %1, %2" : "=v"(r) : "v"(lo), "v"(hi)); return r; }
;     __device__ __forceinline__ void operator()(const f32x4 (&acc)[2][2][4][2], const Unit& u, int wr, int wc, int fr, int fq) const {
;     ...
;                 for (int ai = 0; ai < 2; ++ai)
; #pragma unroll
;                     for (int m = 0; m < 4; ++m) {
;                         const int l = 128 * ai + 64 * wr + 16 * m + frL;
;                         const float rs = rt[l];
;                         if (m == 0) {
;                             const int B = 2 * ai + wr;
;                             prevA = (f32x4){0.f, 0.f, 0.f, 0.f}; prevB = prevA;
;                             if (B > 0 && frL >= 14) { const LAS float* hp = halo + ((B - 1) * 2 + (frL - 14)) * 128 + fl; prevA = *(const LAS f32x4*)hp; prevB = *(const LAS f32x4*)(hp + 4); }
;                         }
;                         unsigned wv[4];
; #pragma unroll
;                         for (int n = 0; n < 2; ++n) {
;                             const f32x4 w0 = n ? Wb0 : Wa0, w1 = n ? Wb1 : Wa1, w2 = n ? Wb2 : Wa2, bb = n ? Wbb : Wab;
;                             const f32x4 cur = acc[ai][1][m][n] * rs, uu = acc[ai][0][m][n] * rs, prev = n ? prevB : prevA;
;                             float ov[4];
; #pragma unroll
;                             for (int e = 0; e < 4; ++e) {
;                                 const float ce = cur[e], pe = prev[e];
;                                 const float g1 = dpp_mv<0x121>(k15 ? pe : ce), g2 = dpp_mv<0x122>(k14 ? pe : ce);
;                                 const float cv = fmaf(w0[e], g2, fmaf(w1[e], g1, fmaf(w2[e], ce, bb[e])));
;                                 ov[e] = siluf_(cv) * uu[e];
;                             }
;                             wv[2 * n] = cvt_pk_bf16(ov[0], ov[1]); wv[2 * n + 1] = cvt_pk_bf16(ov[2], ov[3]);
;                             if (n) prevB = cur; else prevA = cur;
;                         }
;                         if (ai > 0 || m > 0 || l >= 2) *(v4u*)((unsigned char*)ACT + (ob + (unsigned)((128 * ai + 16 * m) * DFF * 2))) = (v4u){wv[0], wv[1], wv[2], wv[3]};
;                         __builtin_amdgcn_sched_barrier(0);
;                     }
	v_pk_mul_f32 v[16:17], v[16:17], v[20:21] op_sel_hi:[1,0]
	s_nop 0
	v_cndmask_b32_e64 v0, v16, v32, s[6:7]
	v_pk_mul_f32 v[18:19], v[18:19], v[20:21] op_sel_hi:[1,0]
	v_cndmask_b32_e32 v21, v32, v16, vcc
	v_fma_f32 v23, v160, v16, v148
	v_mov_b32_dpp v0, v0 row_ror:1 row_mask:0xf bank_mask:0xf bound_ctrl:1
	v_mov_b32_dpp v16, v21 row_ror:2 row_mask:0xf bank_mask:0xf bound_ctrl:1
	v_fmac_f32_e32 v23, v156, v0
	v_fmac_f32_e32 v23, v152, v16
	v_mul_f32_e32 v0, 0xbfb8aa3b, v23
	v_exp_f32_e32 v0, v0
	v_cndmask_b32_e64 v16, v17, v33, s[6:7]
	v_cndmask_b32_e32 v22, v33, v17, vcc
	v_fma_f32 v17, v161, v17, v149
	v_mov_b32_dpp v16, v16 row_ror:1 row_mask:0xf bank_mask:0xf bound_ctrl:1
	v_add_f32_e32 v0, 1.0, v0
	v_rcp_f32_e32 v21, v0
	v_fmac_f32_e32 v17, v157, v16
	v_mov_b32_dpp v0, v22 row_ror:2 row_mask:0xf bank_mask:0xf bound_ctrl:1
	v_fmac_f32_e32 v17, v153, v0
	v_mul_f32_e32 v0, 0xbfb8aa3b, v17
	v_exp_f32_e32 v0, v0
	v_mov_b32_e32 v22, v12
	v_pk_mul_f32 v[22:23], v[22:23], v[20:21]
	v_fma_f32 v29, v162, v18, v150
	v_add_f32_e32 v0, 1.0, v0
	v_rcp_f32_e32 v21, v0
	v_cndmask_b32_e64 v0, v18, v2, s[6:7]
	v_cndmask_b32_e32 v2, v2, v18, vcc
	v_mov_b32_e32 v16, v13
	v_mov_b32_dpp v0, v0 row_ror:1 row_mask:0xf bank_mask:0xf bound_ctrl:1
	v_mov_b32_dpp v2, v2 row_ror:2 row_mask:0xf bank_mask:0xf bound_ctrl:1
	v_fmac_f32_e32 v29, v158, v0
	v_fmac_f32_e32 v29, v154, v2
	v_mul_f32_e32 v0, 0xbfb8aa3b, v29
	v_exp_f32_e32 v0, v0
	v_pk_mul_f32 v[12:13], v[16:17], v[20:21]
	v_cndmask_b32_e32 v2, v3, v19, vcc
	v_fmac_f32_e32 v151, v163, v19
	v_add_f32_e32 v0, 1.0, v0
	v_rcp_f32_e32 v21, v0
	v_cndmask_b32_e64 v0, v19, v3, s[6:7]
	v_mov_b32_dpp v2, v2 row_ror:2 row_mask:0xf bank_mask:0xf bound_ctrl:1
	v_mov_b32_e32 v150, v15
	v_mov_b32_dpp v0, v0 row_ror:1 row_mask:0xf bank_mask:0xf bound_ctrl:1
	v_fmac_f32_e32 v151, v159, v0
	v_fmac_f32_e32 v151, v155, v2
	v_mul_f32_e32 v0, 0xbfb8aa3b, v151
	v_exp_f32_e32 v0, v0
	v_pk_mul_f32 v[2:3], v[28:29], v[20:21]
	v_mul_f32_e32 v16, v22, v23
	v_mul_f32_e32 v14, v2, v3
	v_add_f32_e32 v0, 1.0, v0
	v_rcp_f32_e32 v21, v0
	v_mul_f32_e32 v0, v12, v13
	v_pk_mul_f32 v[2:3], v[8:9], v[20:21] op_sel_hi:[1,0]
	s_nop 0
	v_cndmask_b32_e64 v8, v2, v24, s[6:7]
	v_cndmask_b32_e32 v9, v24, v2, vcc
	v_pk_mul_f32 v[10:11], v[10:11], v[20:21] op_sel_hi:[1,0]
	v_mov_b32_dpp v8, v8 row_ror:1 row_mask:0xf bank_mask:0xf bound_ctrl:1
	v_mov_b32_dpp v12, v9 row_ror:2 row_mask:0xf bank_mask:0xf bound_ctrl:1
	v_fma_f32 v9, v144, v2, v132
	v_fmac_f32_e32 v9, v140, v8
	v_fmac_f32_e32 v9, v136, v12
	v_mul_f32_e32 v2, 0xbfb8aa3b, v9
	v_exp_f32_e32 v2, v2
	v_pk_mul_f32 v[12:13], v[150:151], v[20:21]
	v_cndmask_b32_e32 v8, v25, v3, vcc
	v_mul_f32_e32 v12, v12, v13
	v_add_f32_e32 v2, 1.0, v2
	v_rcp_f32_e32 v21, v2
	v_cndmask_b32_e64 v2, v3, v25, s[6:7]
	v_fma_f32 v13, v145, v3, v133
	v_mov_b32_dpp v8, v8 row_ror:2 row_mask:0xf bank_mask:0xf bound_ctrl:1
	v_mov_b32_dpp v2, v2 row_ror:1 row_mask:0xf bank_mask:0xf bound_ctrl:1
	v_fmac_f32_e32 v13, v141, v2
	v_fmac_f32_e32 v13, v137, v8
	v_mul_f32_e32 v2, 0xbfb8aa3b, v13
	v_exp_f32_e32 v3, v2
	v_cvt_pk_bf16_f32 v2, v16, v0
	v_mov_b32_e32 v8, v4
	v_pk_mul_f32 v[8:9], v[8:9], v[20:21]
	v_add_f32_e32 v0, 1.0, v3
	v_rcp_f32_e32 v21, v0
	v_cndmask_b32_e64 v0, v10, v26, s[6:7]
	v_cndmask_b32_e32 v3, v26, v10, vcc
	v_fma_f32 v15, v146, v10, v134
	v_mov_b32_dpp v0, v0 row_ror:1 row_mask:0xf bank_mask:0xf bound_ctrl:1
	v_mov_b32_dpp v3, v3 row_ror:2 row_mask:0xf bank_mask:0xf bound_ctrl:1
	v_fmac_f32_e32 v15, v142, v0
	v_fmac_f32_e32 v15, v138, v3
	v_mul_f32_e32 v0, 0xbfb8aa3b, v15
	v_exp_f32_e32 v0, v0
	v_cvt_pk_bf16_f32 v3, v14, v12
	v_mov_b32_e32 v12, v5
	v_pk_mul_f32 v[4:5], v[12:13], v[20:21]
	v_add_f32_e32 v0, 1.0, v0
	v_rcp_f32_e32 v21, v0
	v_cndmask_b32_e64 v0, v11, v27, s[6:7]
	v_cndmask_b32_e32 v10, v27, v11, vcc
	v_fmac_f32_e32 v135, v147, v11
	v_mov_b32_dpp v0, v0 row_ror:1 row_mask:0xf bank_mask:0xf bound_ctrl:1
	v_mov_b32_dpp v10, v10 row_ror:2 row_mask:0xf bank_mask:0xf bound_ctrl:1
	v_fmac_f32_e32 v135, v143, v0
	v_fmac_f32_e32 v135, v139, v10
	v_mul_f32_e32 v0, 0xbfb8aa3b, v135
	v_exp_f32_e32 v0, v0
	v_mov_b32_e32 v14, v6
	v_mul_f32_e32 v10, v8, v9
	v_pk_mul_f32 v[8:9], v[14:15], v[20:21]
	v_add_f32_e32 v0, 1.0, v0
	v_rcp_f32_e32 v21, v0
	v_mov_b32_e32 v134, v7
	v_mul_f32_e32 v0, v4, v5
	v_mul_f32_e32 v6, v8, v9
	v_pk_mul_f32 v[4:5], v[134:135], v[20:21]
	s_nop 0
	v_mul_f32_e32 v5, v4, v5
	v_cvt_pk_bf16_f32 v4, v10, v0
	v_add_u32_e32 v0, 0xf2000, v184
	v_cvt_pk_bf16_f32 v5, v6, v5
	global_store_dwordx4 v0, v[2:5], s[0:1] nt
	s_and_b64 vcc, exec, s[4:5]
	s_mov_b64 s[0:1], -1
	s_cbranch_vccnz .LBB0_1168
